# hazard-audited build: K-loop rescheduling, LDS-DMA up-proj, s_setprio, v_max canonicalisation removal (packed-f32 forwarding hazard respected), XCD barrier instead of cg grid.sync
# baseline (speedup 1.0000x reference)
; template <int MODE> ...
;   bf16x8 kf[4][2], kn[4][2];
;   if (wid < ntile) {
; #pragma unroll
;     for (int kt = 0; kt < 4; ++kt)
; #pragma unroll
;       for (int ks = 0; ks < 2; ++ks) kf[kt][ks] = *(const bf16x8*)(kbase + (size_t)(wid * 64 + kt * 16) * PW + ks * 32);
;   }
; #pragma unroll 1
;   for (int n = wid; n < ntile; n += 4) {
;     {
;       const int nn = n + 4 < ntile ? n + 4 : n;
; #pragma unroll
;       for (int kt = 0; kt < 4; ++kt)
; #pragma unroll
;         for (int ks = 0; ks < 2; ++ks) kn[kt][ks] = *(const bf16x8*)(kbase + (size_t)(nn * 64 + kt * 16) * PW + ks * 32);
;     }
;     unsigned base[4] = {0u, 0u, 0u, 0u};
;     u64 word[4] = {0ull, 0ull, 0ull, 0ull};
;     u64 zword[4] = {0ull, 0ull, 0ull, 0ull};
;     if (MODE == 2 && any_tie) {
; #pragma unroll
;       for (int j = 0; j < 4; ++j) base[j] = cnt[(4 * g + j) * 64 + n];
;     }
; #pragma unroll
;     for (int kt = 0; kt < 4; ++kt) {
;       f32x4 sh[4];
; #pragma unroll
;       for (int h = 0; h < 4; ++h) {
;         sh[h] = (f32x4){0.f, 0.f, 0.f, 0.f};
; #pragma unroll
;         for (int ks = 0; ks < 2; ++ks) sh[h] = MFMA16(qf[h][ks], kf[kt][ks], sh[h]);
;       }
; #pragma unroll
;       for (int j = 0; j < 4; ++j) {
;         float sc = w[j][0] * fmaxf(sh[0][j], 0.f) + w[j][1] * fmaxf(sh[1][j], 0.f) + w[j][2] * fmaxf(sh[2][j], 0.f) + w[j][3] * fmaxf(sh[3][j], 0.f);
;         sc += 0.0f;
;         const unsigned u = sortable(sc);
;         if (MODE == 4) {
;           const unsigned um = u & himask;
;           const bool eq = um == pfx[j], zr = u == 0x80000000u;
;           unsigned* qx = hist + (4 * g + j) * C1_HP + 512;
;           if (eq) {
;             const unsigned bin = u & bmask; atomicAdd(&hist[(4 * g + j) * C1_HP + (bin >> 1)], 1u << ((bin & 1u) * 16u));
;             if (!zr) { const unsigned idx = atomicAdd(&qx[320], 1u); if (idx < 64u) qx[256 + idx] = ((unsigned)n << 16) | ((unsigned)(kt * 16 + lr) << 10) | (u & 1023u); }
;           }
;           word[j] |= (u64)((unsigned)(__ballot(um > pfx[j]) >> (16 * g)) & 0xffffu) << (16 * kt);
;           zword[j] |= (u64)((unsigned)(__ballot(zr) >> (16 * g)) & 0xffffu) << (16 * kt);
;         } else if (MODE == 0 || MODE == 3) {
;           if (MODE == 3) base[j] += __popc((unsigned)(__ballot(u == 0x80000000u) >> (16 * g)) & 0xffffu);
.LBB0_993:
	s_waitcnt vmcnt(1)
	v_mov_b64_e32 v[78:79], v[66:67]
	v_mov_b64_e32 v[76:77], v[64:65]
	v_mov_b64_e32 v[66:67], v[42:43]
	v_mov_b64_e32 v[86:87], v[58:59]
	v_mov_b64_e32 v[96:97], v[50:51]
	v_mov_b64_e32 v[64:65], v[40:41]
	v_mov_b64_e32 v[84:85], v[56:57]
	v_mov_b64_e32 v[94:95], v[48:49]
	v_mfma_f32_16x16x32_f16 v[40:43], v[24:27], v[64:67], 0
	v_mov_b64_e32 v[100:101], v[46:47]
	v_mov_b64_e32 v[98:99], v[44:45]
	v_mov_b32_e32 v44, v89
	v_mfma_f32_16x16x32_f16 v[48:51], v[4:7], v[64:67], 0
	v_add_u32_e32 v89, 4, v44
	v_cmp_lt_i32_e32 vcc, s2, v89
	s_waitcnt vmcnt(0)
	v_mov_b64_e32 v[74:75], v[70:71]
	v_mfma_f32_16x16x32_f16 v[56:59], v[12:15], v[64:67], 0
	v_cndmask_b32_e32 v44, v89, v44, vcc
	v_mov_b64_e32 v[72:73], v[68:69]
	v_mov_b64_e32 v[82:83], v[62:63]
	v_mfma_f32_16x16x32_f16 v[154:157], v[20:23], v[64:67], 0
	v_mov_b64_e32 v[92:93], v[54:55]
	v_lshlrev_b32_e32 v68, 6, v44
	v_mov_b64_e32 v[80:81], v[60:61]
	v_mfma_f32_16x16x32_f16 v[136:139], v[0:3], v[98:101], v[40:43]
	v_mov_b64_e32 v[90:91], v[52:53]
	v_mad_i64_i32 v[44:45], s[4:5], v68, s0, v[122:123]
	v_mfma_f32_16x16x32_f16 v[140:143], v[8:11], v[98:101], v[48:51]
	v_or_b32_e32 v52, 16, v68
	s_nop 3
	v_max_f32_e32 v102, 0, v136
	v_mfma_f32_16x16x32_f16 v[144:147], v[16:19], v[98:101], v[56:59]
	v_or_b32_e32 v60, 32, v68
	v_max_f32_e32 v103, v140, v140
	v_max_f32_e32 v103, 0, v103
	v_mfma_f32_16x16x32_f16 v[98:101], v[28:31], v[98:101], v[154:157]
	v_mul_f32_e64 v102, v102, v106
	v_mul_f32_e64 v103, v103, v107
	s_nop 1
	v_max_f32_e32 v105, v144, v144
	v_mov_b32_e32 v140, v102
	v_max_f32_e32 v154, 0, v105
	v_or_b32_e32 v68, 48, v68
	v_max_f32_e32 v155, 0, v98
	v_max_f32_e32 v136, 0, v137
	v_max_f32_e32 v137, 0, v141
	v_pk_mul_f32 v[136:137], v[136:137], v[110:111]
	v_max_f32_e32 v98, 0, v145
	v_max_f32_e32 v99, 0, v99
	v_pk_mul_f32 v[154:155], v[154:155], v[108:109]
	v_pk_mul_f32 v[98:99], v[98:99], v[112:113]
	v_mov_b32_e32 v141, v136
	v_mov_b32_e32 v136, v103
	v_pk_add_f32 v[102:103], v[140:141], v[136:137]
	v_mov_b32_e32 v136, v154
	v_mov_b32_e32 v137, v98
	v_pk_add_f32 v[102:103], v[102:103], v[136:137]
	v_mov_b32_e32 v98, v155
	v_pk_add_f32 v[98:99], v[102:103], v[98:99]
	v_mad_i64_i32 v[52:53], s[4:5], v52, s0, v[122:123]
	v_pk_add_f32 v[98:99], v[98:99], 0 op_sel_hi:[1,0]
	v_mad_i64_i32 v[60:61], s[4:5], v60, s0, v[122:123]
	v_mad_i64_i32 v[68:69], s[4:5], v68, s0, v[122:123]
	v_and_b32_e32 v103, 0x7fffffff, v99
	v_and_b32_e32 v102, 0x7fffffff, v98
	v_xor_b32_e32 v105, -1, v99
	v_pk_add_f32 v[102:103], v[102:103], 0 neg_lo:[1,1] neg_hi:[1,1]
	v_cmp_gt_i32_e64 s[4:5], 0, v99
	v_xor_b32_e32 v135, -1, v98
	global_load_dwordx4 v[40:43], v[44:45], off
	s_nop 0
	global_load_dwordx4 v[44:47], v[44:45], off offset:64
	v_cndmask_b32_e64 v99, v103, v105, s[4:5]
	v_cmp_gt_i32_e64 s[4:5], 0, v98
	v_cmp_eq_u32_e64 s[50:51], v99, v33
	v_max_f32_e32 v99, v142, v142
	v_cndmask_b32_e64 v98, v102, v135, s[4:5]
	v_cmp_eq_u32_e64 s[48:49], v98, v32
	v_max_f32_e32 v98, 0, v138
	v_max_f32_e32 v99, 0, v99
	v_pk_mul_f32 v[102:103], v[98:99], v[114:115]
	v_max_f32_e32 v98, 0, v146
	v_max_f32_e32 v99, 0, v100
	v_pk_mul_f32 v[140:141], v[98:99], v[116:117]
	v_max_f32_e32 v98, 0, v139
	v_max_f32_e32 v99, 0, v143
	v_pk_mul_f32 v[136:137], v[98:99], v[118:119]
	v_max_f32_e32 v138, 0, v147
	v_max_f32_e32 v139, 0, v101
	v_pk_mul_f32 v[142:143], v[138:139], v[120:121]
	v_mov_b32_e32 v138, v102
	v_mov_b32_e32 v139, v136
	v_mov_b32_e32 v136, v103
	v_pk_add_f32 v[102:103], v[138:139], v[136:137]
	v_mov_b32_e32 v144, v140
	v_mov_b32_e32 v145, v142
	v_pk_add_f32 v[102:103], v[102:103], v[144:145]
	v_mov_b32_e32 v142, v141
	v_mfma_f32_16x16x32_f16 v[98:101], v[24:27], v[94:97], 0
	v_add_f32_e64 v102, v102, v142
	v_add_f32_e64 v103, v103, v143
	global_load_dwordx4 v[48:51], v[52:53], off
	s_nop 0
	global_load_dwordx4 v[52:55], v[52:53], off offset:64
	v_pk_add_f32 v[102:103], v[102:103], 0 op_sel_hi:[1,0]
	v_mfma_f32_16x16x32_f16 v[136:139], v[4:7], v[94:97], 0
	v_and_b32_e32 v145, 0x7fffffff, v103
	v_and_b32_e32 v144, 0x7fffffff, v102
	v_xor_b32_e32 v105, -1, v103
	v_mfma_f32_16x16x32_f16 v[140:143], v[12:15], v[94:97], 0
	v_add_f32_e64 v144, -v144, neg(0)
	v_add_f32_e64 v145, -v145, neg(0)
	v_cmp_gt_i32_e64 s[4:5], 0, v103
	v_xor_b32_e32 v135, -1, v102
	v_mfma_f32_16x16x32_f16 v[94:97], v[20:23], v[94:97], 0
	v_cndmask_b32_e64 v103, v145, v105, s[4:5]
	v_cmp_gt_i32_e64 s[4:5], 0, v102
	v_cmp_eq_u32_e64 s[54:55], v103, v35
	v_mfma_f32_16x16x32_f16 v[98:101], v[0:3], v[90:93], v[98:101]
	v_cndmask_b32_e64 v102, v144, v135, s[4:5]
	v_cmp_eq_u32_e64 s[52:53], v102, v34
	global_load_dwordx4 v[56:59], v[60:61], off
	s_nop 0
	global_load_dwordx4 v[60:63], v[60:61], off offset:64
	v_mfma_f32_16x16x32_f16 v[136:139], v[8:11], v[90:93], v[136:139]
	global_load_dwordx4 v[64:67], v[68:69], off
	s_nop 0
	global_load_dwordx4 v[68:71], v[68:69], off offset:64
	v_mfma_f32_16x16x32_f16 v[140:143], v[16:19], v[90:93], v[140:143]
	v_mfma_f32_16x16x32_f16 v[90:93], v[28:31], v[90:93], v[94:97]
	s_nop 2
	v_max_f32_e32 v94, v98, v98
	v_max_f32_e32 v95, v136, v136
	s_nop 2
	v_max_f32_e32 v97, 0, v90
	v_max_f32_e32 v98, 0, v99
	v_max_f32_e32 v94, 0, v94
	v_max_f32_e32 v95, 0, v95
	v_max_f32_e32 v99, 0, v137
	v_pk_mul_f32 v[94:95], v[94:95], v[106:107]
	v_max_f32_e32 v96, 0, v140
	v_pk_mul_f32 v[98:99], v[98:99], v[110:111]
	v_max_f32_e32 v90, 0, v141
	v_max_f32_e32 v91, 0, v91
	v_pk_mul_f32 v[96:97], v[96:97], v[108:109]
	v_pk_mul_f32 v[90:91], v[90:91], v[112:113]
	v_mov_b32_e32 v102, v94
	v_mov_b32_e32 v103, v98
	v_mov_b32_e32 v98, v95
	v_pk_add_f32 v[94:95], v[102:103], v[98:99]
	v_mov_b32_e32 v98, v96
; #define MFMA16(a, b, c) __builtin_amdgcn_mfma_f32_16x16x32_f16((a), (b), (c), 0, 0, 0)
; template <int MODE> ...
;     ...
; #pragma unroll
;     for (int kt = 0; kt < 4; ++kt) {
;       f32x4 sh[4];
; #pragma unroll
;       for (int h = 0; h < 4; ++h) {
;         sh[h] = (f32x4){0.f, 0.f, 0.f, 0.f};
; #pragma unroll
;         for (int ks = 0; ks < 2; ++ks) sh[h] = MFMA16(qf[h][ks], kf[kt][ks], sh[h]);
;       }
; #pragma unroll
;       for (int j = 0; j < 4; ++j) {
;         float sc = w[j][0] * fmaxf(sh[0][j], 0.f) + w[j][1] * fmaxf(sh[1][j], 0.f) + w[j][2] * fmaxf(sh[2][j], 0.f) + w[j][3] * fmaxf(sh[3][j], 0.f);
;         sc += 0.0f;
;         const unsigned u = sortable(sc);
;         if (MODE == 4) {
;           const unsigned um = u & himask;
;           const bool eq = um == pfx[j], zr = u == 0x80000000u;
;           unsigned* qx = hist + (4 * g + j) * C1_HP + 512;
;           if (eq) {
;             const unsigned bin = u & bmask; atomicAdd(&hist[(4 * g + j) * C1_HP + (bin >> 1)], 1u << ((bin & 1u) * 16u));
;             if (!zr) { const unsigned idx = atomicAdd(&qx[320], 1u); if (idx < 64u) qx[256 + idx] = ((unsigned)n << 16) | ((unsigned)(kt * 16 + lr) << 10) | (u & 1023u); }
;           }
;           word[j] |= (u64)((unsigned)(__ballot(um > pfx[j]) >> (16 * g)) & 0xffffu) << (16 * kt);
;           zword[j] |= (u64)((unsigned)(__ballot(zr) >> (16 * g)) & 0xffffu) << (16 * kt);
;         } else if (MODE == 0 || MODE == 3) {
;           if (MODE == 3) base[j] += __popc((unsigned)(__ballot(u == 0x80000000u) >> (16 * g)) & 0xffffu);
;           if (((u ^ pfx[j]) & himask) == 0u) { const unsigned bin = (u >> shift) & bmask; atomicAdd(&hist[(4 * g + j) * C1_HP + (bin >> 1)], 1u << ((bin & 1u) * 16u)); }
;         } else {
;           const bool eq = u == pfx[j];
;           const unsigned fe = (unsigned)(__ballot(eq) >> (16 * g)) & 0xffffu;
;           if (MODE == 1) {
;             base[j] += __popc(fe);
;           } else {
;             const unsigned rank = base[j] + __popc(fe & ((1u << lr) - 1u));
;             const bool sel = (u > pfx[j]) || (eq && rank < need[j]);
;             base[j] += __popc(fe);
;             const unsigned fs = (unsigned)(__ballot(sel) >> (16 * g)) & 0xffffu;
;             word[j] |= (u64)fs << (16 * kt);
;           }
;         }
;       }
;     }
	v_mov_b32_e32 v99, v90
	v_pk_add_f32 v[94:95], v[94:95], v[98:99]
	v_mov_b32_e32 v90, v97
	v_pk_add_f32 v[90:91], v[94:95], v[90:91]
	s_nop 0
	v_pk_add_f32 v[90:91], v[90:91], 0 op_sel_hi:[1,0]
	s_nop 0
	v_and_b32_e32 v95, 0x7fffffff, v91
	v_and_b32_e32 v94, 0x7fffffff, v90
	v_xor_b32_e32 v96, -1, v91
	v_pk_add_f32 v[94:95], v[94:95], 0 neg_lo:[1,1] neg_hi:[1,1]
	v_cmp_gt_i32_e64 s[4:5], 0, v91
	v_xor_b32_e32 v97, -1, v90
	s_nop 0
	v_cndmask_b32_e64 v91, v95, v96, s[4:5]
	v_cmp_gt_i32_e64 s[4:5], 0, v90
	v_cmp_eq_u32_e64 s[58:59], v91, v33
	v_max_f32_e32 v91, v138, v138
	v_cndmask_b32_e64 v90, v94, v97, s[4:5]
	v_cmp_eq_u32_e64 s[56:57], v90, v32
	v_max_f32_e32 v90, 0, v100
	v_max_f32_e32 v91, 0, v91
	v_pk_mul_f32 v[94:95], v[90:91], v[114:115]
	v_max_f32_e32 v90, 0, v142
	v_max_f32_e32 v91, 0, v92
	v_pk_mul_f32 v[98:99], v[90:91], v[116:117]
	v_max_f32_e32 v90, 0, v101
	v_max_f32_e32 v91, 0, v139
	v_pk_mul_f32 v[96:97], v[90:91], v[118:119]
	v_max_f32_e32 v100, 0, v143
	v_max_f32_e32 v101, 0, v93
	v_pk_mul_f32 v[100:101], v[100:101], v[120:121]
	v_mov_b32_e32 v102, v94
	v_mov_b32_e32 v103, v96
	v_mov_b32_e32 v96, v95
	v_pk_add_f32 v[102:103], v[102:103], v[96:97]
	v_mov_b32_e32 v136, v98
	v_mov_b32_e32 v137, v100
	v_pk_add_f32 v[102:103], v[102:103], v[136:137]
	v_mov_b32_e32 v100, v99
	v_pk_add_f32 v[98:99], v[102:103], v[100:101]
	v_mfma_f32_16x16x32_f16 v[90:93], v[24:27], v[84:87], 0
	v_add_f32_e64 v102, v98, 0
	v_add_f32_e64 v103, v99, 0
	v_and_b32_e32 v137, 0x7fffffff, v103
	v_mfma_f32_16x16x32_f16 v[94:97], v[4:7], v[84:87], 0
	v_and_b32_e32 v136, 0x7fffffff, v102
	v_xor_b32_e32 v105, -1, v103
	v_pk_add_f32 v[136:137], v[136:137], 0 neg_lo:[1,1] neg_hi:[1,1]
	v_mfma_f32_16x16x32_f16 v[98:101], v[12:15], v[84:87], 0
	v_cmp_gt_i32_e64 s[4:5], 0, v103
	v_xor_b32_e32 v135, -1, v102
	v_mfma_f32_16x16x32_f16 v[84:87], v[20:23], v[84:87], 0
	v_cndmask_b32_e64 v103, v137, v105, s[4:5]
	v_cmp_gt_i32_e64 s[4:5], 0, v102
	v_cmp_eq_u32_e64 s[6:7], v103, v35
	v_mfma_f32_16x16x32_f16 v[90:93], v[0:3], v[80:83], v[90:93]
	v_cndmask_b32_e64 v102, v136, v135, s[4:5]
	v_cmp_eq_u32_e64 s[4:5], v102, v34
	v_mfma_f32_16x16x32_f16 v[94:97], v[8:11], v[80:83], v[94:97]
	v_mfma_f32_16x16x32_f16 v[98:101], v[16:19], v[80:83], v[98:101]
	v_mfma_f32_16x16x32_f16 v[80:83], v[28:31], v[80:83], v[84:87]
	s_nop 2
	v_max_f32_e32 v84, v90, v90
	s_nop 1
	v_max_f32_e32 v85, v94, v94
	s_nop 0
	v_max_f32_e32 v87, 0, v80
	v_max_f32_e32 v90, 0, v91
	v_max_f32_e32 v84, 0, v84
	v_max_f32_e32 v85, 0, v85
	v_max_f32_e32 v91, 0, v95
	v_pk_mul_f32 v[84:85], v[84:85], v[106:107]
	v_max_f32_e32 v86, 0, v98
	v_pk_mul_f32 v[90:91], v[90:91], v[110:111]
	v_max_f32_e32 v80, 0, v99
	v_max_f32_e32 v81, 0, v81
	v_pk_mul_f32 v[86:87], v[86:87], v[108:109]
	v_pk_mul_f32 v[80:81], v[80:81], v[112:113]
	v_mov_b32_e32 v94, v84
	v_mov_b32_e32 v95, v90
	v_mov_b32_e32 v90, v85
	v_pk_add_f32 v[84:85], v[94:95], v[90:91]
	v_mov_b32_e32 v90, v86
	v_mov_b32_e32 v91, v80
	v_pk_add_f32 v[84:85], v[84:85], v[90:91]
	v_mov_b32_e32 v80, v87
	v_pk_add_f32 v[80:81], v[84:85], v[80:81]
	s_nop 0
	v_pk_add_f32 v[80:81], v[80:81], 0 op_sel_hi:[1,0]
	s_nop 0
	v_and_b32_e32 v85, 0x7fffffff, v81
	v_and_b32_e32 v84, 0x7fffffff, v80
	v_xor_b32_e32 v86, -1, v81
	v_pk_add_f32 v[84:85], v[84:85], 0 neg_lo:[1,1] neg_hi:[1,1]
	v_cmp_gt_i32_e64 s[8:9], 0, v81
	v_xor_b32_e32 v87, -1, v80
	s_nop 0
	v_cndmask_b32_e64 v81, v85, v86, s[8:9]
	v_cmp_gt_i32_e64 s[8:9], 0, v80
	v_cmp_eq_u32_e64 s[10:11], v81, v33
	v_max_f32_e32 v81, v96, v96
	v_cndmask_b32_e64 v80, v84, v87, s[8:9]
	v_cmp_eq_u32_e64 s[8:9], v80, v32
	v_max_f32_e32 v80, 0, v92
	v_max_f32_e32 v81, 0, v81
	v_pk_mul_f32 v[84:85], v[80:81], v[114:115]
	v_max_f32_e32 v80, 0, v100
	v_max_f32_e32 v81, 0, v82
	v_pk_mul_f32 v[90:91], v[80:81], v[116:117]
	v_max_f32_e32 v80, 0, v93
	v_max_f32_e32 v81, 0, v97
	v_pk_mul_f32 v[86:87], v[80:81], v[118:119]
	v_max_f32_e32 v92, 0, v101
	v_max_f32_e32 v93, 0, v83
	v_pk_mul_f32 v[92:93], v[92:93], v[120:121]
	v_mov_b32_e32 v94, v84
	v_mov_b32_e32 v95, v86
	v_mov_b32_e32 v86, v85
	v_pk_add_f32 v[94:95], v[94:95], v[86:87]
	v_mov_b32_e32 v96, v90
	v_mov_b32_e32 v97, v92
	v_pk_add_f32 v[94:95], v[94:95], v[96:97]
	v_mov_b32_e32 v92, v91
	v_pk_add_f32 v[90:91], v[94:95], v[92:93]
	v_mfma_f32_16x16x32_f16 v[80:83], v[24:27], v[76:79], 0
	v_add_f32_e64 v94, v90, 0
	v_add_f32_e64 v95, v91, 0
	v_and_b32_e32 v97, 0x7fffffff, v95
	v_mfma_f32_16x16x32_f16 v[84:87], v[4:7], v[76:79], 0
	v_and_b32_e32 v96, 0x7fffffff, v94
	v_xor_b32_e32 v98, -1, v95
	v_pk_add_f32 v[96:97], v[96:97], 0 neg_lo:[1,1] neg_hi:[1,1]
	v_mfma_f32_16x16x32_f16 v[90:93], v[12:15], v[76:79], 0
	v_cmp_gt_i32_e64 s[12:13], 0, v95
	v_xor_b32_e32 v99, -1, v94
	v_mfma_f32_16x16x32_f16 v[76:79], v[20:23], v[76:79], 0
	v_cndmask_b32_e64 v95, v97, v98, s[12:13]
; template <int MODE> ...
;     ...
; #pragma unroll
;     for (int kt = 0; kt < 4; ++kt) {
;       f32x4 sh[4];
; #pragma unroll
;       for (int h = 0; h < 4; ++h) {
;         sh[h] = (f32x4){0.f, 0.f, 0.f, 0.f};
; #pragma unroll
;         for (int ks = 0; ks < 2; ++ks) sh[h] = MFMA16(qf[h][ks], kf[kt][ks], sh[h]);
;       }
; #pragma unroll
;       for (int j = 0; j < 4; ++j) {
;         float sc = w[j][0] * fmaxf(sh[0][j], 0.f) + w[j][1] * fmaxf(sh[1][j], 0.f) + w[j][2] * fmaxf(sh[2][j], 0.f) + w[j][3] * fmaxf(sh[3][j], 0.f);
;         sc += 0.0f;
;         const unsigned u = sortable(sc);
;         if (MODE == 4) {
;           const unsigned um = u & himask;
;           const bool eq = um == pfx[j], zr = u == 0x80000000u;
;           unsigned* qx = hist + (4 * g + j) * C1_HP + 512;
;           if (eq) {
;             const unsigned bin = u & bmask; atomicAdd(&hist[(4 * g + j) * C1_HP + (bin >> 1)], 1u << ((bin & 1u) * 16u));
;             if (!zr) { const unsigned idx = atomicAdd(&qx[320], 1u); if (idx < 64u) qx[256 + idx] = ((unsigned)n << 16) | ((unsigned)(kt * 16 + lr) << 10) | (u & 1023u); }
;           }
;           word[j] |= (u64)((unsigned)(__ballot(um > pfx[j]) >> (16 * g)) & 0xffffu) << (16 * kt);
;           zword[j] |= (u64)((unsigned)(__ballot(zr) >> (16 * g)) & 0xffffu) << (16 * kt);
;         } else if (MODE == 0 || MODE == 3) {
;           if (MODE == 3) base[j] += __popc((unsigned)(__ballot(u == 0x80000000u) >> (16 * g)) & 0xffffu);
;           if (((u ^ pfx[j]) & himask) == 0u) { const unsigned bin = (u >> shift) & bmask; atomicAdd(&hist[(4 * g + j) * C1_HP + (bin >> 1)], 1u << ((bin & 1u) * 16u)); }
;         } else {
;           const bool eq = u == pfx[j];
;           const unsigned fe = (unsigned)(__ballot(eq) >> (16 * g)) & 0xffffu;
;           if (MODE == 1) {
;             base[j] += __popc(fe);
;           } else {
;             const unsigned rank = base[j] + __popc(fe & ((1u << lr) - 1u));
;             const bool sel = (u > pfx[j]) || (eq && rank < need[j]);
;             base[j] += __popc(fe);
;             const unsigned fs = (unsigned)(__ballot(sel) >> (16 * g)) & 0xffffu;
;             word[j] |= (u64)fs << (16 * kt);
;           }
;         }
;       }
;     }
;     if ((MODE == 1 || MODE == 3) && lr == 0) {
; #pragma unroll
;       for (int j = 0; j < 4; ++j) cnt[(4 * g + j) * 64 + n] = (unsigned short)base[j];
;     }
	v_cmp_gt_i32_e64 s[12:13], 0, v94
	v_cmp_eq_u32_e64 s[14:15], v95, v35
	v_mfma_f32_16x16x32_f16 v[80:83], v[0:3], v[72:75], v[80:83]
	v_cndmask_b32_e64 v94, v96, v99, s[12:13]
	v_cmp_eq_u32_e64 s[12:13], v94, v34
	v_mfma_f32_16x16x32_f16 v[84:87], v[8:11], v[72:75], v[84:87]
	v_mfma_f32_16x16x32_f16 v[90:93], v[16:19], v[72:75], v[90:93]
	v_mfma_f32_16x16x32_f16 v[72:75], v[28:31], v[72:75], v[76:79]
	s_nop 2
	v_max_f32_e32 v76, v80, v80
	s_nop 1
	v_max_f32_e32 v77, v84, v84
	s_nop 0
	v_max_f32_e32 v79, 0, v72
	v_max_f32_e32 v80, 0, v81
	v_max_f32_e32 v76, 0, v76
	v_max_f32_e32 v77, 0, v77
	v_max_f32_e32 v81, 0, v85
	v_pk_mul_f32 v[76:77], v[76:77], v[106:107]
	v_max_f32_e32 v78, 0, v90
	v_pk_mul_f32 v[80:81], v[80:81], v[110:111]
	v_max_f32_e32 v72, 0, v91
	v_max_f32_e32 v73, 0, v73
	v_pk_mul_f32 v[78:79], v[78:79], v[108:109]
	v_pk_mul_f32 v[72:73], v[72:73], v[112:113]
	v_mov_b32_e32 v84, v76
	v_mov_b32_e32 v85, v80
	v_mov_b32_e32 v80, v77
	v_pk_add_f32 v[76:77], v[84:85], v[80:81]
	v_mov_b32_e32 v80, v78
	v_mov_b32_e32 v81, v72
	v_pk_add_f32 v[76:77], v[76:77], v[80:81]
	v_mov_b32_e32 v72, v79
	v_pk_add_f32 v[72:73], v[76:77], v[72:73]
	v_max_f32_e32 v74, v74, v74
	v_pk_add_f32 v[72:73], v[72:73], 0 op_sel_hi:[1,0]
	v_max_f32_e32 v75, v75, v75
	v_and_b32_e32 v77, 0x7fffffff, v73
	v_and_b32_e32 v76, 0x7fffffff, v72
	v_xor_b32_e32 v78, -1, v73
	v_pk_add_f32 v[76:77], v[76:77], 0 neg_lo:[1,1] neg_hi:[1,1]
	v_cmp_gt_i32_e64 s[16:17], 0, v73
	v_xor_b32_e32 v79, -1, v72
	v_max_f32_e32 v75, 0, v75
	v_cndmask_b32_e64 v73, v77, v78, s[16:17]
	v_cmp_gt_i32_e64 s[16:17], 0, v72
	v_max_f32_e32 v77, 0, v74
	v_max_f32_e32 v74, v83, v83
	v_cndmask_b32_e64 v72, v76, v79, s[16:17]
	v_cmp_eq_u32_e64 s[16:17], v72, v32
	v_cmp_eq_u32_e64 s[18:19], v73, v33
	v_max_f32_e32 v78, 0, v74
	v_max_f32_e32 v72, 0, v82
	v_max_f32_e32 v73, 0, v86
	v_max_f32_e32 v79, 0, v87
	v_pk_mul_f32 v[72:73], v[72:73], v[114:115]
	v_max_f32_e32 v76, 0, v92
	v_pk_mul_f32 v[78:79], v[78:79], v[118:119]
	v_max_f32_e32 v74, 0, v93
	v_pk_mul_f32 v[76:77], v[76:77], v[116:117]
	v_pk_mul_f32 v[74:75], v[74:75], v[120:121]
	v_mov_b32_e32 v80, v72
	v_mov_b32_e32 v81, v78
	v_mov_b32_e32 v78, v73
	v_pk_add_f32 v[72:73], v[80:81], v[78:79]
	v_mov_b32_e32 v78, v76
	v_mov_b32_e32 v79, v74
	v_pk_add_f32 v[72:73], v[72:73], v[78:79]
	v_mov_b32_e32 v74, v77
	v_pk_add_f32 v[72:73], v[72:73], v[74:75]
	s_nop 0
	v_pk_add_f32 v[72:73], v[72:73], 0 op_sel_hi:[1,0]
	s_nop 0
	v_and_b32_e32 v75, 0x7fffffff, v73
	v_and_b32_e32 v74, 0x7fffffff, v72
	v_xor_b32_e32 v76, -1, v73
	v_pk_add_f32 v[74:75], v[74:75], 0 neg_lo:[1,1] neg_hi:[1,1]
	v_cmp_gt_i32_e64 s[20:21], 0, v73
	v_xor_b32_e32 v77, -1, v72
	s_nop 0
	v_cndmask_b32_e64 v73, v75, v76, s[20:21]
	v_cmp_gt_i32_e64 s[20:21], 0, v72
	v_cmp_eq_u32_e64 s[22:23], v73, v35
	s_nop 0
	v_cndmask_b32_e64 v72, v74, v77, s[20:21]
	v_cmp_eq_u32_e64 s[20:21], v72, v34
	s_and_saveexec_b64 s[36:37], s[40:41]
	s_cbranch_execz .LBB0_992
	v_lshrrev_b64 v[72:73], v150, s[22:23]
	v_and_b32_e32 v72, 0xffff, v72
	v_bcnt_u32_b32 v74, v72, 0
	v_lshrrev_b64 v[72:73], v150, s[14:15]
	v_and_b32_e32 v72, 0xffff, v72
	v_bcnt_u32_b32 v75, v72, 0
	v_lshrrev_b64 v[72:73], v150, s[6:7]
	v_and_b32_e32 v76, 0xffff, v72
	v_lshrrev_b64 v[72:73], v150, s[54:55]
	v_and_b32_e32 v72, 0xffff, v72
	v_bcnt_u32_b32 v72, v72, 0
	v_bcnt_u32_b32 v72, v76, v72
	v_add3_u32 v74, v72, v75, v74
	v_lshrrev_b64 v[72:73], v150, s[20:21]
	v_and_b32_e32 v72, 0xffff, v72
	v_bcnt_u32_b32 v75, v72, 0
	v_lshrrev_b64 v[72:73], v150, s[12:13]
	v_and_b32_e32 v72, 0xffff, v72
	v_bcnt_u32_b32 v76, v72, 0
	v_lshrrev_b64 v[72:73], v150, s[4:5]
	v_and_b32_e32 v77, 0xffff, v72
	v_lshrrev_b64 v[72:73], v150, s[52:53]
	v_and_b32_e32 v72, 0xffff, v72
	v_bcnt_u32_b32 v72, v72, 0
	v_bcnt_u32_b32 v72, v77, v72
	v_add3_u32 v75, v72, v76, v75
	v_lshrrev_b64 v[72:73], v150, s[18:19]
	v_and_b32_e32 v72, 0xffff, v72
	v_bcnt_u32_b32 v76, v72, 0
	v_lshrrev_b64 v[72:73], v150, s[10:11]
	v_and_b32_e32 v72, 0xffff, v72
	v_bcnt_u32_b32 v77, v72, 0
	v_lshrrev_b64 v[72:73], v150, s[58:59]
	v_and_b32_e32 v78, 0xffff, v72
	v_lshrrev_b64 v[72:73], v150, s[50:51]
	v_and_b32_e32 v72, 0xffff, v72
	v_bcnt_u32_b32 v72, v72, 0
	v_bcnt_u32_b32 v72, v78, v72
	v_add3_u32 v76, v72, v77, v76
	v_lshrrev_b64 v[72:73], v150, s[16:17]
	v_and_b32_e32 v72, 0xffff, v72
	v_bcnt_u32_b32 v77, v72, 0
	v_lshrrev_b64 v[72:73], v150, s[8:9]
	v_and_b32_e32 v72, 0xffff, v72
	v_bcnt_u32_b32 v78, v72, 0
	v_lshrrev_b64 v[72:73], v150, s[56:57]
	v_and_b32_e32 v79, 0xffff, v72
	v_lshrrev_b64 v[72:73], v150, s[48:49]
	v_and_b32_e32 v72, 0xffff, v72
	v_bcnt_u32_b32 v72, v72, 0
	v_bcnt_u32_b32 v72, v79, v72
	v_add3_u32 v72, v72, v78, v77
	ds_write_b16 v88, v72
	ds_write_b16 v88, v76 offset:128
	ds_write_b16 v88, v75 offset:256
	ds_write_b16 v88, v74 offset:384
	s_branch .LBB0_992

; template <int MODE> ...
;     ...
; #pragma unroll
;     for (int kt = 0; kt < 4; ++kt) {
;       f32x4 sh[4];
; #pragma unroll
;       for (int h = 0; h < 4; ++h) {
;         sh[h] = (f32x4){0.f, 0.f, 0.f, 0.f};
; #pragma unroll
;         for (int ks = 0; ks < 2; ++ks) sh[h] = MFMA16(qf[h][ks], kf[kt][ks], sh[h]);
;       }
; #pragma unroll
;       for (int j = 0; j < 4; ++j) {
;         float sc = w[j][0] * fmaxf(sh[0][j], 0.f) + w[j][1] * fmaxf(sh[1][j], 0.f) + w[j][2] * fmaxf(sh[2][j], 0.f) + w[j][3] * fmaxf(sh[3][j], 0.f);
;         sc += 0.0f;
;         const unsigned u = sortable(sc);
;         if (MODE == 4) {
;           const unsigned um = u & himask;
;           const bool eq = um == pfx[j], zr = u == 0x80000000u;
;           unsigned* qx = hist + (4 * g + j) * C1_HP + 512;
;           if (eq) {
;             const unsigned bin = u & bmask; atomicAdd(&hist[(4 * g + j) * C1_HP + (bin >> 1)], 1u << ((bin & 1u) * 16u));
;             if (!zr) { const unsigned idx = atomicAdd(&qx[320], 1u); if (idx < 64u) qx[256 + idx] = ((unsigned)n << 16) | ((unsigned)(kt * 16 + lr) << 10) | (u & 1023u); }
;           }
;           word[j] |= (u64)((unsigned)(__ballot(um > pfx[j]) >> (16 * g)) & 0xffffu) << (16 * kt);
;           zword[j] |= (u64)((unsigned)(__ballot(zr) >> (16 * g)) & 0xffffu) << (16 * kt);
;         } else if (MODE == 0 || MODE == 3) {
;           if (MODE == 3) base[j] += __popc((unsigned)(__ballot(u == 0x80000000u) >> (16 * g)) & 0xffffu);
;           if (((u ^ pfx[j]) & himask) == 0u) { const unsigned bin = (u >> shift) & bmask; atomicAdd(&hist[(4 * g + j) * C1_HP + (bin >> 1)], 1u << ((bin & 1u) * 16u)); }
;         } else {
;           const bool eq = u == pfx[j];
;           const unsigned fe = (unsigned)(__ballot(eq) >> (16 * g)) & 0xffffu;
;           if (MODE == 1) {
;             base[j] += __popc(fe);
;           } else {
;             const unsigned rank = base[j] + __popc(fe & ((1u << lr) - 1u));
;             const bool sel = (u > pfx[j]) || (eq && rank < need[j]);
;             base[j] += __popc(fe);
;             const unsigned fs = (unsigned)(__ballot(sel) >> (16 * g)) & 0xffffu;
;             word[j] |= (u64)fs << (16 * kt);
;           }
;         }
;       }
;     }
;     if ((MODE == 1 || MODE == 3) && lr == 0) {
; #pragma unroll
;       for (int j = 0; j < 4; ++j) cnt[(4 * g + j) * 64 + n] = (unsigned short)base[j];
;     }
.LBB0_1005:
	s_waitcnt vmcnt(15)
	v_mfma_f32_16x16x32_f16 v[132:135], v[24:27], v[100:103], 0
	v_mfma_f32_16x16x32_f16 v[136:139], v[4:7], v[100:103], 0
	v_mfma_f32_16x16x32_f16 v[140:143], v[12:15], v[100:103], 0
	v_mfma_f32_16x16x32_f16 v[100:103], v[20:23], v[100:103], 0
	s_waitcnt vmcnt(14)
	v_mfma_f32_16x16x32_f16 v[132:135], v[0:3], v[96:99], v[132:135]
	v_mfma_f32_16x16x32_f16 v[136:139], v[8:11], v[96:99], v[136:139]
	v_mfma_f32_16x16x32_f16 v[140:143], v[16:19], v[96:99], v[140:143]
	s_nop 5
	v_max_f32_e32 v144, 0, v132
	v_mfma_f32_16x16x32_f16 v[96:99], v[28:31], v[96:99], v[100:103]
	v_max_f32_e32 v145, 0, v136
	v_max_f32_e32 v132, v140, v140
	v_pk_mul_f32 v[144:145], v[144:145], v[106:107]
	v_max_f32_e32 v146, 0, v132
	s_nop 3
	v_max_f32_e32 v147, 0, v96
	v_pk_mul_f32 v[100:101], v[146:147], v[108:109]
	v_add_f32_e32 v96, v144, v145
	v_add_f32_e32 v96, v96, v100
	v_add_f32_e32 v96, v96, v101
	v_add_f32_e32 v96, 0, v96
	v_not_b32_e32 v100, v96
	v_or_b32_e32 v101, 0x80000000, v96
	v_cmp_gt_i32_e32 vcc, 0, v96
	v_max_f32_e32 v97, v97, v97
	v_max_f32_e32 v98, v98, v98
	v_cndmask_b32_e32 v96, v101, v100, vcc
	v_cmp_gt_u32_e32 vcc, v96, v32
	v_max_f32_e32 v97, 0, v97
	v_max_f32_e32 v99, v99, v99
	v_cndmask_b32_e64 v102, 0, 1, vcc
	v_cmp_eq_u32_e32 vcc, v96, v32
	v_max_f32_e32 v99, 0, v99
	s_nop 0
	v_lshrrev_b64 v[100:101], v150, vcc
	v_and_b32_e32 v96, 0xffff, v100
	v_and_b32_e32 v100, v100, v105
	s_waitcnt lgkmcnt(3)
	v_bcnt_u32_b32 v100, v100, v131
	v_cmp_lt_u32_e64 s[4:5], v100, v36
	v_bcnt_u32_b32 v144, v96, v131
	s_nop 0
	v_cndmask_b32_e64 v100, 0, 1, s[4:5]
	v_cndmask_b32_e32 v100, v102, v100, vcc
	v_and_b32_e32 v96, 1, v100
	v_cmp_ne_u32_e32 vcc, 0, v96
	v_max_f32_e32 v100, 0, v133
	v_max_f32_e32 v101, 0, v137
	v_pk_mul_f32 v[136:137], v[100:101], v[110:111]
	v_max_f32_e32 v96, 0, v141
	v_max_f32_e32 v101, 0, v98
	v_pk_mul_f32 v[140:141], v[96:97], v[112:113]
	v_max_f32_e32 v102, 0, v135
	v_max_f32_e32 v96, 0, v134
	v_max_f32_e32 v97, 0, v138
	v_max_f32_e32 v103, 0, v139
	v_pk_mul_f32 v[96:97], v[96:97], v[114:115]
	v_max_f32_e32 v100, 0, v142
	v_pk_mul_f32 v[102:103], v[102:103], v[118:119]
	v_max_f32_e32 v98, 0, v143
	v_pk_mul_f32 v[100:101], v[100:101], v[116:117]
	v_pk_mul_f32 v[98:99], v[98:99], v[120:121]
	v_mov_b32_e32 v132, v96
	v_mov_b32_e32 v133, v102
	v_mov_b32_e32 v102, v97
	v_pk_add_f32 v[96:97], v[132:133], v[102:103]
	v_mov_b32_e32 v102, v100
	v_mov_b32_e32 v103, v98
	v_pk_add_f32 v[96:97], v[96:97], v[102:103]
	v_mov_b32_e32 v98, v101
	v_pk_add_f32 v[96:97], v[96:97], v[98:99]
	s_nop 0
	v_pk_add_f32 v[96:97], v[96:97], 0 op_sel_hi:[1,0]
	s_nop 0
	v_and_b32_e32 v99, 0x7fffffff, v97
	v_and_b32_e32 v98, 0x7fffffff, v96
	v_xor_b32_e32 v101, -1, v96
	v_pk_add_f32 v[98:99], v[98:99], 0 neg_lo:[1,1] neg_hi:[1,1]
	v_cmp_gt_i32_e64 s[4:5], 0, v96
	v_xor_b32_e32 v100, -1, v97
	s_nop 0
	v_cndmask_b32_e64 v101, v98, v101, s[4:5]
	v_cmp_gt_u32_e64 s[6:7], v101, v34
	v_cmp_gt_i32_e64 s[4:5], 0, v97
	s_nop 0
	v_cndmask_b32_e64 v131, 0, 1, s[6:7]
	v_cmp_eq_u32_e64 s[6:7], v101, v34
	v_cndmask_b32_e64 v96, v99, v100, s[4:5]
	v_cmp_gt_u32_e64 s[4:5], v96, v35
	v_lshrrev_b64 v[100:101], v150, s[6:7]
	v_and_b32_e32 v132, 0xffff, v100
	v_and_b32_e32 v100, v100, v105
	s_waitcnt lgkmcnt(1)
	v_bcnt_u32_b32 v133, v100, v130
	v_cmp_lt_u32_e64 s[8:9], v133, v38
	v_cndmask_b32_e64 v138, 0, 1, s[4:5]
	v_cmp_eq_u32_e64 s[4:5], v96, v35
	v_cndmask_b32_e64 v133, 0, 1, s[8:9]
	v_cndmask_b32_e64 v131, v131, v133, s[6:7]
	s_waitcnt vmcnt(13)
	v_mfma_f32_16x16x32_f16 v[96:99], v[24:27], v[92:95], 0
	v_bcnt_u32_b32 v139, v132, v130
	v_and_b32_e32 v130, 1, v131
	v_cmp_ne_u32_e64 s[44:45], 0, v130
	v_mfma_f32_16x16x32_f16 v[100:103], v[4:7], v[92:95], 0
	v_lshrrev_b64 v[134:135], v150, s[4:5]
	v_and_b32_e32 v135, 0xffff, v134
	v_and_b32_e32 v134, v134, v105
	v_mfma_f32_16x16x32_f16 v[130:133], v[12:15], v[92:95], 0
	s_waitcnt lgkmcnt(0)
	v_bcnt_u32_b32 v134, v134, v129
	v_cmp_lt_u32_e64 s[6:7], v134, v39
	v_mfma_f32_16x16x32_f16 v[92:95], v[20:23], v[92:95], 0
	s_nop 0
	v_cndmask_b32_e64 v134, 0, 1, s[6:7]
	v_cndmask_b32_e64 v134, v138, v134, s[4:5]
	v_bcnt_u32_b32 v138, v135, v129
	s_waitcnt vmcnt(12)
	v_mfma_f32_16x16x32_f16 v[96:99], v[0:3], v[88:91], v[96:99]
	v_and_b32_e32 v129, 1, v134
	v_mov_b32_e32 v135, v136
	v_cmp_ne_u32_e64 s[48:49], 0, v129
	v_mfma_f32_16x16x32_f16 v[100:103], v[8:11], v[88:91], v[100:103]
	v_mfma_f32_16x16x32_f16 v[130:133], v[16:19], v[88:91], v[130:133]
	v_mfma_f32_16x16x32_f16 v[88:91], v[28:31], v[88:91], v[92:95]
	s_nop 2
	s_nop 1
	v_max_f32_e32 v92, 0, v96
	v_max_f32_e32 v93, 0, v100
	v_pk_mul_f32 v[92:93], v[92:93], v[106:107]
	v_max_f32_e32 v94, 0, v130
	v_max_f32_e32 v95, 0, v88
	v_pk_mul_f32 v[94:95], v[94:95], v[108:109]
	v_mov_b32_e32 v134, v92
	v_mov_b32_e32 v136, v93
	v_pk_add_f32 v[92:93], v[134:135], v[136:137]
	v_mov_b32_e32 v134, v94
	v_mov_b32_e32 v135, v140
	v_pk_add_f32 v[92:93], v[92:93], v[134:135]
	v_mov_b32_e32 v140, v95
	v_pk_add_f32 v[92:93], v[92:93], v[140:141]
	v_max_f32_e32 v89, v89, v89
	v_pk_add_f32 v[92:93], v[92:93], 0 op_sel_hi:[1,0]
	v_max_f32_e32 v90, v90, v90
	v_and_b32_e32 v95, 0x7fffffff, v93
	v_and_b32_e32 v94, 0x7fffffff, v92
	v_xor_b32_e32 v88, -1, v93
	v_pk_add_f32 v[94:95], v[94:95], 0 neg_lo:[1,1] neg_hi:[1,1]
	v_cmp_gt_i32_e64 s[4:5], 0, v93
	v_xor_b32_e32 v96, -1, v92
	v_max_f32_e32 v89, 0, v89
	v_cndmask_b32_e64 v88, v95, v88, s[4:5]
	v_cmp_gt_i32_e64 s[4:5], 0, v92
	v_cmp_gt_u32_e64 s[6:7], v88, v33
	v_max_f32_e32 v91, v91, v91
	v_cndmask_b32_e64 v92, v94, v96, s[4:5]
	v_cmp_gt_u32_e64 s[4:5], v92, v32
	v_cndmask_b32_e64 v95, 0, 1, s[6:7]
	v_cmp_eq_u32_e64 s[6:7], v88, v33
; template <int MODE> ...
;     ...
; #pragma unroll
;     for (int kt = 0; kt < 4; ++kt) {
;       f32x4 sh[4];
; #pragma unroll
;       for (int h = 0; h < 4; ++h) {
;         sh[h] = (f32x4){0.f, 0.f, 0.f, 0.f};
; #pragma unroll
;         for (int ks = 0; ks < 2; ++ks) sh[h] = MFMA16(qf[h][ks], kf[kt][ks], sh[h]);
;       }
; #pragma unroll
;       for (int j = 0; j < 4; ++j) {
;         float sc = w[j][0] * fmaxf(sh[0][j], 0.f) + w[j][1] * fmaxf(sh[1][j], 0.f) + w[j][2] * fmaxf(sh[2][j], 0.f) + w[j][3] * fmaxf(sh[3][j], 0.f);
;         sc += 0.0f;
;         const unsigned u = sortable(sc);
;         if (MODE == 4) {
;           const unsigned um = u & himask;
;           const bool eq = um == pfx[j], zr = u == 0x80000000u;
;           unsigned* qx = hist + (4 * g + j) * C1_HP + 512;
;           if (eq) {
;             const unsigned bin = u & bmask; atomicAdd(&hist[(4 * g + j) * C1_HP + (bin >> 1)], 1u << ((bin & 1u) * 16u));
;             if (!zr) { const unsigned idx = atomicAdd(&qx[320], 1u); if (idx < 64u) qx[256 + idx] = ((unsigned)n << 16) | ((unsigned)(kt * 16 + lr) << 10) | (u & 1023u); }
;           }
;           word[j] |= (u64)((unsigned)(__ballot(um > pfx[j]) >> (16 * g)) & 0xffffu) << (16 * kt);
;           zword[j] |= (u64)((unsigned)(__ballot(zr) >> (16 * g)) & 0xffffu) << (16 * kt);
;         } else if (MODE == 0 || MODE == 3) {
;           if (MODE == 3) base[j] += __popc((unsigned)(__ballot(u == 0x80000000u) >> (16 * g)) & 0xffffu);
;           if (((u ^ pfx[j]) & himask) == 0u) { const unsigned bin = (u >> shift) & bmask; atomicAdd(&hist[(4 * g + j) * C1_HP + (bin >> 1)], 1u << ((bin & 1u) * 16u)); }
;         } else {
;           const bool eq = u == pfx[j];
;           const unsigned fe = (unsigned)(__ballot(eq) >> (16 * g)) & 0xffffu;
;           if (MODE == 1) {
;             base[j] += __popc(fe);
;           } else {
;             const unsigned rank = base[j] + __popc(fe & ((1u << lr) - 1u));
;             const bool sel = (u > pfx[j]) || (eq && rank < need[j]);
;             base[j] += __popc(fe);
;             const unsigned fs = (unsigned)(__ballot(sel) >> (16 * g)) & 0xffffu;
;             word[j] |= (u64)fs << (16 * kt);
;           }
;         }
;       }
;     }
;     if ((MODE == 1 || MODE == 3) && lr == 0) {
; #pragma unroll
;       for (int j = 0; j < 4; ++j) cnt[(4 * g + j) * 64 + n] = (unsigned short)base[j];
;     }
	v_cndmask_b32_e64 v94, 0, 1, s[4:5]
	v_cmp_eq_u32_e64 s[4:5], v92, v32
	v_lshrrev_b64 v[92:93], v150, s[6:7]
	v_and_b32_e32 v88, 0xffff, v92
	v_and_b32_e32 v92, v92, v105
	v_bcnt_u32_b32 v92, v92, v128
	v_cmp_lt_u32_e64 s[8:9], v92, v37
	v_bcnt_u32_b32 v140, v88, v128
	v_max_f32_e32 v91, 0, v91
	v_cndmask_b32_e64 v92, 0, 1, s[8:9]
	v_cndmask_b32_e64 v92, v95, v92, s[6:7]
	v_and_b32_e32 v88, 1, v92
	v_lshrrev_b64 v[92:93], v150, s[4:5]
	v_cmp_ne_u32_e64 s[50:51], 0, v88
	v_and_b32_e32 v88, 0xffff, v92
	v_and_b32_e32 v92, v92, v105
	v_bcnt_u32_b32 v92, v92, v144
	v_cmp_lt_u32_e64 s[6:7], v92, v36
	v_bcnt_u32_b32 v100, v88, v144
	s_nop 0
	v_cndmask_b32_e64 v92, 0, 1, s[6:7]
	v_cndmask_b32_e64 v92, v94, v92, s[4:5]
	v_and_b32_e32 v88, 1, v92
	v_cmp_ne_u32_e64 s[52:53], 0, v88
	v_max_f32_e32 v92, 0, v97
	v_max_f32_e32 v93, 0, v101
	v_pk_mul_f32 v[134:135], v[92:93], v[110:111]
	v_max_f32_e32 v88, 0, v131
	v_max_f32_e32 v93, 0, v90
	v_pk_mul_f32 v[136:137], v[88:89], v[112:113]
	v_max_f32_e32 v94, 0, v99
	v_max_f32_e32 v88, 0, v98
	v_max_f32_e32 v89, 0, v102
	v_max_f32_e32 v95, 0, v103
	v_pk_mul_f32 v[88:89], v[88:89], v[114:115]
	v_max_f32_e32 v92, 0, v132
	v_pk_mul_f32 v[94:95], v[94:95], v[118:119]
	v_max_f32_e32 v90, 0, v133
	v_pk_mul_f32 v[92:93], v[92:93], v[116:117]
	v_pk_mul_f32 v[90:91], v[90:91], v[120:121]
	v_mov_b32_e32 v96, v88
	v_mov_b32_e32 v97, v94
	v_mov_b32_e32 v94, v89
	v_pk_add_f32 v[88:89], v[96:97], v[94:95]
	v_mov_b32_e32 v94, v92
	v_mov_b32_e32 v95, v90
	v_pk_add_f32 v[88:89], v[88:89], v[94:95]
	v_mov_b32_e32 v90, v93
	v_pk_add_f32 v[88:89], v[88:89], v[90:91]
	s_waitcnt vmcnt(11)
	v_mfma_f32_16x16x32_f16 v[128:131], v[12:15], v[84:87], 0
	v_add_f32_e64 v88, v88, 0
	v_add_f32_e64 v89, v89, 0
	v_and_b32_e32 v91, 0x7fffffff, v89
	v_and_b32_e32 v90, 0x7fffffff, v88
	v_xor_b32_e32 v93, -1, v88
	v_pk_add_f32 v[90:91], v[90:91], 0 neg_lo:[1,1] neg_hi:[1,1]
	v_cmp_gt_i32_e64 s[4:5], 0, v88
	v_xor_b32_e32 v92, -1, v89
	s_waitcnt vmcnt(10)
	v_mfma_f32_16x16x32_f16 v[128:131], v[16:19], v[80:83], v[128:131]
	v_cndmask_b32_e64 v93, v90, v93, s[4:5]
	v_cmp_gt_u32_e64 s[6:7], v93, v34
	v_cmp_gt_i32_e64 s[4:5], 0, v89
	s_nop 0
	v_cndmask_b32_e64 v96, 0, 1, s[6:7]
	v_cmp_eq_u32_e64 s[6:7], v93, v34
	v_cndmask_b32_e64 v88, v91, v92, s[4:5]
	v_cmp_gt_u32_e64 s[4:5], v88, v35
	v_lshrrev_b64 v[92:93], v150, s[6:7]
	v_and_b32_e32 v97, 0xffff, v92
	v_and_b32_e32 v92, v92, v105
	v_bcnt_u32_b32 v98, v92, v139
	v_mfma_f32_16x16x32_f16 v[92:95], v[4:7], v[84:87], 0
	v_cndmask_b32_e64 v99, 0, 1, s[4:5]
	v_cmp_eq_u32_e64 s[4:5], v88, v35
	v_cmp_lt_u32_e64 s[8:9], v98, v38
	v_mfma_f32_16x16x32_f16 v[88:91], v[24:27], v[84:87], 0
	s_nop 0
	v_cndmask_b32_e64 v98, 0, 1, s[8:9]
	v_cndmask_b32_e64 v101, v96, v98, s[6:7]
	v_mfma_f32_16x16x32_f16 v[84:87], v[20:23], v[84:87], 0
	v_bcnt_u32_b32 v98, v97, v139
	v_mfma_f32_16x16x32_f16 v[94:97], v[8:11], v[80:83], v[92:95]
	s_nop 2
	v_and_b32_e32 v92, 1, v101
	v_mfma_f32_16x16x32_f16 v[88:91], v[0:3], v[80:83], v[88:91]
	v_cmp_ne_u32_e64 s[54:55], 0, v92
	v_lshrrev_b64 v[92:93], v150, s[4:5]
	v_and_b32_e32 v93, 0xffff, v92
	v_and_b32_e32 v92, v92, v105
	v_mfma_f32_16x16x32_f16 v[80:83], v[28:31], v[80:83], v[84:87]
	v_bcnt_u32_b32 v92, v92, v138
	v_cmp_lt_u32_e64 s[6:7], v92, v39
	s_nop 0
	v_max_f32_e32 v84, v88, v88
	v_cndmask_b32_e64 v92, 0, 1, s[6:7]
	v_cndmask_b32_e64 v92, v99, v92, s[4:5]
	v_max_f32_e32 v84, 0, v84
	v_max_f32_e32 v85, 0, v94
	v_and_b32_e32 v92, 1, v92
	v_pk_mul_f32 v[84:85], v[84:85], v[106:107]
	v_max_f32_e32 v86, 0, v128
	v_max_f32_e32 v87, 0, v80
	v_bcnt_u32_b32 v99, v93, v138
	v_cmp_ne_u32_e64 s[56:57], 0, v92
	v_pk_mul_f32 v[86:87], v[86:87], v[108:109]
	v_mov_b32_e32 v92, v84
	v_mov_b32_e32 v93, v134
	v_mov_b32_e32 v134, v85
	v_pk_add_f32 v[84:85], v[92:93], v[134:135]
	v_mov_b32_e32 v92, v86
	v_mov_b32_e32 v93, v136
	v_pk_add_f32 v[84:85], v[84:85], v[92:93]
	v_mov_b32_e32 v136, v87
	v_pk_add_f32 v[84:85], v[84:85], v[136:137]
	v_max_f32_e32 v81, v81, v81
	v_pk_add_f32 v[84:85], v[84:85], 0 op_sel_hi:[1,0]
	v_max_f32_e32 v82, v82, v82
	v_and_b32_e32 v87, 0x7fffffff, v85
	v_and_b32_e32 v86, 0x7fffffff, v84
	v_xor_b32_e32 v80, -1, v85
	v_pk_add_f32 v[86:87], v[86:87], 0 neg_lo:[1,1] neg_hi:[1,1]
	v_cmp_gt_i32_e64 s[4:5], 0, v85
	v_xor_b32_e32 v88, -1, v84
	v_max_f32_e32 v81, 0, v81
	v_cndmask_b32_e64 v80, v87, v80, s[4:5]
	v_cmp_gt_i32_e64 s[4:5], 0, v84
	v_max_f32_e32 v83, v83, v83
	v_max_f32_e32 v83, 0, v83
	v_cndmask_b32_e64 v84, v86, v88, s[4:5]
	v_cmp_gt_u32_e64 s[4:5], v84, v32
	v_cmp_eq_u32_e64 s[6:7], v84, v32
	s_nop 0
	v_cndmask_b32_e64 v86, 0, 1, s[4:5]
	v_cmp_gt_u32_e64 s[4:5], v80, v33
	v_lshrrev_b64 v[92:93], v150, s[6:7]
	s_nop 0
	v_cndmask_b32_e64 v87, 0, 1, s[4:5]
	v_cmp_eq_u32_e64 s[4:5], v80, v33
	s_nop 1
	v_lshrrev_b64 v[84:85], v150, s[4:5]
	v_and_b32_e32 v80, 0xffff, v84
	v_and_b32_e32 v84, v84, v105
	v_bcnt_u32_b32 v84, v84, v140
	v_cmp_lt_u32_e64 s[8:9], v84, v37
	v_bcnt_u32_b32 v101, v80, v140
	s_nop 0
	v_cndmask_b32_e64 v84, 0, 1, s[8:9]
	v_cndmask_b32_e64 v84, v87, v84, s[4:5]
	v_and_b32_e32 v80, 1, v84
	v_cmp_ne_u32_e64 s[4:5], 0, v80
	v_and_b32_e32 v80, v92, v105
	v_bcnt_u32_b32 v80, v80, v100
	v_cmp_lt_u32_e64 s[8:9], v80, v36
	s_nop 1
	v_cndmask_b32_e64 v80, 0, 1, s[8:9]
	v_cndmask_b32_e64 v80, v86, v80, s[6:7]
	v_and_b32_e32 v80, 1, v80
	v_cmp_ne_u32_e64 s[58:59], 0, v80
	v_max_f32_e32 v84, 0, v89
	v_max_f32_e32 v85, 0, v95
	v_pk_mul_f32 v[102:103], v[84:85], v[110:111]
	v_max_f32_e32 v80, 0, v129
	v_max_f32_e32 v85, 0, v82
	v_pk_mul_f32 v[128:129], v[80:81], v[112:113]
	v_max_f32_e32 v86, 0, v91
	v_max_f32_e32 v80, 0, v90
	v_max_f32_e32 v81, 0, v96
	v_max_f32_e32 v87, 0, v97
	v_pk_mul_f32 v[80:81], v[80:81], v[114:115]
	v_max_f32_e32 v84, 0, v130
	v_pk_mul_f32 v[86:87], v[86:87], v[118:119]
	v_max_f32_e32 v82, 0, v131
	v_pk_mul_f32 v[84:85], v[84:85], v[116:117]
	v_pk_mul_f32 v[82:83], v[82:83], v[120:121]
	v_mov_b32_e32 v88, v80
	v_mov_b32_e32 v89, v86
	v_mov_b32_e32 v86, v81
	v_pk_add_f32 v[80:81], v[88:89], v[86:87]
	v_mov_b32_e32 v86, v84
	v_mov_b32_e32 v87, v82
	v_pk_add_f32 v[80:81], v[80:81], v[86:87]
	v_mov_b32_e32 v82, v85
	v_pk_add_f32 v[80:81], v[80:81], v[82:83]
	v_mov_b32_e32 v131, v102
	v_pk_add_f32 v[80:81], v[80:81], 0 op_sel_hi:[1,0]
	s_nop 0
	v_and_b32_e32 v83, 0x7fffffff, v81
	v_and_b32_e32 v82, 0x7fffffff, v80
	v_xor_b32_e32 v85, -1, v80
	v_pk_add_f32 v[82:83], v[82:83], 0 neg_lo:[1,1] neg_hi:[1,1]
	v_cmp_gt_i32_e64 s[6:7], 0, v80
	v_xor_b32_e32 v84, -1, v81
	s_nop 0
	v_cndmask_b32_e64 v85, v82, v85, s[6:7]
	v_cmp_gt_i32_e64 s[6:7], 0, v81
	s_nop 1
	v_cndmask_b32_e64 v84, v83, v84, s[6:7]
	v_cmp_gt_u32_e64 s[6:7], v84, v35
	s_waitcnt vmcnt(9)
; #define MFMA16(a, b, c) __builtin_amdgcn_mfma_f32_16x16x32_f16((a), (b), (c), 0, 0, 0)
; DI unsigned sortable(float f) { const unsigned u = __float_as_uint(f); return (u & 0x80000000u) ? ~u : (u | 0x80000000u); }
; template <int MODE> ...
;     ...
;         for (int ks = 0; ks < 2; ++ks) sh[h] = MFMA16(qf[h][ks], kf[kt][ks], sh[h]);
;       }
; #pragma unroll
;       for (int j = 0; j < 4; ++j) {
;         float sc = w[j][0] * fmaxf(sh[0][j], 0.f) + w[j][1] * fmaxf(sh[1][j], 0.f) + w[j][2] * fmaxf(sh[2][j], 0.f) + w[j][3] * fmaxf(sh[3][j], 0.f);
;         sc += 0.0f;
;         const unsigned u = sortable(sc);
;         if (MODE == 4) {
;           const unsigned um = u & himask;
;           const bool eq = um == pfx[j], zr = u == 0x80000000u;
;           unsigned* qx = hist + (4 * g + j) * C1_HP + 512;
;           if (eq) {
;             const unsigned bin = u & bmask; atomicAdd(&hist[(4 * g + j) * C1_HP + (bin >> 1)], 1u << ((bin & 1u) * 16u));
;             if (!zr) { const unsigned idx = atomicAdd(&qx[320], 1u); if (idx < 64u) qx[256 + idx] = ((unsigned)n << 16) | ((unsigned)(kt * 16 + lr) << 10) | (u & 1023u); }
;           }
;           word[j] |= (u64)((unsigned)(__ballot(um > pfx[j]) >> (16 * g)) & 0xffffu) << (16 * kt);
;           zword[j] |= (u64)((unsigned)(__ballot(zr) >> (16 * g)) & 0xffffu) << (16 * kt);
;         } else if (MODE == 0 || MODE == 3) {
;           if (MODE == 3) base[j] += __popc((unsigned)(__ballot(u == 0x80000000u) >> (16 * g)) & 0xffffu);
;           if (((u ^ pfx[j]) & himask) == 0u) { const unsigned bin = (u >> shift) & bmask; atomicAdd(&hist[(4 * g + j) * C1_HP + (bin >> 1)], 1u << ((bin & 1u) * 16u)); }
;         } else {
;           const bool eq = u == pfx[j];
;           const unsigned fe = (unsigned)(__ballot(eq) >> (16 * g)) & 0xffffu;
;           if (MODE == 1) {
;             base[j] += __popc(fe);
;           } else {
;             const unsigned rank = base[j] + __popc(fe & ((1u << lr) - 1u));
;             const bool sel = (u > pfx[j]) || (eq && rank < need[j]);
;             base[j] += __popc(fe);
;             const unsigned fs = (unsigned)(__ballot(sel) >> (16 * g)) & 0xffffu;
;             word[j] |= (u64)fs << (16 * kt);
	v_mfma_f32_16x16x32_f16 v[80:83], v[24:27], v[76:79], 0
	v_cmp_eq_u32_e64 s[8:9], v84, v35
	v_cndmask_b32_e64 v93, 0, 1, s[6:7]
	v_cmp_gt_u32_e64 s[6:7], v85, v34
	s_waitcnt vmcnt(8)
	v_mfma_f32_16x16x32_f16 v[80:83], v[0:3], v[72:75], v[80:83]
	v_lshrrev_b64 v[96:97], v150, s[8:9]
	v_cndmask_b32_e64 v88, 0, 1, s[6:7]
	v_cmp_eq_u32_e64 s[6:7], v85, v34
	v_mfma_f32_16x16x32_f16 v[84:87], v[4:7], v[76:79], 0
	s_nop 0
	v_lshrrev_b64 v[94:95], v150, s[6:7]
	v_and_b32_e32 v89, v94, v105
	v_bcnt_u32_b32 v89, v89, v98
	v_cmp_lt_u32_e64 s[10:11], v89, v38
	v_mfma_f32_16x16x32_f16 v[84:87], v[8:11], v[72:75], v[84:87]
	s_nop 0
	v_cndmask_b32_e64 v89, 0, 1, s[10:11]
	v_cndmask_b32_e64 v88, v88, v89, s[6:7]
	v_and_b32_e32 v95, 1, v88
	v_mfma_f32_16x16x32_f16 v[88:91], v[12:15], v[76:79], 0
	v_cmp_ne_u32_e64 s[6:7], 0, v95
	v_and_b32_e32 v95, v96, v105
	v_bcnt_u32_b32 v95, v95, v99
	v_mfma_f32_16x16x32_f16 v[76:79], v[20:23], v[76:79], 0
	v_cmp_lt_u32_e64 s[10:11], v95, v39
	v_mfma_f32_16x16x32_f16 v[88:91], v[16:19], v[72:75], v[88:91]
	s_nop 0
	v_cndmask_b32_e64 v95, 0, 1, s[10:11]
	v_cndmask_b32_e64 v93, v93, v95, s[8:9]
	v_and_b32_e32 v93, 1, v93
	v_mfma_f32_16x16x32_f16 v[72:75], v[28:31], v[72:75], v[76:79]
	v_cmp_ne_u32_e64 s[8:9], 0, v93
	s_nop 1
	v_max_f32_e32 v76, 0, v80
	v_max_f32_e32 v77, 0, v84
	v_max_f32_e32 v78, v88, v88
	v_pk_mul_f32 v[76:77], v[76:77], v[106:107]
	v_max_f32_e32 v78, 0, v78
	v_max_f32_e32 v79, 0, v72
	v_pk_mul_f32 v[78:79], v[78:79], v[108:109]
	v_mov_b32_e32 v130, v76
	v_mov_b32_e32 v102, v77
	v_pk_add_f32 v[76:77], v[130:131], v[102:103]
	v_mov_b32_e32 v102, v78
	v_mov_b32_e32 v103, v128
	v_pk_add_f32 v[76:77], v[76:77], v[102:103]
	v_mov_b32_e32 v128, v79
	v_pk_add_f32 v[76:77], v[76:77], v[128:129]
	s_nop 0
	v_pk_add_f32 v[76:77], v[76:77], 0 op_sel_hi:[1,0]
	s_nop 0
	v_and_b32_e32 v79, 0x7fffffff, v77
	v_and_b32_e32 v78, 0x7fffffff, v76
	v_xor_b32_e32 v72, -1, v77
	v_pk_add_f32 v[78:79], v[78:79], 0 neg_lo:[1,1] neg_hi:[1,1]
	v_cmp_gt_i32_e64 s[10:11], 0, v77
	v_xor_b32_e32 v80, -1, v76
	s_nop 0
	v_cndmask_b32_e64 v72, v79, v72, s[10:11]
	v_cmp_gt_i32_e64 s[10:11], 0, v76
	s_nop 1
	v_cndmask_b32_e64 v78, v78, v80, s[10:11]
	v_cmp_gt_u32_e64 s[10:11], v72, v33
	v_cmp_eq_u32_e64 s[12:13], v78, v32
	s_nop 0
	v_cndmask_b32_e64 v79, 0, 1, s[10:11]
	v_cmp_eq_u32_e64 s[10:11], v72, v33
	s_nop 1
	v_lshrrev_b64 v[76:77], v150, s[10:11]
	v_and_b32_e32 v72, v76, v105
	v_bcnt_u32_b32 v72, v72, v101
	v_cmp_lt_u32_e64 s[14:15], v72, v37
	s_nop 1
	v_cndmask_b32_e64 v72, 0, 1, s[14:15]
	v_cndmask_b32_e64 v72, v79, v72, s[10:11]
	v_and_b32_e32 v72, 1, v72
	v_cmp_ne_u32_e64 s[10:11], 0, v72
	v_cmp_gt_u32_e64 s[14:15], v78, v32
	s_and_saveexec_b64 s[16:17], s[12:13]
	s_cbranch_execz .LBB0_1007
	v_lshrrev_b64 v[78:79], v150, s[12:13]
	v_and_b32_e32 v72, 0xffff, v92
	v_and_b32_e32 v77, v78, v105
	v_bcnt_u32_b32 v72, v72, 0
	v_bcnt_u32_b32 v77, v77, 0
	v_add3_u32 v72, v72, v100, v77
	v_cmp_lt_u32_e64 s[12:13], v72, v36
	s_andn2_b64 s[14:15], s[14:15], exec
	s_and_b64 s[12:13], s[12:13], exec
	s_or_b64 s[14:15], s[14:15], s[12:13]

; DI int TIDX() { int t = threadIdx.x; asm volatile("" : "+v"(t)); return t; }
; DI int BIDX() { int b = blockIdx.x; asm volatile("" : "+s"(b)); return b; }
; #define GL_LOAD(s_, kt_) if (VAR != 1) { a##s_##0 = GL_A(0, kt_); a##s_##1 = GL_A(1, kt_); a##s_##2 = GL_A(2, kt_); a##s_##3 = GL_A(3, kt_); b##s_##0 = GL_B(0, kt_); b##s_##1 = GL_B(1, kt_); b##s_##2 = GL_B(2, kt_); b##s_##3 = GL_B(3, kt_); }
; #define LDS_STORE(s_, buf_) if (VAR != 2) { LDS_ST1(sA, 0, buf_, a##s_##0) LDS_ST1(sA, 1, buf_, a##s_##1) LDS_ST1(sA, 2, buf_, a##s_##2) LDS_ST1(sA, 3, buf_, a##s_##3) LDS_ST1(sB, 0, buf_, b##s_##0) LDS_ST1(sB, 1, buf_, b##s_##1) LDS_ST1(sB, 2, buf_, b##s_##2) LDS_ST1(sB, 3, buf_, b##s_##3) }
; DI int tile_groups(int MT, int NT) { return (MT >> 6) * ((NT + 7) >> 3) * 512; }
;   const int tid = TIDX(), lane = tid & 63, wid = tid >> 6, wm = wid >> 1, wn = wid & 1, lr = lane & 15, g = lane >> 4;
;   char* sA = smem; char* sB = smem + 2 * LTILE;
;   uint4 a00 = {}, a01 = {}, a02 = {}, a03 = {}, b00 = {}, b01 = {}, b02 = {}, b03 = {}, a10 = {}, a11 = {}, a12 = {}, a13 = {}, b10 = {}, b11 = {}, b12 = {}, b13 = {};
;   constexpr int nk = NK;
;   const int sw0 = (g ^ ((lr >> 1) & 7)) << 4, sw1 = sw0 ^ 64;
;   const int r0 = tid >> 3, kc = tid & 7, kcs = kc ^ ((r0 >> 1) & 7);
;     ...
;   GL_LOAD(0, 0)
;   GL_LOAD(1, 1)
;   LDS_STORE(0, 0)
;   if (VAR != 4) __syncthreads();
; DI void phase_resgemm(const Params& P, const bf16_t* A, int K, const bf16_t* Wt, float* ssq_out, const float* xsrc, char* smem) {
;     ...
;   for (int vb = BIDX(); vb < tile_groups(128, 8); vb += gridDim.x) {
;     int tm, tn; if (!tile_of(vb, 128, 8, tm, tn)) continue;
;     const int m0 = tm * 128, n0 = tn * 128;
;     f32x4 acc[4][4]; zero_acc(acc);
;     if (K == 1024) gemm_kloop<false, true, 16>(acc, A + (size_t)m0 * K, K, Wt + (size_t)n0 * K, K, smem);
;     else gemm_kloop<false, true, 64>(acc, A + (size_t)m0 * K, K, Wt + (size_t)n0 * K, K, smem);
.LBB0_1371:
	s_ashr_i32 s1, s2, 3
	s_andn2_b32 s1, s1, 63
	s_and_b32 s4, s9, 56
	s_or_b32 s1, s1, s4
	s_bfe_u32 s4, s2, 0x30003
	s_or_b32 s1, s1, s4
	s_cmpk_gt_i32 s1, 0x7f
	s_cbranch_scc1 .LBB0_1370
	s_lshl_b32 s4, s1, 7
	s_ashr_i32 s5, s4, 31
	v_mov_b32_e32 v58, v148
	s_and_b32 s10, s8, 0x380
	s_lshl_b64 s[12:13], s[4:5], 13
	s_add_u32 s12, s34, s12
	v_ashrrev_i32_e32 v16, 3, v58
	v_ashrrev_i32_e32 v17, 31, v16
	v_add_u32_e32 v18, 32, v16
	s_addc_u32 s13, s35, s13
	v_lshlrev_b64 v[6:7], 13, v[16:17]
	v_lshlrev_b32_e32 v17, 4, v58
	v_ashrrev_i32_e32 v19, 31, v18
	v_add_u32_e32 v20, 64, v16
	s_waitcnt lgkmcnt(0)
	v_lshl_add_u64 v[0:1], s[12:13], 0, v[6:7]
	v_and_b32_e32 v150, 0x70, v17
	v_lshlrev_b64 v[8:9], 13, v[18:19]
	v_ashrrev_i32_e32 v21, 31, v20
	v_add_u32_e32 v54, 0x60, v16
	s_lshl_b32 s1, s10, 13
	v_lshl_add_u64 v[0:1], v[0:1], 0, v[150:151]
	v_lshl_add_u64 v[2:3], s[12:13], 0, v[8:9]
	v_lshlrev_b64 v[46:47], 13, v[20:21]
	v_ashrrev_i32_e32 v55, 31, v54
	s_add_u32 s14, s6, s1
	global_load_dwordx4 v[22:25], v[0:1], off
	v_lshl_add_u64 v[2:3], v[2:3], 0, v[150:151]
	v_lshl_add_u64 v[4:5], s[12:13], 0, v[46:47]
	v_lshlrev_b64 v[50:51], 13, v[54:55]
	s_addc_u32 s15, s7, 0
	global_load_dwordx4 v[26:29], v[2:3], off
	v_lshl_add_u64 v[4:5], v[4:5], 0, v[150:151]
	v_lshl_add_u64 v[10:11], s[12:13], 0, v[50:51]
	global_load_dwordx4 v[30:33], v[4:5], off
	v_lshl_add_u64 v[14:15], v[10:11], 0, v[150:151]
	v_lshl_add_u64 v[6:7], s[14:15], 0, v[6:7]
	global_load_dwordx4 v[34:37], v[14:15], off
	v_lshl_add_u64 v[10:11], v[6:7], 0, v[150:151]
	v_lshl_add_u64 v[6:7], s[14:15], 0, v[8:9]
	global_load_dwordx4 v[38:41], v[10:11], off
	v_lshl_add_u64 v[12:13], v[6:7], 0, v[150:151]
	v_lshl_add_u64 v[6:7], s[14:15], 0, v[46:47]
	global_load_dwordx4 v[42:45], v[12:13], off
	v_lshl_add_u64 v[8:9], v[6:7], 0, v[150:151]
	v_lshl_add_u64 v[6:7], s[14:15], 0, v[50:51]
	global_load_dwordx4 v[46:49], v[8:9], off
	v_lshl_add_u64 v[6:7], v[6:7], 0, v[150:151]
	global_load_dwordx4 v[50:53], v[6:7], off
	v_and_b32_e32 v19, 15, v58
	v_lshlrev_b32_e32 v21, 3, v58
	v_and_b32_e32 v55, 48, v58
	v_lshrrev_b32_e32 v59, 1, v58
	s_waitcnt vmcnt(10)
	v_lshlrev_b32_e32 v60, 7, v58
	v_and_b32_e32 v90, 0x70, v21
	v_bitop3_b32 v134, v21, v55, s23 bitop3:0x6c
	v_bitop3_b32 v21, v17, s23, v58 bitop3:0x48
	v_and_or_b32 v91, v59, s24, v19
	v_and_b32_e32 v130, 0x2780, v60
	global_load_dwordx4 v[58:61], v[0:1], off offset:128
	global_load_dwordx4 v[62:65], v[2:3], off offset:128
	global_load_dwordx4 v[66:69], v[4:5], off offset:128
	global_load_dwordx4 v[70:73], v[14:15], off offset:128
	global_load_dwordx4 v[74:77], v[10:11], off offset:128
	global_load_dwordx4 v[78:81], v[12:13], off offset:128
	global_load_dwordx4 v[82:85], v[8:9], off offset:128
	global_load_dwordx4 v[86:89], v[6:7], off offset:128
	v_lshl_or_b32 v17, v16, 7, v21
	v_or_b32_e32 v16, v130, v134
	v_lshl_or_b32 v18, v18, 7, v21
	v_lshl_or_b32 v19, v20, 7, v21
	v_lshl_or_b32 v20, v54, 7, v21
	v_lshlrev_b32_e32 v54, 7, v91
	v_bitop3_b32 v21, v54, v90, v55 bitop3:0xf6
	s_movk_i32 s1, 0x1000
	v_readlane_b32 s12, v254, 55
	v_readlane_b32 s13, v254, 56
	v_readlane_b32 s14, v254, 57
	v_readlane_b32 s15, v254, 58
	s_waitcnt vmcnt(15)
	ds_write_b128 v17, v[22:25]
	s_waitcnt vmcnt(14)
	ds_write_b128 v18, v[26:29]
	s_waitcnt vmcnt(13)
	ds_write_b128 v19, v[30:33]
	s_waitcnt vmcnt(12)
	ds_write_b128 v20, v[34:37]
	s_waitcnt vmcnt(11)
	ds_write_b128 v17, v[38:41] offset:32768
	s_waitcnt vmcnt(10)
	ds_write_b128 v18, v[42:45] offset:32768
	s_waitcnt vmcnt(9)
	ds_write_b128 v19, v[46:49] offset:32768
	s_waitcnt vmcnt(8)
	ds_write_b128 v20, v[50:53] offset:32768
	s_waitcnt lgkmcnt(0)
	s_barrier
	s_setprio 1
	ds_read_b128 v[22:25], v16 offset:32768
	ds_read_b128 v[30:33], v21
	s_waitcnt lgkmcnt(0)
	v_mfma_f32_16x16x32_f16 v[38:41], v[22:25], v[30:33], 0
	ds_read_b128 v[26:29], v16 offset:34816
	ds_read_b128 v[34:37], v21 offset:2048
	s_waitcnt lgkmcnt(0)
	v_mfma_f32_16x16x32_f16 v[94:97], v[22:25], v[34:37], 0
	ds_read_b128 v[42:45], v16 offset:36864
	ds_read_b128 v[106:109], v21 offset:4096
	s_waitcnt lgkmcnt(0)
	v_mfma_f32_16x16x32_f16 v[114:117], v[22:25], v[106:109], 0
	ds_read_b128 v[50:53], v16 offset:38912
	ds_read_b128 v[110:113], v21 offset:6144
	s_waitcnt lgkmcnt(0)
	v_mfma_f32_16x16x32_f16 v[126:129], v[22:25], v[110:113], 0
	v_xor_b32_e32 v22, 64, v134
	v_mfma_f32_16x16x32_f16 v[46:49], v[26:29], v[30:33], 0
	v_or_b32_e32 v22, v130, v22
	v_mfma_f32_16x16x32_f16 v[90:93], v[42:45], v[30:33], 0
	ds_read_b128 v[130:133], v22 offset:32768
	v_mfma_f32_16x16x32_f16 v[30:33], v[50:53], v[30:33], 0
	ds_read_b128 v[142:145], v22 offset:36864
	v_mfma_f32_16x16x32_f16 v[98:101], v[26:29], v[34:37], 0
	ds_read_b128 v[154:157], v22 offset:38912
	v_mfma_f32_16x16x32_f16 v[102:105], v[42:45], v[34:37], 0
	v_bitop3_b32 v23, v54, v134, 64 bitop3:0xf6
	v_mfma_f32_16x16x32_f16 v[34:37], v[50:53], v[34:37], 0
	ds_read_b128 v[134:137], v23
	v_mfma_f32_16x16x32_f16 v[118:121], v[26:29], v[106:109], 0
	ds_read_b128 v[138:141], v23 offset:2048
	v_mfma_f32_16x16x32_f16 v[122:125], v[42:45], v[106:109], 0
	s_waitcnt vmcnt(7)
	ds_write_b128 v17, v[58:61] offset:16384
	v_mfma_f32_16x16x32_f16 v[106:109], v[50:53], v[106:109], 0
	s_waitcnt vmcnt(6)
	ds_write_b128 v18, v[62:65] offset:16384
	v_mfma_f32_16x16x32_f16 v[24:27], v[26:29], v[110:113], 0
	s_waitcnt vmcnt(5)
	ds_write_b128 v19, v[66:69] offset:16384
	v_mfma_f32_16x16x32_f16 v[42:45], v[42:45], v[110:113], 0
	s_waitcnt vmcnt(4)
	ds_write_b128 v20, v[70:73] offset:16384
	v_mfma_f32_16x16x32_f16 v[50:53], v[50:53], v[110:113], 0
	ds_read_b128 v[110:113], v22 offset:34816
	s_waitcnt lgkmcnt(6)
; #define GL_LOAD(s_, kt_) if (VAR != 1) { a##s_##0 = GL_A(0, kt_); a##s_##1 = GL_A(1, kt_); a##s_##2 = GL_A(2, kt_); a##s_##3 = GL_A(3, kt_); b##s_##0 = GL_B(0, kt_); b##s_##1 = GL_B(1, kt_); b##s_##2 = GL_B(2, kt_); b##s_##3 = GL_B(3, kt_); }
; #define LDS_STORE(s_, buf_) if (VAR != 2) { LDS_ST1(sA, 0, buf_, a##s_##0) LDS_ST1(sA, 1, buf_, a##s_##1) LDS_ST1(sA, 2, buf_, a##s_##2) LDS_ST1(sA, 3, buf_, a##s_##3) LDS_ST1(sB, 0, buf_, b##s_##0) LDS_ST1(sB, 1, buf_, b##s_##1) LDS_ST1(sB, 2, buf_, b##s_##2) LDS_ST1(sB, 3, buf_, b##s_##3) }
;     ...
;   GL_LOAD(0, 0)
;   GL_LOAD(1, 1)
;   LDS_STORE(0, 0)
;   if (VAR != 4) __syncthreads();
; #pragma unroll
;   for (int kt = 0; kt < nk; kt += 2) {
;     if (kt + 2 < nk) { GL_LOAD(0, kt + 2) }
;     MMA_TILE(0)
;     LDS_STORE(1, 1)
;     if (VAR != 4) __syncthreads();
;     if (kt + 3 < nk) { GL_LOAD(1, kt + 3) }
;     MMA_TILE(1)
;     if (kt + 2 < nk) { LDS_STORE(0, 0) }
;     if (VAR != 4) __syncthreads();
	v_mfma_f32_16x16x32_f16 v[38:41], v[130:133], v[134:137], v[38:41]
	s_waitcnt vmcnt(3)
	ds_write_b128 v17, v[74:77] offset:49152
	v_mfma_f32_16x16x32_f16 v[90:93], v[142:145], v[134:137], v[90:93]
	s_waitcnt vmcnt(2)
	ds_write_b128 v18, v[78:81] offset:49152
	v_mfma_f32_16x16x32_f16 v[28:31], v[154:157], v[134:137], v[30:33]
	s_waitcnt vmcnt(1)
	ds_write_b128 v19, v[82:85] offset:49152
	s_waitcnt lgkmcnt(8)
	v_mfma_f32_16x16x32_f16 v[94:97], v[130:133], v[138:141], v[94:97]
	s_waitcnt vmcnt(0)
	ds_write_b128 v20, v[86:89] offset:49152
	v_mfma_f32_16x16x32_f16 v[102:105], v[142:145], v[138:141], v[102:105]
	v_mfma_f32_16x16x32_f16 v[32:35], v[154:157], v[138:141], v[34:37]
	s_waitcnt lgkmcnt(4)
	v_mfma_f32_16x16x32_f16 v[46:49], v[110:113], v[134:137], v[46:49]
	ds_read_b128 v[134:137], v23 offset:4096
	v_mfma_f32_16x16x32_f16 v[98:101], v[110:113], v[138:141], v[98:101]
	ds_read_b128 v[138:141], v23 offset:6144
	s_waitcnt lgkmcnt(1)
	v_mfma_f32_16x16x32_f16 v[114:117], v[130:133], v[134:137], v[114:117]
	s_waitcnt lgkmcnt(0)
	v_mfma_f32_16x16x32_f16 v[126:129], v[130:133], v[138:141], v[126:129]
	global_load_dwordx4 v[130:133], v[0:1], off offset:256
	v_mfma_f32_16x16x32_f16 v[118:121], v[110:113], v[134:137], v[118:121]
	v_mfma_f32_16x16x32_f16 v[24:27], v[110:113], v[138:141], v[24:27]
	v_mfma_f32_16x16x32_f16 v[122:125], v[142:145], v[134:137], v[122:125]
	v_mfma_f32_16x16x32_f16 v[106:109], v[154:157], v[134:137], v[106:109]
	global_load_dwordx4 v[134:137], v[2:3], off offset:256
	global_load_dwordx4 v[158:161], v[4:5], off offset:256
	global_load_dwordx4 v[162:165], v[14:15], off offset:256
	global_load_dwordx4 v[110:113], v[10:11], off offset:256
	global_load_dwordx4 v[166:169], v[12:13], off offset:256
	global_load_dwordx4 v[190:193], v[8:9], off offset:256
	global_load_dwordx4 v[194:197], v[6:7], off offset:256
	s_waitcnt lgkmcnt(0)
	s_barrier
	v_mfma_f32_16x16x32_f16 v[42:45], v[142:145], v[138:141], v[42:45]
	ds_read_b128 v[58:61], v16 offset:49152
	v_mfma_f32_16x16x32_f16 v[50:53], v[154:157], v[138:141], v[50:53]
	ds_read_b128 v[62:65], v16 offset:51200
	ds_read_b128 v[66:69], v21 offset:16384
	s_waitcnt lgkmcnt(0)
	v_mfma_f32_16x16x32_f16 v[36:39], v[58:61], v[66:69], v[38:41]
	ds_read_b128 v[70:73], v21 offset:18432
	v_mfma_f32_16x16x32_f16 v[46:49], v[62:65], v[66:69], v[46:49]
	ds_read_b128 v[74:77], v16 offset:53248
	s_waitcnt lgkmcnt(0)
	v_mfma_f32_16x16x32_f16 v[82:85], v[74:77], v[66:69], v[90:93]
	ds_read_b128 v[78:81], v16 offset:55296
	s_waitcnt lgkmcnt(0)
	v_mfma_f32_16x16x32_f16 v[28:31], v[78:81], v[66:69], v[28:31]
	v_mfma_f32_16x16x32_f16 v[66:69], v[58:61], v[70:73], v[94:97]
	s_nop 2
	ds_read_b128 v[94:97], v21 offset:22528
	s_waitcnt vmcnt(7)
	ds_write_b128 v17, v[130:133]
	v_mfma_f32_16x16x32_f16 v[86:89], v[62:65], v[70:73], v[98:101]
	s_waitcnt vmcnt(6)
	ds_write_b128 v18, v[134:137]
	s_waitcnt vmcnt(5)
	ds_write_b128 v19, v[158:161]
	v_mfma_f32_16x16x32_f16 v[90:93], v[74:77], v[70:73], v[102:105]
	s_waitcnt vmcnt(4)
	ds_write_b128 v20, v[162:165]
	s_waitcnt vmcnt(3)
	ds_write_b128 v17, v[110:113] offset:32768
	v_mfma_f32_16x16x32_f16 v[32:35], v[78:81], v[70:73], v[32:35]
	ds_read_b128 v[70:73], v21 offset:20480
	s_waitcnt lgkmcnt(0)
	v_mfma_f32_16x16x32_f16 v[98:101], v[58:61], v[70:73], v[114:117]
	s_waitcnt vmcnt(2)
	ds_write_b128 v18, v[166:169] offset:32768
	v_mfma_f32_16x16x32_f16 v[58:61], v[58:61], v[94:97], v[126:129]
	s_waitcnt vmcnt(1)
	ds_write_b128 v19, v[190:193] offset:32768
	v_mfma_f32_16x16x32_f16 v[102:105], v[62:65], v[70:73], v[118:121]
	s_nop 2
	ds_read_b128 v[118:121], v22 offset:55296
	v_mfma_f32_16x16x32_f16 v[24:27], v[62:65], v[94:97], v[24:27]
	ds_read_b128 v[62:65], v22 offset:49152
	v_mfma_f32_16x16x32_f16 v[114:117], v[74:77], v[70:73], v[122:125]
	s_waitcnt vmcnt(0)
	ds_write_b128 v20, v[194:197] offset:32768
	v_mfma_f32_16x16x32_f16 v[40:43], v[74:77], v[94:97], v[42:45]
	ds_read_b128 v[74:77], v22 offset:51200
	v_mfma_f32_16x16x32_f16 v[70:73], v[78:81], v[70:73], v[106:109]
	s_nop 2
	ds_read_b128 v[106:109], v22 offset:53248
	v_mfma_f32_16x16x32_f16 v[50:53], v[78:81], v[94:97], v[50:53]
	ds_read_b128 v[78:81], v23 offset:16384
	s_waitcnt lgkmcnt(0)
	v_mfma_f32_16x16x32_f16 v[36:39], v[62:65], v[78:81], v[36:39]
	ds_read_b128 v[94:97], v23 offset:18432
	s_waitcnt lgkmcnt(0)
	v_mfma_f32_16x16x32_f16 v[66:69], v[62:65], v[94:97], v[66:69]
	v_mfma_f32_16x16x32_f16 v[44:47], v[74:77], v[78:81], v[46:49]
	v_mfma_f32_16x16x32_f16 v[82:85], v[106:109], v[78:81], v[82:85]
	v_mfma_f32_16x16x32_f16 v[28:31], v[118:121], v[78:81], v[28:31]
	v_mfma_f32_16x16x32_f16 v[78:81], v[74:77], v[94:97], v[86:89]
	v_mfma_f32_16x16x32_f16 v[86:89], v[106:109], v[94:97], v[90:93]
	s_nop 2
	ds_read_b128 v[90:93], v23 offset:20480
	v_mfma_f32_16x16x32_f16 v[32:35], v[118:121], v[94:97], v[32:35]
	ds_read_b128 v[94:97], v23 offset:22528
	s_waitcnt lgkmcnt(1)
	v_mfma_f32_16x16x32_f16 v[98:101], v[62:65], v[90:93], v[98:101]
	s_waitcnt lgkmcnt(0)
	v_mfma_f32_16x16x32_f16 v[58:61], v[62:65], v[94:97], v[58:61]
	global_load_dwordx4 v[62:65], v[0:1], off offset:384
	v_mfma_f32_16x16x32_f16 v[102:105], v[74:77], v[90:93], v[102:105]
	v_mfma_f32_16x16x32_f16 v[24:27], v[74:77], v[94:97], v[24:27]
	v_mfma_f32_16x16x32_f16 v[114:117], v[106:109], v[90:93], v[114:117]
	v_mfma_f32_16x16x32_f16 v[40:43], v[106:109], v[94:97], v[40:43]
	v_mfma_f32_16x16x32_f16 v[70:73], v[118:121], v[90:93], v[70:73]
	global_load_dwordx4 v[90:93], v[2:3], off offset:384
	global_load_dwordx4 v[122:125], v[4:5], off offset:384
	global_load_dwordx4 v[126:129], v[14:15], off offset:384
	global_load_dwordx4 v[74:77], v[10:11], off offset:384
	global_load_dwordx4 v[138:141], v[12:13], off offset:384
	global_load_dwordx4 v[142:145], v[8:9], off offset:384
	global_load_dwordx4 v[154:157], v[6:7], off offset:384
	s_waitcnt lgkmcnt(0)
	s_barrier
; #define GL_LOAD(s_, kt_) if (VAR != 1) { a##s_##0 = GL_A(0, kt_); a##s_##1 = GL_A(1, kt_); a##s_##2 = GL_A(2, kt_); a##s_##3 = GL_A(3, kt_); b##s_##0 = GL_B(0, kt_); b##s_##1 = GL_B(1, kt_); b##s_##2 = GL_B(2, kt_); b##s_##3 = GL_B(3, kt_); }
; #define LDS_STORE(s_, buf_) if (VAR != 2) { LDS_ST1(sA, 0, buf_, a##s_##0) LDS_ST1(sA, 1, buf_, a##s_##1) LDS_ST1(sA, 2, buf_, a##s_##2) LDS_ST1(sA, 3, buf_, a##s_##3) LDS_ST1(sB, 0, buf_, b##s_##0) LDS_ST1(sB, 1, buf_, b##s_##1) LDS_ST1(sB, 2, buf_, b##s_##2) LDS_ST1(sB, 3, buf_, b##s_##3) }
;     ...
;   GL_LOAD(0, 0)
;   GL_LOAD(1, 1)
;   LDS_STORE(0, 0)
;   if (VAR != 4) __syncthreads();
; #pragma unroll
;   for (int kt = 0; kt < nk; kt += 2) {
;     if (kt + 2 < nk) { GL_LOAD(0, kt + 2) }
;     MMA_TILE(0)
;     LDS_STORE(1, 1)
;     if (VAR != 4) __syncthreads();
;     if (kt + 3 < nk) { GL_LOAD(1, kt + 3) }
;     MMA_TILE(1)
;     if (kt + 2 < nk) { LDS_STORE(0, 0) }
;     if (VAR != 4) __syncthreads();
	v_mfma_f32_16x16x32_f16 v[48:51], v[118:121], v[94:97], v[50:53]
	ds_read_b128 v[106:109], v16 offset:32768
	ds_read_b128 v[94:97], v21
	s_waitcnt lgkmcnt(0)
	v_mfma_f32_16x16x32_f16 v[36:39], v[106:109], v[94:97], v[36:39]
	ds_read_b128 v[52:55], v16 offset:34816
	ds_read_b128 v[110:113], v21 offset:2048
	s_waitcnt lgkmcnt(0)
	v_mfma_f32_16x16x32_f16 v[66:69], v[106:109], v[110:113], v[66:69]
	ds_read_b128 v[118:121], v16 offset:36864
	v_mfma_f32_16x16x32_f16 v[44:47], v[52:55], v[94:97], v[44:47]
	ds_read_b128 v[130:133], v16 offset:38912
	v_mfma_f32_16x16x32_f16 v[78:81], v[52:55], v[110:113], v[78:81]
	s_waitcnt vmcnt(7)
	ds_write_b128 v17, v[62:65] offset:16384
	s_waitcnt lgkmcnt(2)
	v_mfma_f32_16x16x32_f16 v[82:85], v[118:121], v[94:97], v[82:85]
	s_waitcnt vmcnt(6)
	ds_write_b128 v18, v[90:93] offset:16384
	v_mfma_f32_16x16x32_f16 v[86:89], v[118:121], v[110:113], v[86:89]
	s_waitcnt vmcnt(5)
	ds_write_b128 v19, v[122:125] offset:16384
	s_waitcnt lgkmcnt(3)
	v_mfma_f32_16x16x32_f16 v[28:31], v[130:133], v[94:97], v[28:31]
	ds_read_b128 v[94:97], v21 offset:4096
	v_mfma_f32_16x16x32_f16 v[32:35], v[130:133], v[110:113], v[32:35]
	ds_read_b128 v[110:113], v21 offset:6144
	s_waitcnt lgkmcnt(1)
	v_mfma_f32_16x16x32_f16 v[98:101], v[106:109], v[94:97], v[98:101]
	s_waitcnt vmcnt(4)
	ds_write_b128 v20, v[126:129] offset:16384
	s_waitcnt lgkmcnt(1)
	v_mfma_f32_16x16x32_f16 v[58:61], v[106:109], v[110:113], v[58:61]
	ds_read_b128 v[106:109], v23
	v_mfma_f32_16x16x32_f16 v[102:105], v[52:55], v[94:97], v[102:105]
	s_waitcnt vmcnt(3)
	ds_write_b128 v17, v[74:77] offset:49152
	v_mfma_f32_16x16x32_f16 v[24:27], v[52:55], v[110:113], v[24:27]
	ds_read_b128 v[52:55], v22 offset:32768
	v_mfma_f32_16x16x32_f16 v[114:117], v[118:121], v[94:97], v[114:117]
	s_waitcnt vmcnt(2)
	ds_write_b128 v18, v[138:141] offset:49152
	v_mfma_f32_16x16x32_f16 v[40:43], v[118:121], v[110:113], v[40:43]
	ds_read_b128 v[118:121], v22 offset:36864
	v_mfma_f32_16x16x32_f16 v[70:73], v[130:133], v[94:97], v[70:73]
	ds_read_b128 v[94:97], v22 offset:34816
	v_mfma_f32_16x16x32_f16 v[48:51], v[130:133], v[110:113], v[48:51]
	ds_read_b128 v[110:113], v23 offset:2048
	s_waitcnt lgkmcnt(4)
	v_mfma_f32_16x16x32_f16 v[36:39], v[52:55], v[106:109], v[36:39]
	ds_read_b128 v[130:133], v22 offset:38912
	s_waitcnt lgkmcnt(1)
	v_mfma_f32_16x16x32_f16 v[66:69], v[52:55], v[110:113], v[66:69]
	s_waitcnt vmcnt(1)
	ds_write_b128 v19, v[142:145] offset:49152
	v_mfma_f32_16x16x32_f16 v[44:47], v[94:97], v[106:109], v[44:47]
	s_waitcnt vmcnt(0)
	ds_write_b128 v20, v[154:157] offset:49152
	v_mfma_f32_16x16x32_f16 v[78:81], v[94:97], v[110:113], v[78:81]
	v_mfma_f32_16x16x32_f16 v[82:85], v[118:121], v[106:109], v[82:85]
	v_mfma_f32_16x16x32_f16 v[86:89], v[118:121], v[110:113], v[86:89]
	s_waitcnt lgkmcnt(2)
	v_mfma_f32_16x16x32_f16 v[28:31], v[130:133], v[106:109], v[28:31]
	ds_read_b128 v[106:109], v23 offset:4096
	v_mfma_f32_16x16x32_f16 v[32:35], v[130:133], v[110:113], v[32:35]
	ds_read_b128 v[110:113], v23 offset:6144
	s_waitcnt lgkmcnt(1)
	v_mfma_f32_16x16x32_f16 v[98:101], v[52:55], v[106:109], v[98:101]
	s_waitcnt lgkmcnt(0)
	v_mfma_f32_16x16x32_f16 v[52:55], v[52:55], v[110:113], v[58:61]
	s_nop 2
	global_load_dwordx4 v[58:61], v[0:1], off offset:512
	v_mfma_f32_16x16x32_f16 v[102:105], v[94:97], v[106:109], v[102:105]
	v_mfma_f32_16x16x32_f16 v[24:27], v[94:97], v[110:113], v[24:27]
	v_mfma_f32_16x16x32_f16 v[114:117], v[118:121], v[106:109], v[114:117]
	v_mfma_f32_16x16x32_f16 v[40:43], v[118:121], v[110:113], v[40:43]
	v_mfma_f32_16x16x32_f16 v[70:73], v[130:133], v[106:109], v[70:73]
	global_load_dwordx4 v[106:109], v[2:3], off offset:512
	global_load_dwordx4 v[134:137], v[4:5], off offset:512
	global_load_dwordx4 v[158:161], v[14:15], off offset:512
	global_load_dwordx4 v[94:97], v[10:11], off offset:512
	global_load_dwordx4 v[162:165], v[12:13], off offset:512
	global_load_dwordx4 v[166:169], v[8:9], off offset:512
	global_load_dwordx4 v[190:193], v[6:7], off offset:512
	s_waitcnt lgkmcnt(0)
	s_barrier
	v_mfma_f32_16x16x32_f16 v[48:51], v[130:133], v[110:113], v[48:51]
	ds_read_b128 v[62:65], v16 offset:49152
	ds_read_b128 v[90:93], v21 offset:16384
	s_waitcnt lgkmcnt(0)
	v_mfma_f32_16x16x32_f16 v[36:39], v[62:65], v[90:93], v[36:39]
	ds_read_b128 v[74:77], v16 offset:51200
	ds_read_b128 v[110:113], v21 offset:18432
	s_waitcnt lgkmcnt(0)
	v_mfma_f32_16x16x32_f16 v[66:69], v[62:65], v[110:113], v[66:69]
	ds_read_b128 v[118:121], v16 offset:53248
	v_mfma_f32_16x16x32_f16 v[44:47], v[74:77], v[90:93], v[44:47]
	ds_read_b128 v[122:125], v16 offset:55296
	v_mfma_f32_16x16x32_f16 v[78:81], v[74:77], v[110:113], v[78:81]
	s_waitcnt vmcnt(7)
	ds_write_b128 v17, v[58:61]
	s_waitcnt lgkmcnt(2)
	v_mfma_f32_16x16x32_f16 v[82:85], v[118:121], v[90:93], v[82:85]
	s_waitcnt vmcnt(6)
	ds_write_b128 v18, v[106:109]
	v_mfma_f32_16x16x32_f16 v[86:89], v[118:121], v[110:113], v[86:89]
	s_waitcnt vmcnt(5)
	ds_write_b128 v19, v[134:137]
	s_waitcnt lgkmcnt(3)
	v_mfma_f32_16x16x32_f16 v[28:31], v[122:125], v[90:93], v[28:31]
	ds_read_b128 v[90:93], v21 offset:20480
	v_mfma_f32_16x16x32_f16 v[32:35], v[122:125], v[110:113], v[32:35]
	ds_read_b128 v[110:113], v21 offset:22528
	s_waitcnt lgkmcnt(1)
	v_mfma_f32_16x16x32_f16 v[98:101], v[62:65], v[90:93], v[98:101]
	s_waitcnt vmcnt(4)
	ds_write_b128 v20, v[158:161]
	s_waitcnt lgkmcnt(1)
	v_mfma_f32_16x16x32_f16 v[52:55], v[62:65], v[110:113], v[52:55]
	ds_read_b128 v[62:65], v22 offset:49152
	v_mfma_f32_16x16x32_f16 v[102:105], v[74:77], v[90:93], v[102:105]
	s_waitcnt vmcnt(3)
; #define GL_LOAD(s_, kt_) if (VAR != 1) { a##s_##0 = GL_A(0, kt_); a##s_##1 = GL_A(1, kt_); a##s_##2 = GL_A(2, kt_); a##s_##3 = GL_A(3, kt_); b##s_##0 = GL_B(0, kt_); b##s_##1 = GL_B(1, kt_); b##s_##2 = GL_B(2, kt_); b##s_##3 = GL_B(3, kt_); }
; #define LDS_STORE(s_, buf_) if (VAR != 2) { LDS_ST1(sA, 0, buf_, a##s_##0) LDS_ST1(sA, 1, buf_, a##s_##1) LDS_ST1(sA, 2, buf_, a##s_##2) LDS_ST1(sA, 3, buf_, a##s_##3) LDS_ST1(sB, 0, buf_, b##s_##0) LDS_ST1(sB, 1, buf_, b##s_##1) LDS_ST1(sB, 2, buf_, b##s_##2) LDS_ST1(sB, 3, buf_, b##s_##3) }
;     ...
;   GL_LOAD(0, 0)
;   GL_LOAD(1, 1)
;   LDS_STORE(0, 0)
;   if (VAR != 4) __syncthreads();
; #pragma unroll
;   for (int kt = 0; kt < nk; kt += 2) {
;     if (kt + 2 < nk) { GL_LOAD(0, kt + 2) }
;     MMA_TILE(0)
;     LDS_STORE(1, 1)
;     if (VAR != 4) __syncthreads();
;     if (kt + 3 < nk) { GL_LOAD(1, kt + 3) }
;     MMA_TILE(1)
;     if (kt + 2 < nk) { LDS_STORE(0, 0) }
;     if (VAR != 4) __syncthreads();
	ds_write_b128 v17, v[94:97] offset:32768
	v_mfma_f32_16x16x32_f16 v[24:27], v[74:77], v[110:113], v[24:27]
	ds_read_b128 v[74:77], v22 offset:51200
	v_mfma_f32_16x16x32_f16 v[114:117], v[118:121], v[90:93], v[114:117]
	s_waitcnt vmcnt(2)
	ds_write_b128 v18, v[162:165] offset:32768
	v_mfma_f32_16x16x32_f16 v[40:43], v[118:121], v[110:113], v[40:43]
	ds_read_b128 v[118:121], v22 offset:53248
	v_mfma_f32_16x16x32_f16 v[70:73], v[122:125], v[90:93], v[70:73]
	ds_read_b128 v[90:93], v23 offset:16384
	v_mfma_f32_16x16x32_f16 v[48:51], v[122:125], v[110:113], v[48:51]
	ds_read_b128 v[110:113], v23 offset:18432
	s_waitcnt lgkmcnt(1)
	v_mfma_f32_16x16x32_f16 v[36:39], v[62:65], v[90:93], v[36:39]
	ds_read_b128 v[122:125], v22 offset:55296
	s_waitcnt lgkmcnt(1)
	v_mfma_f32_16x16x32_f16 v[66:69], v[62:65], v[110:113], v[66:69]
	s_waitcnt vmcnt(1)
	ds_write_b128 v19, v[166:169] offset:32768
	v_mfma_f32_16x16x32_f16 v[44:47], v[74:77], v[90:93], v[44:47]
	s_waitcnt vmcnt(0)
	ds_write_b128 v20, v[190:193] offset:32768
	v_mfma_f32_16x16x32_f16 v[78:81], v[74:77], v[110:113], v[78:81]
	v_mfma_f32_16x16x32_f16 v[82:85], v[118:121], v[90:93], v[82:85]
	v_mfma_f32_16x16x32_f16 v[86:89], v[118:121], v[110:113], v[86:89]
	s_waitcnt lgkmcnt(2)
	v_mfma_f32_16x16x32_f16 v[28:31], v[122:125], v[90:93], v[28:31]
	ds_read_b128 v[90:93], v23 offset:20480
	v_mfma_f32_16x16x32_f16 v[32:35], v[122:125], v[110:113], v[32:35]
	ds_read_b128 v[110:113], v23 offset:22528
	s_waitcnt lgkmcnt(1)
	v_mfma_f32_16x16x32_f16 v[98:101], v[62:65], v[90:93], v[98:101]
	s_waitcnt lgkmcnt(0)
	v_mfma_f32_16x16x32_f16 v[52:55], v[62:65], v[110:113], v[52:55]
	global_load_dwordx4 v[62:65], v[0:1], off offset:640
	v_mfma_f32_16x16x32_f16 v[102:105], v[74:77], v[90:93], v[102:105]
	v_mfma_f32_16x16x32_f16 v[24:27], v[74:77], v[110:113], v[24:27]
	v_mfma_f32_16x16x32_f16 v[114:117], v[118:121], v[90:93], v[114:117]
	v_mfma_f32_16x16x32_f16 v[40:43], v[118:121], v[110:113], v[40:43]
	v_mfma_f32_16x16x32_f16 v[70:73], v[122:125], v[90:93], v[70:73]
	global_load_dwordx4 v[90:93], v[2:3], off offset:640
	global_load_dwordx4 v[126:129], v[4:5], off offset:640
	global_load_dwordx4 v[130:133], v[14:15], off offset:640
	global_load_dwordx4 v[74:77], v[10:11], off offset:640
	global_load_dwordx4 v[138:141], v[12:13], off offset:640
	global_load_dwordx4 v[142:145], v[8:9], off offset:640
	global_load_dwordx4 v[154:157], v[6:7], off offset:640
	s_waitcnt lgkmcnt(0)
	s_barrier
	v_mfma_f32_16x16x32_f16 v[48:51], v[122:125], v[110:113], v[48:51]
	ds_read_b128 v[58:61], v16 offset:32768
	ds_read_b128 v[106:109], v21
	s_waitcnt lgkmcnt(0)
	v_mfma_f32_16x16x32_f16 v[36:39], v[58:61], v[106:109], v[36:39]
	ds_read_b128 v[94:97], v16 offset:34816
	ds_read_b128 v[110:113], v21 offset:2048
	s_waitcnt lgkmcnt(0)
	v_mfma_f32_16x16x32_f16 v[66:69], v[58:61], v[110:113], v[66:69]
	ds_read_b128 v[118:121], v16 offset:36864
	v_mfma_f32_16x16x32_f16 v[44:47], v[94:97], v[106:109], v[44:47]
	ds_read_b128 v[122:125], v16 offset:38912
	v_mfma_f32_16x16x32_f16 v[78:81], v[94:97], v[110:113], v[78:81]
	s_waitcnt vmcnt(7)
	ds_write_b128 v17, v[62:65] offset:16384
	s_waitcnt lgkmcnt(2)
	v_mfma_f32_16x16x32_f16 v[82:85], v[118:121], v[106:109], v[82:85]
	s_waitcnt vmcnt(6)
	ds_write_b128 v18, v[90:93] offset:16384
	v_mfma_f32_16x16x32_f16 v[86:89], v[118:121], v[110:113], v[86:89]
	s_waitcnt vmcnt(5)
	ds_write_b128 v19, v[126:129] offset:16384
	s_waitcnt lgkmcnt(3)
	v_mfma_f32_16x16x32_f16 v[28:31], v[122:125], v[106:109], v[28:31]
	ds_read_b128 v[106:109], v21 offset:4096
	v_mfma_f32_16x16x32_f16 v[32:35], v[122:125], v[110:113], v[32:35]
	ds_read_b128 v[110:113], v21 offset:6144
	s_waitcnt lgkmcnt(1)
	v_mfma_f32_16x16x32_f16 v[98:101], v[58:61], v[106:109], v[98:101]
	s_waitcnt vmcnt(4)
	ds_write_b128 v20, v[130:133] offset:16384
	s_waitcnt lgkmcnt(1)
	v_mfma_f32_16x16x32_f16 v[52:55], v[58:61], v[110:113], v[52:55]
	ds_read_b128 v[58:61], v22 offset:32768
	v_mfma_f32_16x16x32_f16 v[102:105], v[94:97], v[106:109], v[102:105]
	s_waitcnt vmcnt(3)
	ds_write_b128 v17, v[74:77] offset:49152
	v_mfma_f32_16x16x32_f16 v[24:27], v[94:97], v[110:113], v[24:27]
	ds_read_b128 v[94:97], v22 offset:34816
	v_mfma_f32_16x16x32_f16 v[114:117], v[118:121], v[106:109], v[114:117]
	s_waitcnt vmcnt(2)
	ds_write_b128 v18, v[138:141] offset:49152
	v_mfma_f32_16x16x32_f16 v[40:43], v[118:121], v[110:113], v[40:43]
	ds_read_b128 v[118:121], v22 offset:36864
	v_mfma_f32_16x16x32_f16 v[70:73], v[122:125], v[106:109], v[70:73]
	ds_read_b128 v[106:109], v23
	v_mfma_f32_16x16x32_f16 v[48:51], v[122:125], v[110:113], v[48:51]
	ds_read_b128 v[110:113], v23 offset:2048
	s_waitcnt lgkmcnt(1)
	v_mfma_f32_16x16x32_f16 v[36:39], v[58:61], v[106:109], v[36:39]
	ds_read_b128 v[122:125], v22 offset:38912
	s_waitcnt lgkmcnt(1)
	v_mfma_f32_16x16x32_f16 v[66:69], v[58:61], v[110:113], v[66:69]
	s_waitcnt vmcnt(1)
	ds_write_b128 v19, v[142:145] offset:49152
	v_mfma_f32_16x16x32_f16 v[44:47], v[94:97], v[106:109], v[44:47]
	s_waitcnt vmcnt(0)
	ds_write_b128 v20, v[154:157] offset:49152
	v_mfma_f32_16x16x32_f16 v[78:81], v[94:97], v[110:113], v[78:81]
	v_mfma_f32_16x16x32_f16 v[82:85], v[118:121], v[106:109], v[82:85]
	v_mfma_f32_16x16x32_f16 v[86:89], v[118:121], v[110:113], v[86:89]
	s_waitcnt lgkmcnt(2)
	v_mfma_f32_16x16x32_f16 v[28:31], v[122:125], v[106:109], v[28:31]
	ds_read_b128 v[106:109], v23 offset:4096
	v_mfma_f32_16x16x32_f16 v[32:35], v[122:125], v[110:113], v[32:35]
	ds_read_b128 v[110:113], v23 offset:6144
	s_waitcnt lgkmcnt(1)
	v_mfma_f32_16x16x32_f16 v[98:101], v[58:61], v[106:109], v[98:101]
	s_waitcnt lgkmcnt(0)
	v_mfma_f32_16x16x32_f16 v[52:55], v[58:61], v[110:113], v[52:55]
	global_load_dwordx4 v[58:61], v[0:1], off offset:768
	v_mfma_f32_16x16x32_f16 v[102:105], v[94:97], v[106:109], v[102:105]
	v_mfma_f32_16x16x32_f16 v[24:27], v[94:97], v[110:113], v[24:27]
	v_mfma_f32_16x16x32_f16 v[114:117], v[118:121], v[106:109], v[114:117]
	v_mfma_f32_16x16x32_f16 v[40:43], v[118:121], v[110:113], v[40:43]
	v_mfma_f32_16x16x32_f16 v[70:73], v[122:125], v[106:109], v[70:73]
	global_load_dwordx4 v[106:109], v[2:3], off offset:768
	global_load_dwordx4 v[134:137], v[4:5], off offset:768
	global_load_dwordx4 v[158:161], v[14:15], off offset:768
	global_load_dwordx4 v[94:97], v[10:11], off offset:768
	global_load_dwordx4 v[162:165], v[12:13], off offset:768
	global_load_dwordx4 v[166:169], v[8:9], off offset:768
	global_load_dwordx4 v[190:193], v[6:7], off offset:768
	s_waitcnt lgkmcnt(0)
	s_barrier
; #define GL_LOAD(s_, kt_) if (VAR != 1) { a##s_##0 = GL_A(0, kt_); a##s_##1 = GL_A(1, kt_); a##s_##2 = GL_A(2, kt_); a##s_##3 = GL_A(3, kt_); b##s_##0 = GL_B(0, kt_); b##s_##1 = GL_B(1, kt_); b##s_##2 = GL_B(2, kt_); b##s_##3 = GL_B(3, kt_); }
; #define LDS_STORE(s_, buf_) if (VAR != 2) { LDS_ST1(sA, 0, buf_, a##s_##0) LDS_ST1(sA, 1, buf_, a##s_##1) LDS_ST1(sA, 2, buf_, a##s_##2) LDS_ST1(sA, 3, buf_, a##s_##3) LDS_ST1(sB, 0, buf_, b##s_##0) LDS_ST1(sB, 1, buf_, b##s_##1) LDS_ST1(sB, 2, buf_, b##s_##2) LDS_ST1(sB, 3, buf_, b##s_##3) }
;     ...
;   GL_LOAD(0, 0)
;   GL_LOAD(1, 1)
;   LDS_STORE(0, 0)
;   if (VAR != 4) __syncthreads();
; #pragma unroll
;   for (int kt = 0; kt < nk; kt += 2) {
;     if (kt + 2 < nk) { GL_LOAD(0, kt + 2) }
;     MMA_TILE(0)
;     LDS_STORE(1, 1)
;     if (VAR != 4) __syncthreads();
;     if (kt + 3 < nk) { GL_LOAD(1, kt + 3) }
;     MMA_TILE(1)
;     if (kt + 2 < nk) { LDS_STORE(0, 0) }
;     if (VAR != 4) __syncthreads();
	v_mfma_f32_16x16x32_f16 v[48:51], v[122:125], v[110:113], v[48:51]
	ds_read_b128 v[62:65], v16 offset:49152
	ds_read_b128 v[90:93], v21 offset:16384
	s_waitcnt lgkmcnt(0)
	v_mfma_f32_16x16x32_f16 v[36:39], v[62:65], v[90:93], v[36:39]
	ds_read_b128 v[74:77], v16 offset:51200
	ds_read_b128 v[110:113], v21 offset:18432
	s_waitcnt lgkmcnt(0)
	v_mfma_f32_16x16x32_f16 v[66:69], v[62:65], v[110:113], v[66:69]
	ds_read_b128 v[118:121], v16 offset:53248
	v_mfma_f32_16x16x32_f16 v[44:47], v[74:77], v[90:93], v[44:47]
	ds_read_b128 v[122:125], v16 offset:55296
	v_mfma_f32_16x16x32_f16 v[78:81], v[74:77], v[110:113], v[78:81]
	s_waitcnt vmcnt(7)
	ds_write_b128 v17, v[58:61]
	s_waitcnt lgkmcnt(2)
	v_mfma_f32_16x16x32_f16 v[82:85], v[118:121], v[90:93], v[82:85]
	s_waitcnt vmcnt(6)
	ds_write_b128 v18, v[106:109]
	v_mfma_f32_16x16x32_f16 v[86:89], v[118:121], v[110:113], v[86:89]
	s_waitcnt vmcnt(5)
	ds_write_b128 v19, v[134:137]
	s_waitcnt lgkmcnt(3)
	v_mfma_f32_16x16x32_f16 v[28:31], v[122:125], v[90:93], v[28:31]
	ds_read_b128 v[90:93], v21 offset:20480
	v_mfma_f32_16x16x32_f16 v[32:35], v[122:125], v[110:113], v[32:35]
	ds_read_b128 v[110:113], v21 offset:22528
	s_waitcnt lgkmcnt(1)
	v_mfma_f32_16x16x32_f16 v[98:101], v[62:65], v[90:93], v[98:101]
	s_waitcnt vmcnt(4)
	ds_write_b128 v20, v[158:161]
	s_waitcnt lgkmcnt(1)
	v_mfma_f32_16x16x32_f16 v[52:55], v[62:65], v[110:113], v[52:55]
	ds_read_b128 v[62:65], v22 offset:49152
	v_mfma_f32_16x16x32_f16 v[102:105], v[74:77], v[90:93], v[102:105]
	s_waitcnt vmcnt(3)
	ds_write_b128 v17, v[94:97] offset:32768
	v_mfma_f32_16x16x32_f16 v[24:27], v[74:77], v[110:113], v[24:27]
	ds_read_b128 v[74:77], v22 offset:51200
	v_mfma_f32_16x16x32_f16 v[114:117], v[118:121], v[90:93], v[114:117]
	s_waitcnt vmcnt(2)
	ds_write_b128 v18, v[162:165] offset:32768
	v_mfma_f32_16x16x32_f16 v[40:43], v[118:121], v[110:113], v[40:43]
	ds_read_b128 v[118:121], v22 offset:53248
	v_mfma_f32_16x16x32_f16 v[70:73], v[122:125], v[90:93], v[70:73]
	ds_read_b128 v[90:93], v23 offset:16384
	v_mfma_f32_16x16x32_f16 v[48:51], v[122:125], v[110:113], v[48:51]
	ds_read_b128 v[110:113], v23 offset:18432
	s_waitcnt lgkmcnt(1)
	v_mfma_f32_16x16x32_f16 v[36:39], v[62:65], v[90:93], v[36:39]
	ds_read_b128 v[122:125], v22 offset:55296
	s_waitcnt lgkmcnt(1)
	v_mfma_f32_16x16x32_f16 v[66:69], v[62:65], v[110:113], v[66:69]
	s_waitcnt vmcnt(1)
	ds_write_b128 v19, v[166:169] offset:32768
	v_mfma_f32_16x16x32_f16 v[44:47], v[74:77], v[90:93], v[44:47]
	s_waitcnt vmcnt(0)
	ds_write_b128 v20, v[190:193] offset:32768
	v_mfma_f32_16x16x32_f16 v[78:81], v[74:77], v[110:113], v[78:81]
	v_mfma_f32_16x16x32_f16 v[82:85], v[118:121], v[90:93], v[82:85]
	v_mfma_f32_16x16x32_f16 v[86:89], v[118:121], v[110:113], v[86:89]
	s_waitcnt lgkmcnt(2)
	v_mfma_f32_16x16x32_f16 v[28:31], v[122:125], v[90:93], v[28:31]
	ds_read_b128 v[90:93], v23 offset:20480
	v_mfma_f32_16x16x32_f16 v[32:35], v[122:125], v[110:113], v[32:35]
	ds_read_b128 v[110:113], v23 offset:22528
	s_waitcnt lgkmcnt(1)
	v_mfma_f32_16x16x32_f16 v[98:101], v[62:65], v[90:93], v[98:101]
	s_waitcnt lgkmcnt(0)
	v_mfma_f32_16x16x32_f16 v[52:55], v[62:65], v[110:113], v[52:55]
	global_load_dwordx4 v[62:65], v[0:1], off offset:896
	v_mfma_f32_16x16x32_f16 v[102:105], v[74:77], v[90:93], v[102:105]
	v_mfma_f32_16x16x32_f16 v[24:27], v[74:77], v[110:113], v[24:27]
	v_mfma_f32_16x16x32_f16 v[114:117], v[118:121], v[90:93], v[114:117]
	v_mfma_f32_16x16x32_f16 v[40:43], v[118:121], v[110:113], v[40:43]
	v_mfma_f32_16x16x32_f16 v[70:73], v[122:125], v[90:93], v[70:73]
	global_load_dwordx4 v[90:93], v[2:3], off offset:896
	global_load_dwordx4 v[126:129], v[4:5], off offset:896
	global_load_dwordx4 v[130:133], v[14:15], off offset:896
	global_load_dwordx4 v[74:77], v[10:11], off offset:896
	global_load_dwordx4 v[138:141], v[12:13], off offset:896
	global_load_dwordx4 v[142:145], v[8:9], off offset:896
	global_load_dwordx4 v[154:157], v[6:7], off offset:896
	s_waitcnt lgkmcnt(0)
	s_barrier
	v_mfma_f32_16x16x32_f16 v[48:51], v[122:125], v[110:113], v[48:51]
	ds_read_b128 v[58:61], v16 offset:32768
	ds_read_b128 v[106:109], v21
	s_waitcnt lgkmcnt(0)
	v_mfma_f32_16x16x32_f16 v[36:39], v[58:61], v[106:109], v[36:39]
	ds_read_b128 v[94:97], v16 offset:34816
	ds_read_b128 v[110:113], v21 offset:2048
	s_waitcnt lgkmcnt(0)
	v_mfma_f32_16x16x32_f16 v[66:69], v[58:61], v[110:113], v[66:69]
	ds_read_b128 v[118:121], v16 offset:36864
	v_mfma_f32_16x16x32_f16 v[44:47], v[94:97], v[106:109], v[44:47]
	ds_read_b128 v[122:125], v16 offset:38912
	v_mfma_f32_16x16x32_f16 v[78:81], v[94:97], v[110:113], v[78:81]
	s_waitcnt vmcnt(7)
	ds_write_b128 v17, v[62:65] offset:16384
	s_waitcnt lgkmcnt(2)
	v_mfma_f32_16x16x32_f16 v[82:85], v[118:121], v[106:109], v[82:85]
	s_waitcnt vmcnt(6)
	ds_write_b128 v18, v[90:93] offset:16384
	v_mfma_f32_16x16x32_f16 v[86:89], v[118:121], v[110:113], v[86:89]
	s_waitcnt vmcnt(5)
	ds_write_b128 v19, v[126:129] offset:16384
	s_waitcnt lgkmcnt(3)
	v_mfma_f32_16x16x32_f16 v[28:31], v[122:125], v[106:109], v[28:31]
	ds_read_b128 v[106:109], v21 offset:4096
	v_mfma_f32_16x16x32_f16 v[32:35], v[122:125], v[110:113], v[32:35]
	ds_read_b128 v[110:113], v21 offset:6144
	s_waitcnt lgkmcnt(1)
	v_mfma_f32_16x16x32_f16 v[98:101], v[58:61], v[106:109], v[98:101]
	s_waitcnt vmcnt(4)
	ds_write_b128 v20, v[130:133] offset:16384
	s_waitcnt lgkmcnt(1)
	v_mfma_f32_16x16x32_f16 v[52:55], v[58:61], v[110:113], v[52:55]
	ds_read_b128 v[58:61], v22 offset:32768
	v_mfma_f32_16x16x32_f16 v[102:105], v[94:97], v[106:109], v[102:105]
	s_waitcnt vmcnt(3)
; #define GL_LOAD(s_, kt_) if (VAR != 1) { a##s_##0 = GL_A(0, kt_); a##s_##1 = GL_A(1, kt_); a##s_##2 = GL_A(2, kt_); a##s_##3 = GL_A(3, kt_); b##s_##0 = GL_B(0, kt_); b##s_##1 = GL_B(1, kt_); b##s_##2 = GL_B(2, kt_); b##s_##3 = GL_B(3, kt_); }
; #define LDS_STORE(s_, buf_) if (VAR != 2) { LDS_ST1(sA, 0, buf_, a##s_##0) LDS_ST1(sA, 1, buf_, a##s_##1) LDS_ST1(sA, 2, buf_, a##s_##2) LDS_ST1(sA, 3, buf_, a##s_##3) LDS_ST1(sB, 0, buf_, b##s_##0) LDS_ST1(sB, 1, buf_, b##s_##1) LDS_ST1(sB, 2, buf_, b##s_##2) LDS_ST1(sB, 3, buf_, b##s_##3) }
;     ...
;   GL_LOAD(0, 0)
;   GL_LOAD(1, 1)
;   LDS_STORE(0, 0)
;   if (VAR != 4) __syncthreads();
; #pragma unroll
;   for (int kt = 0; kt < nk; kt += 2) {
;     if (kt + 2 < nk) { GL_LOAD(0, kt + 2) }
;     MMA_TILE(0)
;     LDS_STORE(1, 1)
;     if (VAR != 4) __syncthreads();
;     if (kt + 3 < nk) { GL_LOAD(1, kt + 3) }
;     MMA_TILE(1)
;     if (kt + 2 < nk) { LDS_STORE(0, 0) }
;     if (VAR != 4) __syncthreads();
	ds_write_b128 v17, v[74:77] offset:49152
	v_mfma_f32_16x16x32_f16 v[24:27], v[94:97], v[110:113], v[24:27]
	ds_read_b128 v[94:97], v22 offset:34816
	v_mfma_f32_16x16x32_f16 v[114:117], v[118:121], v[106:109], v[114:117]
	s_waitcnt vmcnt(2)
	ds_write_b128 v18, v[138:141] offset:49152
	v_mfma_f32_16x16x32_f16 v[40:43], v[118:121], v[110:113], v[40:43]
	ds_read_b128 v[118:121], v22 offset:36864
	v_mfma_f32_16x16x32_f16 v[70:73], v[122:125], v[106:109], v[70:73]
	ds_read_b128 v[106:109], v23
	v_mfma_f32_16x16x32_f16 v[48:51], v[122:125], v[110:113], v[48:51]
	ds_read_b128 v[110:113], v23 offset:2048
	s_waitcnt lgkmcnt(1)
	v_mfma_f32_16x16x32_f16 v[36:39], v[58:61], v[106:109], v[36:39]
	ds_read_b128 v[122:125], v22 offset:38912
	s_waitcnt lgkmcnt(1)
	v_mfma_f32_16x16x32_f16 v[66:69], v[58:61], v[110:113], v[66:69]
	s_waitcnt vmcnt(1)
	ds_write_b128 v19, v[142:145] offset:49152
	v_mfma_f32_16x16x32_f16 v[44:47], v[94:97], v[106:109], v[44:47]
	s_waitcnt vmcnt(0)
	ds_write_b128 v20, v[154:157] offset:49152
	v_mfma_f32_16x16x32_f16 v[78:81], v[94:97], v[110:113], v[78:81]
	v_mfma_f32_16x16x32_f16 v[82:85], v[118:121], v[106:109], v[82:85]
	v_mfma_f32_16x16x32_f16 v[86:89], v[118:121], v[110:113], v[86:89]
	s_waitcnt lgkmcnt(2)
	v_mfma_f32_16x16x32_f16 v[28:31], v[122:125], v[106:109], v[28:31]
	ds_read_b128 v[106:109], v23 offset:4096
	v_mfma_f32_16x16x32_f16 v[32:35], v[122:125], v[110:113], v[32:35]
	ds_read_b128 v[110:113], v23 offset:6144
	s_waitcnt lgkmcnt(1)
	v_mfma_f32_16x16x32_f16 v[98:101], v[58:61], v[106:109], v[98:101]
	s_waitcnt lgkmcnt(0)
	v_mfma_f32_16x16x32_f16 v[52:55], v[58:61], v[110:113], v[52:55]
	global_load_dwordx4 v[58:61], v[0:1], off offset:1024
	v_mfma_f32_16x16x32_f16 v[102:105], v[94:97], v[106:109], v[102:105]
	v_mfma_f32_16x16x32_f16 v[24:27], v[94:97], v[110:113], v[24:27]
	v_mfma_f32_16x16x32_f16 v[114:117], v[118:121], v[106:109], v[114:117]
	v_mfma_f32_16x16x32_f16 v[40:43], v[118:121], v[110:113], v[40:43]
	v_mfma_f32_16x16x32_f16 v[70:73], v[122:125], v[106:109], v[70:73]
	global_load_dwordx4 v[106:109], v[2:3], off offset:1024
	global_load_dwordx4 v[134:137], v[4:5], off offset:1024
	global_load_dwordx4 v[158:161], v[14:15], off offset:1024
	global_load_dwordx4 v[94:97], v[10:11], off offset:1024
	global_load_dwordx4 v[162:165], v[12:13], off offset:1024
	global_load_dwordx4 v[166:169], v[8:9], off offset:1024
	global_load_dwordx4 v[190:193], v[6:7], off offset:1024
	s_waitcnt lgkmcnt(0)
	s_barrier
	v_mfma_f32_16x16x32_f16 v[48:51], v[122:125], v[110:113], v[48:51]
	ds_read_b128 v[62:65], v16 offset:49152
	ds_read_b128 v[90:93], v21 offset:16384
	s_waitcnt lgkmcnt(0)
	v_mfma_f32_16x16x32_f16 v[36:39], v[62:65], v[90:93], v[36:39]
	ds_read_b128 v[74:77], v16 offset:51200
	ds_read_b128 v[110:113], v21 offset:18432
	s_waitcnt lgkmcnt(0)
	v_mfma_f32_16x16x32_f16 v[66:69], v[62:65], v[110:113], v[66:69]
	ds_read_b128 v[118:121], v16 offset:53248
	v_mfma_f32_16x16x32_f16 v[44:47], v[74:77], v[90:93], v[44:47]
	ds_read_b128 v[122:125], v16 offset:55296
	v_mfma_f32_16x16x32_f16 v[78:81], v[74:77], v[110:113], v[78:81]
	s_waitcnt vmcnt(7)
	ds_write_b128 v17, v[58:61]
	s_waitcnt lgkmcnt(2)
	v_mfma_f32_16x16x32_f16 v[82:85], v[118:121], v[90:93], v[82:85]
	s_waitcnt vmcnt(6)
	ds_write_b128 v18, v[106:109]
	v_mfma_f32_16x16x32_f16 v[86:89], v[118:121], v[110:113], v[86:89]
	s_waitcnt vmcnt(5)
	ds_write_b128 v19, v[134:137]
	s_waitcnt lgkmcnt(3)
	v_mfma_f32_16x16x32_f16 v[28:31], v[122:125], v[90:93], v[28:31]
	ds_read_b128 v[90:93], v21 offset:20480
	v_mfma_f32_16x16x32_f16 v[32:35], v[122:125], v[110:113], v[32:35]
	ds_read_b128 v[110:113], v21 offset:22528
	s_waitcnt lgkmcnt(1)
	v_mfma_f32_16x16x32_f16 v[98:101], v[62:65], v[90:93], v[98:101]
	s_waitcnt vmcnt(4)
	ds_write_b128 v20, v[158:161]
	s_waitcnt lgkmcnt(1)
	v_mfma_f32_16x16x32_f16 v[52:55], v[62:65], v[110:113], v[52:55]
	ds_read_b128 v[62:65], v22 offset:49152
	v_mfma_f32_16x16x32_f16 v[102:105], v[74:77], v[90:93], v[102:105]
	s_waitcnt vmcnt(3)
	ds_write_b128 v17, v[94:97] offset:32768
	v_mfma_f32_16x16x32_f16 v[24:27], v[74:77], v[110:113], v[24:27]
	ds_read_b128 v[74:77], v22 offset:51200
	v_mfma_f32_16x16x32_f16 v[114:117], v[118:121], v[90:93], v[114:117]
	s_waitcnt vmcnt(2)
	ds_write_b128 v18, v[162:165] offset:32768
	v_mfma_f32_16x16x32_f16 v[40:43], v[118:121], v[110:113], v[40:43]
	ds_read_b128 v[118:121], v22 offset:53248
	v_mfma_f32_16x16x32_f16 v[70:73], v[122:125], v[90:93], v[70:73]
	ds_read_b128 v[90:93], v23 offset:16384
	v_mfma_f32_16x16x32_f16 v[48:51], v[122:125], v[110:113], v[48:51]
	ds_read_b128 v[110:113], v23 offset:18432
	s_waitcnt lgkmcnt(1)
	v_mfma_f32_16x16x32_f16 v[36:39], v[62:65], v[90:93], v[36:39]
	ds_read_b128 v[122:125], v22 offset:55296
	s_waitcnt lgkmcnt(1)
	v_mfma_f32_16x16x32_f16 v[66:69], v[62:65], v[110:113], v[66:69]
	s_waitcnt vmcnt(1)
	ds_write_b128 v19, v[166:169] offset:32768
	v_mfma_f32_16x16x32_f16 v[44:47], v[74:77], v[90:93], v[44:47]
	s_waitcnt vmcnt(0)
	ds_write_b128 v20, v[190:193] offset:32768
	v_mfma_f32_16x16x32_f16 v[78:81], v[74:77], v[110:113], v[78:81]
	v_mfma_f32_16x16x32_f16 v[82:85], v[118:121], v[90:93], v[82:85]
	v_mfma_f32_16x16x32_f16 v[86:89], v[118:121], v[110:113], v[86:89]
	s_waitcnt lgkmcnt(2)
	v_mfma_f32_16x16x32_f16 v[28:31], v[122:125], v[90:93], v[28:31]
	ds_read_b128 v[90:93], v23 offset:20480
	v_mfma_f32_16x16x32_f16 v[32:35], v[122:125], v[110:113], v[32:35]
	ds_read_b128 v[110:113], v23 offset:22528
	s_waitcnt lgkmcnt(1)
	v_mfma_f32_16x16x32_f16 v[98:101], v[62:65], v[90:93], v[98:101]
	s_waitcnt lgkmcnt(0)
	v_mfma_f32_16x16x32_f16 v[52:55], v[62:65], v[110:113], v[52:55]
	global_load_dwordx4 v[62:65], v[0:1], off offset:1152
	v_mfma_f32_16x16x32_f16 v[102:105], v[74:77], v[90:93], v[102:105]
	v_mfma_f32_16x16x32_f16 v[24:27], v[74:77], v[110:113], v[24:27]
	v_mfma_f32_16x16x32_f16 v[114:117], v[118:121], v[90:93], v[114:117]
	v_mfma_f32_16x16x32_f16 v[40:43], v[118:121], v[110:113], v[40:43]
	v_mfma_f32_16x16x32_f16 v[70:73], v[122:125], v[90:93], v[70:73]
	global_load_dwordx4 v[90:93], v[2:3], off offset:1152
	global_load_dwordx4 v[126:129], v[4:5], off offset:1152
	global_load_dwordx4 v[130:133], v[14:15], off offset:1152
	global_load_dwordx4 v[74:77], v[10:11], off offset:1152
	global_load_dwordx4 v[138:141], v[12:13], off offset:1152
	global_load_dwordx4 v[142:145], v[8:9], off offset:1152
	global_load_dwordx4 v[154:157], v[6:7], off offset:1152
	s_waitcnt lgkmcnt(0)
	s_barrier
; #define GL_LOAD(s_, kt_) if (VAR != 1) { a##s_##0 = GL_A(0, kt_); a##s_##1 = GL_A(1, kt_); a##s_##2 = GL_A(2, kt_); a##s_##3 = GL_A(3, kt_); b##s_##0 = GL_B(0, kt_); b##s_##1 = GL_B(1, kt_); b##s_##2 = GL_B(2, kt_); b##s_##3 = GL_B(3, kt_); }
; #define LDS_STORE(s_, buf_) if (VAR != 2) { LDS_ST1(sA, 0, buf_, a##s_##0) LDS_ST1(sA, 1, buf_, a##s_##1) LDS_ST1(sA, 2, buf_, a##s_##2) LDS_ST1(sA, 3, buf_, a##s_##3) LDS_ST1(sB, 0, buf_, b##s_##0) LDS_ST1(sB, 1, buf_, b##s_##1) LDS_ST1(sB, 2, buf_, b##s_##2) LDS_ST1(sB, 3, buf_, b##s_##3) }
;     ...
;   GL_LOAD(0, 0)
;   GL_LOAD(1, 1)
;   LDS_STORE(0, 0)
;   if (VAR != 4) __syncthreads();
; #pragma unroll
;   for (int kt = 0; kt < nk; kt += 2) {
;     if (kt + 2 < nk) { GL_LOAD(0, kt + 2) }
;     MMA_TILE(0)
;     LDS_STORE(1, 1)
;     if (VAR != 4) __syncthreads();
;     if (kt + 3 < nk) { GL_LOAD(1, kt + 3) }
;     MMA_TILE(1)
;     if (kt + 2 < nk) { LDS_STORE(0, 0) }
;     if (VAR != 4) __syncthreads();
	v_mfma_f32_16x16x32_f16 v[48:51], v[122:125], v[110:113], v[48:51]
	ds_read_b128 v[58:61], v16 offset:32768
	ds_read_b128 v[106:109], v21
	s_waitcnt lgkmcnt(0)
	v_mfma_f32_16x16x32_f16 v[36:39], v[58:61], v[106:109], v[36:39]
	ds_read_b128 v[94:97], v16 offset:34816
	ds_read_b128 v[110:113], v21 offset:2048
	s_waitcnt lgkmcnt(0)
	v_mfma_f32_16x16x32_f16 v[66:69], v[58:61], v[110:113], v[66:69]
	ds_read_b128 v[118:121], v16 offset:36864
	v_mfma_f32_16x16x32_f16 v[44:47], v[94:97], v[106:109], v[44:47]
	ds_read_b128 v[122:125], v16 offset:38912
	v_mfma_f32_16x16x32_f16 v[78:81], v[94:97], v[110:113], v[78:81]
	s_waitcnt vmcnt(7)
	ds_write_b128 v17, v[62:65] offset:16384
	s_waitcnt lgkmcnt(2)
	v_mfma_f32_16x16x32_f16 v[82:85], v[118:121], v[106:109], v[82:85]
	s_waitcnt vmcnt(6)
	ds_write_b128 v18, v[90:93] offset:16384
	v_mfma_f32_16x16x32_f16 v[86:89], v[118:121], v[110:113], v[86:89]
	s_waitcnt vmcnt(5)
	ds_write_b128 v19, v[126:129] offset:16384
	s_waitcnt lgkmcnt(3)
	v_mfma_f32_16x16x32_f16 v[28:31], v[122:125], v[106:109], v[28:31]
	ds_read_b128 v[106:109], v21 offset:4096
	v_mfma_f32_16x16x32_f16 v[32:35], v[122:125], v[110:113], v[32:35]
	ds_read_b128 v[110:113], v21 offset:6144
	s_waitcnt lgkmcnt(1)
	v_mfma_f32_16x16x32_f16 v[98:101], v[58:61], v[106:109], v[98:101]
	s_waitcnt vmcnt(4)
	ds_write_b128 v20, v[130:133] offset:16384
	s_waitcnt lgkmcnt(1)
	v_mfma_f32_16x16x32_f16 v[52:55], v[58:61], v[110:113], v[52:55]
	ds_read_b128 v[58:61], v22 offset:32768
	v_mfma_f32_16x16x32_f16 v[102:105], v[94:97], v[106:109], v[102:105]
	s_waitcnt vmcnt(3)
	ds_write_b128 v17, v[74:77] offset:49152
	v_mfma_f32_16x16x32_f16 v[24:27], v[94:97], v[110:113], v[24:27]
	ds_read_b128 v[94:97], v22 offset:34816
	v_mfma_f32_16x16x32_f16 v[114:117], v[118:121], v[106:109], v[114:117]
	s_waitcnt vmcnt(2)
	ds_write_b128 v18, v[138:141] offset:49152
	v_mfma_f32_16x16x32_f16 v[40:43], v[118:121], v[110:113], v[40:43]
	ds_read_b128 v[118:121], v22 offset:36864
	v_mfma_f32_16x16x32_f16 v[70:73], v[122:125], v[106:109], v[70:73]
	ds_read_b128 v[106:109], v23
	v_mfma_f32_16x16x32_f16 v[48:51], v[122:125], v[110:113], v[48:51]
	ds_read_b128 v[110:113], v23 offset:2048
	s_waitcnt lgkmcnt(1)
	v_mfma_f32_16x16x32_f16 v[36:39], v[58:61], v[106:109], v[36:39]
	ds_read_b128 v[122:125], v22 offset:38912
	s_waitcnt lgkmcnt(1)
	v_mfma_f32_16x16x32_f16 v[66:69], v[58:61], v[110:113], v[66:69]
	s_waitcnt vmcnt(1)
	ds_write_b128 v19, v[142:145] offset:49152
	v_mfma_f32_16x16x32_f16 v[44:47], v[94:97], v[106:109], v[44:47]
	s_waitcnt vmcnt(0)
	ds_write_b128 v20, v[154:157] offset:49152
	v_mfma_f32_16x16x32_f16 v[78:81], v[94:97], v[110:113], v[78:81]
	v_mfma_f32_16x16x32_f16 v[82:85], v[118:121], v[106:109], v[82:85]
	v_mfma_f32_16x16x32_f16 v[86:89], v[118:121], v[110:113], v[86:89]
	s_waitcnt lgkmcnt(2)
	v_mfma_f32_16x16x32_f16 v[28:31], v[122:125], v[106:109], v[28:31]
	ds_read_b128 v[106:109], v23 offset:4096
	v_mfma_f32_16x16x32_f16 v[32:35], v[122:125], v[110:113], v[32:35]
	ds_read_b128 v[110:113], v23 offset:6144
	s_waitcnt lgkmcnt(1)
	v_mfma_f32_16x16x32_f16 v[98:101], v[58:61], v[106:109], v[98:101]
	s_waitcnt lgkmcnt(0)
	v_mfma_f32_16x16x32_f16 v[52:55], v[58:61], v[110:113], v[52:55]
	global_load_dwordx4 v[58:61], v[0:1], off offset:1280
	v_mfma_f32_16x16x32_f16 v[102:105], v[94:97], v[106:109], v[102:105]
	v_mfma_f32_16x16x32_f16 v[24:27], v[94:97], v[110:113], v[24:27]
	v_mfma_f32_16x16x32_f16 v[114:117], v[118:121], v[106:109], v[114:117]
	v_mfma_f32_16x16x32_f16 v[40:43], v[118:121], v[110:113], v[40:43]
	v_mfma_f32_16x16x32_f16 v[70:73], v[122:125], v[106:109], v[70:73]
	global_load_dwordx4 v[106:109], v[2:3], off offset:1280
	global_load_dwordx4 v[134:137], v[4:5], off offset:1280
	global_load_dwordx4 v[158:161], v[14:15], off offset:1280
	global_load_dwordx4 v[94:97], v[10:11], off offset:1280
	global_load_dwordx4 v[162:165], v[12:13], off offset:1280
	global_load_dwordx4 v[166:169], v[8:9], off offset:1280
	global_load_dwordx4 v[190:193], v[6:7], off offset:1280
	s_waitcnt lgkmcnt(0)
	s_barrier
	v_mfma_f32_16x16x32_f16 v[48:51], v[122:125], v[110:113], v[48:51]
	ds_read_b128 v[62:65], v16 offset:49152
	ds_read_b128 v[90:93], v21 offset:16384
	s_waitcnt lgkmcnt(0)
	v_mfma_f32_16x16x32_f16 v[36:39], v[62:65], v[90:93], v[36:39]
	ds_read_b128 v[74:77], v16 offset:51200
	ds_read_b128 v[110:113], v21 offset:18432
	s_waitcnt lgkmcnt(0)
	v_mfma_f32_16x16x32_f16 v[66:69], v[62:65], v[110:113], v[66:69]
	ds_read_b128 v[118:121], v16 offset:53248
	v_mfma_f32_16x16x32_f16 v[44:47], v[74:77], v[90:93], v[44:47]
	ds_read_b128 v[122:125], v16 offset:55296
	v_mfma_f32_16x16x32_f16 v[78:81], v[74:77], v[110:113], v[78:81]
	s_waitcnt vmcnt(7)
	ds_write_b128 v17, v[58:61]
	s_waitcnt lgkmcnt(2)
	v_mfma_f32_16x16x32_f16 v[82:85], v[118:121], v[90:93], v[82:85]
	s_waitcnt vmcnt(6)
	ds_write_b128 v18, v[106:109]
	v_mfma_f32_16x16x32_f16 v[86:89], v[118:121], v[110:113], v[86:89]
	s_waitcnt vmcnt(5)
	ds_write_b128 v19, v[134:137]
	s_waitcnt lgkmcnt(3)
	v_mfma_f32_16x16x32_f16 v[28:31], v[122:125], v[90:93], v[28:31]
	ds_read_b128 v[90:93], v21 offset:20480
	v_mfma_f32_16x16x32_f16 v[32:35], v[122:125], v[110:113], v[32:35]
	ds_read_b128 v[110:113], v21 offset:22528
	s_waitcnt lgkmcnt(1)
	v_mfma_f32_16x16x32_f16 v[98:101], v[62:65], v[90:93], v[98:101]
	s_waitcnt vmcnt(4)
	ds_write_b128 v20, v[158:161]
	s_waitcnt lgkmcnt(1)
	v_mfma_f32_16x16x32_f16 v[52:55], v[62:65], v[110:113], v[52:55]
	ds_read_b128 v[62:65], v22 offset:49152
	v_mfma_f32_16x16x32_f16 v[102:105], v[74:77], v[90:93], v[102:105]
	s_waitcnt vmcnt(3)
; #define GL_LOAD(s_, kt_) if (VAR != 1) { a##s_##0 = GL_A(0, kt_); a##s_##1 = GL_A(1, kt_); a##s_##2 = GL_A(2, kt_); a##s_##3 = GL_A(3, kt_); b##s_##0 = GL_B(0, kt_); b##s_##1 = GL_B(1, kt_); b##s_##2 = GL_B(2, kt_); b##s_##3 = GL_B(3, kt_); }
; #define LDS_STORE(s_, buf_) if (VAR != 2) { LDS_ST1(sA, 0, buf_, a##s_##0) LDS_ST1(sA, 1, buf_, a##s_##1) LDS_ST1(sA, 2, buf_, a##s_##2) LDS_ST1(sA, 3, buf_, a##s_##3) LDS_ST1(sB, 0, buf_, b##s_##0) LDS_ST1(sB, 1, buf_, b##s_##1) LDS_ST1(sB, 2, buf_, b##s_##2) LDS_ST1(sB, 3, buf_, b##s_##3) }
;     ...
;   GL_LOAD(0, 0)
;   GL_LOAD(1, 1)
;   LDS_STORE(0, 0)
;   if (VAR != 4) __syncthreads();
; #pragma unroll
;   for (int kt = 0; kt < nk; kt += 2) {
;     if (kt + 2 < nk) { GL_LOAD(0, kt + 2) }
;     MMA_TILE(0)
;     LDS_STORE(1, 1)
;     if (VAR != 4) __syncthreads();
;     if (kt + 3 < nk) { GL_LOAD(1, kt + 3) }
;     MMA_TILE(1)
;     if (kt + 2 < nk) { LDS_STORE(0, 0) }
;     if (VAR != 4) __syncthreads();
	ds_write_b128 v17, v[94:97] offset:32768
	v_mfma_f32_16x16x32_f16 v[24:27], v[74:77], v[110:113], v[24:27]
	ds_read_b128 v[74:77], v22 offset:51200
	v_mfma_f32_16x16x32_f16 v[114:117], v[118:121], v[90:93], v[114:117]
	s_waitcnt vmcnt(2)
	ds_write_b128 v18, v[162:165] offset:32768
	v_mfma_f32_16x16x32_f16 v[40:43], v[118:121], v[110:113], v[40:43]
	ds_read_b128 v[118:121], v22 offset:53248
	v_mfma_f32_16x16x32_f16 v[70:73], v[122:125], v[90:93], v[70:73]
	ds_read_b128 v[90:93], v23 offset:16384
	v_mfma_f32_16x16x32_f16 v[48:51], v[122:125], v[110:113], v[48:51]
	ds_read_b128 v[110:113], v23 offset:18432
	s_waitcnt lgkmcnt(1)
	v_mfma_f32_16x16x32_f16 v[36:39], v[62:65], v[90:93], v[36:39]
	ds_read_b128 v[122:125], v22 offset:55296
	s_waitcnt lgkmcnt(1)
	v_mfma_f32_16x16x32_f16 v[66:69], v[62:65], v[110:113], v[66:69]
	s_waitcnt vmcnt(1)
	ds_write_b128 v19, v[166:169] offset:32768
	v_mfma_f32_16x16x32_f16 v[44:47], v[74:77], v[90:93], v[44:47]
	s_waitcnt vmcnt(0)
	ds_write_b128 v20, v[190:193] offset:32768
	v_mfma_f32_16x16x32_f16 v[78:81], v[74:77], v[110:113], v[78:81]
	v_mfma_f32_16x16x32_f16 v[82:85], v[118:121], v[90:93], v[82:85]
	v_mfma_f32_16x16x32_f16 v[86:89], v[118:121], v[110:113], v[86:89]
	s_waitcnt lgkmcnt(2)
	v_mfma_f32_16x16x32_f16 v[28:31], v[122:125], v[90:93], v[28:31]
	ds_read_b128 v[90:93], v23 offset:20480
	v_mfma_f32_16x16x32_f16 v[32:35], v[122:125], v[110:113], v[32:35]
	ds_read_b128 v[110:113], v23 offset:22528
	s_waitcnt lgkmcnt(1)
	v_mfma_f32_16x16x32_f16 v[98:101], v[62:65], v[90:93], v[98:101]
	s_waitcnt lgkmcnt(0)
	v_mfma_f32_16x16x32_f16 v[52:55], v[62:65], v[110:113], v[52:55]
	global_load_dwordx4 v[62:65], v[0:1], off offset:1408
	v_mfma_f32_16x16x32_f16 v[102:105], v[74:77], v[90:93], v[102:105]
	v_mfma_f32_16x16x32_f16 v[24:27], v[74:77], v[110:113], v[24:27]
	v_mfma_f32_16x16x32_f16 v[114:117], v[118:121], v[90:93], v[114:117]
	v_mfma_f32_16x16x32_f16 v[40:43], v[118:121], v[110:113], v[40:43]
	v_mfma_f32_16x16x32_f16 v[70:73], v[122:125], v[90:93], v[70:73]
	global_load_dwordx4 v[90:93], v[2:3], off offset:1408
	global_load_dwordx4 v[126:129], v[4:5], off offset:1408
	global_load_dwordx4 v[130:133], v[14:15], off offset:1408
	global_load_dwordx4 v[74:77], v[10:11], off offset:1408
	global_load_dwordx4 v[138:141], v[12:13], off offset:1408
	global_load_dwordx4 v[142:145], v[8:9], off offset:1408
	global_load_dwordx4 v[154:157], v[6:7], off offset:1408
	s_waitcnt lgkmcnt(0)
	s_barrier
	v_mfma_f32_16x16x32_f16 v[48:51], v[122:125], v[110:113], v[48:51]
	ds_read_b128 v[58:61], v16 offset:32768
	ds_read_b128 v[106:109], v21
	s_waitcnt lgkmcnt(0)
	v_mfma_f32_16x16x32_f16 v[36:39], v[58:61], v[106:109], v[36:39]
	ds_read_b128 v[94:97], v16 offset:34816
	ds_read_b128 v[110:113], v21 offset:2048
	s_waitcnt lgkmcnt(0)
	v_mfma_f32_16x16x32_f16 v[66:69], v[58:61], v[110:113], v[66:69]
	ds_read_b128 v[118:121], v16 offset:36864
	v_mfma_f32_16x16x32_f16 v[44:47], v[94:97], v[106:109], v[44:47]
	ds_read_b128 v[122:125], v16 offset:38912
	v_mfma_f32_16x16x32_f16 v[78:81], v[94:97], v[110:113], v[78:81]
	s_waitcnt vmcnt(7)
	ds_write_b128 v17, v[62:65] offset:16384
	s_waitcnt lgkmcnt(2)
	v_mfma_f32_16x16x32_f16 v[82:85], v[118:121], v[106:109], v[82:85]
	s_waitcnt vmcnt(6)
	ds_write_b128 v18, v[90:93] offset:16384
	v_mfma_f32_16x16x32_f16 v[86:89], v[118:121], v[110:113], v[86:89]
	s_waitcnt vmcnt(5)
	ds_write_b128 v19, v[126:129] offset:16384
	s_waitcnt lgkmcnt(3)
	v_mfma_f32_16x16x32_f16 v[28:31], v[122:125], v[106:109], v[28:31]
	ds_read_b128 v[106:109], v21 offset:4096
	v_mfma_f32_16x16x32_f16 v[32:35], v[122:125], v[110:113], v[32:35]
	ds_read_b128 v[110:113], v21 offset:6144
	s_waitcnt lgkmcnt(1)
	v_mfma_f32_16x16x32_f16 v[98:101], v[58:61], v[106:109], v[98:101]
	s_waitcnt vmcnt(4)
	ds_write_b128 v20, v[130:133] offset:16384
	s_waitcnt lgkmcnt(1)
	v_mfma_f32_16x16x32_f16 v[52:55], v[58:61], v[110:113], v[52:55]
	ds_read_b128 v[58:61], v22 offset:32768
	v_mfma_f32_16x16x32_f16 v[102:105], v[94:97], v[106:109], v[102:105]
	s_waitcnt vmcnt(3)
	ds_write_b128 v17, v[74:77] offset:49152
	v_mfma_f32_16x16x32_f16 v[24:27], v[94:97], v[110:113], v[24:27]
	ds_read_b128 v[94:97], v22 offset:34816
	v_mfma_f32_16x16x32_f16 v[114:117], v[118:121], v[106:109], v[114:117]
	s_waitcnt vmcnt(2)
	ds_write_b128 v18, v[138:141] offset:49152
	v_mfma_f32_16x16x32_f16 v[40:43], v[118:121], v[110:113], v[40:43]
	ds_read_b128 v[118:121], v22 offset:36864
	v_mfma_f32_16x16x32_f16 v[70:73], v[122:125], v[106:109], v[70:73]
	ds_read_b128 v[106:109], v23
	v_mfma_f32_16x16x32_f16 v[48:51], v[122:125], v[110:113], v[48:51]
	ds_read_b128 v[110:113], v23 offset:2048
	s_waitcnt lgkmcnt(1)
	v_mfma_f32_16x16x32_f16 v[36:39], v[58:61], v[106:109], v[36:39]
	ds_read_b128 v[122:125], v22 offset:38912
	s_waitcnt lgkmcnt(1)
	v_mfma_f32_16x16x32_f16 v[66:69], v[58:61], v[110:113], v[66:69]
	s_waitcnt vmcnt(1)
	ds_write_b128 v19, v[142:145] offset:49152
	v_mfma_f32_16x16x32_f16 v[44:47], v[94:97], v[106:109], v[44:47]
	s_waitcnt vmcnt(0)
	ds_write_b128 v20, v[154:157] offset:49152
	v_mfma_f32_16x16x32_f16 v[78:81], v[94:97], v[110:113], v[78:81]
	v_mfma_f32_16x16x32_f16 v[82:85], v[118:121], v[106:109], v[82:85]
	v_mfma_f32_16x16x32_f16 v[86:89], v[118:121], v[110:113], v[86:89]
	s_waitcnt lgkmcnt(2)
	v_mfma_f32_16x16x32_f16 v[28:31], v[122:125], v[106:109], v[28:31]
	ds_read_b128 v[106:109], v23 offset:4096
	v_mfma_f32_16x16x32_f16 v[32:35], v[122:125], v[110:113], v[32:35]
	ds_read_b128 v[110:113], v23 offset:6144
	s_waitcnt lgkmcnt(1)
	v_mfma_f32_16x16x32_f16 v[98:101], v[58:61], v[106:109], v[98:101]
	s_waitcnt lgkmcnt(0)
	v_mfma_f32_16x16x32_f16 v[52:55], v[58:61], v[110:113], v[52:55]
	global_load_dwordx4 v[58:61], v[0:1], off offset:1536
	v_mfma_f32_16x16x32_f16 v[102:105], v[94:97], v[106:109], v[102:105]
	v_mfma_f32_16x16x32_f16 v[24:27], v[94:97], v[110:113], v[24:27]
	v_mfma_f32_16x16x32_f16 v[114:117], v[118:121], v[106:109], v[114:117]
	v_mfma_f32_16x16x32_f16 v[40:43], v[118:121], v[110:113], v[40:43]
	v_mfma_f32_16x16x32_f16 v[70:73], v[122:125], v[106:109], v[70:73]
	global_load_dwordx4 v[106:109], v[2:3], off offset:1536
	global_load_dwordx4 v[134:137], v[4:5], off offset:1536
	global_load_dwordx4 v[158:161], v[14:15], off offset:1536
	global_load_dwordx4 v[94:97], v[10:11], off offset:1536
	global_load_dwordx4 v[162:165], v[12:13], off offset:1536
	global_load_dwordx4 v[166:169], v[8:9], off offset:1536
	global_load_dwordx4 v[190:193], v[6:7], off offset:1536
	s_waitcnt lgkmcnt(0)
	s_barrier
; #define GL_LOAD(s_, kt_) if (VAR != 1) { a##s_##0 = GL_A(0, kt_); a##s_##1 = GL_A(1, kt_); a##s_##2 = GL_A(2, kt_); a##s_##3 = GL_A(3, kt_); b##s_##0 = GL_B(0, kt_); b##s_##1 = GL_B(1, kt_); b##s_##2 = GL_B(2, kt_); b##s_##3 = GL_B(3, kt_); }
; #define LDS_STORE(s_, buf_) if (VAR != 2) { LDS_ST1(sA, 0, buf_, a##s_##0) LDS_ST1(sA, 1, buf_, a##s_##1) LDS_ST1(sA, 2, buf_, a##s_##2) LDS_ST1(sA, 3, buf_, a##s_##3) LDS_ST1(sB, 0, buf_, b##s_##0) LDS_ST1(sB, 1, buf_, b##s_##1) LDS_ST1(sB, 2, buf_, b##s_##2) LDS_ST1(sB, 3, buf_, b##s_##3) }
;     ...
;   GL_LOAD(0, 0)
;   GL_LOAD(1, 1)
;   LDS_STORE(0, 0)
;   if (VAR != 4) __syncthreads();
; #pragma unroll
;   for (int kt = 0; kt < nk; kt += 2) {
;     if (kt + 2 < nk) { GL_LOAD(0, kt + 2) }
;     MMA_TILE(0)
;     LDS_STORE(1, 1)
;     if (VAR != 4) __syncthreads();
;     if (kt + 3 < nk) { GL_LOAD(1, kt + 3) }
;     MMA_TILE(1)
;     if (kt + 2 < nk) { LDS_STORE(0, 0) }
;     if (VAR != 4) __syncthreads();
	v_mfma_f32_16x16x32_f16 v[48:51], v[122:125], v[110:113], v[48:51]
	ds_read_b128 v[62:65], v16 offset:49152
	ds_read_b128 v[90:93], v21 offset:16384
	s_waitcnt lgkmcnt(0)
	v_mfma_f32_16x16x32_f16 v[36:39], v[62:65], v[90:93], v[36:39]
	ds_read_b128 v[74:77], v16 offset:51200
	ds_read_b128 v[110:113], v21 offset:18432
	s_waitcnt lgkmcnt(0)
	v_mfma_f32_16x16x32_f16 v[66:69], v[62:65], v[110:113], v[66:69]
	ds_read_b128 v[118:121], v16 offset:53248
	v_mfma_f32_16x16x32_f16 v[44:47], v[74:77], v[90:93], v[44:47]
	ds_read_b128 v[122:125], v16 offset:55296
	v_mfma_f32_16x16x32_f16 v[78:81], v[74:77], v[110:113], v[78:81]
	s_waitcnt vmcnt(7)
	ds_write_b128 v17, v[58:61]
	s_waitcnt lgkmcnt(2)
	v_mfma_f32_16x16x32_f16 v[82:85], v[118:121], v[90:93], v[82:85]
	s_waitcnt vmcnt(6)
	ds_write_b128 v18, v[106:109]
	v_mfma_f32_16x16x32_f16 v[86:89], v[118:121], v[110:113], v[86:89]
	s_waitcnt vmcnt(5)
	ds_write_b128 v19, v[134:137]
	s_waitcnt lgkmcnt(3)
	v_mfma_f32_16x16x32_f16 v[28:31], v[122:125], v[90:93], v[28:31]
	ds_read_b128 v[90:93], v21 offset:20480
	v_mfma_f32_16x16x32_f16 v[32:35], v[122:125], v[110:113], v[32:35]
	ds_read_b128 v[110:113], v21 offset:22528
	s_waitcnt lgkmcnt(1)
	v_mfma_f32_16x16x32_f16 v[98:101], v[62:65], v[90:93], v[98:101]
	s_waitcnt vmcnt(4)
	ds_write_b128 v20, v[158:161]
	s_waitcnt lgkmcnt(1)
	v_mfma_f32_16x16x32_f16 v[52:55], v[62:65], v[110:113], v[52:55]
	ds_read_b128 v[62:65], v22 offset:49152
	v_mfma_f32_16x16x32_f16 v[102:105], v[74:77], v[90:93], v[102:105]
	s_waitcnt vmcnt(3)
	ds_write_b128 v17, v[94:97] offset:32768
	v_mfma_f32_16x16x32_f16 v[24:27], v[74:77], v[110:113], v[24:27]
	ds_read_b128 v[74:77], v22 offset:51200
	v_mfma_f32_16x16x32_f16 v[114:117], v[118:121], v[90:93], v[114:117]
	s_waitcnt vmcnt(2)
	ds_write_b128 v18, v[162:165] offset:32768
	v_mfma_f32_16x16x32_f16 v[40:43], v[118:121], v[110:113], v[40:43]
	ds_read_b128 v[118:121], v22 offset:53248
	v_mfma_f32_16x16x32_f16 v[70:73], v[122:125], v[90:93], v[70:73]
	ds_read_b128 v[90:93], v23 offset:16384
	v_mfma_f32_16x16x32_f16 v[48:51], v[122:125], v[110:113], v[48:51]
	ds_read_b128 v[110:113], v23 offset:18432
	s_waitcnt lgkmcnt(1)
	v_mfma_f32_16x16x32_f16 v[36:39], v[62:65], v[90:93], v[36:39]
	ds_read_b128 v[122:125], v22 offset:55296
	s_waitcnt lgkmcnt(1)
	v_mfma_f32_16x16x32_f16 v[66:69], v[62:65], v[110:113], v[66:69]
	s_waitcnt vmcnt(1)
	ds_write_b128 v19, v[166:169] offset:32768
	v_mfma_f32_16x16x32_f16 v[44:47], v[74:77], v[90:93], v[44:47]
	s_waitcnt vmcnt(0)
	ds_write_b128 v20, v[190:193] offset:32768
	v_mfma_f32_16x16x32_f16 v[78:81], v[74:77], v[110:113], v[78:81]
	v_mfma_f32_16x16x32_f16 v[82:85], v[118:121], v[90:93], v[82:85]
	v_mfma_f32_16x16x32_f16 v[86:89], v[118:121], v[110:113], v[86:89]
	s_waitcnt lgkmcnt(2)
	v_mfma_f32_16x16x32_f16 v[28:31], v[122:125], v[90:93], v[28:31]
	ds_read_b128 v[90:93], v23 offset:20480
	v_mfma_f32_16x16x32_f16 v[32:35], v[122:125], v[110:113], v[32:35]
	ds_read_b128 v[110:113], v23 offset:22528
	s_waitcnt lgkmcnt(1)
	v_mfma_f32_16x16x32_f16 v[98:101], v[62:65], v[90:93], v[98:101]
	s_waitcnt lgkmcnt(0)
	v_mfma_f32_16x16x32_f16 v[52:55], v[62:65], v[110:113], v[52:55]
	global_load_dwordx4 v[62:65], v[0:1], off offset:1664
	v_mfma_f32_16x16x32_f16 v[102:105], v[74:77], v[90:93], v[102:105]
	v_mfma_f32_16x16x32_f16 v[24:27], v[74:77], v[110:113], v[24:27]
	v_mfma_f32_16x16x32_f16 v[114:117], v[118:121], v[90:93], v[114:117]
	v_mfma_f32_16x16x32_f16 v[40:43], v[118:121], v[110:113], v[40:43]
	v_mfma_f32_16x16x32_f16 v[70:73], v[122:125], v[90:93], v[70:73]
	global_load_dwordx4 v[90:93], v[2:3], off offset:1664
	global_load_dwordx4 v[126:129], v[4:5], off offset:1664
	global_load_dwordx4 v[130:133], v[14:15], off offset:1664
	global_load_dwordx4 v[74:77], v[10:11], off offset:1664
	global_load_dwordx4 v[138:141], v[12:13], off offset:1664
	global_load_dwordx4 v[142:145], v[8:9], off offset:1664
	global_load_dwordx4 v[154:157], v[6:7], off offset:1664
	s_waitcnt lgkmcnt(0)
	s_barrier
	v_mfma_f32_16x16x32_f16 v[48:51], v[122:125], v[110:113], v[48:51]
	ds_read_b128 v[58:61], v16 offset:32768
	ds_read_b128 v[106:109], v21
	s_waitcnt lgkmcnt(0)
	v_mfma_f32_16x16x32_f16 v[36:39], v[58:61], v[106:109], v[36:39]
	ds_read_b128 v[94:97], v16 offset:34816
	ds_read_b128 v[110:113], v21 offset:2048
	s_waitcnt lgkmcnt(0)
	v_mfma_f32_16x16x32_f16 v[66:69], v[58:61], v[110:113], v[66:69]
	ds_read_b128 v[118:121], v16 offset:36864
	v_mfma_f32_16x16x32_f16 v[44:47], v[94:97], v[106:109], v[44:47]
	ds_read_b128 v[122:125], v16 offset:38912
	v_mfma_f32_16x16x32_f16 v[78:81], v[94:97], v[110:113], v[78:81]
	s_waitcnt vmcnt(7)
	ds_write_b128 v17, v[62:65] offset:16384
	s_waitcnt lgkmcnt(2)
	v_mfma_f32_16x16x32_f16 v[82:85], v[118:121], v[106:109], v[82:85]
	s_waitcnt vmcnt(6)
	ds_write_b128 v18, v[90:93] offset:16384
	v_mfma_f32_16x16x32_f16 v[86:89], v[118:121], v[110:113], v[86:89]
	s_waitcnt vmcnt(5)
	ds_write_b128 v19, v[126:129] offset:16384
	s_waitcnt lgkmcnt(3)
	v_mfma_f32_16x16x32_f16 v[28:31], v[122:125], v[106:109], v[28:31]
	ds_read_b128 v[106:109], v21 offset:4096
	v_mfma_f32_16x16x32_f16 v[32:35], v[122:125], v[110:113], v[32:35]
	ds_read_b128 v[110:113], v21 offset:6144
	s_waitcnt lgkmcnt(1)
	v_mfma_f32_16x16x32_f16 v[98:101], v[58:61], v[106:109], v[98:101]
	s_waitcnt vmcnt(4)
	ds_write_b128 v20, v[130:133] offset:16384
	s_waitcnt lgkmcnt(1)
	v_mfma_f32_16x16x32_f16 v[52:55], v[58:61], v[110:113], v[52:55]
	ds_read_b128 v[58:61], v22 offset:32768
	v_mfma_f32_16x16x32_f16 v[102:105], v[94:97], v[106:109], v[102:105]
	s_waitcnt vmcnt(3)
; #define GL_LOAD(s_, kt_) if (VAR != 1) { a##s_##0 = GL_A(0, kt_); a##s_##1 = GL_A(1, kt_); a##s_##2 = GL_A(2, kt_); a##s_##3 = GL_A(3, kt_); b##s_##0 = GL_B(0, kt_); b##s_##1 = GL_B(1, kt_); b##s_##2 = GL_B(2, kt_); b##s_##3 = GL_B(3, kt_); }
; #define LDS_STORE(s_, buf_) if (VAR != 2) { LDS_ST1(sA, 0, buf_, a##s_##0) LDS_ST1(sA, 1, buf_, a##s_##1) LDS_ST1(sA, 2, buf_, a##s_##2) LDS_ST1(sA, 3, buf_, a##s_##3) LDS_ST1(sB, 0, buf_, b##s_##0) LDS_ST1(sB, 1, buf_, b##s_##1) LDS_ST1(sB, 2, buf_, b##s_##2) LDS_ST1(sB, 3, buf_, b##s_##3) }
;     ...
;   GL_LOAD(0, 0)
;   GL_LOAD(1, 1)
;   LDS_STORE(0, 0)
;   if (VAR != 4) __syncthreads();
; #pragma unroll
;   for (int kt = 0; kt < nk; kt += 2) {
;     if (kt + 2 < nk) { GL_LOAD(0, kt + 2) }
;     MMA_TILE(0)
;     LDS_STORE(1, 1)
;     if (VAR != 4) __syncthreads();
;     if (kt + 3 < nk) { GL_LOAD(1, kt + 3) }
;     MMA_TILE(1)
;     if (kt + 2 < nk) { LDS_STORE(0, 0) }
;     if (VAR != 4) __syncthreads();
	ds_write_b128 v17, v[74:77] offset:49152
	v_mfma_f32_16x16x32_f16 v[24:27], v[94:97], v[110:113], v[24:27]
	ds_read_b128 v[94:97], v22 offset:34816
	v_mfma_f32_16x16x32_f16 v[114:117], v[118:121], v[106:109], v[114:117]
	s_waitcnt vmcnt(2)
	ds_write_b128 v18, v[138:141] offset:49152
	v_mfma_f32_16x16x32_f16 v[40:43], v[118:121], v[110:113], v[40:43]
	ds_read_b128 v[118:121], v22 offset:36864
	v_mfma_f32_16x16x32_f16 v[70:73], v[122:125], v[106:109], v[70:73]
	ds_read_b128 v[106:109], v23
	v_mfma_f32_16x16x32_f16 v[48:51], v[122:125], v[110:113], v[48:51]
	ds_read_b128 v[110:113], v23 offset:2048
	s_waitcnt lgkmcnt(1)
	v_mfma_f32_16x16x32_f16 v[36:39], v[58:61], v[106:109], v[36:39]
	ds_read_b128 v[122:125], v22 offset:38912
	s_waitcnt lgkmcnt(1)
	v_mfma_f32_16x16x32_f16 v[66:69], v[58:61], v[110:113], v[66:69]
	s_waitcnt vmcnt(1)
	ds_write_b128 v19, v[142:145] offset:49152
	v_mfma_f32_16x16x32_f16 v[44:47], v[94:97], v[106:109], v[44:47]
	s_waitcnt vmcnt(0)
	ds_write_b128 v20, v[154:157] offset:49152
	v_mfma_f32_16x16x32_f16 v[78:81], v[94:97], v[110:113], v[78:81]
	v_mfma_f32_16x16x32_f16 v[82:85], v[118:121], v[106:109], v[82:85]
	v_mfma_f32_16x16x32_f16 v[86:89], v[118:121], v[110:113], v[86:89]
	s_waitcnt lgkmcnt(2)
	v_mfma_f32_16x16x32_f16 v[28:31], v[122:125], v[106:109], v[28:31]
	ds_read_b128 v[106:109], v23 offset:4096
	v_mfma_f32_16x16x32_f16 v[32:35], v[122:125], v[110:113], v[32:35]
	ds_read_b128 v[110:113], v23 offset:6144
	s_waitcnt lgkmcnt(1)
	v_mfma_f32_16x16x32_f16 v[98:101], v[58:61], v[106:109], v[98:101]
	s_waitcnt lgkmcnt(0)
	v_mfma_f32_16x16x32_f16 v[52:55], v[58:61], v[110:113], v[52:55]
	global_load_dwordx4 v[58:61], v[0:1], off offset:1792
	v_mfma_f32_16x16x32_f16 v[102:105], v[94:97], v[106:109], v[102:105]
	v_mfma_f32_16x16x32_f16 v[24:27], v[94:97], v[110:113], v[24:27]
	v_mfma_f32_16x16x32_f16 v[114:117], v[118:121], v[106:109], v[114:117]
	v_mfma_f32_16x16x32_f16 v[40:43], v[118:121], v[110:113], v[40:43]
	v_mfma_f32_16x16x32_f16 v[70:73], v[122:125], v[106:109], v[70:73]
	global_load_dwordx4 v[106:109], v[2:3], off offset:1792
	global_load_dwordx4 v[134:137], v[4:5], off offset:1792
	global_load_dwordx4 v[158:161], v[14:15], off offset:1792
	global_load_dwordx4 v[94:97], v[10:11], off offset:1792
	global_load_dwordx4 v[162:165], v[12:13], off offset:1792
	global_load_dwordx4 v[166:169], v[8:9], off offset:1792
	global_load_dwordx4 v[190:193], v[6:7], off offset:1792
	s_waitcnt lgkmcnt(0)
	s_barrier
	v_mfma_f32_16x16x32_f16 v[48:51], v[122:125], v[110:113], v[48:51]
	ds_read_b128 v[62:65], v16 offset:49152
	ds_read_b128 v[90:93], v21 offset:16384
	s_waitcnt lgkmcnt(0)
	v_mfma_f32_16x16x32_f16 v[36:39], v[62:65], v[90:93], v[36:39]
	ds_read_b128 v[74:77], v16 offset:51200
	ds_read_b128 v[110:113], v21 offset:18432
	s_waitcnt lgkmcnt(0)
	v_mfma_f32_16x16x32_f16 v[66:69], v[62:65], v[110:113], v[66:69]
	ds_read_b128 v[118:121], v16 offset:53248
	v_mfma_f32_16x16x32_f16 v[44:47], v[74:77], v[90:93], v[44:47]
	ds_read_b128 v[122:125], v16 offset:55296
	v_mfma_f32_16x16x32_f16 v[78:81], v[74:77], v[110:113], v[78:81]
	s_waitcnt vmcnt(7)
	ds_write_b128 v17, v[58:61]
	s_waitcnt lgkmcnt(2)
	v_mfma_f32_16x16x32_f16 v[82:85], v[118:121], v[90:93], v[82:85]
	s_waitcnt vmcnt(6)
	ds_write_b128 v18, v[106:109]
	v_mfma_f32_16x16x32_f16 v[86:89], v[118:121], v[110:113], v[86:89]
	s_waitcnt vmcnt(5)
	ds_write_b128 v19, v[134:137]
	s_waitcnt lgkmcnt(3)
	v_mfma_f32_16x16x32_f16 v[28:31], v[122:125], v[90:93], v[28:31]
	ds_read_b128 v[90:93], v21 offset:20480
	v_mfma_f32_16x16x32_f16 v[32:35], v[122:125], v[110:113], v[32:35]
	ds_read_b128 v[110:113], v21 offset:22528
	s_waitcnt lgkmcnt(1)
	v_mfma_f32_16x16x32_f16 v[98:101], v[62:65], v[90:93], v[98:101]
	s_waitcnt vmcnt(4)
	ds_write_b128 v20, v[158:161]
	s_waitcnt lgkmcnt(1)
	v_mfma_f32_16x16x32_f16 v[52:55], v[62:65], v[110:113], v[52:55]
	ds_read_b128 v[62:65], v22 offset:49152
	v_mfma_f32_16x16x32_f16 v[102:105], v[74:77], v[90:93], v[102:105]
	s_waitcnt vmcnt(3)
	ds_write_b128 v17, v[94:97] offset:32768
	v_mfma_f32_16x16x32_f16 v[24:27], v[74:77], v[110:113], v[24:27]
	ds_read_b128 v[74:77], v22 offset:51200
	v_mfma_f32_16x16x32_f16 v[114:117], v[118:121], v[90:93], v[114:117]
	s_waitcnt vmcnt(2)
	ds_write_b128 v18, v[162:165] offset:32768
	v_mfma_f32_16x16x32_f16 v[40:43], v[118:121], v[110:113], v[40:43]
	ds_read_b128 v[118:121], v22 offset:53248
	v_mfma_f32_16x16x32_f16 v[70:73], v[122:125], v[90:93], v[70:73]
	ds_read_b128 v[90:93], v23 offset:16384
	v_mfma_f32_16x16x32_f16 v[48:51], v[122:125], v[110:113], v[48:51]
	ds_read_b128 v[110:113], v23 offset:18432
	s_waitcnt lgkmcnt(1)
	v_mfma_f32_16x16x32_f16 v[36:39], v[62:65], v[90:93], v[36:39]
	ds_read_b128 v[122:125], v22 offset:55296
	s_waitcnt lgkmcnt(1)
	v_mfma_f32_16x16x32_f16 v[66:69], v[62:65], v[110:113], v[66:69]
	s_waitcnt vmcnt(1)
	ds_write_b128 v19, v[166:169] offset:32768
	v_mfma_f32_16x16x32_f16 v[44:47], v[74:77], v[90:93], v[44:47]
	s_waitcnt vmcnt(0)
	ds_write_b128 v20, v[190:193] offset:32768
	v_mfma_f32_16x16x32_f16 v[78:81], v[74:77], v[110:113], v[78:81]
	v_mfma_f32_16x16x32_f16 v[82:85], v[118:121], v[90:93], v[82:85]
	v_mfma_f32_16x16x32_f16 v[86:89], v[118:121], v[110:113], v[86:89]
	s_waitcnt lgkmcnt(2)
	v_mfma_f32_16x16x32_f16 v[28:31], v[122:125], v[90:93], v[28:31]
	ds_read_b128 v[90:93], v23 offset:20480
	v_mfma_f32_16x16x32_f16 v[32:35], v[122:125], v[110:113], v[32:35]
	ds_read_b128 v[110:113], v23 offset:22528
	s_waitcnt lgkmcnt(1)
	v_mfma_f32_16x16x32_f16 v[98:101], v[62:65], v[90:93], v[98:101]
	s_waitcnt lgkmcnt(0)
	v_mfma_f32_16x16x32_f16 v[52:55], v[62:65], v[110:113], v[52:55]
	global_load_dwordx4 v[62:65], v[0:1], off offset:1920
	v_mfma_f32_16x16x32_f16 v[102:105], v[74:77], v[90:93], v[102:105]
	v_mfma_f32_16x16x32_f16 v[24:27], v[74:77], v[110:113], v[24:27]
	v_mfma_f32_16x16x32_f16 v[114:117], v[118:121], v[90:93], v[114:117]
	v_mfma_f32_16x16x32_f16 v[40:43], v[118:121], v[110:113], v[40:43]
	v_mfma_f32_16x16x32_f16 v[70:73], v[122:125], v[90:93], v[70:73]
	global_load_dwordx4 v[90:93], v[2:3], off offset:1920
	global_load_dwordx4 v[126:129], v[4:5], off offset:1920
	global_load_dwordx4 v[130:133], v[14:15], off offset:1920
	global_load_dwordx4 v[74:77], v[10:11], off offset:1920
	global_load_dwordx4 v[138:141], v[12:13], off offset:1920
	global_load_dwordx4 v[142:145], v[8:9], off offset:1920
	global_load_dwordx4 v[154:157], v[6:7], off offset:1920
	s_waitcnt lgkmcnt(0)
	s_barrier
; #define GL_LOAD(s_, kt_) if (VAR != 1) { a##s_##0 = GL_A(0, kt_); a##s_##1 = GL_A(1, kt_); a##s_##2 = GL_A(2, kt_); a##s_##3 = GL_A(3, kt_); b##s_##0 = GL_B(0, kt_); b##s_##1 = GL_B(1, kt_); b##s_##2 = GL_B(2, kt_); b##s_##3 = GL_B(3, kt_); }
; #define LDS_STORE(s_, buf_) if (VAR != 2) { LDS_ST1(sA, 0, buf_, a##s_##0) LDS_ST1(sA, 1, buf_, a##s_##1) LDS_ST1(sA, 2, buf_, a##s_##2) LDS_ST1(sA, 3, buf_, a##s_##3) LDS_ST1(sB, 0, buf_, b##s_##0) LDS_ST1(sB, 1, buf_, b##s_##1) LDS_ST1(sB, 2, buf_, b##s_##2) LDS_ST1(sB, 3, buf_, b##s_##3) }
;     ...
;   GL_LOAD(0, 0)
;   GL_LOAD(1, 1)
;   LDS_STORE(0, 0)
;   if (VAR != 4) __syncthreads();
; #pragma unroll
;   for (int kt = 0; kt < nk; kt += 2) {
;     if (kt + 2 < nk) { GL_LOAD(0, kt + 2) }
;     MMA_TILE(0)
;     LDS_STORE(1, 1)
;     if (VAR != 4) __syncthreads();
;     if (kt + 3 < nk) { GL_LOAD(1, kt + 3) }
;     MMA_TILE(1)
;     if (kt + 2 < nk) { LDS_STORE(0, 0) }
;     if (VAR != 4) __syncthreads();
	v_mfma_f32_16x16x32_f16 v[48:51], v[122:125], v[110:113], v[48:51]
	ds_read_b128 v[58:61], v16 offset:32768
	ds_read_b128 v[106:109], v21
	s_waitcnt lgkmcnt(0)
	v_mfma_f32_16x16x32_f16 v[36:39], v[58:61], v[106:109], v[36:39]
	ds_read_b128 v[94:97], v16 offset:34816
	ds_read_b128 v[110:113], v21 offset:2048
	s_waitcnt lgkmcnt(0)
	v_mfma_f32_16x16x32_f16 v[66:69], v[58:61], v[110:113], v[66:69]
	ds_read_b128 v[118:121], v16 offset:36864
	v_mfma_f32_16x16x32_f16 v[44:47], v[94:97], v[106:109], v[44:47]
	ds_read_b128 v[122:125], v16 offset:38912
	v_mfma_f32_16x16x32_f16 v[78:81], v[94:97], v[110:113], v[78:81]
	s_waitcnt vmcnt(7)
	ds_write_b128 v17, v[62:65] offset:16384
	s_waitcnt lgkmcnt(2)
	v_mfma_f32_16x16x32_f16 v[82:85], v[118:121], v[106:109], v[82:85]
	s_waitcnt vmcnt(6)
	ds_write_b128 v18, v[90:93] offset:16384
	v_mfma_f32_16x16x32_f16 v[86:89], v[118:121], v[110:113], v[86:89]
	s_waitcnt vmcnt(5)
	ds_write_b128 v19, v[126:129] offset:16384
	s_waitcnt lgkmcnt(3)
	v_mfma_f32_16x16x32_f16 v[28:31], v[122:125], v[106:109], v[28:31]
	ds_read_b128 v[106:109], v21 offset:4096
	v_mfma_f32_16x16x32_f16 v[32:35], v[122:125], v[110:113], v[32:35]
	ds_read_b128 v[110:113], v21 offset:6144
	s_waitcnt lgkmcnt(1)
	v_mfma_f32_16x16x32_f16 v[98:101], v[58:61], v[106:109], v[98:101]
	s_waitcnt vmcnt(4)
	ds_write_b128 v20, v[130:133] offset:16384
	s_waitcnt lgkmcnt(1)
	v_mfma_f32_16x16x32_f16 v[52:55], v[58:61], v[110:113], v[52:55]
	ds_read_b128 v[58:61], v22 offset:32768
	v_mfma_f32_16x16x32_f16 v[102:105], v[94:97], v[106:109], v[102:105]
	s_waitcnt vmcnt(3)
	ds_write_b128 v17, v[74:77] offset:49152
	v_mfma_f32_16x16x32_f16 v[24:27], v[94:97], v[110:113], v[24:27]
	ds_read_b128 v[94:97], v22 offset:34816
	v_mfma_f32_16x16x32_f16 v[114:117], v[118:121], v[106:109], v[114:117]
	s_waitcnt vmcnt(2)
	ds_write_b128 v18, v[138:141] offset:49152
	v_mfma_f32_16x16x32_f16 v[40:43], v[118:121], v[110:113], v[40:43]
	ds_read_b128 v[118:121], v22 offset:36864
	v_mfma_f32_16x16x32_f16 v[70:73], v[122:125], v[106:109], v[70:73]
	ds_read_b128 v[106:109], v23
	v_mfma_f32_16x16x32_f16 v[48:51], v[122:125], v[110:113], v[48:51]
	ds_read_b128 v[110:113], v23 offset:2048
	s_waitcnt lgkmcnt(1)
	v_mfma_f32_16x16x32_f16 v[36:39], v[58:61], v[106:109], v[36:39]
	ds_read_b128 v[122:125], v22 offset:38912
	s_waitcnt lgkmcnt(1)
	v_mfma_f32_16x16x32_f16 v[66:69], v[58:61], v[110:113], v[66:69]
	s_waitcnt vmcnt(1)
	ds_write_b128 v19, v[142:145] offset:49152
	v_mfma_f32_16x16x32_f16 v[44:47], v[94:97], v[106:109], v[44:47]
	s_waitcnt vmcnt(0)
	ds_write_b128 v20, v[154:157] offset:49152
	v_mfma_f32_16x16x32_f16 v[78:81], v[94:97], v[110:113], v[78:81]
	v_mfma_f32_16x16x32_f16 v[82:85], v[118:121], v[106:109], v[82:85]
	v_mfma_f32_16x16x32_f16 v[86:89], v[118:121], v[110:113], v[86:89]
	s_waitcnt lgkmcnt(2)
	v_mfma_f32_16x16x32_f16 v[28:31], v[122:125], v[106:109], v[28:31]
	ds_read_b128 v[106:109], v23 offset:4096
	v_mfma_f32_16x16x32_f16 v[32:35], v[122:125], v[110:113], v[32:35]
	ds_read_b128 v[110:113], v23 offset:6144
	s_waitcnt lgkmcnt(1)
	v_mfma_f32_16x16x32_f16 v[98:101], v[58:61], v[106:109], v[98:101]
	s_waitcnt lgkmcnt(0)
	v_mfma_f32_16x16x32_f16 v[52:55], v[58:61], v[110:113], v[52:55]
	global_load_dwordx4 v[58:61], v[0:1], off offset:2048
	v_mfma_f32_16x16x32_f16 v[102:105], v[94:97], v[106:109], v[102:105]
	v_mfma_f32_16x16x32_f16 v[24:27], v[94:97], v[110:113], v[24:27]
	v_mfma_f32_16x16x32_f16 v[114:117], v[118:121], v[106:109], v[114:117]
	v_mfma_f32_16x16x32_f16 v[40:43], v[118:121], v[110:113], v[40:43]
	v_mfma_f32_16x16x32_f16 v[70:73], v[122:125], v[106:109], v[70:73]
	global_load_dwordx4 v[106:109], v[2:3], off offset:2048
	global_load_dwordx4 v[134:137], v[4:5], off offset:2048
	global_load_dwordx4 v[158:161], v[14:15], off offset:2048
	global_load_dwordx4 v[94:97], v[10:11], off offset:2048
	global_load_dwordx4 v[162:165], v[12:13], off offset:2048
	global_load_dwordx4 v[166:169], v[8:9], off offset:2048
	global_load_dwordx4 v[190:193], v[6:7], off offset:2048
	s_waitcnt lgkmcnt(0)
	s_barrier
	v_mfma_f32_16x16x32_f16 v[48:51], v[122:125], v[110:113], v[48:51]
	ds_read_b128 v[62:65], v16 offset:49152
	ds_read_b128 v[90:93], v21 offset:16384
	s_waitcnt lgkmcnt(0)
	v_mfma_f32_16x16x32_f16 v[36:39], v[62:65], v[90:93], v[36:39]
	ds_read_b128 v[74:77], v16 offset:51200
	ds_read_b128 v[110:113], v21 offset:18432
	s_waitcnt lgkmcnt(0)
	v_mfma_f32_16x16x32_f16 v[66:69], v[62:65], v[110:113], v[66:69]
	ds_read_b128 v[118:121], v16 offset:53248
	v_mfma_f32_16x16x32_f16 v[44:47], v[74:77], v[90:93], v[44:47]
	ds_read_b128 v[122:125], v16 offset:55296
	v_mfma_f32_16x16x32_f16 v[78:81], v[74:77], v[110:113], v[78:81]
	s_waitcnt vmcnt(7)
	ds_write_b128 v17, v[58:61]
	s_waitcnt lgkmcnt(2)
	v_mfma_f32_16x16x32_f16 v[82:85], v[118:121], v[90:93], v[82:85]
	s_waitcnt vmcnt(6)
	ds_write_b128 v18, v[106:109]
	v_mfma_f32_16x16x32_f16 v[86:89], v[118:121], v[110:113], v[86:89]
	s_waitcnt vmcnt(5)
	ds_write_b128 v19, v[134:137]
	s_waitcnt lgkmcnt(3)
	v_mfma_f32_16x16x32_f16 v[28:31], v[122:125], v[90:93], v[28:31]
	ds_read_b128 v[90:93], v21 offset:20480
	v_mfma_f32_16x16x32_f16 v[32:35], v[122:125], v[110:113], v[32:35]
	ds_read_b128 v[110:113], v21 offset:22528
	s_waitcnt lgkmcnt(1)
	v_mfma_f32_16x16x32_f16 v[98:101], v[62:65], v[90:93], v[98:101]
	s_waitcnt vmcnt(4)
	ds_write_b128 v20, v[158:161]
	s_waitcnt lgkmcnt(1)
	v_mfma_f32_16x16x32_f16 v[52:55], v[62:65], v[110:113], v[52:55]
	ds_read_b128 v[62:65], v22 offset:49152
	v_mfma_f32_16x16x32_f16 v[102:105], v[74:77], v[90:93], v[102:105]
	s_waitcnt vmcnt(3)
; #define GL_LOAD(s_, kt_) if (VAR != 1) { a##s_##0 = GL_A(0, kt_); a##s_##1 = GL_A(1, kt_); a##s_##2 = GL_A(2, kt_); a##s_##3 = GL_A(3, kt_); b##s_##0 = GL_B(0, kt_); b##s_##1 = GL_B(1, kt_); b##s_##2 = GL_B(2, kt_); b##s_##3 = GL_B(3, kt_); }
; #define LDS_STORE(s_, buf_) if (VAR != 2) { LDS_ST1(sA, 0, buf_, a##s_##0) LDS_ST1(sA, 1, buf_, a##s_##1) LDS_ST1(sA, 2, buf_, a##s_##2) LDS_ST1(sA, 3, buf_, a##s_##3) LDS_ST1(sB, 0, buf_, b##s_##0) LDS_ST1(sB, 1, buf_, b##s_##1) LDS_ST1(sB, 2, buf_, b##s_##2) LDS_ST1(sB, 3, buf_, b##s_##3) }
;     ...
;   GL_LOAD(0, 0)
;   GL_LOAD(1, 1)
;   LDS_STORE(0, 0)
;   if (VAR != 4) __syncthreads();
; #pragma unroll
;   for (int kt = 0; kt < nk; kt += 2) {
;     if (kt + 2 < nk) { GL_LOAD(0, kt + 2) }
;     MMA_TILE(0)
;     LDS_STORE(1, 1)
;     if (VAR != 4) __syncthreads();
;     if (kt + 3 < nk) { GL_LOAD(1, kt + 3) }
;     MMA_TILE(1)
;     if (kt + 2 < nk) { LDS_STORE(0, 0) }
;     if (VAR != 4) __syncthreads();
	ds_write_b128 v17, v[94:97] offset:32768
	v_mfma_f32_16x16x32_f16 v[24:27], v[74:77], v[110:113], v[24:27]
	ds_read_b128 v[74:77], v22 offset:51200
	v_mfma_f32_16x16x32_f16 v[114:117], v[118:121], v[90:93], v[114:117]
	s_waitcnt vmcnt(2)
	ds_write_b128 v18, v[162:165] offset:32768
	v_mfma_f32_16x16x32_f16 v[40:43], v[118:121], v[110:113], v[40:43]
	ds_read_b128 v[118:121], v22 offset:53248
	v_mfma_f32_16x16x32_f16 v[70:73], v[122:125], v[90:93], v[70:73]
	ds_read_b128 v[90:93], v23 offset:16384
	v_mfma_f32_16x16x32_f16 v[48:51], v[122:125], v[110:113], v[48:51]
	ds_read_b128 v[110:113], v23 offset:18432
	s_waitcnt lgkmcnt(1)
	v_mfma_f32_16x16x32_f16 v[36:39], v[62:65], v[90:93], v[36:39]
	ds_read_b128 v[122:125], v22 offset:55296
	s_waitcnt lgkmcnt(1)
	v_mfma_f32_16x16x32_f16 v[66:69], v[62:65], v[110:113], v[66:69]
	s_waitcnt vmcnt(1)
	ds_write_b128 v19, v[166:169] offset:32768
	v_mfma_f32_16x16x32_f16 v[44:47], v[74:77], v[90:93], v[44:47]
	s_waitcnt vmcnt(0)
	ds_write_b128 v20, v[190:193] offset:32768
	v_mfma_f32_16x16x32_f16 v[78:81], v[74:77], v[110:113], v[78:81]
	v_mfma_f32_16x16x32_f16 v[82:85], v[118:121], v[90:93], v[82:85]
	v_mfma_f32_16x16x32_f16 v[86:89], v[118:121], v[110:113], v[86:89]
	s_waitcnt lgkmcnt(2)
	v_mfma_f32_16x16x32_f16 v[28:31], v[122:125], v[90:93], v[28:31]
	ds_read_b128 v[90:93], v23 offset:20480
	v_mfma_f32_16x16x32_f16 v[32:35], v[122:125], v[110:113], v[32:35]
	ds_read_b128 v[110:113], v23 offset:22528
	s_waitcnt lgkmcnt(1)
	v_mfma_f32_16x16x32_f16 v[98:101], v[62:65], v[90:93], v[98:101]
	s_waitcnt lgkmcnt(0)
	v_mfma_f32_16x16x32_f16 v[52:55], v[62:65], v[110:113], v[52:55]
	global_load_dwordx4 v[62:65], v[0:1], off offset:2176
	v_mfma_f32_16x16x32_f16 v[102:105], v[74:77], v[90:93], v[102:105]
	v_mfma_f32_16x16x32_f16 v[24:27], v[74:77], v[110:113], v[24:27]
	v_mfma_f32_16x16x32_f16 v[114:117], v[118:121], v[90:93], v[114:117]
	v_mfma_f32_16x16x32_f16 v[40:43], v[118:121], v[110:113], v[40:43]
	v_mfma_f32_16x16x32_f16 v[70:73], v[122:125], v[90:93], v[70:73]
	global_load_dwordx4 v[90:93], v[2:3], off offset:2176
	global_load_dwordx4 v[126:129], v[4:5], off offset:2176
	global_load_dwordx4 v[130:133], v[14:15], off offset:2176
	global_load_dwordx4 v[74:77], v[10:11], off offset:2176
	global_load_dwordx4 v[138:141], v[12:13], off offset:2176
	global_load_dwordx4 v[142:145], v[8:9], off offset:2176
	global_load_dwordx4 v[154:157], v[6:7], off offset:2176
	s_waitcnt lgkmcnt(0)
	s_barrier
	v_mfma_f32_16x16x32_f16 v[48:51], v[122:125], v[110:113], v[48:51]
	ds_read_b128 v[58:61], v16 offset:32768
	ds_read_b128 v[106:109], v21
	s_waitcnt lgkmcnt(0)
	v_mfma_f32_16x16x32_f16 v[36:39], v[58:61], v[106:109], v[36:39]
	ds_read_b128 v[94:97], v16 offset:34816
	ds_read_b128 v[110:113], v21 offset:2048
	s_waitcnt lgkmcnt(0)
	v_mfma_f32_16x16x32_f16 v[66:69], v[58:61], v[110:113], v[66:69]
	ds_read_b128 v[118:121], v16 offset:36864
	v_mfma_f32_16x16x32_f16 v[44:47], v[94:97], v[106:109], v[44:47]
	ds_read_b128 v[122:125], v16 offset:38912
	v_mfma_f32_16x16x32_f16 v[78:81], v[94:97], v[110:113], v[78:81]
	s_waitcnt vmcnt(7)
	ds_write_b128 v17, v[62:65] offset:16384
	s_waitcnt lgkmcnt(2)
	v_mfma_f32_16x16x32_f16 v[82:85], v[118:121], v[106:109], v[82:85]
	s_waitcnt vmcnt(6)
	ds_write_b128 v18, v[90:93] offset:16384
	v_mfma_f32_16x16x32_f16 v[86:89], v[118:121], v[110:113], v[86:89]
	s_waitcnt vmcnt(5)
	ds_write_b128 v19, v[126:129] offset:16384
	s_waitcnt lgkmcnt(3)
	v_mfma_f32_16x16x32_f16 v[28:31], v[122:125], v[106:109], v[28:31]
	ds_read_b128 v[106:109], v21 offset:4096
	v_mfma_f32_16x16x32_f16 v[32:35], v[122:125], v[110:113], v[32:35]
	ds_read_b128 v[110:113], v21 offset:6144
	s_waitcnt lgkmcnt(1)
	v_mfma_f32_16x16x32_f16 v[98:101], v[58:61], v[106:109], v[98:101]
	s_waitcnt vmcnt(4)
	ds_write_b128 v20, v[130:133] offset:16384
	s_waitcnt lgkmcnt(1)
	v_mfma_f32_16x16x32_f16 v[52:55], v[58:61], v[110:113], v[52:55]
	ds_read_b128 v[58:61], v22 offset:32768
	v_mfma_f32_16x16x32_f16 v[102:105], v[94:97], v[106:109], v[102:105]
	s_waitcnt vmcnt(3)
	ds_write_b128 v17, v[74:77] offset:49152
	v_mfma_f32_16x16x32_f16 v[24:27], v[94:97], v[110:113], v[24:27]
	ds_read_b128 v[94:97], v22 offset:34816
	v_mfma_f32_16x16x32_f16 v[114:117], v[118:121], v[106:109], v[114:117]
	s_waitcnt vmcnt(2)
	ds_write_b128 v18, v[138:141] offset:49152
	v_mfma_f32_16x16x32_f16 v[40:43], v[118:121], v[110:113], v[40:43]
	ds_read_b128 v[118:121], v22 offset:36864
	v_mfma_f32_16x16x32_f16 v[70:73], v[122:125], v[106:109], v[70:73]
	ds_read_b128 v[106:109], v23
	v_mfma_f32_16x16x32_f16 v[48:51], v[122:125], v[110:113], v[48:51]
	ds_read_b128 v[110:113], v23 offset:2048
	s_waitcnt lgkmcnt(1)
	v_mfma_f32_16x16x32_f16 v[36:39], v[58:61], v[106:109], v[36:39]
	ds_read_b128 v[122:125], v22 offset:38912
	s_waitcnt lgkmcnt(1)
	v_mfma_f32_16x16x32_f16 v[66:69], v[58:61], v[110:113], v[66:69]
	s_waitcnt vmcnt(1)
	ds_write_b128 v19, v[142:145] offset:49152
	v_mfma_f32_16x16x32_f16 v[44:47], v[94:97], v[106:109], v[44:47]
	s_waitcnt vmcnt(0)
	ds_write_b128 v20, v[154:157] offset:49152
	v_mfma_f32_16x16x32_f16 v[78:81], v[94:97], v[110:113], v[78:81]
	v_mfma_f32_16x16x32_f16 v[82:85], v[118:121], v[106:109], v[82:85]
	v_mfma_f32_16x16x32_f16 v[86:89], v[118:121], v[110:113], v[86:89]
	s_waitcnt lgkmcnt(2)
	v_mfma_f32_16x16x32_f16 v[28:31], v[122:125], v[106:109], v[28:31]
	ds_read_b128 v[106:109], v23 offset:4096
	v_mfma_f32_16x16x32_f16 v[32:35], v[122:125], v[110:113], v[32:35]
	ds_read_b128 v[110:113], v23 offset:6144
	s_waitcnt lgkmcnt(1)
	v_mfma_f32_16x16x32_f16 v[98:101], v[58:61], v[106:109], v[98:101]
	s_waitcnt lgkmcnt(0)
	v_mfma_f32_16x16x32_f16 v[52:55], v[58:61], v[110:113], v[52:55]
	global_load_dwordx4 v[58:61], v[0:1], off offset:2304
	v_mfma_f32_16x16x32_f16 v[102:105], v[94:97], v[106:109], v[102:105]
	v_mfma_f32_16x16x32_f16 v[24:27], v[94:97], v[110:113], v[24:27]
	v_mfma_f32_16x16x32_f16 v[114:117], v[118:121], v[106:109], v[114:117]
	v_mfma_f32_16x16x32_f16 v[40:43], v[118:121], v[110:113], v[40:43]
	v_mfma_f32_16x16x32_f16 v[70:73], v[122:125], v[106:109], v[70:73]
	global_load_dwordx4 v[106:109], v[2:3], off offset:2304
	global_load_dwordx4 v[134:137], v[4:5], off offset:2304
	global_load_dwordx4 v[158:161], v[14:15], off offset:2304
	global_load_dwordx4 v[94:97], v[10:11], off offset:2304
	global_load_dwordx4 v[162:165], v[12:13], off offset:2304
	global_load_dwordx4 v[166:169], v[8:9], off offset:2304
	global_load_dwordx4 v[190:193], v[6:7], off offset:2304
	s_waitcnt lgkmcnt(0)
	s_barrier
; #define GL_LOAD(s_, kt_) if (VAR != 1) { a##s_##0 = GL_A(0, kt_); a##s_##1 = GL_A(1, kt_); a##s_##2 = GL_A(2, kt_); a##s_##3 = GL_A(3, kt_); b##s_##0 = GL_B(0, kt_); b##s_##1 = GL_B(1, kt_); b##s_##2 = GL_B(2, kt_); b##s_##3 = GL_B(3, kt_); }
; #define LDS_STORE(s_, buf_) if (VAR != 2) { LDS_ST1(sA, 0, buf_, a##s_##0) LDS_ST1(sA, 1, buf_, a##s_##1) LDS_ST1(sA, 2, buf_, a##s_##2) LDS_ST1(sA, 3, buf_, a##s_##3) LDS_ST1(sB, 0, buf_, b##s_##0) LDS_ST1(sB, 1, buf_, b##s_##1) LDS_ST1(sB, 2, buf_, b##s_##2) LDS_ST1(sB, 3, buf_, b##s_##3) }
;     ...
;   GL_LOAD(0, 0)
;   GL_LOAD(1, 1)
;   LDS_STORE(0, 0)
;   if (VAR != 4) __syncthreads();
; #pragma unroll
;   for (int kt = 0; kt < nk; kt += 2) {
;     if (kt + 2 < nk) { GL_LOAD(0, kt + 2) }
;     MMA_TILE(0)
;     LDS_STORE(1, 1)
;     if (VAR != 4) __syncthreads();
;     if (kt + 3 < nk) { GL_LOAD(1, kt + 3) }
;     MMA_TILE(1)
;     if (kt + 2 < nk) { LDS_STORE(0, 0) }
;     if (VAR != 4) __syncthreads();
	v_mfma_f32_16x16x32_f16 v[48:51], v[122:125], v[110:113], v[48:51]
	ds_read_b128 v[62:65], v16 offset:49152
	ds_read_b128 v[90:93], v21 offset:16384
	s_waitcnt lgkmcnt(0)
	v_mfma_f32_16x16x32_f16 v[36:39], v[62:65], v[90:93], v[36:39]
	ds_read_b128 v[74:77], v16 offset:51200
	ds_read_b128 v[110:113], v21 offset:18432
	s_waitcnt lgkmcnt(0)
	v_mfma_f32_16x16x32_f16 v[66:69], v[62:65], v[110:113], v[66:69]
	ds_read_b128 v[118:121], v16 offset:53248
	v_mfma_f32_16x16x32_f16 v[44:47], v[74:77], v[90:93], v[44:47]
	ds_read_b128 v[122:125], v16 offset:55296
	v_mfma_f32_16x16x32_f16 v[78:81], v[74:77], v[110:113], v[78:81]
	s_waitcnt vmcnt(7)
	ds_write_b128 v17, v[58:61]
	s_waitcnt lgkmcnt(2)
	v_mfma_f32_16x16x32_f16 v[82:85], v[118:121], v[90:93], v[82:85]
	s_waitcnt vmcnt(6)
	ds_write_b128 v18, v[106:109]
	v_mfma_f32_16x16x32_f16 v[86:89], v[118:121], v[110:113], v[86:89]
	s_waitcnt vmcnt(5)
	ds_write_b128 v19, v[134:137]
	s_waitcnt lgkmcnt(3)
	v_mfma_f32_16x16x32_f16 v[28:31], v[122:125], v[90:93], v[28:31]
	ds_read_b128 v[90:93], v21 offset:20480
	v_mfma_f32_16x16x32_f16 v[32:35], v[122:125], v[110:113], v[32:35]
	ds_read_b128 v[110:113], v21 offset:22528
	s_waitcnt lgkmcnt(1)
	v_mfma_f32_16x16x32_f16 v[98:101], v[62:65], v[90:93], v[98:101]
	s_waitcnt vmcnt(4)
	ds_write_b128 v20, v[158:161]
	s_waitcnt lgkmcnt(1)
	v_mfma_f32_16x16x32_f16 v[52:55], v[62:65], v[110:113], v[52:55]
	ds_read_b128 v[62:65], v22 offset:49152
	v_mfma_f32_16x16x32_f16 v[102:105], v[74:77], v[90:93], v[102:105]
	s_waitcnt vmcnt(3)
	ds_write_b128 v17, v[94:97] offset:32768
	v_mfma_f32_16x16x32_f16 v[24:27], v[74:77], v[110:113], v[24:27]
	ds_read_b128 v[74:77], v22 offset:51200
	v_mfma_f32_16x16x32_f16 v[114:117], v[118:121], v[90:93], v[114:117]
	s_waitcnt vmcnt(2)
	ds_write_b128 v18, v[162:165] offset:32768
	v_mfma_f32_16x16x32_f16 v[40:43], v[118:121], v[110:113], v[40:43]
	ds_read_b128 v[118:121], v22 offset:53248
	v_mfma_f32_16x16x32_f16 v[70:73], v[122:125], v[90:93], v[70:73]
	ds_read_b128 v[90:93], v23 offset:16384
	v_mfma_f32_16x16x32_f16 v[48:51], v[122:125], v[110:113], v[48:51]
	ds_read_b128 v[110:113], v23 offset:18432
	s_waitcnt lgkmcnt(1)
	v_mfma_f32_16x16x32_f16 v[36:39], v[62:65], v[90:93], v[36:39]
	ds_read_b128 v[122:125], v22 offset:55296
	s_waitcnt lgkmcnt(1)
	v_mfma_f32_16x16x32_f16 v[66:69], v[62:65], v[110:113], v[66:69]
	s_waitcnt vmcnt(1)
	ds_write_b128 v19, v[166:169] offset:32768
	v_mfma_f32_16x16x32_f16 v[44:47], v[74:77], v[90:93], v[44:47]
	s_waitcnt vmcnt(0)
	ds_write_b128 v20, v[190:193] offset:32768
	v_mfma_f32_16x16x32_f16 v[78:81], v[74:77], v[110:113], v[78:81]
	v_mfma_f32_16x16x32_f16 v[82:85], v[118:121], v[90:93], v[82:85]
	v_mfma_f32_16x16x32_f16 v[86:89], v[118:121], v[110:113], v[86:89]
	s_waitcnt lgkmcnt(2)
	v_mfma_f32_16x16x32_f16 v[28:31], v[122:125], v[90:93], v[28:31]
	ds_read_b128 v[90:93], v23 offset:20480
	v_mfma_f32_16x16x32_f16 v[32:35], v[122:125], v[110:113], v[32:35]
	ds_read_b128 v[110:113], v23 offset:22528
	s_waitcnt lgkmcnt(1)
	v_mfma_f32_16x16x32_f16 v[98:101], v[62:65], v[90:93], v[98:101]
	s_waitcnt lgkmcnt(0)
	v_mfma_f32_16x16x32_f16 v[52:55], v[62:65], v[110:113], v[52:55]
	global_load_dwordx4 v[62:65], v[0:1], off offset:2432
	v_mfma_f32_16x16x32_f16 v[102:105], v[74:77], v[90:93], v[102:105]
	v_mfma_f32_16x16x32_f16 v[24:27], v[74:77], v[110:113], v[24:27]
	v_mfma_f32_16x16x32_f16 v[114:117], v[118:121], v[90:93], v[114:117]
	v_mfma_f32_16x16x32_f16 v[40:43], v[118:121], v[110:113], v[40:43]
	v_mfma_f32_16x16x32_f16 v[70:73], v[122:125], v[90:93], v[70:73]
	global_load_dwordx4 v[90:93], v[2:3], off offset:2432
	global_load_dwordx4 v[126:129], v[4:5], off offset:2432
	global_load_dwordx4 v[130:133], v[14:15], off offset:2432
	global_load_dwordx4 v[74:77], v[10:11], off offset:2432
	global_load_dwordx4 v[138:141], v[12:13], off offset:2432
	global_load_dwordx4 v[142:145], v[8:9], off offset:2432
	global_load_dwordx4 v[154:157], v[6:7], off offset:2432
	s_waitcnt lgkmcnt(0)
	s_barrier
	v_mfma_f32_16x16x32_f16 v[48:51], v[122:125], v[110:113], v[48:51]
	ds_read_b128 v[58:61], v16 offset:32768
	ds_read_b128 v[106:109], v21
	s_waitcnt lgkmcnt(0)
	v_mfma_f32_16x16x32_f16 v[36:39], v[58:61], v[106:109], v[36:39]
	ds_read_b128 v[94:97], v16 offset:34816
	ds_read_b128 v[110:113], v21 offset:2048
	s_waitcnt lgkmcnt(0)
	v_mfma_f32_16x16x32_f16 v[66:69], v[58:61], v[110:113], v[66:69]
	ds_read_b128 v[118:121], v16 offset:36864
	v_mfma_f32_16x16x32_f16 v[44:47], v[94:97], v[106:109], v[44:47]
	ds_read_b128 v[122:125], v16 offset:38912
	v_mfma_f32_16x16x32_f16 v[78:81], v[94:97], v[110:113], v[78:81]
	s_waitcnt vmcnt(7)
	ds_write_b128 v17, v[62:65] offset:16384
	s_waitcnt lgkmcnt(2)
	v_mfma_f32_16x16x32_f16 v[82:85], v[118:121], v[106:109], v[82:85]
	s_waitcnt vmcnt(6)
	ds_write_b128 v18, v[90:93] offset:16384
	v_mfma_f32_16x16x32_f16 v[86:89], v[118:121], v[110:113], v[86:89]
	s_waitcnt vmcnt(5)
	ds_write_b128 v19, v[126:129] offset:16384
	s_waitcnt lgkmcnt(3)
	v_mfma_f32_16x16x32_f16 v[28:31], v[122:125], v[106:109], v[28:31]
	ds_read_b128 v[106:109], v21 offset:4096
	v_mfma_f32_16x16x32_f16 v[32:35], v[122:125], v[110:113], v[32:35]
	ds_read_b128 v[110:113], v21 offset:6144
	s_waitcnt lgkmcnt(1)
	v_mfma_f32_16x16x32_f16 v[98:101], v[58:61], v[106:109], v[98:101]
	s_waitcnt vmcnt(4)
	ds_write_b128 v20, v[130:133] offset:16384
	s_waitcnt lgkmcnt(1)
	v_mfma_f32_16x16x32_f16 v[52:55], v[58:61], v[110:113], v[52:55]
	ds_read_b128 v[58:61], v22 offset:32768
	v_mfma_f32_16x16x32_f16 v[102:105], v[94:97], v[106:109], v[102:105]
	s_waitcnt vmcnt(3)
; #define GL_LOAD(s_, kt_) if (VAR != 1) { a##s_##0 = GL_A(0, kt_); a##s_##1 = GL_A(1, kt_); a##s_##2 = GL_A(2, kt_); a##s_##3 = GL_A(3, kt_); b##s_##0 = GL_B(0, kt_); b##s_##1 = GL_B(1, kt_); b##s_##2 = GL_B(2, kt_); b##s_##3 = GL_B(3, kt_); }
; #define LDS_STORE(s_, buf_) if (VAR != 2) { LDS_ST1(sA, 0, buf_, a##s_##0) LDS_ST1(sA, 1, buf_, a##s_##1) LDS_ST1(sA, 2, buf_, a##s_##2) LDS_ST1(sA, 3, buf_, a##s_##3) LDS_ST1(sB, 0, buf_, b##s_##0) LDS_ST1(sB, 1, buf_, b##s_##1) LDS_ST1(sB, 2, buf_, b##s_##2) LDS_ST1(sB, 3, buf_, b##s_##3) }
;     ...
;   GL_LOAD(0, 0)
;   GL_LOAD(1, 1)
;   LDS_STORE(0, 0)
;   if (VAR != 4) __syncthreads();
; #pragma unroll
;   for (int kt = 0; kt < nk; kt += 2) {
;     if (kt + 2 < nk) { GL_LOAD(0, kt + 2) }
;     MMA_TILE(0)
;     LDS_STORE(1, 1)
;     if (VAR != 4) __syncthreads();
;     if (kt + 3 < nk) { GL_LOAD(1, kt + 3) }
;     MMA_TILE(1)
;     if (kt + 2 < nk) { LDS_STORE(0, 0) }
;     if (VAR != 4) __syncthreads();
	ds_write_b128 v17, v[74:77] offset:49152
	v_mfma_f32_16x16x32_f16 v[24:27], v[94:97], v[110:113], v[24:27]
	ds_read_b128 v[94:97], v22 offset:34816
	v_mfma_f32_16x16x32_f16 v[114:117], v[118:121], v[106:109], v[114:117]
	s_waitcnt vmcnt(2)
	ds_write_b128 v18, v[138:141] offset:49152
	v_mfma_f32_16x16x32_f16 v[40:43], v[118:121], v[110:113], v[40:43]
	ds_read_b128 v[118:121], v22 offset:36864
	v_mfma_f32_16x16x32_f16 v[70:73], v[122:125], v[106:109], v[70:73]
	ds_read_b128 v[106:109], v23
	v_mfma_f32_16x16x32_f16 v[48:51], v[122:125], v[110:113], v[48:51]
	ds_read_b128 v[110:113], v23 offset:2048
	s_waitcnt lgkmcnt(1)
	v_mfma_f32_16x16x32_f16 v[36:39], v[58:61], v[106:109], v[36:39]
	ds_read_b128 v[122:125], v22 offset:38912
	s_waitcnt lgkmcnt(1)
	v_mfma_f32_16x16x32_f16 v[66:69], v[58:61], v[110:113], v[66:69]
	s_waitcnt vmcnt(1)
	ds_write_b128 v19, v[142:145] offset:49152
	v_mfma_f32_16x16x32_f16 v[44:47], v[94:97], v[106:109], v[44:47]
	s_waitcnt vmcnt(0)
	ds_write_b128 v20, v[154:157] offset:49152
	v_mfma_f32_16x16x32_f16 v[78:81], v[94:97], v[110:113], v[78:81]
	v_mfma_f32_16x16x32_f16 v[82:85], v[118:121], v[106:109], v[82:85]
	v_mfma_f32_16x16x32_f16 v[86:89], v[118:121], v[110:113], v[86:89]
	s_waitcnt lgkmcnt(2)
	v_mfma_f32_16x16x32_f16 v[28:31], v[122:125], v[106:109], v[28:31]
	ds_read_b128 v[106:109], v23 offset:4096
	v_mfma_f32_16x16x32_f16 v[32:35], v[122:125], v[110:113], v[32:35]
	ds_read_b128 v[110:113], v23 offset:6144
	s_waitcnt lgkmcnt(1)
	v_mfma_f32_16x16x32_f16 v[98:101], v[58:61], v[106:109], v[98:101]
	s_waitcnt lgkmcnt(0)
	v_mfma_f32_16x16x32_f16 v[52:55], v[58:61], v[110:113], v[52:55]
	global_load_dwordx4 v[58:61], v[0:1], off offset:2560
	v_mfma_f32_16x16x32_f16 v[102:105], v[94:97], v[106:109], v[102:105]
	v_mfma_f32_16x16x32_f16 v[24:27], v[94:97], v[110:113], v[24:27]
	v_mfma_f32_16x16x32_f16 v[114:117], v[118:121], v[106:109], v[114:117]
	v_mfma_f32_16x16x32_f16 v[40:43], v[118:121], v[110:113], v[40:43]
	v_mfma_f32_16x16x32_f16 v[70:73], v[122:125], v[106:109], v[70:73]
	global_load_dwordx4 v[106:109], v[2:3], off offset:2560
	global_load_dwordx4 v[134:137], v[4:5], off offset:2560
	global_load_dwordx4 v[158:161], v[14:15], off offset:2560
	global_load_dwordx4 v[94:97], v[10:11], off offset:2560
	global_load_dwordx4 v[162:165], v[12:13], off offset:2560
	global_load_dwordx4 v[166:169], v[8:9], off offset:2560
	global_load_dwordx4 v[190:193], v[6:7], off offset:2560
	s_waitcnt lgkmcnt(0)
	s_barrier
	v_mfma_f32_16x16x32_f16 v[48:51], v[122:125], v[110:113], v[48:51]
	ds_read_b128 v[62:65], v16 offset:49152
	ds_read_b128 v[90:93], v21 offset:16384
	s_waitcnt lgkmcnt(0)
	v_mfma_f32_16x16x32_f16 v[36:39], v[62:65], v[90:93], v[36:39]
	ds_read_b128 v[74:77], v16 offset:51200
	ds_read_b128 v[110:113], v21 offset:18432
	s_waitcnt lgkmcnt(0)
	v_mfma_f32_16x16x32_f16 v[66:69], v[62:65], v[110:113], v[66:69]
	ds_read_b128 v[118:121], v16 offset:53248
	v_mfma_f32_16x16x32_f16 v[44:47], v[74:77], v[90:93], v[44:47]
	ds_read_b128 v[122:125], v16 offset:55296
	v_mfma_f32_16x16x32_f16 v[78:81], v[74:77], v[110:113], v[78:81]
	s_waitcnt vmcnt(7)
	ds_write_b128 v17, v[58:61]
	s_waitcnt lgkmcnt(2)
	v_mfma_f32_16x16x32_f16 v[82:85], v[118:121], v[90:93], v[82:85]
	s_waitcnt vmcnt(6)
	ds_write_b128 v18, v[106:109]
	v_mfma_f32_16x16x32_f16 v[86:89], v[118:121], v[110:113], v[86:89]
	s_waitcnt vmcnt(5)
	ds_write_b128 v19, v[134:137]
	s_waitcnt lgkmcnt(3)
	v_mfma_f32_16x16x32_f16 v[28:31], v[122:125], v[90:93], v[28:31]
	ds_read_b128 v[90:93], v21 offset:20480
	v_mfma_f32_16x16x32_f16 v[32:35], v[122:125], v[110:113], v[32:35]
	ds_read_b128 v[110:113], v21 offset:22528
	s_waitcnt lgkmcnt(1)
	v_mfma_f32_16x16x32_f16 v[98:101], v[62:65], v[90:93], v[98:101]
	s_waitcnt vmcnt(4)
	ds_write_b128 v20, v[158:161]
	s_waitcnt lgkmcnt(1)
	v_mfma_f32_16x16x32_f16 v[52:55], v[62:65], v[110:113], v[52:55]
	ds_read_b128 v[62:65], v22 offset:49152
	v_mfma_f32_16x16x32_f16 v[102:105], v[74:77], v[90:93], v[102:105]
	s_waitcnt vmcnt(3)
	ds_write_b128 v17, v[94:97] offset:32768
	v_mfma_f32_16x16x32_f16 v[24:27], v[74:77], v[110:113], v[24:27]
	ds_read_b128 v[74:77], v22 offset:51200
	v_mfma_f32_16x16x32_f16 v[114:117], v[118:121], v[90:93], v[114:117]
	s_waitcnt vmcnt(2)
	ds_write_b128 v18, v[162:165] offset:32768
	v_mfma_f32_16x16x32_f16 v[40:43], v[118:121], v[110:113], v[40:43]
	ds_read_b128 v[118:121], v22 offset:53248
	v_mfma_f32_16x16x32_f16 v[70:73], v[122:125], v[90:93], v[70:73]
	ds_read_b128 v[90:93], v23 offset:16384
	v_mfma_f32_16x16x32_f16 v[48:51], v[122:125], v[110:113], v[48:51]
	ds_read_b128 v[110:113], v23 offset:18432
	s_waitcnt lgkmcnt(1)
	v_mfma_f32_16x16x32_f16 v[36:39], v[62:65], v[90:93], v[36:39]
	ds_read_b128 v[122:125], v22 offset:55296
	s_waitcnt lgkmcnt(1)
	v_mfma_f32_16x16x32_f16 v[66:69], v[62:65], v[110:113], v[66:69]
	s_waitcnt vmcnt(1)
	ds_write_b128 v19, v[166:169] offset:32768
	v_mfma_f32_16x16x32_f16 v[44:47], v[74:77], v[90:93], v[44:47]
	s_waitcnt vmcnt(0)
	ds_write_b128 v20, v[190:193] offset:32768
	v_mfma_f32_16x16x32_f16 v[78:81], v[74:77], v[110:113], v[78:81]
	v_mfma_f32_16x16x32_f16 v[82:85], v[118:121], v[90:93], v[82:85]
	v_mfma_f32_16x16x32_f16 v[86:89], v[118:121], v[110:113], v[86:89]
	s_waitcnt lgkmcnt(2)
	v_mfma_f32_16x16x32_f16 v[28:31], v[122:125], v[90:93], v[28:31]
	ds_read_b128 v[90:93], v23 offset:20480
	v_mfma_f32_16x16x32_f16 v[32:35], v[122:125], v[110:113], v[32:35]
	ds_read_b128 v[110:113], v23 offset:22528
	s_waitcnt lgkmcnt(1)
	v_mfma_f32_16x16x32_f16 v[98:101], v[62:65], v[90:93], v[98:101]
	s_waitcnt lgkmcnt(0)
	v_mfma_f32_16x16x32_f16 v[52:55], v[62:65], v[110:113], v[52:55]
	global_load_dwordx4 v[62:65], v[0:1], off offset:2688
	v_mfma_f32_16x16x32_f16 v[102:105], v[74:77], v[90:93], v[102:105]
	v_mfma_f32_16x16x32_f16 v[24:27], v[74:77], v[110:113], v[24:27]
	v_mfma_f32_16x16x32_f16 v[114:117], v[118:121], v[90:93], v[114:117]
	v_mfma_f32_16x16x32_f16 v[40:43], v[118:121], v[110:113], v[40:43]
	v_mfma_f32_16x16x32_f16 v[70:73], v[122:125], v[90:93], v[70:73]
	global_load_dwordx4 v[90:93], v[2:3], off offset:2688
	global_load_dwordx4 v[126:129], v[4:5], off offset:2688
	global_load_dwordx4 v[130:133], v[14:15], off offset:2688
	global_load_dwordx4 v[74:77], v[10:11], off offset:2688
	global_load_dwordx4 v[138:141], v[12:13], off offset:2688
	global_load_dwordx4 v[142:145], v[8:9], off offset:2688
	global_load_dwordx4 v[154:157], v[6:7], off offset:2688
	s_waitcnt lgkmcnt(0)
	s_barrier
; #define GL_LOAD(s_, kt_) if (VAR != 1) { a##s_##0 = GL_A(0, kt_); a##s_##1 = GL_A(1, kt_); a##s_##2 = GL_A(2, kt_); a##s_##3 = GL_A(3, kt_); b##s_##0 = GL_B(0, kt_); b##s_##1 = GL_B(1, kt_); b##s_##2 = GL_B(2, kt_); b##s_##3 = GL_B(3, kt_); }
; #define LDS_STORE(s_, buf_) if (VAR != 2) { LDS_ST1(sA, 0, buf_, a##s_##0) LDS_ST1(sA, 1, buf_, a##s_##1) LDS_ST1(sA, 2, buf_, a##s_##2) LDS_ST1(sA, 3, buf_, a##s_##3) LDS_ST1(sB, 0, buf_, b##s_##0) LDS_ST1(sB, 1, buf_, b##s_##1) LDS_ST1(sB, 2, buf_, b##s_##2) LDS_ST1(sB, 3, buf_, b##s_##3) }
;     ...
;   GL_LOAD(0, 0)
;   GL_LOAD(1, 1)
;   LDS_STORE(0, 0)
;   if (VAR != 4) __syncthreads();
; #pragma unroll
;   for (int kt = 0; kt < nk; kt += 2) {
;     if (kt + 2 < nk) { GL_LOAD(0, kt + 2) }
;     MMA_TILE(0)
;     LDS_STORE(1, 1)
;     if (VAR != 4) __syncthreads();
;     if (kt + 3 < nk) { GL_LOAD(1, kt + 3) }
;     MMA_TILE(1)
;     if (kt + 2 < nk) { LDS_STORE(0, 0) }
;     if (VAR != 4) __syncthreads();
	v_mfma_f32_16x16x32_f16 v[48:51], v[122:125], v[110:113], v[48:51]
	ds_read_b128 v[58:61], v16 offset:32768
	ds_read_b128 v[106:109], v21
	s_waitcnt lgkmcnt(0)
	v_mfma_f32_16x16x32_f16 v[36:39], v[58:61], v[106:109], v[36:39]
	ds_read_b128 v[94:97], v16 offset:34816
	ds_read_b128 v[110:113], v21 offset:2048
	s_waitcnt lgkmcnt(0)
	v_mfma_f32_16x16x32_f16 v[66:69], v[58:61], v[110:113], v[66:69]
	ds_read_b128 v[118:121], v16 offset:36864
	v_mfma_f32_16x16x32_f16 v[44:47], v[94:97], v[106:109], v[44:47]
	ds_read_b128 v[122:125], v16 offset:38912
	v_mfma_f32_16x16x32_f16 v[78:81], v[94:97], v[110:113], v[78:81]
	s_waitcnt vmcnt(7)
	ds_write_b128 v17, v[62:65] offset:16384
	s_waitcnt lgkmcnt(2)
	v_mfma_f32_16x16x32_f16 v[82:85], v[118:121], v[106:109], v[82:85]
	s_waitcnt vmcnt(6)
	ds_write_b128 v18, v[90:93] offset:16384
	v_mfma_f32_16x16x32_f16 v[86:89], v[118:121], v[110:113], v[86:89]
	s_waitcnt vmcnt(5)
	ds_write_b128 v19, v[126:129] offset:16384
	s_waitcnt lgkmcnt(3)
	v_mfma_f32_16x16x32_f16 v[28:31], v[122:125], v[106:109], v[28:31]
	ds_read_b128 v[106:109], v21 offset:4096
	v_mfma_f32_16x16x32_f16 v[32:35], v[122:125], v[110:113], v[32:35]
	ds_read_b128 v[110:113], v21 offset:6144
	s_waitcnt lgkmcnt(1)
	v_mfma_f32_16x16x32_f16 v[98:101], v[58:61], v[106:109], v[98:101]
	s_waitcnt vmcnt(4)
	ds_write_b128 v20, v[130:133] offset:16384
	s_waitcnt lgkmcnt(1)
	v_mfma_f32_16x16x32_f16 v[52:55], v[58:61], v[110:113], v[52:55]
	ds_read_b128 v[58:61], v22 offset:32768
	v_mfma_f32_16x16x32_f16 v[102:105], v[94:97], v[106:109], v[102:105]
	s_waitcnt vmcnt(3)
	ds_write_b128 v17, v[74:77] offset:49152
	v_mfma_f32_16x16x32_f16 v[24:27], v[94:97], v[110:113], v[24:27]
	ds_read_b128 v[94:97], v22 offset:34816
	v_mfma_f32_16x16x32_f16 v[114:117], v[118:121], v[106:109], v[114:117]
	s_waitcnt vmcnt(2)
	ds_write_b128 v18, v[138:141] offset:49152
	v_mfma_f32_16x16x32_f16 v[40:43], v[118:121], v[110:113], v[40:43]
	ds_read_b128 v[118:121], v22 offset:36864
	v_mfma_f32_16x16x32_f16 v[70:73], v[122:125], v[106:109], v[70:73]
	ds_read_b128 v[106:109], v23
	v_mfma_f32_16x16x32_f16 v[48:51], v[122:125], v[110:113], v[48:51]
	ds_read_b128 v[110:113], v23 offset:2048
	s_waitcnt lgkmcnt(1)
	v_mfma_f32_16x16x32_f16 v[36:39], v[58:61], v[106:109], v[36:39]
	ds_read_b128 v[122:125], v22 offset:38912
	s_waitcnt lgkmcnt(1)
	v_mfma_f32_16x16x32_f16 v[66:69], v[58:61], v[110:113], v[66:69]
	s_waitcnt vmcnt(1)
	ds_write_b128 v19, v[142:145] offset:49152
	v_mfma_f32_16x16x32_f16 v[44:47], v[94:97], v[106:109], v[44:47]
	s_waitcnt vmcnt(0)
	ds_write_b128 v20, v[154:157] offset:49152
	v_mfma_f32_16x16x32_f16 v[78:81], v[94:97], v[110:113], v[78:81]
	v_mfma_f32_16x16x32_f16 v[82:85], v[118:121], v[106:109], v[82:85]
	v_mfma_f32_16x16x32_f16 v[86:89], v[118:121], v[110:113], v[86:89]
	s_waitcnt lgkmcnt(2)
	v_mfma_f32_16x16x32_f16 v[28:31], v[122:125], v[106:109], v[28:31]
	ds_read_b128 v[106:109], v23 offset:4096
	v_mfma_f32_16x16x32_f16 v[32:35], v[122:125], v[110:113], v[32:35]
	ds_read_b128 v[110:113], v23 offset:6144
	s_waitcnt lgkmcnt(1)
	v_mfma_f32_16x16x32_f16 v[98:101], v[58:61], v[106:109], v[98:101]
	s_waitcnt lgkmcnt(0)
	v_mfma_f32_16x16x32_f16 v[52:55], v[58:61], v[110:113], v[52:55]
	global_load_dwordx4 v[58:61], v[0:1], off offset:2816
	v_mfma_f32_16x16x32_f16 v[102:105], v[94:97], v[106:109], v[102:105]
	v_mfma_f32_16x16x32_f16 v[24:27], v[94:97], v[110:113], v[24:27]
	v_mfma_f32_16x16x32_f16 v[114:117], v[118:121], v[106:109], v[114:117]
	v_mfma_f32_16x16x32_f16 v[40:43], v[118:121], v[110:113], v[40:43]
	v_mfma_f32_16x16x32_f16 v[70:73], v[122:125], v[106:109], v[70:73]
	global_load_dwordx4 v[106:109], v[2:3], off offset:2816
	global_load_dwordx4 v[134:137], v[4:5], off offset:2816
	global_load_dwordx4 v[158:161], v[14:15], off offset:2816
	global_load_dwordx4 v[94:97], v[10:11], off offset:2816
	global_load_dwordx4 v[162:165], v[12:13], off offset:2816
	global_load_dwordx4 v[166:169], v[8:9], off offset:2816
	global_load_dwordx4 v[190:193], v[6:7], off offset:2816
	s_waitcnt lgkmcnt(0)
	s_barrier
	v_mfma_f32_16x16x32_f16 v[48:51], v[122:125], v[110:113], v[48:51]
	ds_read_b128 v[62:65], v16 offset:49152
	ds_read_b128 v[90:93], v21 offset:16384
	s_waitcnt lgkmcnt(0)
	v_mfma_f32_16x16x32_f16 v[36:39], v[62:65], v[90:93], v[36:39]
	ds_read_b128 v[74:77], v16 offset:51200
	ds_read_b128 v[110:113], v21 offset:18432
	s_waitcnt lgkmcnt(0)
	v_mfma_f32_16x16x32_f16 v[66:69], v[62:65], v[110:113], v[66:69]
	ds_read_b128 v[118:121], v16 offset:53248
	v_mfma_f32_16x16x32_f16 v[44:47], v[74:77], v[90:93], v[44:47]
	ds_read_b128 v[122:125], v16 offset:55296
	v_mfma_f32_16x16x32_f16 v[78:81], v[74:77], v[110:113], v[78:81]
	s_waitcnt vmcnt(7)
	ds_write_b128 v17, v[58:61]
	s_waitcnt lgkmcnt(2)
	v_mfma_f32_16x16x32_f16 v[82:85], v[118:121], v[90:93], v[82:85]
	s_waitcnt vmcnt(6)
	ds_write_b128 v18, v[106:109]
	v_mfma_f32_16x16x32_f16 v[86:89], v[118:121], v[110:113], v[86:89]
	s_waitcnt vmcnt(5)
	ds_write_b128 v19, v[134:137]
	s_waitcnt lgkmcnt(3)
	v_mfma_f32_16x16x32_f16 v[28:31], v[122:125], v[90:93], v[28:31]
	ds_read_b128 v[90:93], v21 offset:20480
	v_mfma_f32_16x16x32_f16 v[32:35], v[122:125], v[110:113], v[32:35]
	ds_read_b128 v[110:113], v21 offset:22528
	s_waitcnt lgkmcnt(1)
	v_mfma_f32_16x16x32_f16 v[98:101], v[62:65], v[90:93], v[98:101]
	s_waitcnt vmcnt(4)
	ds_write_b128 v20, v[158:161]
	s_waitcnt lgkmcnt(1)
	v_mfma_f32_16x16x32_f16 v[52:55], v[62:65], v[110:113], v[52:55]
	ds_read_b128 v[62:65], v22 offset:49152
	v_mfma_f32_16x16x32_f16 v[102:105], v[74:77], v[90:93], v[102:105]
	s_waitcnt vmcnt(3)
; #define GL_LOAD(s_, kt_) if (VAR != 1) { a##s_##0 = GL_A(0, kt_); a##s_##1 = GL_A(1, kt_); a##s_##2 = GL_A(2, kt_); a##s_##3 = GL_A(3, kt_); b##s_##0 = GL_B(0, kt_); b##s_##1 = GL_B(1, kt_); b##s_##2 = GL_B(2, kt_); b##s_##3 = GL_B(3, kt_); }
; #define LDS_STORE(s_, buf_) if (VAR != 2) { LDS_ST1(sA, 0, buf_, a##s_##0) LDS_ST1(sA, 1, buf_, a##s_##1) LDS_ST1(sA, 2, buf_, a##s_##2) LDS_ST1(sA, 3, buf_, a##s_##3) LDS_ST1(sB, 0, buf_, b##s_##0) LDS_ST1(sB, 1, buf_, b##s_##1) LDS_ST1(sB, 2, buf_, b##s_##2) LDS_ST1(sB, 3, buf_, b##s_##3) }
;     ...
;   GL_LOAD(0, 0)
;   GL_LOAD(1, 1)
;   LDS_STORE(0, 0)
;   if (VAR != 4) __syncthreads();
; #pragma unroll
;   for (int kt = 0; kt < nk; kt += 2) {
;     if (kt + 2 < nk) { GL_LOAD(0, kt + 2) }
;     MMA_TILE(0)
;     LDS_STORE(1, 1)
;     if (VAR != 4) __syncthreads();
;     if (kt + 3 < nk) { GL_LOAD(1, kt + 3) }
;     MMA_TILE(1)
;     if (kt + 2 < nk) { LDS_STORE(0, 0) }
;     if (VAR != 4) __syncthreads();
	ds_write_b128 v17, v[94:97] offset:32768
	v_mfma_f32_16x16x32_f16 v[24:27], v[74:77], v[110:113], v[24:27]
	ds_read_b128 v[74:77], v22 offset:51200
	v_mfma_f32_16x16x32_f16 v[114:117], v[118:121], v[90:93], v[114:117]
	s_waitcnt vmcnt(2)
	ds_write_b128 v18, v[162:165] offset:32768
	v_mfma_f32_16x16x32_f16 v[40:43], v[118:121], v[110:113], v[40:43]
	ds_read_b128 v[118:121], v22 offset:53248
	v_mfma_f32_16x16x32_f16 v[70:73], v[122:125], v[90:93], v[70:73]
	ds_read_b128 v[90:93], v23 offset:16384
	v_mfma_f32_16x16x32_f16 v[48:51], v[122:125], v[110:113], v[48:51]
	ds_read_b128 v[110:113], v23 offset:18432
	s_waitcnt lgkmcnt(1)
	v_mfma_f32_16x16x32_f16 v[36:39], v[62:65], v[90:93], v[36:39]
	ds_read_b128 v[122:125], v22 offset:55296
	s_waitcnt lgkmcnt(1)
	v_mfma_f32_16x16x32_f16 v[66:69], v[62:65], v[110:113], v[66:69]
	s_waitcnt vmcnt(1)
	ds_write_b128 v19, v[166:169] offset:32768
	v_mfma_f32_16x16x32_f16 v[44:47], v[74:77], v[90:93], v[44:47]
	s_waitcnt vmcnt(0)
	ds_write_b128 v20, v[190:193] offset:32768
	v_mfma_f32_16x16x32_f16 v[78:81], v[74:77], v[110:113], v[78:81]
	v_mfma_f32_16x16x32_f16 v[82:85], v[118:121], v[90:93], v[82:85]
	v_mfma_f32_16x16x32_f16 v[86:89], v[118:121], v[110:113], v[86:89]
	s_waitcnt lgkmcnt(2)
	v_mfma_f32_16x16x32_f16 v[28:31], v[122:125], v[90:93], v[28:31]
	ds_read_b128 v[90:93], v23 offset:20480
	v_mfma_f32_16x16x32_f16 v[32:35], v[122:125], v[110:113], v[32:35]
	ds_read_b128 v[110:113], v23 offset:22528
	s_waitcnt lgkmcnt(1)
	v_mfma_f32_16x16x32_f16 v[98:101], v[62:65], v[90:93], v[98:101]
	s_waitcnt lgkmcnt(0)
	v_mfma_f32_16x16x32_f16 v[52:55], v[62:65], v[110:113], v[52:55]
	global_load_dwordx4 v[62:65], v[0:1], off offset:2944
	v_mfma_f32_16x16x32_f16 v[102:105], v[74:77], v[90:93], v[102:105]
	v_mfma_f32_16x16x32_f16 v[24:27], v[74:77], v[110:113], v[24:27]
	v_mfma_f32_16x16x32_f16 v[114:117], v[118:121], v[90:93], v[114:117]
	v_mfma_f32_16x16x32_f16 v[40:43], v[118:121], v[110:113], v[40:43]
	v_mfma_f32_16x16x32_f16 v[70:73], v[122:125], v[90:93], v[70:73]
	global_load_dwordx4 v[90:93], v[2:3], off offset:2944
	global_load_dwordx4 v[126:129], v[4:5], off offset:2944
	global_load_dwordx4 v[130:133], v[14:15], off offset:2944
	global_load_dwordx4 v[74:77], v[10:11], off offset:2944
	global_load_dwordx4 v[138:141], v[12:13], off offset:2944
	global_load_dwordx4 v[142:145], v[8:9], off offset:2944
	global_load_dwordx4 v[154:157], v[6:7], off offset:2944
	s_waitcnt lgkmcnt(0)
	s_barrier
	v_mfma_f32_16x16x32_f16 v[48:51], v[122:125], v[110:113], v[48:51]
	ds_read_b128 v[58:61], v16 offset:32768
	ds_read_b128 v[106:109], v21
	s_waitcnt lgkmcnt(0)
	v_mfma_f32_16x16x32_f16 v[36:39], v[58:61], v[106:109], v[36:39]
	ds_read_b128 v[94:97], v16 offset:34816
	ds_read_b128 v[110:113], v21 offset:2048
	s_waitcnt lgkmcnt(0)
	v_mfma_f32_16x16x32_f16 v[66:69], v[58:61], v[110:113], v[66:69]
	ds_read_b128 v[118:121], v16 offset:36864
	v_mfma_f32_16x16x32_f16 v[44:47], v[94:97], v[106:109], v[44:47]
	ds_read_b128 v[122:125], v16 offset:38912
	v_mfma_f32_16x16x32_f16 v[78:81], v[94:97], v[110:113], v[78:81]
	s_waitcnt vmcnt(7)
	ds_write_b128 v17, v[62:65] offset:16384
	s_waitcnt lgkmcnt(2)
	v_mfma_f32_16x16x32_f16 v[82:85], v[118:121], v[106:109], v[82:85]
	s_waitcnt vmcnt(6)
	ds_write_b128 v18, v[90:93] offset:16384
	v_mfma_f32_16x16x32_f16 v[86:89], v[118:121], v[110:113], v[86:89]
	s_waitcnt vmcnt(5)
	ds_write_b128 v19, v[126:129] offset:16384
	s_waitcnt lgkmcnt(3)
	v_mfma_f32_16x16x32_f16 v[28:31], v[122:125], v[106:109], v[28:31]
	ds_read_b128 v[106:109], v21 offset:4096
	v_mfma_f32_16x16x32_f16 v[32:35], v[122:125], v[110:113], v[32:35]
	ds_read_b128 v[110:113], v21 offset:6144
	s_waitcnt lgkmcnt(1)
	v_mfma_f32_16x16x32_f16 v[98:101], v[58:61], v[106:109], v[98:101]
	s_waitcnt vmcnt(4)
	ds_write_b128 v20, v[130:133] offset:16384
	s_waitcnt lgkmcnt(1)
	v_mfma_f32_16x16x32_f16 v[52:55], v[58:61], v[110:113], v[52:55]
	ds_read_b128 v[58:61], v22 offset:32768
	v_mfma_f32_16x16x32_f16 v[102:105], v[94:97], v[106:109], v[102:105]
	s_waitcnt vmcnt(3)
	ds_write_b128 v17, v[74:77] offset:49152
	v_mfma_f32_16x16x32_f16 v[24:27], v[94:97], v[110:113], v[24:27]
	ds_read_b128 v[94:97], v22 offset:34816
	v_mfma_f32_16x16x32_f16 v[114:117], v[118:121], v[106:109], v[114:117]
	s_waitcnt vmcnt(2)
	ds_write_b128 v18, v[138:141] offset:49152
	v_mfma_f32_16x16x32_f16 v[40:43], v[118:121], v[110:113], v[40:43]
	ds_read_b128 v[118:121], v22 offset:36864
	v_mfma_f32_16x16x32_f16 v[70:73], v[122:125], v[106:109], v[70:73]
	ds_read_b128 v[106:109], v23
	v_mfma_f32_16x16x32_f16 v[48:51], v[122:125], v[110:113], v[48:51]
	ds_read_b128 v[110:113], v23 offset:2048
	s_waitcnt lgkmcnt(1)
	v_mfma_f32_16x16x32_f16 v[36:39], v[58:61], v[106:109], v[36:39]
	ds_read_b128 v[122:125], v22 offset:38912
	s_waitcnt lgkmcnt(1)
	v_mfma_f32_16x16x32_f16 v[66:69], v[58:61], v[110:113], v[66:69]
	s_waitcnt vmcnt(1)
	ds_write_b128 v19, v[142:145] offset:49152
	v_mfma_f32_16x16x32_f16 v[44:47], v[94:97], v[106:109], v[44:47]
	s_waitcnt vmcnt(0)
	ds_write_b128 v20, v[154:157] offset:49152
	v_mfma_f32_16x16x32_f16 v[78:81], v[94:97], v[110:113], v[78:81]
	v_mfma_f32_16x16x32_f16 v[82:85], v[118:121], v[106:109], v[82:85]
	v_mfma_f32_16x16x32_f16 v[86:89], v[118:121], v[110:113], v[86:89]
	s_waitcnt lgkmcnt(2)
	v_mfma_f32_16x16x32_f16 v[28:31], v[122:125], v[106:109], v[28:31]
	ds_read_b128 v[106:109], v23 offset:4096
	v_mfma_f32_16x16x32_f16 v[32:35], v[122:125], v[110:113], v[32:35]
	ds_read_b128 v[110:113], v23 offset:6144
	s_waitcnt lgkmcnt(1)
	v_mfma_f32_16x16x32_f16 v[98:101], v[58:61], v[106:109], v[98:101]
	s_waitcnt lgkmcnt(0)
	v_mfma_f32_16x16x32_f16 v[52:55], v[58:61], v[110:113], v[52:55]
	global_load_dwordx4 v[58:61], v[0:1], off offset:3072
	v_mfma_f32_16x16x32_f16 v[102:105], v[94:97], v[106:109], v[102:105]
	v_mfma_f32_16x16x32_f16 v[24:27], v[94:97], v[110:113], v[24:27]
	v_mfma_f32_16x16x32_f16 v[114:117], v[118:121], v[106:109], v[114:117]
	v_mfma_f32_16x16x32_f16 v[40:43], v[118:121], v[110:113], v[40:43]
	v_mfma_f32_16x16x32_f16 v[70:73], v[122:125], v[106:109], v[70:73]
	global_load_dwordx4 v[106:109], v[2:3], off offset:3072
	global_load_dwordx4 v[134:137], v[4:5], off offset:3072
	global_load_dwordx4 v[158:161], v[14:15], off offset:3072
	global_load_dwordx4 v[94:97], v[10:11], off offset:3072
	global_load_dwordx4 v[162:165], v[12:13], off offset:3072
	global_load_dwordx4 v[166:169], v[8:9], off offset:3072
	global_load_dwordx4 v[190:193], v[6:7], off offset:3072
	s_waitcnt lgkmcnt(0)
	s_barrier
; #define GL_LOAD(s_, kt_) if (VAR != 1) { a##s_##0 = GL_A(0, kt_); a##s_##1 = GL_A(1, kt_); a##s_##2 = GL_A(2, kt_); a##s_##3 = GL_A(3, kt_); b##s_##0 = GL_B(0, kt_); b##s_##1 = GL_B(1, kt_); b##s_##2 = GL_B(2, kt_); b##s_##3 = GL_B(3, kt_); }
; #define LDS_STORE(s_, buf_) if (VAR != 2) { LDS_ST1(sA, 0, buf_, a##s_##0) LDS_ST1(sA, 1, buf_, a##s_##1) LDS_ST1(sA, 2, buf_, a##s_##2) LDS_ST1(sA, 3, buf_, a##s_##3) LDS_ST1(sB, 0, buf_, b##s_##0) LDS_ST1(sB, 1, buf_, b##s_##1) LDS_ST1(sB, 2, buf_, b##s_##2) LDS_ST1(sB, 3, buf_, b##s_##3) }
;     ...
;   GL_LOAD(0, 0)
;   GL_LOAD(1, 1)
;   LDS_STORE(0, 0)
;   if (VAR != 4) __syncthreads();
; #pragma unroll
;   for (int kt = 0; kt < nk; kt += 2) {
;     if (kt + 2 < nk) { GL_LOAD(0, kt + 2) }
;     MMA_TILE(0)
;     LDS_STORE(1, 1)
;     if (VAR != 4) __syncthreads();
;     if (kt + 3 < nk) { GL_LOAD(1, kt + 3) }
;     MMA_TILE(1)
;     if (kt + 2 < nk) { LDS_STORE(0, 0) }
;     if (VAR != 4) __syncthreads();
	v_mfma_f32_16x16x32_f16 v[48:51], v[122:125], v[110:113], v[48:51]
	ds_read_b128 v[62:65], v16 offset:49152
	ds_read_b128 v[90:93], v21 offset:16384
	s_waitcnt lgkmcnt(0)
	v_mfma_f32_16x16x32_f16 v[36:39], v[62:65], v[90:93], v[36:39]
	ds_read_b128 v[74:77], v16 offset:51200
	ds_read_b128 v[110:113], v21 offset:18432
	s_waitcnt lgkmcnt(0)
	v_mfma_f32_16x16x32_f16 v[66:69], v[62:65], v[110:113], v[66:69]
	ds_read_b128 v[118:121], v16 offset:53248
	v_mfma_f32_16x16x32_f16 v[44:47], v[74:77], v[90:93], v[44:47]
	ds_read_b128 v[122:125], v16 offset:55296
	v_mfma_f32_16x16x32_f16 v[78:81], v[74:77], v[110:113], v[78:81]
	s_waitcnt vmcnt(7)
	ds_write_b128 v17, v[58:61]
	s_waitcnt lgkmcnt(2)
	v_mfma_f32_16x16x32_f16 v[82:85], v[118:121], v[90:93], v[82:85]
	s_waitcnt vmcnt(6)
	ds_write_b128 v18, v[106:109]
	v_mfma_f32_16x16x32_f16 v[86:89], v[118:121], v[110:113], v[86:89]
	s_waitcnt vmcnt(5)
	ds_write_b128 v19, v[134:137]
	s_waitcnt lgkmcnt(3)
	v_mfma_f32_16x16x32_f16 v[28:31], v[122:125], v[90:93], v[28:31]
	ds_read_b128 v[90:93], v21 offset:20480
	v_mfma_f32_16x16x32_f16 v[32:35], v[122:125], v[110:113], v[32:35]
	ds_read_b128 v[110:113], v21 offset:22528
	s_waitcnt lgkmcnt(1)
	v_mfma_f32_16x16x32_f16 v[98:101], v[62:65], v[90:93], v[98:101]
	s_waitcnt vmcnt(4)
	ds_write_b128 v20, v[158:161]
	s_waitcnt lgkmcnt(1)
	v_mfma_f32_16x16x32_f16 v[52:55], v[62:65], v[110:113], v[52:55]
	ds_read_b128 v[62:65], v22 offset:49152
	v_mfma_f32_16x16x32_f16 v[102:105], v[74:77], v[90:93], v[102:105]
	s_waitcnt vmcnt(3)
	ds_write_b128 v17, v[94:97] offset:32768
	v_mfma_f32_16x16x32_f16 v[24:27], v[74:77], v[110:113], v[24:27]
	ds_read_b128 v[74:77], v22 offset:51200
	v_mfma_f32_16x16x32_f16 v[114:117], v[118:121], v[90:93], v[114:117]
	s_waitcnt vmcnt(2)
	ds_write_b128 v18, v[162:165] offset:32768
	v_mfma_f32_16x16x32_f16 v[40:43], v[118:121], v[110:113], v[40:43]
	ds_read_b128 v[118:121], v22 offset:53248
	v_mfma_f32_16x16x32_f16 v[70:73], v[122:125], v[90:93], v[70:73]
	ds_read_b128 v[90:93], v23 offset:16384
	v_mfma_f32_16x16x32_f16 v[48:51], v[122:125], v[110:113], v[48:51]
	ds_read_b128 v[110:113], v23 offset:18432
	s_waitcnt lgkmcnt(1)
	v_mfma_f32_16x16x32_f16 v[36:39], v[62:65], v[90:93], v[36:39]
	ds_read_b128 v[122:125], v22 offset:55296
	s_waitcnt lgkmcnt(1)
	v_mfma_f32_16x16x32_f16 v[66:69], v[62:65], v[110:113], v[66:69]
	s_waitcnt vmcnt(1)
	ds_write_b128 v19, v[166:169] offset:32768
	v_mfma_f32_16x16x32_f16 v[44:47], v[74:77], v[90:93], v[44:47]
	s_waitcnt vmcnt(0)
	ds_write_b128 v20, v[190:193] offset:32768
	v_mfma_f32_16x16x32_f16 v[78:81], v[74:77], v[110:113], v[78:81]
	v_mfma_f32_16x16x32_f16 v[82:85], v[118:121], v[90:93], v[82:85]
	v_mfma_f32_16x16x32_f16 v[86:89], v[118:121], v[110:113], v[86:89]
	s_waitcnt lgkmcnt(2)
	v_mfma_f32_16x16x32_f16 v[28:31], v[122:125], v[90:93], v[28:31]
	ds_read_b128 v[90:93], v23 offset:20480
	v_mfma_f32_16x16x32_f16 v[32:35], v[122:125], v[110:113], v[32:35]
	ds_read_b128 v[110:113], v23 offset:22528
	s_waitcnt lgkmcnt(1)
	v_mfma_f32_16x16x32_f16 v[98:101], v[62:65], v[90:93], v[98:101]
	s_waitcnt lgkmcnt(0)
	v_mfma_f32_16x16x32_f16 v[52:55], v[62:65], v[110:113], v[52:55]
	global_load_dwordx4 v[62:65], v[0:1], off offset:3200
	v_mfma_f32_16x16x32_f16 v[102:105], v[74:77], v[90:93], v[102:105]
	v_mfma_f32_16x16x32_f16 v[24:27], v[74:77], v[110:113], v[24:27]
	v_mfma_f32_16x16x32_f16 v[114:117], v[118:121], v[90:93], v[114:117]
	v_mfma_f32_16x16x32_f16 v[40:43], v[118:121], v[110:113], v[40:43]
	v_mfma_f32_16x16x32_f16 v[70:73], v[122:125], v[90:93], v[70:73]
	global_load_dwordx4 v[90:93], v[2:3], off offset:3200
	global_load_dwordx4 v[126:129], v[4:5], off offset:3200
	global_load_dwordx4 v[130:133], v[14:15], off offset:3200
	global_load_dwordx4 v[74:77], v[10:11], off offset:3200
	global_load_dwordx4 v[138:141], v[12:13], off offset:3200
	global_load_dwordx4 v[142:145], v[8:9], off offset:3200
	global_load_dwordx4 v[154:157], v[6:7], off offset:3200
	s_waitcnt lgkmcnt(0)
	s_barrier
	v_mfma_f32_16x16x32_f16 v[48:51], v[122:125], v[110:113], v[48:51]
	ds_read_b128 v[58:61], v16 offset:32768
	ds_read_b128 v[106:109], v21
	s_waitcnt lgkmcnt(0)
	v_mfma_f32_16x16x32_f16 v[36:39], v[58:61], v[106:109], v[36:39]
	ds_read_b128 v[94:97], v16 offset:34816
	ds_read_b128 v[110:113], v21 offset:2048
	s_waitcnt lgkmcnt(0)
	v_mfma_f32_16x16x32_f16 v[66:69], v[58:61], v[110:113], v[66:69]
	ds_read_b128 v[118:121], v16 offset:36864
	v_mfma_f32_16x16x32_f16 v[44:47], v[94:97], v[106:109], v[44:47]
	ds_read_b128 v[122:125], v16 offset:38912
	v_mfma_f32_16x16x32_f16 v[78:81], v[94:97], v[110:113], v[78:81]
	s_waitcnt vmcnt(7)
	ds_write_b128 v17, v[62:65] offset:16384
	s_waitcnt lgkmcnt(2)
	v_mfma_f32_16x16x32_f16 v[82:85], v[118:121], v[106:109], v[82:85]
	s_waitcnt vmcnt(6)
	ds_write_b128 v18, v[90:93] offset:16384
	v_mfma_f32_16x16x32_f16 v[86:89], v[118:121], v[110:113], v[86:89]
	s_waitcnt vmcnt(5)
	ds_write_b128 v19, v[126:129] offset:16384
	s_waitcnt lgkmcnt(3)
	v_mfma_f32_16x16x32_f16 v[28:31], v[122:125], v[106:109], v[28:31]
	ds_read_b128 v[106:109], v21 offset:4096
	v_mfma_f32_16x16x32_f16 v[32:35], v[122:125], v[110:113], v[32:35]
	ds_read_b128 v[110:113], v21 offset:6144
	s_waitcnt lgkmcnt(1)
	v_mfma_f32_16x16x32_f16 v[98:101], v[58:61], v[106:109], v[98:101]
	s_waitcnt vmcnt(4)
	ds_write_b128 v20, v[130:133] offset:16384
	s_waitcnt lgkmcnt(1)
	v_mfma_f32_16x16x32_f16 v[52:55], v[58:61], v[110:113], v[52:55]
	ds_read_b128 v[58:61], v22 offset:32768
	v_mfma_f32_16x16x32_f16 v[102:105], v[94:97], v[106:109], v[102:105]
	s_waitcnt vmcnt(3)
; #define GL_LOAD(s_, kt_) if (VAR != 1) { a##s_##0 = GL_A(0, kt_); a##s_##1 = GL_A(1, kt_); a##s_##2 = GL_A(2, kt_); a##s_##3 = GL_A(3, kt_); b##s_##0 = GL_B(0, kt_); b##s_##1 = GL_B(1, kt_); b##s_##2 = GL_B(2, kt_); b##s_##3 = GL_B(3, kt_); }
; #define LDS_STORE(s_, buf_) if (VAR != 2) { LDS_ST1(sA, 0, buf_, a##s_##0) LDS_ST1(sA, 1, buf_, a##s_##1) LDS_ST1(sA, 2, buf_, a##s_##2) LDS_ST1(sA, 3, buf_, a##s_##3) LDS_ST1(sB, 0, buf_, b##s_##0) LDS_ST1(sB, 1, buf_, b##s_##1) LDS_ST1(sB, 2, buf_, b##s_##2) LDS_ST1(sB, 3, buf_, b##s_##3) }
;     ...
;   GL_LOAD(0, 0)
;   GL_LOAD(1, 1)
;   LDS_STORE(0, 0)
;   if (VAR != 4) __syncthreads();
; #pragma unroll
;   for (int kt = 0; kt < nk; kt += 2) {
;     if (kt + 2 < nk) { GL_LOAD(0, kt + 2) }
;     MMA_TILE(0)
;     LDS_STORE(1, 1)
;     if (VAR != 4) __syncthreads();
;     if (kt + 3 < nk) { GL_LOAD(1, kt + 3) }
;     MMA_TILE(1)
;     if (kt + 2 < nk) { LDS_STORE(0, 0) }
;     if (VAR != 4) __syncthreads();
	ds_write_b128 v17, v[74:77] offset:49152
	v_mfma_f32_16x16x32_f16 v[24:27], v[94:97], v[110:113], v[24:27]
	ds_read_b128 v[94:97], v22 offset:34816
	v_mfma_f32_16x16x32_f16 v[114:117], v[118:121], v[106:109], v[114:117]
	s_waitcnt vmcnt(2)
	ds_write_b128 v18, v[138:141] offset:49152
	v_mfma_f32_16x16x32_f16 v[40:43], v[118:121], v[110:113], v[40:43]
	ds_read_b128 v[118:121], v22 offset:36864
	v_mfma_f32_16x16x32_f16 v[70:73], v[122:125], v[106:109], v[70:73]
	ds_read_b128 v[106:109], v23
	v_mfma_f32_16x16x32_f16 v[48:51], v[122:125], v[110:113], v[48:51]
	ds_read_b128 v[110:113], v23 offset:2048
	s_waitcnt lgkmcnt(1)
	v_mfma_f32_16x16x32_f16 v[36:39], v[58:61], v[106:109], v[36:39]
	ds_read_b128 v[122:125], v22 offset:38912
	s_waitcnt lgkmcnt(1)
	v_mfma_f32_16x16x32_f16 v[66:69], v[58:61], v[110:113], v[66:69]
	s_waitcnt vmcnt(1)
	ds_write_b128 v19, v[142:145] offset:49152
	v_mfma_f32_16x16x32_f16 v[44:47], v[94:97], v[106:109], v[44:47]
	s_waitcnt vmcnt(0)
	ds_write_b128 v20, v[154:157] offset:49152
	v_mfma_f32_16x16x32_f16 v[78:81], v[94:97], v[110:113], v[78:81]
	v_mfma_f32_16x16x32_f16 v[82:85], v[118:121], v[106:109], v[82:85]
	v_mfma_f32_16x16x32_f16 v[86:89], v[118:121], v[110:113], v[86:89]
	s_waitcnt lgkmcnt(2)
	v_mfma_f32_16x16x32_f16 v[28:31], v[122:125], v[106:109], v[28:31]
	ds_read_b128 v[106:109], v23 offset:4096
	v_mfma_f32_16x16x32_f16 v[32:35], v[122:125], v[110:113], v[32:35]
	ds_read_b128 v[110:113], v23 offset:6144
	s_waitcnt lgkmcnt(1)
	v_mfma_f32_16x16x32_f16 v[98:101], v[58:61], v[106:109], v[98:101]
	s_waitcnt lgkmcnt(0)
	v_mfma_f32_16x16x32_f16 v[52:55], v[58:61], v[110:113], v[52:55]
	global_load_dwordx4 v[58:61], v[0:1], off offset:3328
	v_mfma_f32_16x16x32_f16 v[102:105], v[94:97], v[106:109], v[102:105]
	v_mfma_f32_16x16x32_f16 v[24:27], v[94:97], v[110:113], v[24:27]
	v_mfma_f32_16x16x32_f16 v[114:117], v[118:121], v[106:109], v[114:117]
	v_mfma_f32_16x16x32_f16 v[40:43], v[118:121], v[110:113], v[40:43]
	v_mfma_f32_16x16x32_f16 v[70:73], v[122:125], v[106:109], v[70:73]
	global_load_dwordx4 v[106:109], v[2:3], off offset:3328
	global_load_dwordx4 v[134:137], v[4:5], off offset:3328
	global_load_dwordx4 v[158:161], v[14:15], off offset:3328
	global_load_dwordx4 v[94:97], v[10:11], off offset:3328
	global_load_dwordx4 v[162:165], v[12:13], off offset:3328
	global_load_dwordx4 v[166:169], v[8:9], off offset:3328
	global_load_dwordx4 v[190:193], v[6:7], off offset:3328
	s_waitcnt lgkmcnt(0)
	s_barrier
	v_mfma_f32_16x16x32_f16 v[48:51], v[122:125], v[110:113], v[48:51]
	ds_read_b128 v[62:65], v16 offset:49152
	ds_read_b128 v[90:93], v21 offset:16384
	s_waitcnt lgkmcnt(0)
	v_mfma_f32_16x16x32_f16 v[36:39], v[62:65], v[90:93], v[36:39]
	ds_read_b128 v[74:77], v16 offset:51200
	ds_read_b128 v[110:113], v21 offset:18432
	s_waitcnt lgkmcnt(0)
	v_mfma_f32_16x16x32_f16 v[66:69], v[62:65], v[110:113], v[66:69]
	ds_read_b128 v[118:121], v16 offset:53248
	v_mfma_f32_16x16x32_f16 v[44:47], v[74:77], v[90:93], v[44:47]
	ds_read_b128 v[122:125], v16 offset:55296
	v_mfma_f32_16x16x32_f16 v[78:81], v[74:77], v[110:113], v[78:81]
	s_waitcnt vmcnt(7)
	ds_write_b128 v17, v[58:61]
	s_waitcnt lgkmcnt(2)
	v_mfma_f32_16x16x32_f16 v[82:85], v[118:121], v[90:93], v[82:85]
	s_waitcnt vmcnt(6)
	ds_write_b128 v18, v[106:109]
	v_mfma_f32_16x16x32_f16 v[86:89], v[118:121], v[110:113], v[86:89]
	s_waitcnt vmcnt(5)
	ds_write_b128 v19, v[134:137]
	s_waitcnt lgkmcnt(3)
	v_mfma_f32_16x16x32_f16 v[28:31], v[122:125], v[90:93], v[28:31]
	ds_read_b128 v[90:93], v21 offset:20480
	v_mfma_f32_16x16x32_f16 v[32:35], v[122:125], v[110:113], v[32:35]
	ds_read_b128 v[110:113], v21 offset:22528
	s_waitcnt lgkmcnt(1)
	v_mfma_f32_16x16x32_f16 v[98:101], v[62:65], v[90:93], v[98:101]
	s_waitcnt vmcnt(4)
	ds_write_b128 v20, v[158:161]
	s_waitcnt lgkmcnt(1)
	v_mfma_f32_16x16x32_f16 v[52:55], v[62:65], v[110:113], v[52:55]
	ds_read_b128 v[62:65], v22 offset:49152
	v_mfma_f32_16x16x32_f16 v[102:105], v[74:77], v[90:93], v[102:105]
	s_waitcnt vmcnt(3)
	ds_write_b128 v17, v[94:97] offset:32768
	v_mfma_f32_16x16x32_f16 v[24:27], v[74:77], v[110:113], v[24:27]
	ds_read_b128 v[74:77], v22 offset:51200
	v_mfma_f32_16x16x32_f16 v[114:117], v[118:121], v[90:93], v[114:117]
	s_waitcnt vmcnt(2)
	ds_write_b128 v18, v[162:165] offset:32768
	v_mfma_f32_16x16x32_f16 v[40:43], v[118:121], v[110:113], v[40:43]
	ds_read_b128 v[118:121], v22 offset:53248
	v_mfma_f32_16x16x32_f16 v[70:73], v[122:125], v[90:93], v[70:73]
	ds_read_b128 v[90:93], v23 offset:16384
	v_mfma_f32_16x16x32_f16 v[48:51], v[122:125], v[110:113], v[48:51]
	ds_read_b128 v[110:113], v23 offset:18432
	s_waitcnt lgkmcnt(1)
	v_mfma_f32_16x16x32_f16 v[36:39], v[62:65], v[90:93], v[36:39]
	ds_read_b128 v[122:125], v22 offset:55296
	s_waitcnt lgkmcnt(1)
	v_mfma_f32_16x16x32_f16 v[66:69], v[62:65], v[110:113], v[66:69]
	s_waitcnt vmcnt(1)
	ds_write_b128 v19, v[166:169] offset:32768
	v_mfma_f32_16x16x32_f16 v[44:47], v[74:77], v[90:93], v[44:47]
	s_waitcnt vmcnt(0)
	ds_write_b128 v20, v[190:193] offset:32768
	v_mfma_f32_16x16x32_f16 v[78:81], v[74:77], v[110:113], v[78:81]
	v_mfma_f32_16x16x32_f16 v[82:85], v[118:121], v[90:93], v[82:85]
	v_mfma_f32_16x16x32_f16 v[86:89], v[118:121], v[110:113], v[86:89]
	s_waitcnt lgkmcnt(2)
	v_mfma_f32_16x16x32_f16 v[28:31], v[122:125], v[90:93], v[28:31]
	ds_read_b128 v[90:93], v23 offset:20480
	v_mfma_f32_16x16x32_f16 v[32:35], v[122:125], v[110:113], v[32:35]
	ds_read_b128 v[110:113], v23 offset:22528
	s_waitcnt lgkmcnt(1)
	v_mfma_f32_16x16x32_f16 v[98:101], v[62:65], v[90:93], v[98:101]
	s_waitcnt lgkmcnt(0)
	v_mfma_f32_16x16x32_f16 v[52:55], v[62:65], v[110:113], v[52:55]
	global_load_dwordx4 v[62:65], v[0:1], off offset:3456
	v_mfma_f32_16x16x32_f16 v[102:105], v[74:77], v[90:93], v[102:105]
	v_mfma_f32_16x16x32_f16 v[24:27], v[74:77], v[110:113], v[24:27]
	v_mfma_f32_16x16x32_f16 v[114:117], v[118:121], v[90:93], v[114:117]
	v_mfma_f32_16x16x32_f16 v[40:43], v[118:121], v[110:113], v[40:43]
	v_mfma_f32_16x16x32_f16 v[70:73], v[122:125], v[90:93], v[70:73]
	global_load_dwordx4 v[90:93], v[2:3], off offset:3456
	global_load_dwordx4 v[126:129], v[4:5], off offset:3456
	global_load_dwordx4 v[130:133], v[14:15], off offset:3456
	global_load_dwordx4 v[74:77], v[10:11], off offset:3456
	global_load_dwordx4 v[138:141], v[12:13], off offset:3456
	global_load_dwordx4 v[142:145], v[8:9], off offset:3456
	global_load_dwordx4 v[154:157], v[6:7], off offset:3456
	s_waitcnt lgkmcnt(0)
	s_barrier
; #define GL_LOAD(s_, kt_) if (VAR != 1) { a##s_##0 = GL_A(0, kt_); a##s_##1 = GL_A(1, kt_); a##s_##2 = GL_A(2, kt_); a##s_##3 = GL_A(3, kt_); b##s_##0 = GL_B(0, kt_); b##s_##1 = GL_B(1, kt_); b##s_##2 = GL_B(2, kt_); b##s_##3 = GL_B(3, kt_); }
; #define LDS_STORE(s_, buf_) if (VAR != 2) { LDS_ST1(sA, 0, buf_, a##s_##0) LDS_ST1(sA, 1, buf_, a##s_##1) LDS_ST1(sA, 2, buf_, a##s_##2) LDS_ST1(sA, 3, buf_, a##s_##3) LDS_ST1(sB, 0, buf_, b##s_##0) LDS_ST1(sB, 1, buf_, b##s_##1) LDS_ST1(sB, 2, buf_, b##s_##2) LDS_ST1(sB, 3, buf_, b##s_##3) }
;     ...
;   GL_LOAD(0, 0)
;   GL_LOAD(1, 1)
;   LDS_STORE(0, 0)
;   if (VAR != 4) __syncthreads();
; #pragma unroll
;   for (int kt = 0; kt < nk; kt += 2) {
;     if (kt + 2 < nk) { GL_LOAD(0, kt + 2) }
;     MMA_TILE(0)
;     LDS_STORE(1, 1)
;     if (VAR != 4) __syncthreads();
;     if (kt + 3 < nk) { GL_LOAD(1, kt + 3) }
;     MMA_TILE(1)
;     if (kt + 2 < nk) { LDS_STORE(0, 0) }
;     if (VAR != 4) __syncthreads();
	v_mfma_f32_16x16x32_f16 v[48:51], v[122:125], v[110:113], v[48:51]
	ds_read_b128 v[58:61], v16 offset:32768
	ds_read_b128 v[106:109], v21
	s_waitcnt lgkmcnt(0)
	v_mfma_f32_16x16x32_f16 v[36:39], v[58:61], v[106:109], v[36:39]
	ds_read_b128 v[94:97], v16 offset:34816
	ds_read_b128 v[110:113], v21 offset:2048
	s_waitcnt lgkmcnt(0)
	v_mfma_f32_16x16x32_f16 v[66:69], v[58:61], v[110:113], v[66:69]
	ds_read_b128 v[118:121], v16 offset:36864
	v_mfma_f32_16x16x32_f16 v[44:47], v[94:97], v[106:109], v[44:47]
	ds_read_b128 v[122:125], v16 offset:38912
	v_mfma_f32_16x16x32_f16 v[78:81], v[94:97], v[110:113], v[78:81]
	s_waitcnt vmcnt(7)
	ds_write_b128 v17, v[62:65] offset:16384
	s_waitcnt lgkmcnt(2)
	v_mfma_f32_16x16x32_f16 v[82:85], v[118:121], v[106:109], v[82:85]
	s_waitcnt vmcnt(6)
	ds_write_b128 v18, v[90:93] offset:16384
	v_mfma_f32_16x16x32_f16 v[86:89], v[118:121], v[110:113], v[86:89]
	s_waitcnt vmcnt(5)
	ds_write_b128 v19, v[126:129] offset:16384
	s_waitcnt lgkmcnt(3)
	v_mfma_f32_16x16x32_f16 v[28:31], v[122:125], v[106:109], v[28:31]
	ds_read_b128 v[106:109], v21 offset:4096
	v_mfma_f32_16x16x32_f16 v[32:35], v[122:125], v[110:113], v[32:35]
	ds_read_b128 v[110:113], v21 offset:6144
	s_waitcnt lgkmcnt(1)
	v_mfma_f32_16x16x32_f16 v[98:101], v[58:61], v[106:109], v[98:101]
	s_waitcnt vmcnt(4)
	ds_write_b128 v20, v[130:133] offset:16384
	s_waitcnt lgkmcnt(1)
	v_mfma_f32_16x16x32_f16 v[52:55], v[58:61], v[110:113], v[52:55]
	ds_read_b128 v[58:61], v22 offset:32768
	v_mfma_f32_16x16x32_f16 v[102:105], v[94:97], v[106:109], v[102:105]
	s_waitcnt vmcnt(3)
	ds_write_b128 v17, v[74:77] offset:49152
	v_mfma_f32_16x16x32_f16 v[24:27], v[94:97], v[110:113], v[24:27]
	ds_read_b128 v[94:97], v22 offset:34816
	v_mfma_f32_16x16x32_f16 v[114:117], v[118:121], v[106:109], v[114:117]
	s_waitcnt vmcnt(2)
	ds_write_b128 v18, v[138:141] offset:49152
	v_mfma_f32_16x16x32_f16 v[40:43], v[118:121], v[110:113], v[40:43]
	ds_read_b128 v[118:121], v22 offset:36864
	v_mfma_f32_16x16x32_f16 v[70:73], v[122:125], v[106:109], v[70:73]
	ds_read_b128 v[106:109], v23
	v_mfma_f32_16x16x32_f16 v[48:51], v[122:125], v[110:113], v[48:51]
	ds_read_b128 v[110:113], v23 offset:2048
	s_waitcnt lgkmcnt(1)
	v_mfma_f32_16x16x32_f16 v[36:39], v[58:61], v[106:109], v[36:39]
	ds_read_b128 v[122:125], v22 offset:38912
	s_waitcnt lgkmcnt(1)
	v_mfma_f32_16x16x32_f16 v[66:69], v[58:61], v[110:113], v[66:69]
	s_waitcnt vmcnt(1)
	ds_write_b128 v19, v[142:145] offset:49152
	v_mfma_f32_16x16x32_f16 v[44:47], v[94:97], v[106:109], v[44:47]
	s_waitcnt vmcnt(0)
	ds_write_b128 v20, v[154:157] offset:49152
	v_mfma_f32_16x16x32_f16 v[78:81], v[94:97], v[110:113], v[78:81]
	v_mfma_f32_16x16x32_f16 v[82:85], v[118:121], v[106:109], v[82:85]
	v_mfma_f32_16x16x32_f16 v[86:89], v[118:121], v[110:113], v[86:89]
	s_waitcnt lgkmcnt(2)
	v_mfma_f32_16x16x32_f16 v[28:31], v[122:125], v[106:109], v[28:31]
	ds_read_b128 v[106:109], v23 offset:4096
	v_mfma_f32_16x16x32_f16 v[32:35], v[122:125], v[110:113], v[32:35]
	ds_read_b128 v[110:113], v23 offset:6144
	s_waitcnt lgkmcnt(1)
	v_mfma_f32_16x16x32_f16 v[98:101], v[58:61], v[106:109], v[98:101]
	s_waitcnt lgkmcnt(0)
	v_mfma_f32_16x16x32_f16 v[52:55], v[58:61], v[110:113], v[52:55]
	global_load_dwordx4 v[58:61], v[0:1], off offset:3584
	v_mfma_f32_16x16x32_f16 v[102:105], v[94:97], v[106:109], v[102:105]
	v_mfma_f32_16x16x32_f16 v[24:27], v[94:97], v[110:113], v[24:27]
	v_mfma_f32_16x16x32_f16 v[114:117], v[118:121], v[106:109], v[114:117]
	v_mfma_f32_16x16x32_f16 v[40:43], v[118:121], v[110:113], v[40:43]
	v_mfma_f32_16x16x32_f16 v[70:73], v[122:125], v[106:109], v[70:73]
	global_load_dwordx4 v[106:109], v[2:3], off offset:3584
	global_load_dwordx4 v[134:137], v[4:5], off offset:3584
	global_load_dwordx4 v[158:161], v[14:15], off offset:3584
	global_load_dwordx4 v[94:97], v[10:11], off offset:3584
	global_load_dwordx4 v[162:165], v[12:13], off offset:3584
	global_load_dwordx4 v[166:169], v[8:9], off offset:3584
	global_load_dwordx4 v[190:193], v[6:7], off offset:3584
	s_waitcnt lgkmcnt(0)
	s_barrier
	v_mfma_f32_16x16x32_f16 v[48:51], v[122:125], v[110:113], v[48:51]
	ds_read_b128 v[62:65], v16 offset:49152
	ds_read_b128 v[90:93], v21 offset:16384
	s_waitcnt lgkmcnt(0)
	v_mfma_f32_16x16x32_f16 v[36:39], v[62:65], v[90:93], v[36:39]
	ds_read_b128 v[74:77], v16 offset:51200
	ds_read_b128 v[110:113], v21 offset:18432
	s_waitcnt lgkmcnt(0)
	v_mfma_f32_16x16x32_f16 v[66:69], v[62:65], v[110:113], v[66:69]
	ds_read_b128 v[118:121], v16 offset:53248
	v_mfma_f32_16x16x32_f16 v[44:47], v[74:77], v[90:93], v[44:47]
	ds_read_b128 v[122:125], v16 offset:55296
	v_mfma_f32_16x16x32_f16 v[78:81], v[74:77], v[110:113], v[78:81]
	s_waitcnt vmcnt(7)
	ds_write_b128 v17, v[58:61]
	s_waitcnt lgkmcnt(2)
	v_mfma_f32_16x16x32_f16 v[82:85], v[118:121], v[90:93], v[82:85]
	s_waitcnt vmcnt(6)
	ds_write_b128 v18, v[106:109]
	v_mfma_f32_16x16x32_f16 v[86:89], v[118:121], v[110:113], v[86:89]
	s_waitcnt vmcnt(5)
	ds_write_b128 v19, v[134:137]
	s_waitcnt lgkmcnt(3)
	v_mfma_f32_16x16x32_f16 v[28:31], v[122:125], v[90:93], v[28:31]
	ds_read_b128 v[90:93], v21 offset:20480
	v_mfma_f32_16x16x32_f16 v[32:35], v[122:125], v[110:113], v[32:35]
	ds_read_b128 v[110:113], v21 offset:22528
	s_waitcnt lgkmcnt(1)
	v_mfma_f32_16x16x32_f16 v[98:101], v[62:65], v[90:93], v[98:101]
	s_waitcnt vmcnt(4)
	ds_write_b128 v20, v[158:161]
	s_waitcnt lgkmcnt(1)
	v_mfma_f32_16x16x32_f16 v[52:55], v[62:65], v[110:113], v[52:55]
	ds_read_b128 v[62:65], v22 offset:49152
	v_mfma_f32_16x16x32_f16 v[102:105], v[74:77], v[90:93], v[102:105]
	s_waitcnt vmcnt(3)
; #define GL_LOAD(s_, kt_) if (VAR != 1) { a##s_##0 = GL_A(0, kt_); a##s_##1 = GL_A(1, kt_); a##s_##2 = GL_A(2, kt_); a##s_##3 = GL_A(3, kt_); b##s_##0 = GL_B(0, kt_); b##s_##1 = GL_B(1, kt_); b##s_##2 = GL_B(2, kt_); b##s_##3 = GL_B(3, kt_); }
; #define LDS_STORE(s_, buf_) if (VAR != 2) { LDS_ST1(sA, 0, buf_, a##s_##0) LDS_ST1(sA, 1, buf_, a##s_##1) LDS_ST1(sA, 2, buf_, a##s_##2) LDS_ST1(sA, 3, buf_, a##s_##3) LDS_ST1(sB, 0, buf_, b##s_##0) LDS_ST1(sB, 1, buf_, b##s_##1) LDS_ST1(sB, 2, buf_, b##s_##2) LDS_ST1(sB, 3, buf_, b##s_##3) }
;     ...
;   GL_LOAD(0, 0)
;   GL_LOAD(1, 1)
;   LDS_STORE(0, 0)
;   if (VAR != 4) __syncthreads();
; #pragma unroll
;   for (int kt = 0; kt < nk; kt += 2) {
;     if (kt + 2 < nk) { GL_LOAD(0, kt + 2) }
;     MMA_TILE(0)
;     LDS_STORE(1, 1)
;     if (VAR != 4) __syncthreads();
;     if (kt + 3 < nk) { GL_LOAD(1, kt + 3) }
;     MMA_TILE(1)
;     if (kt + 2 < nk) { LDS_STORE(0, 0) }
;     if (VAR != 4) __syncthreads();
	ds_write_b128 v17, v[94:97] offset:32768
	v_mfma_f32_16x16x32_f16 v[24:27], v[74:77], v[110:113], v[24:27]
	ds_read_b128 v[74:77], v22 offset:51200
	v_mfma_f32_16x16x32_f16 v[114:117], v[118:121], v[90:93], v[114:117]
	s_waitcnt vmcnt(2)
	ds_write_b128 v18, v[162:165] offset:32768
	v_mfma_f32_16x16x32_f16 v[40:43], v[118:121], v[110:113], v[40:43]
	ds_read_b128 v[118:121], v22 offset:53248
	v_mfma_f32_16x16x32_f16 v[70:73], v[122:125], v[90:93], v[70:73]
	ds_read_b128 v[90:93], v23 offset:16384
	v_mfma_f32_16x16x32_f16 v[48:51], v[122:125], v[110:113], v[48:51]
	ds_read_b128 v[110:113], v23 offset:18432
	s_waitcnt lgkmcnt(1)
	v_mfma_f32_16x16x32_f16 v[36:39], v[62:65], v[90:93], v[36:39]
	ds_read_b128 v[122:125], v22 offset:55296
	s_waitcnt lgkmcnt(1)
	v_mfma_f32_16x16x32_f16 v[66:69], v[62:65], v[110:113], v[66:69]
	s_waitcnt vmcnt(1)
	ds_write_b128 v19, v[166:169] offset:32768
	v_mfma_f32_16x16x32_f16 v[44:47], v[74:77], v[90:93], v[44:47]
	s_waitcnt vmcnt(0)
	ds_write_b128 v20, v[190:193] offset:32768
	v_mfma_f32_16x16x32_f16 v[78:81], v[74:77], v[110:113], v[78:81]
	v_mfma_f32_16x16x32_f16 v[82:85], v[118:121], v[90:93], v[82:85]
	v_mfma_f32_16x16x32_f16 v[86:89], v[118:121], v[110:113], v[86:89]
	s_waitcnt lgkmcnt(2)
	v_mfma_f32_16x16x32_f16 v[28:31], v[122:125], v[90:93], v[28:31]
	ds_read_b128 v[90:93], v23 offset:20480
	v_mfma_f32_16x16x32_f16 v[32:35], v[122:125], v[110:113], v[32:35]
	ds_read_b128 v[110:113], v23 offset:22528
	s_waitcnt lgkmcnt(1)
	v_mfma_f32_16x16x32_f16 v[98:101], v[62:65], v[90:93], v[98:101]
	s_waitcnt lgkmcnt(0)
	v_mfma_f32_16x16x32_f16 v[52:55], v[62:65], v[110:113], v[52:55]
	global_load_dwordx4 v[62:65], v[0:1], off offset:3712
	v_mfma_f32_16x16x32_f16 v[102:105], v[74:77], v[90:93], v[102:105]
	v_mfma_f32_16x16x32_f16 v[24:27], v[74:77], v[110:113], v[24:27]
	v_mfma_f32_16x16x32_f16 v[114:117], v[118:121], v[90:93], v[114:117]
	v_mfma_f32_16x16x32_f16 v[40:43], v[118:121], v[110:113], v[40:43]
	v_mfma_f32_16x16x32_f16 v[70:73], v[122:125], v[90:93], v[70:73]
	global_load_dwordx4 v[90:93], v[2:3], off offset:3712
	global_load_dwordx4 v[126:129], v[4:5], off offset:3712
	global_load_dwordx4 v[130:133], v[14:15], off offset:3712
	global_load_dwordx4 v[74:77], v[10:11], off offset:3712
	global_load_dwordx4 v[138:141], v[12:13], off offset:3712
	global_load_dwordx4 v[142:145], v[8:9], off offset:3712
	global_load_dwordx4 v[154:157], v[6:7], off offset:3712
	s_waitcnt lgkmcnt(0)
	s_barrier
	v_mfma_f32_16x16x32_f16 v[48:51], v[122:125], v[110:113], v[48:51]
	ds_read_b128 v[58:61], v16 offset:32768
	ds_read_b128 v[106:109], v21
	s_waitcnt lgkmcnt(0)
	v_mfma_f32_16x16x32_f16 v[36:39], v[58:61], v[106:109], v[36:39]
	ds_read_b128 v[94:97], v16 offset:34816
	ds_read_b128 v[110:113], v21 offset:2048
	s_waitcnt lgkmcnt(0)
	v_mfma_f32_16x16x32_f16 v[66:69], v[58:61], v[110:113], v[66:69]
	ds_read_b128 v[118:121], v16 offset:36864
	v_mfma_f32_16x16x32_f16 v[44:47], v[94:97], v[106:109], v[44:47]
	ds_read_b128 v[122:125], v16 offset:38912
	v_mfma_f32_16x16x32_f16 v[78:81], v[94:97], v[110:113], v[78:81]
	s_waitcnt vmcnt(7)
	ds_write_b128 v17, v[62:65] offset:16384
	s_waitcnt lgkmcnt(2)
	v_mfma_f32_16x16x32_f16 v[82:85], v[118:121], v[106:109], v[82:85]
	s_waitcnt vmcnt(6)
	ds_write_b128 v18, v[90:93] offset:16384
	v_mfma_f32_16x16x32_f16 v[86:89], v[118:121], v[110:113], v[86:89]
	s_waitcnt vmcnt(5)
	ds_write_b128 v19, v[126:129] offset:16384
	s_waitcnt lgkmcnt(3)
	v_mfma_f32_16x16x32_f16 v[28:31], v[122:125], v[106:109], v[28:31]
	ds_read_b128 v[106:109], v21 offset:4096
	v_mfma_f32_16x16x32_f16 v[32:35], v[122:125], v[110:113], v[32:35]
	ds_read_b128 v[110:113], v21 offset:6144
	s_waitcnt lgkmcnt(1)
	v_mfma_f32_16x16x32_f16 v[98:101], v[58:61], v[106:109], v[98:101]
	s_waitcnt vmcnt(4)
	ds_write_b128 v20, v[130:133] offset:16384
	s_waitcnt lgkmcnt(1)
	v_mfma_f32_16x16x32_f16 v[52:55], v[58:61], v[110:113], v[52:55]
	ds_read_b128 v[58:61], v22 offset:32768
	v_mfma_f32_16x16x32_f16 v[102:105], v[94:97], v[106:109], v[102:105]
	s_waitcnt vmcnt(3)
	ds_write_b128 v17, v[74:77] offset:49152
	v_mfma_f32_16x16x32_f16 v[24:27], v[94:97], v[110:113], v[24:27]
	ds_read_b128 v[94:97], v22 offset:34816
	v_mfma_f32_16x16x32_f16 v[114:117], v[118:121], v[106:109], v[114:117]
	s_waitcnt vmcnt(2)
	ds_write_b128 v18, v[138:141] offset:49152
	v_mfma_f32_16x16x32_f16 v[40:43], v[118:121], v[110:113], v[40:43]
	ds_read_b128 v[118:121], v22 offset:36864
	v_mfma_f32_16x16x32_f16 v[70:73], v[122:125], v[106:109], v[70:73]
	ds_read_b128 v[106:109], v23
	v_mfma_f32_16x16x32_f16 v[48:51], v[122:125], v[110:113], v[48:51]
	ds_read_b128 v[110:113], v23 offset:2048
	s_waitcnt lgkmcnt(1)
	v_mfma_f32_16x16x32_f16 v[36:39], v[58:61], v[106:109], v[36:39]
	ds_read_b128 v[122:125], v22 offset:38912
	s_waitcnt lgkmcnt(1)
	v_mfma_f32_16x16x32_f16 v[66:69], v[58:61], v[110:113], v[66:69]
	s_waitcnt vmcnt(1)
	ds_write_b128 v19, v[142:145] offset:49152
	v_mfma_f32_16x16x32_f16 v[44:47], v[94:97], v[106:109], v[44:47]
	s_waitcnt vmcnt(0)
	ds_write_b128 v20, v[154:157] offset:49152
	v_mfma_f32_16x16x32_f16 v[78:81], v[94:97], v[110:113], v[78:81]
	v_mfma_f32_16x16x32_f16 v[82:85], v[118:121], v[106:109], v[82:85]
	v_mfma_f32_16x16x32_f16 v[86:89], v[118:121], v[110:113], v[86:89]
	s_waitcnt lgkmcnt(2)
	v_mfma_f32_16x16x32_f16 v[28:31], v[122:125], v[106:109], v[28:31]
	ds_read_b128 v[106:109], v23 offset:4096
	v_mfma_f32_16x16x32_f16 v[32:35], v[122:125], v[110:113], v[32:35]
	ds_read_b128 v[110:113], v23 offset:6144
	s_waitcnt lgkmcnt(1)
	v_mfma_f32_16x16x32_f16 v[98:101], v[58:61], v[106:109], v[98:101]
	s_waitcnt lgkmcnt(0)
	v_mfma_f32_16x16x32_f16 v[52:55], v[58:61], v[110:113], v[52:55]
	global_load_dwordx4 v[58:61], v[0:1], off offset:3840
	v_mfma_f32_16x16x32_f16 v[102:105], v[94:97], v[106:109], v[102:105]
	v_mfma_f32_16x16x32_f16 v[24:27], v[94:97], v[110:113], v[24:27]
	v_mfma_f32_16x16x32_f16 v[114:117], v[118:121], v[106:109], v[114:117]
	v_mfma_f32_16x16x32_f16 v[40:43], v[118:121], v[110:113], v[40:43]
	v_mfma_f32_16x16x32_f16 v[70:73], v[122:125], v[106:109], v[70:73]
	global_load_dwordx4 v[106:109], v[2:3], off offset:3840
	global_load_dwordx4 v[134:137], v[4:5], off offset:3840
	global_load_dwordx4 v[158:161], v[14:15], off offset:3840
	global_load_dwordx4 v[94:97], v[10:11], off offset:3840
	global_load_dwordx4 v[162:165], v[12:13], off offset:3840
	global_load_dwordx4 v[166:169], v[8:9], off offset:3840
	global_load_dwordx4 v[190:193], v[6:7], off offset:3840
	s_waitcnt lgkmcnt(0)
	s_barrier
; #define GL_LOAD(s_, kt_) if (VAR != 1) { a##s_##0 = GL_A(0, kt_); a##s_##1 = GL_A(1, kt_); a##s_##2 = GL_A(2, kt_); a##s_##3 = GL_A(3, kt_); b##s_##0 = GL_B(0, kt_); b##s_##1 = GL_B(1, kt_); b##s_##2 = GL_B(2, kt_); b##s_##3 = GL_B(3, kt_); }
; #define LDS_STORE(s_, buf_) if (VAR != 2) { LDS_ST1(sA, 0, buf_, a##s_##0) LDS_ST1(sA, 1, buf_, a##s_##1) LDS_ST1(sA, 2, buf_, a##s_##2) LDS_ST1(sA, 3, buf_, a##s_##3) LDS_ST1(sB, 0, buf_, b##s_##0) LDS_ST1(sB, 1, buf_, b##s_##1) LDS_ST1(sB, 2, buf_, b##s_##2) LDS_ST1(sB, 3, buf_, b##s_##3) }
;     ...
;   GL_LOAD(0, 0)
;   GL_LOAD(1, 1)
;   LDS_STORE(0, 0)
;   if (VAR != 4) __syncthreads();
; #pragma unroll
;   for (int kt = 0; kt < nk; kt += 2) {
;     if (kt + 2 < nk) { GL_LOAD(0, kt + 2) }
;     MMA_TILE(0)
;     LDS_STORE(1, 1)
;     if (VAR != 4) __syncthreads();
;     if (kt + 3 < nk) { GL_LOAD(1, kt + 3) }
;     MMA_TILE(1)
;     if (kt + 2 < nk) { LDS_STORE(0, 0) }
;     if (VAR != 4) __syncthreads();
	v_mfma_f32_16x16x32_f16 v[48:51], v[122:125], v[110:113], v[48:51]
	ds_read_b128 v[62:65], v16 offset:49152
	ds_read_b128 v[90:93], v21 offset:16384
	s_waitcnt lgkmcnt(0)
	v_mfma_f32_16x16x32_f16 v[36:39], v[62:65], v[90:93], v[36:39]
	ds_read_b128 v[74:77], v16 offset:51200
	ds_read_b128 v[110:113], v21 offset:18432
	s_waitcnt lgkmcnt(0)
	v_mfma_f32_16x16x32_f16 v[66:69], v[62:65], v[110:113], v[66:69]
	ds_read_b128 v[118:121], v16 offset:53248
	v_mfma_f32_16x16x32_f16 v[44:47], v[74:77], v[90:93], v[44:47]
	ds_read_b128 v[122:125], v16 offset:55296
	v_mfma_f32_16x16x32_f16 v[78:81], v[74:77], v[110:113], v[78:81]
	s_waitcnt vmcnt(7)
	ds_write_b128 v17, v[58:61]
	s_waitcnt lgkmcnt(2)
	v_mfma_f32_16x16x32_f16 v[82:85], v[118:121], v[90:93], v[82:85]
	s_waitcnt vmcnt(6)
	ds_write_b128 v18, v[106:109]
	v_mfma_f32_16x16x32_f16 v[86:89], v[118:121], v[110:113], v[86:89]
	s_waitcnt vmcnt(5)
	ds_write_b128 v19, v[134:137]
	s_waitcnt lgkmcnt(3)
	v_mfma_f32_16x16x32_f16 v[28:31], v[122:125], v[90:93], v[28:31]
	ds_read_b128 v[90:93], v21 offset:20480
	v_mfma_f32_16x16x32_f16 v[32:35], v[122:125], v[110:113], v[32:35]
	ds_read_b128 v[110:113], v21 offset:22528
	s_waitcnt lgkmcnt(1)
	v_mfma_f32_16x16x32_f16 v[98:101], v[62:65], v[90:93], v[98:101]
	s_waitcnt vmcnt(4)
	ds_write_b128 v20, v[158:161]
	s_waitcnt lgkmcnt(1)
	v_mfma_f32_16x16x32_f16 v[52:55], v[62:65], v[110:113], v[52:55]
	ds_read_b128 v[62:65], v22 offset:49152
	v_mfma_f32_16x16x32_f16 v[102:105], v[74:77], v[90:93], v[102:105]
	s_waitcnt vmcnt(3)
	ds_write_b128 v17, v[94:97] offset:32768
	v_mfma_f32_16x16x32_f16 v[24:27], v[74:77], v[110:113], v[24:27]
	ds_read_b128 v[74:77], v22 offset:51200
	v_mfma_f32_16x16x32_f16 v[114:117], v[118:121], v[90:93], v[114:117]
	s_waitcnt vmcnt(2)
	ds_write_b128 v18, v[162:165] offset:32768
	v_mfma_f32_16x16x32_f16 v[40:43], v[118:121], v[110:113], v[40:43]
	ds_read_b128 v[118:121], v22 offset:53248
	v_mfma_f32_16x16x32_f16 v[70:73], v[122:125], v[90:93], v[70:73]
	ds_read_b128 v[90:93], v23 offset:16384
	v_mfma_f32_16x16x32_f16 v[48:51], v[122:125], v[110:113], v[48:51]
	ds_read_b128 v[110:113], v23 offset:18432
	s_waitcnt lgkmcnt(1)
	v_mfma_f32_16x16x32_f16 v[36:39], v[62:65], v[90:93], v[36:39]
	ds_read_b128 v[122:125], v22 offset:55296
	s_waitcnt lgkmcnt(1)
	v_mfma_f32_16x16x32_f16 v[66:69], v[62:65], v[110:113], v[66:69]
	s_waitcnt vmcnt(1)
	ds_write_b128 v19, v[166:169] offset:32768
	v_mfma_f32_16x16x32_f16 v[44:47], v[74:77], v[90:93], v[44:47]
	s_waitcnt vmcnt(0)
	ds_write_b128 v20, v[190:193] offset:32768
	v_mfma_f32_16x16x32_f16 v[78:81], v[74:77], v[110:113], v[78:81]
	v_mfma_f32_16x16x32_f16 v[82:85], v[118:121], v[90:93], v[82:85]
	v_mfma_f32_16x16x32_f16 v[86:89], v[118:121], v[110:113], v[86:89]
	s_waitcnt lgkmcnt(2)
	v_mfma_f32_16x16x32_f16 v[28:31], v[122:125], v[90:93], v[28:31]
	ds_read_b128 v[90:93], v23 offset:20480
	v_mfma_f32_16x16x32_f16 v[32:35], v[122:125], v[110:113], v[32:35]
	ds_read_b128 v[110:113], v23 offset:22528
	s_waitcnt lgkmcnt(1)
	v_mfma_f32_16x16x32_f16 v[98:101], v[62:65], v[90:93], v[98:101]
	s_waitcnt lgkmcnt(0)
	v_mfma_f32_16x16x32_f16 v[52:55], v[62:65], v[110:113], v[52:55]
	global_load_dwordx4 v[62:65], v[0:1], off offset:3968
	v_add_co_u32_e32 v0, vcc, s1, v0
	v_mfma_f32_16x16x32_f16 v[102:105], v[74:77], v[90:93], v[102:105]
	v_mfma_f32_16x16x32_f16 v[24:27], v[74:77], v[110:113], v[24:27]
	v_mfma_f32_16x16x32_f16 v[114:117], v[118:121], v[90:93], v[114:117]
	v_mfma_f32_16x16x32_f16 v[40:43], v[118:121], v[110:113], v[40:43]
	v_mfma_f32_16x16x32_f16 v[70:73], v[122:125], v[90:93], v[70:73]
	global_load_dwordx4 v[90:93], v[2:3], off offset:3968
	global_load_dwordx4 v[126:129], v[4:5], off offset:3968
	global_load_dwordx4 v[130:133], v[14:15], off offset:3968
	global_load_dwordx4 v[74:77], v[10:11], off offset:3968
	global_load_dwordx4 v[138:141], v[12:13], off offset:3968
	global_load_dwordx4 v[142:145], v[8:9], off offset:3968
	global_load_dwordx4 v[154:157], v[6:7], off offset:3968
	s_waitcnt lgkmcnt(0)
	s_barrier
	v_mfma_f32_16x16x32_f16 v[48:51], v[122:125], v[110:113], v[48:51]
	ds_read_b128 v[58:61], v16 offset:32768
	ds_read_b128 v[106:109], v21
	s_waitcnt lgkmcnt(0)
	v_mfma_f32_16x16x32_f16 v[36:39], v[58:61], v[106:109], v[36:39]
	ds_read_b128 v[94:97], v16 offset:34816
	ds_read_b128 v[110:113], v21 offset:2048
	s_waitcnt lgkmcnt(0)
	v_mfma_f32_16x16x32_f16 v[66:69], v[58:61], v[110:113], v[66:69]
	ds_read_b128 v[118:121], v16 offset:36864
	v_mfma_f32_16x16x32_f16 v[44:47], v[94:97], v[106:109], v[44:47]
	ds_read_b128 v[122:125], v16 offset:38912
	v_mfma_f32_16x16x32_f16 v[78:81], v[94:97], v[110:113], v[78:81]
	ds_read_b128 v[158:161], v23 offset:6144
	s_waitcnt lgkmcnt(2)
	v_mfma_f32_16x16x32_f16 v[82:85], v[118:121], v[106:109], v[82:85]
	v_addc_co_u32_e32 v1, vcc, 0, v1, vcc
	v_mfma_f32_16x16x32_f16 v[86:89], v[118:121], v[110:113], v[86:89]
	v_add_co_u32_e32 v2, vcc, s1, v2
	s_waitcnt lgkmcnt(1)
	v_mfma_f32_16x16x32_f16 v[28:31], v[122:125], v[106:109], v[28:31]
	ds_read_b128 v[106:109], v21 offset:4096
	v_mfma_f32_16x16x32_f16 v[32:35], v[122:125], v[110:113], v[32:35]
	ds_read_b128 v[110:113], v21 offset:6144
	s_waitcnt lgkmcnt(1)
	v_mfma_f32_16x16x32_f16 v[98:101], v[58:61], v[106:109], v[98:101]
	v_addc_co_u32_e32 v3, vcc, 0, v3, vcc
	s_waitcnt lgkmcnt(0)
; #define GL_LOAD(s_, kt_) if (VAR != 1) { a##s_##0 = GL_A(0, kt_); a##s_##1 = GL_A(1, kt_); a##s_##2 = GL_A(2, kt_); a##s_##3 = GL_A(3, kt_); b##s_##0 = GL_B(0, kt_); b##s_##1 = GL_B(1, kt_); b##s_##2 = GL_B(2, kt_); b##s_##3 = GL_B(3, kt_); }
; #define LDS_STORE(s_, buf_) if (VAR != 2) { LDS_ST1(sA, 0, buf_, a##s_##0) LDS_ST1(sA, 1, buf_, a##s_##1) LDS_ST1(sA, 2, buf_, a##s_##2) LDS_ST1(sA, 3, buf_, a##s_##3) LDS_ST1(sB, 0, buf_, b##s_##0) LDS_ST1(sB, 1, buf_, b##s_##1) LDS_ST1(sB, 2, buf_, b##s_##2) LDS_ST1(sB, 3, buf_, b##s_##3) }
;     ...
;   GL_LOAD(0, 0)
;   GL_LOAD(1, 1)
;   LDS_STORE(0, 0)
;   if (VAR != 4) __syncthreads();
; #pragma unroll
;   for (int kt = 0; kt < nk; kt += 2) {
;     if (kt + 2 < nk) { GL_LOAD(0, kt + 2) }
;     MMA_TILE(0)
;     LDS_STORE(1, 1)
;     if (VAR != 4) __syncthreads();
;     if (kt + 3 < nk) { GL_LOAD(1, kt + 3) }
;     MMA_TILE(1)
;     if (kt + 2 < nk) { LDS_STORE(0, 0) }
;     if (VAR != 4) __syncthreads();
	v_mfma_f32_16x16x32_f16 v[52:55], v[58:61], v[110:113], v[52:55]
	ds_read_b128 v[58:61], v22 offset:32768
	v_mfma_f32_16x16x32_f16 v[102:105], v[94:97], v[106:109], v[102:105]
	v_add_co_u32_e32 v4, vcc, s1, v4
	v_mfma_f32_16x16x32_f16 v[24:27], v[94:97], v[110:113], v[24:27]
	ds_read_b128 v[94:97], v22 offset:34816
	v_addc_co_u32_e32 v5, vcc, 0, v5, vcc
	v_mfma_f32_16x16x32_f16 v[114:117], v[118:121], v[106:109], v[114:117]
	v_add_co_u32_e32 v14, vcc, s1, v14
	s_nop 1
	v_addc_co_u32_e32 v15, vcc, 0, v15, vcc
	v_mfma_f32_16x16x32_f16 v[40:43], v[118:121], v[110:113], v[40:43]
	ds_read_b128 v[118:121], v22 offset:36864
	v_add_co_u32_e32 v10, vcc, s1, v10
	v_mfma_f32_16x16x32_f16 v[70:73], v[122:125], v[106:109], v[70:73]
	ds_read_b128 v[106:109], v23
	v_addc_co_u32_e32 v11, vcc, 0, v11, vcc
	v_mfma_f32_16x16x32_f16 v[48:51], v[122:125], v[110:113], v[48:51]
	ds_read_b128 v[110:113], v23 offset:2048
	ds_read_b128 v[122:125], v22 offset:38912
	s_waitcnt lgkmcnt(2)
	v_mfma_f32_16x16x32_f16 v[36:39], v[58:61], v[106:109], v[36:39]
	v_add_co_u32_e32 v12, vcc, s1, v12
	s_nop 1
	v_addc_co_u32_e32 v13, vcc, 0, v13, vcc
	s_waitcnt lgkmcnt(1)
	v_mfma_f32_16x16x32_f16 v[66:69], v[58:61], v[110:113], v[66:69]
	v_add_co_u32_e32 v8, vcc, s1, v8
	s_nop 1
	v_addc_co_u32_e32 v9, vcc, 0, v9, vcc
	v_mfma_f32_16x16x32_f16 v[44:47], v[94:97], v[106:109], v[44:47]
	v_add_co_u32_e32 v6, vcc, s1, v6
	s_nop 1
	v_addc_co_u32_e32 v7, vcc, 0, v7, vcc
	v_mfma_f32_16x16x32_f16 v[78:81], v[94:97], v[110:113], v[78:81]
	s_waitcnt vmcnt(7)
	ds_write_b128 v17, v[62:65] offset:16384
	s_waitcnt vmcnt(6)
	ds_write_b128 v18, v[90:93] offset:16384
	v_mfma_f32_16x16x32_f16 v[52:55], v[58:61], v[158:161], v[52:55]
	s_waitcnt vmcnt(5)
	ds_write_b128 v19, v[126:129] offset:16384
	s_waitcnt vmcnt(4)
	ds_write_b128 v20, v[130:133] offset:16384
	v_mfma_f32_16x16x32_f16 v[24:27], v[94:97], v[158:161], v[24:27]
	s_waitcnt vmcnt(3)
	ds_write_b128 v17, v[74:77] offset:49152
	s_waitcnt vmcnt(2)
	ds_write_b128 v18, v[138:141] offset:49152
	v_mfma_f32_16x16x32_f16 v[82:85], v[118:121], v[106:109], v[82:85]
	s_waitcnt vmcnt(1)
	ds_write_b128 v19, v[142:145] offset:49152
	s_waitcnt vmcnt(0)
	ds_write_b128 v20, v[154:157] offset:49152
	v_mfma_f32_16x16x32_f16 v[86:89], v[118:121], v[110:113], v[86:89]
	s_waitcnt lgkmcnt(8)
	v_mfma_f32_16x16x32_f16 v[28:31], v[122:125], v[106:109], v[28:31]
	ds_read_b128 v[106:109], v23 offset:4096
	v_mfma_f32_16x16x32_f16 v[32:35], v[122:125], v[110:113], v[32:35]
	global_load_dwordx4 v[110:113], v[0:1], off
	global_load_dwordx4 v[134:137], v[2:3], off
	v_mfma_f32_16x16x32_f16 v[40:43], v[118:121], v[158:161], v[40:43]
	global_load_dwordx4 v[162:165], v[4:5], off
	s_waitcnt lgkmcnt(0)
	v_mfma_f32_16x16x32_f16 v[98:101], v[58:61], v[106:109], v[98:101]
	global_load_dwordx4 v[166:169], v[14:15], off
	v_mfma_f32_16x16x32_f16 v[102:105], v[94:97], v[106:109], v[102:105]
	v_mfma_f32_16x16x32_f16 v[114:117], v[118:121], v[106:109], v[114:117]
	v_mfma_f32_16x16x32_f16 v[70:73], v[122:125], v[106:109], v[70:73]
	global_load_dwordx4 v[106:109], v[10:11], off
	global_load_dwordx4 v[190:193], v[12:13], off
	global_load_dwordx4 v[58:61], v[8:9], off
	global_load_dwordx4 v[94:97], v[6:7], off
	s_waitcnt lgkmcnt(0)
	s_barrier
	v_mfma_f32_16x16x32_f16 v[48:51], v[122:125], v[158:161], v[48:51]
	ds_read_b128 v[62:65], v16 offset:49152
	ds_read_b128 v[90:93], v21 offset:16384
	s_waitcnt lgkmcnt(0)
	v_mfma_f32_16x16x32_f16 v[36:39], v[62:65], v[90:93], v[36:39]
	ds_read_b128 v[74:77], v16 offset:51200
	ds_read_b128 v[118:121], v21 offset:18432
	s_waitcnt lgkmcnt(0)
	v_mfma_f32_16x16x32_f16 v[66:69], v[62:65], v[118:121], v[66:69]
	ds_read_b128 v[122:125], v16 offset:53248
	v_mfma_f32_16x16x32_f16 v[44:47], v[74:77], v[90:93], v[44:47]
	ds_read_b128 v[126:129], v16 offset:55296
	v_mfma_f32_16x16x32_f16 v[78:81], v[74:77], v[118:121], v[78:81]
	s_waitcnt vmcnt(7)
	ds_write_b128 v17, v[110:113]
	s_waitcnt lgkmcnt(2)
	v_mfma_f32_16x16x32_f16 v[82:85], v[122:125], v[90:93], v[82:85]
	s_waitcnt vmcnt(6)
	ds_write_b128 v18, v[134:137]
	v_mfma_f32_16x16x32_f16 v[86:89], v[122:125], v[118:121], v[86:89]
	s_waitcnt vmcnt(5)
	ds_write_b128 v19, v[162:165]
	s_waitcnt lgkmcnt(3)
	v_mfma_f32_16x16x32_f16 v[28:31], v[126:129], v[90:93], v[28:31]
	ds_read_b128 v[90:93], v21 offset:20480
	v_mfma_f32_16x16x32_f16 v[32:35], v[126:129], v[118:121], v[32:35]
	ds_read_b128 v[118:121], v21 offset:22528
	s_waitcnt lgkmcnt(1)
	v_mfma_f32_16x16x32_f16 v[98:101], v[62:65], v[90:93], v[98:101]
	s_waitcnt vmcnt(4)
	ds_write_b128 v20, v[166:169]
	s_waitcnt lgkmcnt(1)
	v_mfma_f32_16x16x32_f16 v[52:55], v[62:65], v[118:121], v[52:55]
	ds_read_b128 v[62:65], v22 offset:49152
	v_mfma_f32_16x16x32_f16 v[102:105], v[74:77], v[90:93], v[102:105]
	s_waitcnt vmcnt(3)
	ds_write_b128 v17, v[106:109] offset:32768
	v_mfma_f32_16x16x32_f16 v[24:27], v[74:77], v[118:121], v[24:27]
	ds_read_b128 v[74:77], v22 offset:51200
	v_mfma_f32_16x16x32_f16 v[114:117], v[122:125], v[90:93], v[114:117]
	s_waitcnt vmcnt(2)
	ds_write_b128 v18, v[190:193] offset:32768
	v_mfma_f32_16x16x32_f16 v[40:43], v[122:125], v[118:121], v[40:43]
	ds_read_b128 v[122:125], v22 offset:53248
	v_mfma_f32_16x16x32_f16 v[70:73], v[126:129], v[90:93], v[70:73]
	ds_read_b128 v[90:93], v23 offset:16384
	v_mfma_f32_16x16x32_f16 v[48:51], v[126:129], v[118:121], v[48:51]
	ds_read_b128 v[118:121], v23 offset:18432
	s_waitcnt lgkmcnt(1)
	v_mfma_f32_16x16x32_f16 v[36:39], v[62:65], v[90:93], v[36:39]
	ds_read_b128 v[126:129], v22 offset:55296
	s_waitcnt lgkmcnt(1)
	v_mfma_f32_16x16x32_f16 v[66:69], v[62:65], v[118:121], v[66:69]
	s_waitcnt vmcnt(1)
; #define GL_LOAD(s_, kt_) if (VAR != 1) { a##s_##0 = GL_A(0, kt_); a##s_##1 = GL_A(1, kt_); a##s_##2 = GL_A(2, kt_); a##s_##3 = GL_A(3, kt_); b##s_##0 = GL_B(0, kt_); b##s_##1 = GL_B(1, kt_); b##s_##2 = GL_B(2, kt_); b##s_##3 = GL_B(3, kt_); }
; #define LDS_STORE(s_, buf_) if (VAR != 2) { LDS_ST1(sA, 0, buf_, a##s_##0) LDS_ST1(sA, 1, buf_, a##s_##1) LDS_ST1(sA, 2, buf_, a##s_##2) LDS_ST1(sA, 3, buf_, a##s_##3) LDS_ST1(sB, 0, buf_, b##s_##0) LDS_ST1(sB, 1, buf_, b##s_##1) LDS_ST1(sB, 2, buf_, b##s_##2) LDS_ST1(sB, 3, buf_, b##s_##3) }
;     ...
;   GL_LOAD(0, 0)
;   GL_LOAD(1, 1)
;   LDS_STORE(0, 0)
;   if (VAR != 4) __syncthreads();
; #pragma unroll
;   for (int kt = 0; kt < nk; kt += 2) {
;     if (kt + 2 < nk) { GL_LOAD(0, kt + 2) }
;     MMA_TILE(0)
;     LDS_STORE(1, 1)
;     if (VAR != 4) __syncthreads();
;     if (kt + 3 < nk) { GL_LOAD(1, kt + 3) }
;     MMA_TILE(1)
;     if (kt + 2 < nk) { LDS_STORE(0, 0) }
;     if (VAR != 4) __syncthreads();
	ds_write_b128 v19, v[58:61] offset:32768
	v_mfma_f32_16x16x32_f16 v[44:47], v[74:77], v[90:93], v[44:47]
	s_waitcnt vmcnt(0)
	ds_write_b128 v20, v[94:97] offset:32768
	v_mfma_f32_16x16x32_f16 v[78:81], v[74:77], v[118:121], v[78:81]
	v_mfma_f32_16x16x32_f16 v[82:85], v[122:125], v[90:93], v[82:85]
	v_mfma_f32_16x16x32_f16 v[86:89], v[122:125], v[118:121], v[86:89]
	s_waitcnt lgkmcnt(2)
	v_mfma_f32_16x16x32_f16 v[28:31], v[126:129], v[90:93], v[28:31]
	ds_read_b128 v[90:93], v23 offset:20480
	v_mfma_f32_16x16x32_f16 v[32:35], v[126:129], v[118:121], v[32:35]
	ds_read_b128 v[118:121], v23 offset:22528
	s_waitcnt lgkmcnt(1)
	v_mfma_f32_16x16x32_f16 v[98:101], v[62:65], v[90:93], v[98:101]
	s_waitcnt lgkmcnt(0)
	v_mfma_f32_16x16x32_f16 v[52:55], v[62:65], v[118:121], v[52:55]
	global_load_dwordx4 v[62:65], v[0:1], off offset:128
	v_mfma_f32_16x16x32_f16 v[102:105], v[74:77], v[90:93], v[102:105]
	v_mfma_f32_16x16x32_f16 v[24:27], v[74:77], v[118:121], v[24:27]
	v_mfma_f32_16x16x32_f16 v[114:117], v[122:125], v[90:93], v[114:117]
	v_mfma_f32_16x16x32_f16 v[40:43], v[122:125], v[118:121], v[40:43]
	v_mfma_f32_16x16x32_f16 v[70:73], v[126:129], v[90:93], v[70:73]
	global_load_dwordx4 v[90:93], v[2:3], off offset:128
	global_load_dwordx4 v[130:133], v[4:5], off offset:128
	global_load_dwordx4 v[138:141], v[14:15], off offset:128
	global_load_dwordx4 v[74:77], v[10:11], off offset:128
	global_load_dwordx4 v[142:145], v[12:13], off offset:128
	global_load_dwordx4 v[154:157], v[8:9], off offset:128
	global_load_dwordx4 v[158:161], v[6:7], off offset:128
	s_waitcnt lgkmcnt(0)
	s_barrier
	v_mfma_f32_16x16x32_f16 v[48:51], v[126:129], v[118:121], v[48:51]
	ds_read_b128 v[58:61], v16 offset:32768
	ds_read_b128 v[106:109], v21
	s_waitcnt lgkmcnt(0)
	v_mfma_f32_16x16x32_f16 v[36:39], v[58:61], v[106:109], v[36:39]
	ds_read_b128 v[94:97], v16 offset:34816
	ds_read_b128 v[110:113], v21 offset:2048
	s_waitcnt lgkmcnt(0)
	v_mfma_f32_16x16x32_f16 v[66:69], v[58:61], v[110:113], v[66:69]
	ds_read_b128 v[118:121], v16 offset:36864
	v_mfma_f32_16x16x32_f16 v[44:47], v[94:97], v[106:109], v[44:47]
	ds_read_b128 v[122:125], v16 offset:38912
	v_mfma_f32_16x16x32_f16 v[78:81], v[94:97], v[110:113], v[78:81]
	s_waitcnt vmcnt(7)
	ds_write_b128 v17, v[62:65] offset:16384
	s_waitcnt lgkmcnt(2)
	v_mfma_f32_16x16x32_f16 v[82:85], v[118:121], v[106:109], v[82:85]
	s_waitcnt vmcnt(6)
	ds_write_b128 v18, v[90:93] offset:16384
	v_mfma_f32_16x16x32_f16 v[86:89], v[118:121], v[110:113], v[86:89]
	s_waitcnt vmcnt(5)
	ds_write_b128 v19, v[130:133] offset:16384
	s_waitcnt lgkmcnt(3)
	v_mfma_f32_16x16x32_f16 v[28:31], v[122:125], v[106:109], v[28:31]
	ds_read_b128 v[106:109], v21 offset:4096
	v_mfma_f32_16x16x32_f16 v[32:35], v[122:125], v[110:113], v[32:35]
	ds_read_b128 v[110:113], v21 offset:6144
	s_waitcnt lgkmcnt(1)
	v_mfma_f32_16x16x32_f16 v[98:101], v[58:61], v[106:109], v[98:101]
	s_waitcnt vmcnt(4)
	ds_write_b128 v20, v[138:141] offset:16384
	s_waitcnt lgkmcnt(1)
	v_mfma_f32_16x16x32_f16 v[52:55], v[58:61], v[110:113], v[52:55]
	ds_read_b128 v[58:61], v22 offset:32768
	v_mfma_f32_16x16x32_f16 v[102:105], v[94:97], v[106:109], v[102:105]
	s_waitcnt vmcnt(3)
	ds_write_b128 v17, v[74:77] offset:49152
	v_mfma_f32_16x16x32_f16 v[24:27], v[94:97], v[110:113], v[24:27]
	ds_read_b128 v[94:97], v22 offset:34816
	v_mfma_f32_16x16x32_f16 v[114:117], v[118:121], v[106:109], v[114:117]
	s_waitcnt vmcnt(2)
	ds_write_b128 v18, v[142:145] offset:49152
	v_mfma_f32_16x16x32_f16 v[40:43], v[118:121], v[110:113], v[40:43]
	ds_read_b128 v[118:121], v22 offset:36864
	v_mfma_f32_16x16x32_f16 v[70:73], v[122:125], v[106:109], v[70:73]
	ds_read_b128 v[106:109], v23
	v_mfma_f32_16x16x32_f16 v[48:51], v[122:125], v[110:113], v[48:51]
	ds_read_b128 v[110:113], v23 offset:2048
	s_waitcnt lgkmcnt(1)
	v_mfma_f32_16x16x32_f16 v[36:39], v[58:61], v[106:109], v[36:39]
	ds_read_b128 v[122:125], v22 offset:38912
	s_waitcnt lgkmcnt(1)
	v_mfma_f32_16x16x32_f16 v[66:69], v[58:61], v[110:113], v[66:69]
	s_waitcnt vmcnt(1)
	ds_write_b128 v19, v[154:157] offset:49152
	v_mfma_f32_16x16x32_f16 v[44:47], v[94:97], v[106:109], v[44:47]
	s_waitcnt vmcnt(0)
	ds_write_b128 v20, v[158:161] offset:49152
	v_mfma_f32_16x16x32_f16 v[78:81], v[94:97], v[110:113], v[78:81]
	v_mfma_f32_16x16x32_f16 v[82:85], v[118:121], v[106:109], v[82:85]
	v_mfma_f32_16x16x32_f16 v[86:89], v[118:121], v[110:113], v[86:89]
	s_waitcnt lgkmcnt(2)
	v_mfma_f32_16x16x32_f16 v[28:31], v[122:125], v[106:109], v[28:31]
	ds_read_b128 v[106:109], v23 offset:4096
	v_mfma_f32_16x16x32_f16 v[32:35], v[122:125], v[110:113], v[32:35]
	ds_read_b128 v[110:113], v23 offset:6144
	s_waitcnt lgkmcnt(1)
	v_mfma_f32_16x16x32_f16 v[98:101], v[58:61], v[106:109], v[98:101]
	s_waitcnt lgkmcnt(0)
	v_mfma_f32_16x16x32_f16 v[52:55], v[58:61], v[110:113], v[52:55]
	global_load_dwordx4 v[58:61], v[0:1], off offset:256
	v_mfma_f32_16x16x32_f16 v[102:105], v[94:97], v[106:109], v[102:105]
	v_mfma_f32_16x16x32_f16 v[24:27], v[94:97], v[110:113], v[24:27]
	v_mfma_f32_16x16x32_f16 v[114:117], v[118:121], v[106:109], v[114:117]
	v_mfma_f32_16x16x32_f16 v[40:43], v[118:121], v[110:113], v[40:43]
	v_mfma_f32_16x16x32_f16 v[70:73], v[122:125], v[106:109], v[70:73]
	global_load_dwordx4 v[106:109], v[2:3], off offset:256
	global_load_dwordx4 v[126:129], v[4:5], off offset:256
	global_load_dwordx4 v[134:137], v[14:15], off offset:256
	global_load_dwordx4 v[94:97], v[10:11], off offset:256
	global_load_dwordx4 v[162:165], v[12:13], off offset:256
	global_load_dwordx4 v[166:169], v[8:9], off offset:256
	global_load_dwordx4 v[190:193], v[6:7], off offset:256
	s_waitcnt lgkmcnt(0)
	s_barrier
; #define GL_LOAD(s_, kt_) if (VAR != 1) { a##s_##0 = GL_A(0, kt_); a##s_##1 = GL_A(1, kt_); a##s_##2 = GL_A(2, kt_); a##s_##3 = GL_A(3, kt_); b##s_##0 = GL_B(0, kt_); b##s_##1 = GL_B(1, kt_); b##s_##2 = GL_B(2, kt_); b##s_##3 = GL_B(3, kt_); }
; #define LDS_STORE(s_, buf_) if (VAR != 2) { LDS_ST1(sA, 0, buf_, a##s_##0) LDS_ST1(sA, 1, buf_, a##s_##1) LDS_ST1(sA, 2, buf_, a##s_##2) LDS_ST1(sA, 3, buf_, a##s_##3) LDS_ST1(sB, 0, buf_, b##s_##0) LDS_ST1(sB, 1, buf_, b##s_##1) LDS_ST1(sB, 2, buf_, b##s_##2) LDS_ST1(sB, 3, buf_, b##s_##3) }
;     ...
;   GL_LOAD(0, 0)
;   GL_LOAD(1, 1)
;   LDS_STORE(0, 0)
;   if (VAR != 4) __syncthreads();
; #pragma unroll
;   for (int kt = 0; kt < nk; kt += 2) {
;     if (kt + 2 < nk) { GL_LOAD(0, kt + 2) }
;     MMA_TILE(0)
;     LDS_STORE(1, 1)
;     if (VAR != 4) __syncthreads();
;     if (kt + 3 < nk) { GL_LOAD(1, kt + 3) }
;     MMA_TILE(1)
;     if (kt + 2 < nk) { LDS_STORE(0, 0) }
;     if (VAR != 4) __syncthreads();
	v_mfma_f32_16x16x32_f16 v[48:51], v[122:125], v[110:113], v[48:51]
	ds_read_b128 v[62:65], v16 offset:49152
	ds_read_b128 v[90:93], v21 offset:16384
	s_waitcnt lgkmcnt(0)
	v_mfma_f32_16x16x32_f16 v[36:39], v[62:65], v[90:93], v[36:39]
	ds_read_b128 v[74:77], v16 offset:51200
	ds_read_b128 v[110:113], v21 offset:18432
	s_waitcnt lgkmcnt(0)
	v_mfma_f32_16x16x32_f16 v[66:69], v[62:65], v[110:113], v[66:69]
	ds_read_b128 v[118:121], v16 offset:53248
	v_mfma_f32_16x16x32_f16 v[44:47], v[74:77], v[90:93], v[44:47]
	ds_read_b128 v[122:125], v16 offset:55296
	v_mfma_f32_16x16x32_f16 v[78:81], v[74:77], v[110:113], v[78:81]
	s_waitcnt vmcnt(7)
	ds_write_b128 v17, v[58:61]
	s_waitcnt lgkmcnt(2)
	v_mfma_f32_16x16x32_f16 v[82:85], v[118:121], v[90:93], v[82:85]
	s_waitcnt vmcnt(6)
	ds_write_b128 v18, v[106:109]
	v_mfma_f32_16x16x32_f16 v[86:89], v[118:121], v[110:113], v[86:89]
	s_waitcnt vmcnt(5)
	ds_write_b128 v19, v[126:129]
	s_waitcnt lgkmcnt(3)
	v_mfma_f32_16x16x32_f16 v[28:31], v[122:125], v[90:93], v[28:31]
	ds_read_b128 v[90:93], v21 offset:20480
	v_mfma_f32_16x16x32_f16 v[32:35], v[122:125], v[110:113], v[32:35]
	ds_read_b128 v[110:113], v21 offset:22528
	s_waitcnt lgkmcnt(1)
	v_mfma_f32_16x16x32_f16 v[98:101], v[62:65], v[90:93], v[98:101]
	s_waitcnt vmcnt(4)
	ds_write_b128 v20, v[134:137]
	s_waitcnt lgkmcnt(1)
	v_mfma_f32_16x16x32_f16 v[52:55], v[62:65], v[110:113], v[52:55]
	ds_read_b128 v[62:65], v22 offset:49152
	v_mfma_f32_16x16x32_f16 v[102:105], v[74:77], v[90:93], v[102:105]
	s_waitcnt vmcnt(3)
	ds_write_b128 v17, v[94:97] offset:32768
	v_mfma_f32_16x16x32_f16 v[24:27], v[74:77], v[110:113], v[24:27]
	ds_read_b128 v[74:77], v22 offset:51200
	v_mfma_f32_16x16x32_f16 v[114:117], v[118:121], v[90:93], v[114:117]
	s_waitcnt vmcnt(2)
	ds_write_b128 v18, v[162:165] offset:32768
	v_mfma_f32_16x16x32_f16 v[40:43], v[118:121], v[110:113], v[40:43]
	ds_read_b128 v[118:121], v22 offset:53248
	v_mfma_f32_16x16x32_f16 v[70:73], v[122:125], v[90:93], v[70:73]
	ds_read_b128 v[90:93], v23 offset:16384
	v_mfma_f32_16x16x32_f16 v[48:51], v[122:125], v[110:113], v[48:51]
	ds_read_b128 v[110:113], v23 offset:18432
	s_waitcnt lgkmcnt(1)
	v_mfma_f32_16x16x32_f16 v[36:39], v[62:65], v[90:93], v[36:39]
	ds_read_b128 v[122:125], v22 offset:55296
	s_waitcnt lgkmcnt(1)
	v_mfma_f32_16x16x32_f16 v[66:69], v[62:65], v[110:113], v[66:69]
	s_waitcnt vmcnt(1)
	ds_write_b128 v19, v[166:169] offset:32768
	v_mfma_f32_16x16x32_f16 v[44:47], v[74:77], v[90:93], v[44:47]
	s_waitcnt vmcnt(0)
	ds_write_b128 v20, v[190:193] offset:32768
	v_mfma_f32_16x16x32_f16 v[78:81], v[74:77], v[110:113], v[78:81]
	v_mfma_f32_16x16x32_f16 v[82:85], v[118:121], v[90:93], v[82:85]
	v_mfma_f32_16x16x32_f16 v[86:89], v[118:121], v[110:113], v[86:89]
	s_waitcnt lgkmcnt(2)
	v_mfma_f32_16x16x32_f16 v[28:31], v[122:125], v[90:93], v[28:31]
	ds_read_b128 v[90:93], v23 offset:20480
	v_mfma_f32_16x16x32_f16 v[32:35], v[122:125], v[110:113], v[32:35]
	ds_read_b128 v[110:113], v23 offset:22528
	s_waitcnt lgkmcnt(1)
	v_mfma_f32_16x16x32_f16 v[98:101], v[62:65], v[90:93], v[98:101]
	s_waitcnt lgkmcnt(0)
	v_mfma_f32_16x16x32_f16 v[52:55], v[62:65], v[110:113], v[52:55]
	global_load_dwordx4 v[62:65], v[0:1], off offset:384
	v_mfma_f32_16x16x32_f16 v[102:105], v[74:77], v[90:93], v[102:105]
	v_mfma_f32_16x16x32_f16 v[24:27], v[74:77], v[110:113], v[24:27]
	v_mfma_f32_16x16x32_f16 v[114:117], v[118:121], v[90:93], v[114:117]
	v_mfma_f32_16x16x32_f16 v[40:43], v[118:121], v[110:113], v[40:43]
	v_mfma_f32_16x16x32_f16 v[70:73], v[122:125], v[90:93], v[70:73]
	global_load_dwordx4 v[90:93], v[2:3], off offset:384
	global_load_dwordx4 v[130:133], v[4:5], off offset:384
	global_load_dwordx4 v[138:141], v[14:15], off offset:384
	global_load_dwordx4 v[74:77], v[10:11], off offset:384
	global_load_dwordx4 v[142:145], v[12:13], off offset:384
	global_load_dwordx4 v[154:157], v[8:9], off offset:384
	global_load_dwordx4 v[158:161], v[6:7], off offset:384
	s_waitcnt lgkmcnt(0)
	s_barrier
	v_mfma_f32_16x16x32_f16 v[48:51], v[122:125], v[110:113], v[48:51]
	ds_read_b128 v[58:61], v16 offset:32768
	ds_read_b128 v[106:109], v21
	s_waitcnt lgkmcnt(0)
	v_mfma_f32_16x16x32_f16 v[36:39], v[58:61], v[106:109], v[36:39]
	ds_read_b128 v[94:97], v16 offset:34816
	ds_read_b128 v[110:113], v21 offset:2048
	s_waitcnt lgkmcnt(0)
	v_mfma_f32_16x16x32_f16 v[66:69], v[58:61], v[110:113], v[66:69]
	ds_read_b128 v[118:121], v16 offset:36864
	v_mfma_f32_16x16x32_f16 v[44:47], v[94:97], v[106:109], v[44:47]
	ds_read_b128 v[122:125], v16 offset:38912
	v_mfma_f32_16x16x32_f16 v[78:81], v[94:97], v[110:113], v[78:81]
	s_waitcnt vmcnt(7)
	ds_write_b128 v17, v[62:65] offset:16384
	s_waitcnt lgkmcnt(2)
	v_mfma_f32_16x16x32_f16 v[82:85], v[118:121], v[106:109], v[82:85]
	s_waitcnt vmcnt(6)
	ds_write_b128 v18, v[90:93] offset:16384
	v_mfma_f32_16x16x32_f16 v[86:89], v[118:121], v[110:113], v[86:89]
	s_waitcnt vmcnt(5)
	ds_write_b128 v19, v[130:133] offset:16384
	s_waitcnt lgkmcnt(3)
	v_mfma_f32_16x16x32_f16 v[28:31], v[122:125], v[106:109], v[28:31]
	ds_read_b128 v[106:109], v21 offset:4096
	v_mfma_f32_16x16x32_f16 v[32:35], v[122:125], v[110:113], v[32:35]
	ds_read_b128 v[110:113], v21 offset:6144
	s_waitcnt lgkmcnt(1)
	v_mfma_f32_16x16x32_f16 v[98:101], v[58:61], v[106:109], v[98:101]
	s_waitcnt vmcnt(4)
	ds_write_b128 v20, v[138:141] offset:16384
	s_waitcnt lgkmcnt(1)
	v_mfma_f32_16x16x32_f16 v[52:55], v[58:61], v[110:113], v[52:55]
	ds_read_b128 v[58:61], v22 offset:32768
	v_mfma_f32_16x16x32_f16 v[102:105], v[94:97], v[106:109], v[102:105]
	s_waitcnt vmcnt(3)
; #define GL_LOAD(s_, kt_) if (VAR != 1) { a##s_##0 = GL_A(0, kt_); a##s_##1 = GL_A(1, kt_); a##s_##2 = GL_A(2, kt_); a##s_##3 = GL_A(3, kt_); b##s_##0 = GL_B(0, kt_); b##s_##1 = GL_B(1, kt_); b##s_##2 = GL_B(2, kt_); b##s_##3 = GL_B(3, kt_); }
; #define LDS_STORE(s_, buf_) if (VAR != 2) { LDS_ST1(sA, 0, buf_, a##s_##0) LDS_ST1(sA, 1, buf_, a##s_##1) LDS_ST1(sA, 2, buf_, a##s_##2) LDS_ST1(sA, 3, buf_, a##s_##3) LDS_ST1(sB, 0, buf_, b##s_##0) LDS_ST1(sB, 1, buf_, b##s_##1) LDS_ST1(sB, 2, buf_, b##s_##2) LDS_ST1(sB, 3, buf_, b##s_##3) }
;     ...
;   GL_LOAD(0, 0)
;   GL_LOAD(1, 1)
;   LDS_STORE(0, 0)
;   if (VAR != 4) __syncthreads();
; #pragma unroll
;   for (int kt = 0; kt < nk; kt += 2) {
;     if (kt + 2 < nk) { GL_LOAD(0, kt + 2) }
;     MMA_TILE(0)
;     LDS_STORE(1, 1)
;     if (VAR != 4) __syncthreads();
;     if (kt + 3 < nk) { GL_LOAD(1, kt + 3) }
;     MMA_TILE(1)
;     if (kt + 2 < nk) { LDS_STORE(0, 0) }
;     if (VAR != 4) __syncthreads();
	ds_write_b128 v17, v[74:77] offset:49152
	v_mfma_f32_16x16x32_f16 v[24:27], v[94:97], v[110:113], v[24:27]
	ds_read_b128 v[94:97], v22 offset:34816
	v_mfma_f32_16x16x32_f16 v[114:117], v[118:121], v[106:109], v[114:117]
	s_waitcnt vmcnt(2)
	ds_write_b128 v18, v[142:145] offset:49152
	v_mfma_f32_16x16x32_f16 v[40:43], v[118:121], v[110:113], v[40:43]
	ds_read_b128 v[118:121], v22 offset:36864
	v_mfma_f32_16x16x32_f16 v[70:73], v[122:125], v[106:109], v[70:73]
	ds_read_b128 v[106:109], v23
	v_mfma_f32_16x16x32_f16 v[48:51], v[122:125], v[110:113], v[48:51]
	ds_read_b128 v[110:113], v23 offset:2048
	s_waitcnt lgkmcnt(1)
	v_mfma_f32_16x16x32_f16 v[36:39], v[58:61], v[106:109], v[36:39]
	ds_read_b128 v[122:125], v22 offset:38912
	s_waitcnt lgkmcnt(1)
	v_mfma_f32_16x16x32_f16 v[66:69], v[58:61], v[110:113], v[66:69]
	s_waitcnt vmcnt(1)
	ds_write_b128 v19, v[154:157] offset:49152
	v_mfma_f32_16x16x32_f16 v[44:47], v[94:97], v[106:109], v[44:47]
	s_waitcnt vmcnt(0)
	ds_write_b128 v20, v[158:161] offset:49152
	v_mfma_f32_16x16x32_f16 v[78:81], v[94:97], v[110:113], v[78:81]
	v_mfma_f32_16x16x32_f16 v[82:85], v[118:121], v[106:109], v[82:85]
	v_mfma_f32_16x16x32_f16 v[86:89], v[118:121], v[110:113], v[86:89]
	s_waitcnt lgkmcnt(2)
	v_mfma_f32_16x16x32_f16 v[28:31], v[122:125], v[106:109], v[28:31]
	ds_read_b128 v[106:109], v23 offset:4096
	v_mfma_f32_16x16x32_f16 v[32:35], v[122:125], v[110:113], v[32:35]
	ds_read_b128 v[110:113], v23 offset:6144
	s_waitcnt lgkmcnt(1)
	v_mfma_f32_16x16x32_f16 v[98:101], v[58:61], v[106:109], v[98:101]
	s_waitcnt lgkmcnt(0)
	v_mfma_f32_16x16x32_f16 v[52:55], v[58:61], v[110:113], v[52:55]
	global_load_dwordx4 v[58:61], v[0:1], off offset:512
	v_mfma_f32_16x16x32_f16 v[102:105], v[94:97], v[106:109], v[102:105]
	v_mfma_f32_16x16x32_f16 v[24:27], v[94:97], v[110:113], v[24:27]
	v_mfma_f32_16x16x32_f16 v[114:117], v[118:121], v[106:109], v[114:117]
	v_mfma_f32_16x16x32_f16 v[40:43], v[118:121], v[110:113], v[40:43]
	v_mfma_f32_16x16x32_f16 v[70:73], v[122:125], v[106:109], v[70:73]
	global_load_dwordx4 v[106:109], v[2:3], off offset:512
	global_load_dwordx4 v[126:129], v[4:5], off offset:512
	global_load_dwordx4 v[134:137], v[14:15], off offset:512
	global_load_dwordx4 v[94:97], v[10:11], off offset:512
	global_load_dwordx4 v[162:165], v[12:13], off offset:512
	global_load_dwordx4 v[166:169], v[8:9], off offset:512
	global_load_dwordx4 v[190:193], v[6:7], off offset:512
	s_waitcnt lgkmcnt(0)
	s_barrier
	v_mfma_f32_16x16x32_f16 v[48:51], v[122:125], v[110:113], v[48:51]
	ds_read_b128 v[62:65], v16 offset:49152
	ds_read_b128 v[90:93], v21 offset:16384
	s_waitcnt lgkmcnt(0)
	v_mfma_f32_16x16x32_f16 v[36:39], v[62:65], v[90:93], v[36:39]
	ds_read_b128 v[74:77], v16 offset:51200
	ds_read_b128 v[110:113], v21 offset:18432
	s_waitcnt lgkmcnt(0)
	v_mfma_f32_16x16x32_f16 v[66:69], v[62:65], v[110:113], v[66:69]
	ds_read_b128 v[118:121], v16 offset:53248
	v_mfma_f32_16x16x32_f16 v[44:47], v[74:77], v[90:93], v[44:47]
	ds_read_b128 v[122:125], v16 offset:55296
	v_mfma_f32_16x16x32_f16 v[78:81], v[74:77], v[110:113], v[78:81]
	s_waitcnt vmcnt(7)
	ds_write_b128 v17, v[58:61]
	s_waitcnt lgkmcnt(2)
	v_mfma_f32_16x16x32_f16 v[82:85], v[118:121], v[90:93], v[82:85]
	s_waitcnt vmcnt(6)
	ds_write_b128 v18, v[106:109]
	v_mfma_f32_16x16x32_f16 v[86:89], v[118:121], v[110:113], v[86:89]
	s_waitcnt vmcnt(5)
	ds_write_b128 v19, v[126:129]
	s_waitcnt lgkmcnt(3)
	v_mfma_f32_16x16x32_f16 v[28:31], v[122:125], v[90:93], v[28:31]
	ds_read_b128 v[90:93], v21 offset:20480
	v_mfma_f32_16x16x32_f16 v[32:35], v[122:125], v[110:113], v[32:35]
	ds_read_b128 v[110:113], v21 offset:22528
	s_waitcnt lgkmcnt(1)
	v_mfma_f32_16x16x32_f16 v[98:101], v[62:65], v[90:93], v[98:101]
	s_waitcnt vmcnt(4)
	ds_write_b128 v20, v[134:137]
	s_waitcnt lgkmcnt(1)
	v_mfma_f32_16x16x32_f16 v[52:55], v[62:65], v[110:113], v[52:55]
	ds_read_b128 v[62:65], v22 offset:49152
	v_mfma_f32_16x16x32_f16 v[102:105], v[74:77], v[90:93], v[102:105]
	s_waitcnt vmcnt(3)
	ds_write_b128 v17, v[94:97] offset:32768
	v_mfma_f32_16x16x32_f16 v[24:27], v[74:77], v[110:113], v[24:27]
	ds_read_b128 v[74:77], v22 offset:51200
	v_mfma_f32_16x16x32_f16 v[114:117], v[118:121], v[90:93], v[114:117]
	s_waitcnt vmcnt(2)
	ds_write_b128 v18, v[162:165] offset:32768
	v_mfma_f32_16x16x32_f16 v[40:43], v[118:121], v[110:113], v[40:43]
	ds_read_b128 v[118:121], v22 offset:53248
	v_mfma_f32_16x16x32_f16 v[70:73], v[122:125], v[90:93], v[70:73]
	ds_read_b128 v[90:93], v23 offset:16384
	v_mfma_f32_16x16x32_f16 v[48:51], v[122:125], v[110:113], v[48:51]
	ds_read_b128 v[110:113], v23 offset:18432
	s_waitcnt lgkmcnt(1)
	v_mfma_f32_16x16x32_f16 v[36:39], v[62:65], v[90:93], v[36:39]
	ds_read_b128 v[122:125], v22 offset:55296
	s_waitcnt lgkmcnt(1)
	v_mfma_f32_16x16x32_f16 v[66:69], v[62:65], v[110:113], v[66:69]
	s_waitcnt vmcnt(1)
	ds_write_b128 v19, v[166:169] offset:32768
	v_mfma_f32_16x16x32_f16 v[44:47], v[74:77], v[90:93], v[44:47]
	s_waitcnt vmcnt(0)
	ds_write_b128 v20, v[190:193] offset:32768
	v_mfma_f32_16x16x32_f16 v[78:81], v[74:77], v[110:113], v[78:81]
	v_mfma_f32_16x16x32_f16 v[82:85], v[118:121], v[90:93], v[82:85]
	v_mfma_f32_16x16x32_f16 v[86:89], v[118:121], v[110:113], v[86:89]
	s_waitcnt lgkmcnt(2)
	v_mfma_f32_16x16x32_f16 v[28:31], v[122:125], v[90:93], v[28:31]
	ds_read_b128 v[90:93], v23 offset:20480
	v_mfma_f32_16x16x32_f16 v[32:35], v[122:125], v[110:113], v[32:35]
	ds_read_b128 v[110:113], v23 offset:22528
	s_waitcnt lgkmcnt(1)
	v_mfma_f32_16x16x32_f16 v[98:101], v[62:65], v[90:93], v[98:101]
	s_waitcnt lgkmcnt(0)
	v_mfma_f32_16x16x32_f16 v[52:55], v[62:65], v[110:113], v[52:55]
	global_load_dwordx4 v[62:65], v[0:1], off offset:640
	v_mfma_f32_16x16x32_f16 v[102:105], v[74:77], v[90:93], v[102:105]
	v_mfma_f32_16x16x32_f16 v[24:27], v[74:77], v[110:113], v[24:27]
	v_mfma_f32_16x16x32_f16 v[114:117], v[118:121], v[90:93], v[114:117]
	v_mfma_f32_16x16x32_f16 v[40:43], v[118:121], v[110:113], v[40:43]
	v_mfma_f32_16x16x32_f16 v[70:73], v[122:125], v[90:93], v[70:73]
	global_load_dwordx4 v[90:93], v[2:3], off offset:640
	global_load_dwordx4 v[130:133], v[4:5], off offset:640
	global_load_dwordx4 v[138:141], v[14:15], off offset:640
	global_load_dwordx4 v[74:77], v[10:11], off offset:640
	global_load_dwordx4 v[142:145], v[12:13], off offset:640
	global_load_dwordx4 v[154:157], v[8:9], off offset:640
	global_load_dwordx4 v[158:161], v[6:7], off offset:640
	s_waitcnt lgkmcnt(0)
	s_barrier
; #define GL_LOAD(s_, kt_) if (VAR != 1) { a##s_##0 = GL_A(0, kt_); a##s_##1 = GL_A(1, kt_); a##s_##2 = GL_A(2, kt_); a##s_##3 = GL_A(3, kt_); b##s_##0 = GL_B(0, kt_); b##s_##1 = GL_B(1, kt_); b##s_##2 = GL_B(2, kt_); b##s_##3 = GL_B(3, kt_); }
; #define LDS_STORE(s_, buf_) if (VAR != 2) { LDS_ST1(sA, 0, buf_, a##s_##0) LDS_ST1(sA, 1, buf_, a##s_##1) LDS_ST1(sA, 2, buf_, a##s_##2) LDS_ST1(sA, 3, buf_, a##s_##3) LDS_ST1(sB, 0, buf_, b##s_##0) LDS_ST1(sB, 1, buf_, b##s_##1) LDS_ST1(sB, 2, buf_, b##s_##2) LDS_ST1(sB, 3, buf_, b##s_##3) }
;     ...
;   GL_LOAD(0, 0)
;   GL_LOAD(1, 1)
;   LDS_STORE(0, 0)
;   if (VAR != 4) __syncthreads();
; #pragma unroll
;   for (int kt = 0; kt < nk; kt += 2) {
;     if (kt + 2 < nk) { GL_LOAD(0, kt + 2) }
;     MMA_TILE(0)
;     LDS_STORE(1, 1)
;     if (VAR != 4) __syncthreads();
;     if (kt + 3 < nk) { GL_LOAD(1, kt + 3) }
;     MMA_TILE(1)
;     if (kt + 2 < nk) { LDS_STORE(0, 0) }
;     if (VAR != 4) __syncthreads();
	v_mfma_f32_16x16x32_f16 v[48:51], v[122:125], v[110:113], v[48:51]
	ds_read_b128 v[58:61], v16 offset:32768
	ds_read_b128 v[106:109], v21
	s_waitcnt lgkmcnt(0)
	v_mfma_f32_16x16x32_f16 v[36:39], v[58:61], v[106:109], v[36:39]
	ds_read_b128 v[94:97], v16 offset:34816
	ds_read_b128 v[110:113], v21 offset:2048
	s_waitcnt lgkmcnt(0)
	v_mfma_f32_16x16x32_f16 v[66:69], v[58:61], v[110:113], v[66:69]
	ds_read_b128 v[118:121], v16 offset:36864
	v_mfma_f32_16x16x32_f16 v[44:47], v[94:97], v[106:109], v[44:47]
	ds_read_b128 v[122:125], v16 offset:38912
	v_mfma_f32_16x16x32_f16 v[78:81], v[94:97], v[110:113], v[78:81]
	s_waitcnt vmcnt(7)
	ds_write_b128 v17, v[62:65] offset:16384
	s_waitcnt lgkmcnt(2)
	v_mfma_f32_16x16x32_f16 v[82:85], v[118:121], v[106:109], v[82:85]
	s_waitcnt vmcnt(6)
	ds_write_b128 v18, v[90:93] offset:16384
	v_mfma_f32_16x16x32_f16 v[86:89], v[118:121], v[110:113], v[86:89]
	s_waitcnt vmcnt(5)
	ds_write_b128 v19, v[130:133] offset:16384
	s_waitcnt lgkmcnt(3)
	v_mfma_f32_16x16x32_f16 v[28:31], v[122:125], v[106:109], v[28:31]
	ds_read_b128 v[106:109], v21 offset:4096
	v_mfma_f32_16x16x32_f16 v[32:35], v[122:125], v[110:113], v[32:35]
	ds_read_b128 v[110:113], v21 offset:6144
	s_waitcnt lgkmcnt(1)
	v_mfma_f32_16x16x32_f16 v[98:101], v[58:61], v[106:109], v[98:101]
	s_waitcnt vmcnt(4)
	ds_write_b128 v20, v[138:141] offset:16384
	s_waitcnt lgkmcnt(1)
	v_mfma_f32_16x16x32_f16 v[52:55], v[58:61], v[110:113], v[52:55]
	ds_read_b128 v[58:61], v22 offset:32768
	v_mfma_f32_16x16x32_f16 v[102:105], v[94:97], v[106:109], v[102:105]
	s_waitcnt vmcnt(3)
	ds_write_b128 v17, v[74:77] offset:49152
	v_mfma_f32_16x16x32_f16 v[24:27], v[94:97], v[110:113], v[24:27]
	ds_read_b128 v[94:97], v22 offset:34816
	v_mfma_f32_16x16x32_f16 v[114:117], v[118:121], v[106:109], v[114:117]
	s_waitcnt vmcnt(2)
	ds_write_b128 v18, v[142:145] offset:49152
	v_mfma_f32_16x16x32_f16 v[40:43], v[118:121], v[110:113], v[40:43]
	ds_read_b128 v[118:121], v22 offset:36864
	v_mfma_f32_16x16x32_f16 v[70:73], v[122:125], v[106:109], v[70:73]
	ds_read_b128 v[106:109], v23
	v_mfma_f32_16x16x32_f16 v[48:51], v[122:125], v[110:113], v[48:51]
	ds_read_b128 v[110:113], v23 offset:2048
	s_waitcnt lgkmcnt(1)
	v_mfma_f32_16x16x32_f16 v[36:39], v[58:61], v[106:109], v[36:39]
	ds_read_b128 v[122:125], v22 offset:38912
	s_waitcnt lgkmcnt(1)
	v_mfma_f32_16x16x32_f16 v[66:69], v[58:61], v[110:113], v[66:69]
	s_waitcnt vmcnt(1)
	ds_write_b128 v19, v[154:157] offset:49152
	v_mfma_f32_16x16x32_f16 v[44:47], v[94:97], v[106:109], v[44:47]
	s_waitcnt vmcnt(0)
	ds_write_b128 v20, v[158:161] offset:49152
	v_mfma_f32_16x16x32_f16 v[78:81], v[94:97], v[110:113], v[78:81]
	v_mfma_f32_16x16x32_f16 v[82:85], v[118:121], v[106:109], v[82:85]
	v_mfma_f32_16x16x32_f16 v[86:89], v[118:121], v[110:113], v[86:89]
	s_waitcnt lgkmcnt(2)
	v_mfma_f32_16x16x32_f16 v[28:31], v[122:125], v[106:109], v[28:31]
	ds_read_b128 v[106:109], v23 offset:4096
	v_mfma_f32_16x16x32_f16 v[32:35], v[122:125], v[110:113], v[32:35]
	ds_read_b128 v[110:113], v23 offset:6144
	s_waitcnt lgkmcnt(1)
	v_mfma_f32_16x16x32_f16 v[98:101], v[58:61], v[106:109], v[98:101]
	s_waitcnt lgkmcnt(0)
	v_mfma_f32_16x16x32_f16 v[52:55], v[58:61], v[110:113], v[52:55]
	global_load_dwordx4 v[58:61], v[0:1], off offset:768
	v_mfma_f32_16x16x32_f16 v[102:105], v[94:97], v[106:109], v[102:105]
	v_mfma_f32_16x16x32_f16 v[24:27], v[94:97], v[110:113], v[24:27]
	v_mfma_f32_16x16x32_f16 v[114:117], v[118:121], v[106:109], v[114:117]
	v_mfma_f32_16x16x32_f16 v[40:43], v[118:121], v[110:113], v[40:43]
	v_mfma_f32_16x16x32_f16 v[70:73], v[122:125], v[106:109], v[70:73]
	global_load_dwordx4 v[106:109], v[2:3], off offset:768
	global_load_dwordx4 v[126:129], v[4:5], off offset:768
	global_load_dwordx4 v[134:137], v[14:15], off offset:768
	global_load_dwordx4 v[94:97], v[10:11], off offset:768
	global_load_dwordx4 v[162:165], v[12:13], off offset:768
	global_load_dwordx4 v[166:169], v[8:9], off offset:768
	global_load_dwordx4 v[190:193], v[6:7], off offset:768
	s_waitcnt lgkmcnt(0)
	s_barrier
	v_mfma_f32_16x16x32_f16 v[48:51], v[122:125], v[110:113], v[48:51]
	ds_read_b128 v[62:65], v16 offset:49152
	ds_read_b128 v[90:93], v21 offset:16384
	s_waitcnt lgkmcnt(0)
	v_mfma_f32_16x16x32_f16 v[36:39], v[62:65], v[90:93], v[36:39]
	ds_read_b128 v[74:77], v16 offset:51200
	ds_read_b128 v[110:113], v21 offset:18432
	s_waitcnt lgkmcnt(0)
	v_mfma_f32_16x16x32_f16 v[66:69], v[62:65], v[110:113], v[66:69]
	ds_read_b128 v[118:121], v16 offset:53248
	v_mfma_f32_16x16x32_f16 v[44:47], v[74:77], v[90:93], v[44:47]
	ds_read_b128 v[122:125], v16 offset:55296
	v_mfma_f32_16x16x32_f16 v[78:81], v[74:77], v[110:113], v[78:81]
	s_waitcnt vmcnt(7)
	ds_write_b128 v17, v[58:61]
	s_waitcnt lgkmcnt(2)
	v_mfma_f32_16x16x32_f16 v[82:85], v[118:121], v[90:93], v[82:85]
	s_waitcnt vmcnt(6)
	ds_write_b128 v18, v[106:109]
	v_mfma_f32_16x16x32_f16 v[86:89], v[118:121], v[110:113], v[86:89]
	s_waitcnt vmcnt(5)
	ds_write_b128 v19, v[126:129]
	s_waitcnt lgkmcnt(3)
	v_mfma_f32_16x16x32_f16 v[28:31], v[122:125], v[90:93], v[28:31]
	ds_read_b128 v[90:93], v21 offset:20480
	v_mfma_f32_16x16x32_f16 v[32:35], v[122:125], v[110:113], v[32:35]
	ds_read_b128 v[110:113], v21 offset:22528
	s_waitcnt lgkmcnt(1)
	v_mfma_f32_16x16x32_f16 v[98:101], v[62:65], v[90:93], v[98:101]
	s_waitcnt vmcnt(4)
	ds_write_b128 v20, v[134:137]
	s_waitcnt lgkmcnt(1)
	v_mfma_f32_16x16x32_f16 v[52:55], v[62:65], v[110:113], v[52:55]
	ds_read_b128 v[62:65], v22 offset:49152
	v_mfma_f32_16x16x32_f16 v[102:105], v[74:77], v[90:93], v[102:105]
	s_waitcnt vmcnt(3)
; #define GL_LOAD(s_, kt_) if (VAR != 1) { a##s_##0 = GL_A(0, kt_); a##s_##1 = GL_A(1, kt_); a##s_##2 = GL_A(2, kt_); a##s_##3 = GL_A(3, kt_); b##s_##0 = GL_B(0, kt_); b##s_##1 = GL_B(1, kt_); b##s_##2 = GL_B(2, kt_); b##s_##3 = GL_B(3, kt_); }
; #define LDS_STORE(s_, buf_) if (VAR != 2) { LDS_ST1(sA, 0, buf_, a##s_##0) LDS_ST1(sA, 1, buf_, a##s_##1) LDS_ST1(sA, 2, buf_, a##s_##2) LDS_ST1(sA, 3, buf_, a##s_##3) LDS_ST1(sB, 0, buf_, b##s_##0) LDS_ST1(sB, 1, buf_, b##s_##1) LDS_ST1(sB, 2, buf_, b##s_##2) LDS_ST1(sB, 3, buf_, b##s_##3) }
;     ...
;   GL_LOAD(0, 0)
;   GL_LOAD(1, 1)
;   LDS_STORE(0, 0)
;   if (VAR != 4) __syncthreads();
; #pragma unroll
;   for (int kt = 0; kt < nk; kt += 2) {
;     if (kt + 2 < nk) { GL_LOAD(0, kt + 2) }
;     MMA_TILE(0)
;     LDS_STORE(1, 1)
;     if (VAR != 4) __syncthreads();
;     if (kt + 3 < nk) { GL_LOAD(1, kt + 3) }
;     MMA_TILE(1)
;     if (kt + 2 < nk) { LDS_STORE(0, 0) }
;     if (VAR != 4) __syncthreads();
	ds_write_b128 v17, v[94:97] offset:32768
	v_mfma_f32_16x16x32_f16 v[24:27], v[74:77], v[110:113], v[24:27]
	ds_read_b128 v[74:77], v22 offset:51200
	v_mfma_f32_16x16x32_f16 v[114:117], v[118:121], v[90:93], v[114:117]
	s_waitcnt vmcnt(2)
	ds_write_b128 v18, v[162:165] offset:32768
	v_mfma_f32_16x16x32_f16 v[40:43], v[118:121], v[110:113], v[40:43]
	ds_read_b128 v[118:121], v22 offset:53248
	v_mfma_f32_16x16x32_f16 v[70:73], v[122:125], v[90:93], v[70:73]
	ds_read_b128 v[90:93], v23 offset:16384
	v_mfma_f32_16x16x32_f16 v[48:51], v[122:125], v[110:113], v[48:51]
	ds_read_b128 v[110:113], v23 offset:18432
	s_waitcnt lgkmcnt(1)
	v_mfma_f32_16x16x32_f16 v[36:39], v[62:65], v[90:93], v[36:39]
	ds_read_b128 v[122:125], v22 offset:55296
	s_waitcnt lgkmcnt(1)
	v_mfma_f32_16x16x32_f16 v[66:69], v[62:65], v[110:113], v[66:69]
	s_waitcnt vmcnt(1)
	ds_write_b128 v19, v[166:169] offset:32768
	v_mfma_f32_16x16x32_f16 v[44:47], v[74:77], v[90:93], v[44:47]
	s_waitcnt vmcnt(0)
	ds_write_b128 v20, v[190:193] offset:32768
	v_mfma_f32_16x16x32_f16 v[78:81], v[74:77], v[110:113], v[78:81]
	v_mfma_f32_16x16x32_f16 v[82:85], v[118:121], v[90:93], v[82:85]
	v_mfma_f32_16x16x32_f16 v[86:89], v[118:121], v[110:113], v[86:89]
	s_waitcnt lgkmcnt(2)
	v_mfma_f32_16x16x32_f16 v[28:31], v[122:125], v[90:93], v[28:31]
	ds_read_b128 v[90:93], v23 offset:20480
	v_mfma_f32_16x16x32_f16 v[32:35], v[122:125], v[110:113], v[32:35]
	ds_read_b128 v[110:113], v23 offset:22528
	s_waitcnt lgkmcnt(1)
	v_mfma_f32_16x16x32_f16 v[98:101], v[62:65], v[90:93], v[98:101]
	s_waitcnt lgkmcnt(0)
	v_mfma_f32_16x16x32_f16 v[52:55], v[62:65], v[110:113], v[52:55]
	global_load_dwordx4 v[62:65], v[0:1], off offset:896
	v_mfma_f32_16x16x32_f16 v[102:105], v[74:77], v[90:93], v[102:105]
	v_mfma_f32_16x16x32_f16 v[24:27], v[74:77], v[110:113], v[24:27]
	v_mfma_f32_16x16x32_f16 v[114:117], v[118:121], v[90:93], v[114:117]
	v_mfma_f32_16x16x32_f16 v[40:43], v[118:121], v[110:113], v[40:43]
	v_mfma_f32_16x16x32_f16 v[70:73], v[122:125], v[90:93], v[70:73]
	global_load_dwordx4 v[90:93], v[2:3], off offset:896
	global_load_dwordx4 v[130:133], v[4:5], off offset:896
	global_load_dwordx4 v[138:141], v[14:15], off offset:896
	global_load_dwordx4 v[74:77], v[10:11], off offset:896
	global_load_dwordx4 v[142:145], v[12:13], off offset:896
	global_load_dwordx4 v[154:157], v[8:9], off offset:896
	global_load_dwordx4 v[158:161], v[6:7], off offset:896
	s_waitcnt lgkmcnt(0)
	s_barrier
	v_mfma_f32_16x16x32_f16 v[48:51], v[122:125], v[110:113], v[48:51]
	ds_read_b128 v[58:61], v16 offset:32768
	ds_read_b128 v[106:109], v21
	s_waitcnt lgkmcnt(0)
	v_mfma_f32_16x16x32_f16 v[36:39], v[58:61], v[106:109], v[36:39]
	ds_read_b128 v[94:97], v16 offset:34816
	ds_read_b128 v[110:113], v21 offset:2048
	s_waitcnt lgkmcnt(0)
	v_mfma_f32_16x16x32_f16 v[66:69], v[58:61], v[110:113], v[66:69]
	ds_read_b128 v[118:121], v16 offset:36864
	v_mfma_f32_16x16x32_f16 v[44:47], v[94:97], v[106:109], v[44:47]
	ds_read_b128 v[122:125], v16 offset:38912
	v_mfma_f32_16x16x32_f16 v[78:81], v[94:97], v[110:113], v[78:81]
	s_waitcnt vmcnt(7)
	ds_write_b128 v17, v[62:65] offset:16384
	s_waitcnt lgkmcnt(2)
	v_mfma_f32_16x16x32_f16 v[82:85], v[118:121], v[106:109], v[82:85]
	s_waitcnt vmcnt(6)
	ds_write_b128 v18, v[90:93] offset:16384
	v_mfma_f32_16x16x32_f16 v[86:89], v[118:121], v[110:113], v[86:89]
	s_waitcnt vmcnt(5)
	ds_write_b128 v19, v[130:133] offset:16384
	s_waitcnt lgkmcnt(3)
	v_mfma_f32_16x16x32_f16 v[28:31], v[122:125], v[106:109], v[28:31]
	ds_read_b128 v[106:109], v21 offset:4096
	v_mfma_f32_16x16x32_f16 v[32:35], v[122:125], v[110:113], v[32:35]
	ds_read_b128 v[110:113], v21 offset:6144
	s_waitcnt lgkmcnt(1)
	v_mfma_f32_16x16x32_f16 v[98:101], v[58:61], v[106:109], v[98:101]
	s_waitcnt vmcnt(4)
	ds_write_b128 v20, v[138:141] offset:16384
	s_waitcnt lgkmcnt(1)
	v_mfma_f32_16x16x32_f16 v[52:55], v[58:61], v[110:113], v[52:55]
	ds_read_b128 v[58:61], v22 offset:32768
	v_mfma_f32_16x16x32_f16 v[102:105], v[94:97], v[106:109], v[102:105]
	s_waitcnt vmcnt(3)
	ds_write_b128 v17, v[74:77] offset:49152
	v_mfma_f32_16x16x32_f16 v[24:27], v[94:97], v[110:113], v[24:27]
	ds_read_b128 v[94:97], v22 offset:34816
	v_mfma_f32_16x16x32_f16 v[114:117], v[118:121], v[106:109], v[114:117]
	s_waitcnt vmcnt(2)
	ds_write_b128 v18, v[142:145] offset:49152
	v_mfma_f32_16x16x32_f16 v[40:43], v[118:121], v[110:113], v[40:43]
	ds_read_b128 v[118:121], v22 offset:36864
	v_mfma_f32_16x16x32_f16 v[70:73], v[122:125], v[106:109], v[70:73]
	ds_read_b128 v[106:109], v23
	v_mfma_f32_16x16x32_f16 v[48:51], v[122:125], v[110:113], v[48:51]
	ds_read_b128 v[110:113], v23 offset:2048
	s_waitcnt lgkmcnt(1)
	v_mfma_f32_16x16x32_f16 v[36:39], v[58:61], v[106:109], v[36:39]
	ds_read_b128 v[122:125], v22 offset:38912
	s_waitcnt lgkmcnt(1)
	v_mfma_f32_16x16x32_f16 v[66:69], v[58:61], v[110:113], v[66:69]
	s_waitcnt vmcnt(1)
	ds_write_b128 v19, v[154:157] offset:49152
	v_mfma_f32_16x16x32_f16 v[44:47], v[94:97], v[106:109], v[44:47]
	s_waitcnt vmcnt(0)
	ds_write_b128 v20, v[158:161] offset:49152
	v_mfma_f32_16x16x32_f16 v[78:81], v[94:97], v[110:113], v[78:81]
	v_mfma_f32_16x16x32_f16 v[82:85], v[118:121], v[106:109], v[82:85]
	v_mfma_f32_16x16x32_f16 v[86:89], v[118:121], v[110:113], v[86:89]
	s_waitcnt lgkmcnt(2)
	v_mfma_f32_16x16x32_f16 v[28:31], v[122:125], v[106:109], v[28:31]
	ds_read_b128 v[106:109], v23 offset:4096
	v_mfma_f32_16x16x32_f16 v[32:35], v[122:125], v[110:113], v[32:35]
	ds_read_b128 v[110:113], v23 offset:6144
	s_waitcnt lgkmcnt(1)
	v_mfma_f32_16x16x32_f16 v[98:101], v[58:61], v[106:109], v[98:101]
	s_waitcnt lgkmcnt(0)
	v_mfma_f32_16x16x32_f16 v[52:55], v[58:61], v[110:113], v[52:55]
	global_load_dwordx4 v[58:61], v[0:1], off offset:1024
	v_mfma_f32_16x16x32_f16 v[102:105], v[94:97], v[106:109], v[102:105]
	v_mfma_f32_16x16x32_f16 v[24:27], v[94:97], v[110:113], v[24:27]
	v_mfma_f32_16x16x32_f16 v[114:117], v[118:121], v[106:109], v[114:117]
	v_mfma_f32_16x16x32_f16 v[40:43], v[118:121], v[110:113], v[40:43]
	v_mfma_f32_16x16x32_f16 v[70:73], v[122:125], v[106:109], v[70:73]
	global_load_dwordx4 v[106:109], v[2:3], off offset:1024
	global_load_dwordx4 v[126:129], v[4:5], off offset:1024
	global_load_dwordx4 v[134:137], v[14:15], off offset:1024
	global_load_dwordx4 v[94:97], v[10:11], off offset:1024
	global_load_dwordx4 v[162:165], v[12:13], off offset:1024
	global_load_dwordx4 v[166:169], v[8:9], off offset:1024
	global_load_dwordx4 v[190:193], v[6:7], off offset:1024
	s_waitcnt lgkmcnt(0)
	s_barrier
; #define GL_LOAD(s_, kt_) if (VAR != 1) { a##s_##0 = GL_A(0, kt_); a##s_##1 = GL_A(1, kt_); a##s_##2 = GL_A(2, kt_); a##s_##3 = GL_A(3, kt_); b##s_##0 = GL_B(0, kt_); b##s_##1 = GL_B(1, kt_); b##s_##2 = GL_B(2, kt_); b##s_##3 = GL_B(3, kt_); }
; #define LDS_STORE(s_, buf_) if (VAR != 2) { LDS_ST1(sA, 0, buf_, a##s_##0) LDS_ST1(sA, 1, buf_, a##s_##1) LDS_ST1(sA, 2, buf_, a##s_##2) LDS_ST1(sA, 3, buf_, a##s_##3) LDS_ST1(sB, 0, buf_, b##s_##0) LDS_ST1(sB, 1, buf_, b##s_##1) LDS_ST1(sB, 2, buf_, b##s_##2) LDS_ST1(sB, 3, buf_, b##s_##3) }
;     ...
;   GL_LOAD(0, 0)
;   GL_LOAD(1, 1)
;   LDS_STORE(0, 0)
;   if (VAR != 4) __syncthreads();
; #pragma unroll
;   for (int kt = 0; kt < nk; kt += 2) {
;     if (kt + 2 < nk) { GL_LOAD(0, kt + 2) }
;     MMA_TILE(0)
;     LDS_STORE(1, 1)
;     if (VAR != 4) __syncthreads();
;     if (kt + 3 < nk) { GL_LOAD(1, kt + 3) }
;     MMA_TILE(1)
;     if (kt + 2 < nk) { LDS_STORE(0, 0) }
;     if (VAR != 4) __syncthreads();
	v_mfma_f32_16x16x32_f16 v[48:51], v[122:125], v[110:113], v[48:51]
	ds_read_b128 v[62:65], v16 offset:49152
	ds_read_b128 v[90:93], v21 offset:16384
	s_waitcnt lgkmcnt(0)
	v_mfma_f32_16x16x32_f16 v[36:39], v[62:65], v[90:93], v[36:39]
	ds_read_b128 v[74:77], v16 offset:51200
	ds_read_b128 v[110:113], v21 offset:18432
	s_waitcnt lgkmcnt(0)
	v_mfma_f32_16x16x32_f16 v[66:69], v[62:65], v[110:113], v[66:69]
	ds_read_b128 v[118:121], v16 offset:53248
	v_mfma_f32_16x16x32_f16 v[44:47], v[74:77], v[90:93], v[44:47]
	ds_read_b128 v[122:125], v16 offset:55296
	v_mfma_f32_16x16x32_f16 v[78:81], v[74:77], v[110:113], v[78:81]
	s_waitcnt vmcnt(7)
	ds_write_b128 v17, v[58:61]
	s_waitcnt lgkmcnt(2)
	v_mfma_f32_16x16x32_f16 v[82:85], v[118:121], v[90:93], v[82:85]
	s_waitcnt vmcnt(6)
	ds_write_b128 v18, v[106:109]
	v_mfma_f32_16x16x32_f16 v[86:89], v[118:121], v[110:113], v[86:89]
	s_waitcnt vmcnt(5)
	ds_write_b128 v19, v[126:129]
	s_waitcnt lgkmcnt(3)
	v_mfma_f32_16x16x32_f16 v[28:31], v[122:125], v[90:93], v[28:31]
	ds_read_b128 v[90:93], v21 offset:20480
	v_mfma_f32_16x16x32_f16 v[32:35], v[122:125], v[110:113], v[32:35]
	ds_read_b128 v[110:113], v21 offset:22528
	s_waitcnt lgkmcnt(1)
	v_mfma_f32_16x16x32_f16 v[98:101], v[62:65], v[90:93], v[98:101]
	s_waitcnt vmcnt(4)
	ds_write_b128 v20, v[134:137]
	s_waitcnt lgkmcnt(1)
	v_mfma_f32_16x16x32_f16 v[52:55], v[62:65], v[110:113], v[52:55]
	ds_read_b128 v[62:65], v22 offset:49152
	v_mfma_f32_16x16x32_f16 v[102:105], v[74:77], v[90:93], v[102:105]
	s_waitcnt vmcnt(3)
	ds_write_b128 v17, v[94:97] offset:32768
	v_mfma_f32_16x16x32_f16 v[24:27], v[74:77], v[110:113], v[24:27]
	ds_read_b128 v[74:77], v22 offset:51200
	v_mfma_f32_16x16x32_f16 v[114:117], v[118:121], v[90:93], v[114:117]
	s_waitcnt vmcnt(2)
	ds_write_b128 v18, v[162:165] offset:32768
	v_mfma_f32_16x16x32_f16 v[40:43], v[118:121], v[110:113], v[40:43]
	ds_read_b128 v[118:121], v22 offset:53248
	v_mfma_f32_16x16x32_f16 v[70:73], v[122:125], v[90:93], v[70:73]
	ds_read_b128 v[90:93], v23 offset:16384
	v_mfma_f32_16x16x32_f16 v[48:51], v[122:125], v[110:113], v[48:51]
	ds_read_b128 v[110:113], v23 offset:18432
	s_waitcnt lgkmcnt(1)
	v_mfma_f32_16x16x32_f16 v[36:39], v[62:65], v[90:93], v[36:39]
	ds_read_b128 v[122:125], v22 offset:55296
	s_waitcnt lgkmcnt(1)
	v_mfma_f32_16x16x32_f16 v[66:69], v[62:65], v[110:113], v[66:69]
	s_waitcnt vmcnt(1)
	ds_write_b128 v19, v[166:169] offset:32768
	v_mfma_f32_16x16x32_f16 v[44:47], v[74:77], v[90:93], v[44:47]
	s_waitcnt vmcnt(0)
	ds_write_b128 v20, v[190:193] offset:32768
	v_mfma_f32_16x16x32_f16 v[78:81], v[74:77], v[110:113], v[78:81]
	v_mfma_f32_16x16x32_f16 v[82:85], v[118:121], v[90:93], v[82:85]
	v_mfma_f32_16x16x32_f16 v[86:89], v[118:121], v[110:113], v[86:89]
	s_waitcnt lgkmcnt(2)
	v_mfma_f32_16x16x32_f16 v[28:31], v[122:125], v[90:93], v[28:31]
	ds_read_b128 v[90:93], v23 offset:20480
	v_mfma_f32_16x16x32_f16 v[32:35], v[122:125], v[110:113], v[32:35]
	ds_read_b128 v[110:113], v23 offset:22528
	s_waitcnt lgkmcnt(1)
	v_mfma_f32_16x16x32_f16 v[98:101], v[62:65], v[90:93], v[98:101]
	s_waitcnt lgkmcnt(0)
	v_mfma_f32_16x16x32_f16 v[52:55], v[62:65], v[110:113], v[52:55]
	global_load_dwordx4 v[62:65], v[0:1], off offset:1152
	v_mfma_f32_16x16x32_f16 v[102:105], v[74:77], v[90:93], v[102:105]
	v_mfma_f32_16x16x32_f16 v[24:27], v[74:77], v[110:113], v[24:27]
	v_mfma_f32_16x16x32_f16 v[114:117], v[118:121], v[90:93], v[114:117]
	v_mfma_f32_16x16x32_f16 v[40:43], v[118:121], v[110:113], v[40:43]
	v_mfma_f32_16x16x32_f16 v[70:73], v[122:125], v[90:93], v[70:73]
	global_load_dwordx4 v[90:93], v[2:3], off offset:1152
	global_load_dwordx4 v[130:133], v[4:5], off offset:1152
	global_load_dwordx4 v[138:141], v[14:15], off offset:1152
	global_load_dwordx4 v[74:77], v[10:11], off offset:1152
	global_load_dwordx4 v[142:145], v[12:13], off offset:1152
	global_load_dwordx4 v[154:157], v[8:9], off offset:1152
	global_load_dwordx4 v[158:161], v[6:7], off offset:1152
	s_waitcnt lgkmcnt(0)
	s_barrier
	v_mfma_f32_16x16x32_f16 v[48:51], v[122:125], v[110:113], v[48:51]
	ds_read_b128 v[58:61], v16 offset:32768
	ds_read_b128 v[106:109], v21
	s_waitcnt lgkmcnt(0)
	v_mfma_f32_16x16x32_f16 v[36:39], v[58:61], v[106:109], v[36:39]
	ds_read_b128 v[94:97], v16 offset:34816
	ds_read_b128 v[110:113], v21 offset:2048
	s_waitcnt lgkmcnt(0)
	v_mfma_f32_16x16x32_f16 v[66:69], v[58:61], v[110:113], v[66:69]
	ds_read_b128 v[118:121], v16 offset:36864
	v_mfma_f32_16x16x32_f16 v[44:47], v[94:97], v[106:109], v[44:47]
	ds_read_b128 v[122:125], v16 offset:38912
	v_mfma_f32_16x16x32_f16 v[78:81], v[94:97], v[110:113], v[78:81]
	s_waitcnt vmcnt(7)
	ds_write_b128 v17, v[62:65] offset:16384
	s_waitcnt lgkmcnt(2)
	v_mfma_f32_16x16x32_f16 v[82:85], v[118:121], v[106:109], v[82:85]
	s_waitcnt vmcnt(6)
	ds_write_b128 v18, v[90:93] offset:16384
	v_mfma_f32_16x16x32_f16 v[86:89], v[118:121], v[110:113], v[86:89]
	s_waitcnt vmcnt(5)
	ds_write_b128 v19, v[130:133] offset:16384
	s_waitcnt lgkmcnt(3)
	v_mfma_f32_16x16x32_f16 v[28:31], v[122:125], v[106:109], v[28:31]
	ds_read_b128 v[106:109], v21 offset:4096
	v_mfma_f32_16x16x32_f16 v[32:35], v[122:125], v[110:113], v[32:35]
	ds_read_b128 v[110:113], v21 offset:6144
	s_waitcnt lgkmcnt(1)
	v_mfma_f32_16x16x32_f16 v[98:101], v[58:61], v[106:109], v[98:101]
	s_waitcnt vmcnt(4)
	ds_write_b128 v20, v[138:141] offset:16384
	s_waitcnt lgkmcnt(1)
	v_mfma_f32_16x16x32_f16 v[52:55], v[58:61], v[110:113], v[52:55]
	ds_read_b128 v[58:61], v22 offset:32768
	v_mfma_f32_16x16x32_f16 v[102:105], v[94:97], v[106:109], v[102:105]
	s_waitcnt vmcnt(3)
; #define GL_LOAD(s_, kt_) if (VAR != 1) { a##s_##0 = GL_A(0, kt_); a##s_##1 = GL_A(1, kt_); a##s_##2 = GL_A(2, kt_); a##s_##3 = GL_A(3, kt_); b##s_##0 = GL_B(0, kt_); b##s_##1 = GL_B(1, kt_); b##s_##2 = GL_B(2, kt_); b##s_##3 = GL_B(3, kt_); }
; #define LDS_STORE(s_, buf_) if (VAR != 2) { LDS_ST1(sA, 0, buf_, a##s_##0) LDS_ST1(sA, 1, buf_, a##s_##1) LDS_ST1(sA, 2, buf_, a##s_##2) LDS_ST1(sA, 3, buf_, a##s_##3) LDS_ST1(sB, 0, buf_, b##s_##0) LDS_ST1(sB, 1, buf_, b##s_##1) LDS_ST1(sB, 2, buf_, b##s_##2) LDS_ST1(sB, 3, buf_, b##s_##3) }
;     ...
;   GL_LOAD(0, 0)
;   GL_LOAD(1, 1)
;   LDS_STORE(0, 0)
;   if (VAR != 4) __syncthreads();
; #pragma unroll
;   for (int kt = 0; kt < nk; kt += 2) {
;     if (kt + 2 < nk) { GL_LOAD(0, kt + 2) }
;     MMA_TILE(0)
;     LDS_STORE(1, 1)
;     if (VAR != 4) __syncthreads();
;     if (kt + 3 < nk) { GL_LOAD(1, kt + 3) }
;     MMA_TILE(1)
;     if (kt + 2 < nk) { LDS_STORE(0, 0) }
;     if (VAR != 4) __syncthreads();
	ds_write_b128 v17, v[74:77] offset:49152
	v_mfma_f32_16x16x32_f16 v[24:27], v[94:97], v[110:113], v[24:27]
	ds_read_b128 v[94:97], v22 offset:34816
	v_mfma_f32_16x16x32_f16 v[114:117], v[118:121], v[106:109], v[114:117]
	s_waitcnt vmcnt(2)
	ds_write_b128 v18, v[142:145] offset:49152
	v_mfma_f32_16x16x32_f16 v[40:43], v[118:121], v[110:113], v[40:43]
	ds_read_b128 v[118:121], v22 offset:36864
	v_mfma_f32_16x16x32_f16 v[70:73], v[122:125], v[106:109], v[70:73]
	ds_read_b128 v[106:109], v23
	v_mfma_f32_16x16x32_f16 v[48:51], v[122:125], v[110:113], v[48:51]
	ds_read_b128 v[110:113], v23 offset:2048
	s_waitcnt lgkmcnt(1)
	v_mfma_f32_16x16x32_f16 v[36:39], v[58:61], v[106:109], v[36:39]
	ds_read_b128 v[122:125], v22 offset:38912
	s_waitcnt lgkmcnt(1)
	v_mfma_f32_16x16x32_f16 v[66:69], v[58:61], v[110:113], v[66:69]
	s_waitcnt vmcnt(1)
	ds_write_b128 v19, v[154:157] offset:49152
	v_mfma_f32_16x16x32_f16 v[44:47], v[94:97], v[106:109], v[44:47]
	s_waitcnt vmcnt(0)
	ds_write_b128 v20, v[158:161] offset:49152
	v_mfma_f32_16x16x32_f16 v[78:81], v[94:97], v[110:113], v[78:81]
	v_mfma_f32_16x16x32_f16 v[82:85], v[118:121], v[106:109], v[82:85]
	v_mfma_f32_16x16x32_f16 v[86:89], v[118:121], v[110:113], v[86:89]
	s_waitcnt lgkmcnt(2)
	v_mfma_f32_16x16x32_f16 v[28:31], v[122:125], v[106:109], v[28:31]
	ds_read_b128 v[106:109], v23 offset:4096
	v_mfma_f32_16x16x32_f16 v[32:35], v[122:125], v[110:113], v[32:35]
	ds_read_b128 v[110:113], v23 offset:6144
	s_waitcnt lgkmcnt(1)
	v_mfma_f32_16x16x32_f16 v[98:101], v[58:61], v[106:109], v[98:101]
	s_waitcnt lgkmcnt(0)
	v_mfma_f32_16x16x32_f16 v[52:55], v[58:61], v[110:113], v[52:55]
	global_load_dwordx4 v[58:61], v[0:1], off offset:1280
	v_mfma_f32_16x16x32_f16 v[102:105], v[94:97], v[106:109], v[102:105]
	v_mfma_f32_16x16x32_f16 v[24:27], v[94:97], v[110:113], v[24:27]
	v_mfma_f32_16x16x32_f16 v[114:117], v[118:121], v[106:109], v[114:117]
	v_mfma_f32_16x16x32_f16 v[40:43], v[118:121], v[110:113], v[40:43]
	v_mfma_f32_16x16x32_f16 v[70:73], v[122:125], v[106:109], v[70:73]
	global_load_dwordx4 v[106:109], v[2:3], off offset:1280
	global_load_dwordx4 v[126:129], v[4:5], off offset:1280
	global_load_dwordx4 v[134:137], v[14:15], off offset:1280
	global_load_dwordx4 v[94:97], v[10:11], off offset:1280
	global_load_dwordx4 v[162:165], v[12:13], off offset:1280
	global_load_dwordx4 v[166:169], v[8:9], off offset:1280
	global_load_dwordx4 v[190:193], v[6:7], off offset:1280
	s_waitcnt lgkmcnt(0)
	s_barrier
	v_mfma_f32_16x16x32_f16 v[48:51], v[122:125], v[110:113], v[48:51]
	ds_read_b128 v[62:65], v16 offset:49152
	ds_read_b128 v[90:93], v21 offset:16384
	s_waitcnt lgkmcnt(0)
	v_mfma_f32_16x16x32_f16 v[36:39], v[62:65], v[90:93], v[36:39]
	ds_read_b128 v[74:77], v16 offset:51200
	ds_read_b128 v[110:113], v21 offset:18432
	s_waitcnt lgkmcnt(0)
	v_mfma_f32_16x16x32_f16 v[66:69], v[62:65], v[110:113], v[66:69]
	ds_read_b128 v[118:121], v16 offset:53248
	v_mfma_f32_16x16x32_f16 v[44:47], v[74:77], v[90:93], v[44:47]
	ds_read_b128 v[122:125], v16 offset:55296
	v_mfma_f32_16x16x32_f16 v[78:81], v[74:77], v[110:113], v[78:81]
	s_waitcnt vmcnt(7)
	ds_write_b128 v17, v[58:61]
	s_waitcnt lgkmcnt(2)
	v_mfma_f32_16x16x32_f16 v[82:85], v[118:121], v[90:93], v[82:85]
	s_waitcnt vmcnt(6)
	ds_write_b128 v18, v[106:109]
	v_mfma_f32_16x16x32_f16 v[86:89], v[118:121], v[110:113], v[86:89]
	s_waitcnt vmcnt(5)
	ds_write_b128 v19, v[126:129]
	s_waitcnt lgkmcnt(3)
	v_mfma_f32_16x16x32_f16 v[28:31], v[122:125], v[90:93], v[28:31]
	ds_read_b128 v[90:93], v21 offset:20480
	v_mfma_f32_16x16x32_f16 v[32:35], v[122:125], v[110:113], v[32:35]
	ds_read_b128 v[110:113], v21 offset:22528
	s_waitcnt lgkmcnt(1)
	v_mfma_f32_16x16x32_f16 v[98:101], v[62:65], v[90:93], v[98:101]
	s_waitcnt vmcnt(4)
	ds_write_b128 v20, v[134:137]
	s_waitcnt lgkmcnt(1)
	v_mfma_f32_16x16x32_f16 v[52:55], v[62:65], v[110:113], v[52:55]
	ds_read_b128 v[62:65], v22 offset:49152
	v_mfma_f32_16x16x32_f16 v[102:105], v[74:77], v[90:93], v[102:105]
	s_waitcnt vmcnt(3)
	ds_write_b128 v17, v[94:97] offset:32768
	v_mfma_f32_16x16x32_f16 v[24:27], v[74:77], v[110:113], v[24:27]
	ds_read_b128 v[74:77], v22 offset:51200
	v_mfma_f32_16x16x32_f16 v[114:117], v[118:121], v[90:93], v[114:117]
	s_waitcnt vmcnt(2)
	ds_write_b128 v18, v[162:165] offset:32768
	v_mfma_f32_16x16x32_f16 v[40:43], v[118:121], v[110:113], v[40:43]
	ds_read_b128 v[118:121], v22 offset:53248
	v_mfma_f32_16x16x32_f16 v[70:73], v[122:125], v[90:93], v[70:73]
	ds_read_b128 v[90:93], v23 offset:16384
	v_mfma_f32_16x16x32_f16 v[48:51], v[122:125], v[110:113], v[48:51]
	ds_read_b128 v[110:113], v23 offset:18432
	s_waitcnt lgkmcnt(1)
	v_mfma_f32_16x16x32_f16 v[36:39], v[62:65], v[90:93], v[36:39]
	ds_read_b128 v[122:125], v22 offset:55296
	s_waitcnt lgkmcnt(1)
	v_mfma_f32_16x16x32_f16 v[66:69], v[62:65], v[110:113], v[66:69]
	s_waitcnt vmcnt(1)
	ds_write_b128 v19, v[166:169] offset:32768
	v_mfma_f32_16x16x32_f16 v[44:47], v[74:77], v[90:93], v[44:47]
	s_waitcnt vmcnt(0)
	ds_write_b128 v20, v[190:193] offset:32768
	v_mfma_f32_16x16x32_f16 v[78:81], v[74:77], v[110:113], v[78:81]
	v_mfma_f32_16x16x32_f16 v[82:85], v[118:121], v[90:93], v[82:85]
	v_mfma_f32_16x16x32_f16 v[86:89], v[118:121], v[110:113], v[86:89]
	s_waitcnt lgkmcnt(2)
	v_mfma_f32_16x16x32_f16 v[28:31], v[122:125], v[90:93], v[28:31]
	ds_read_b128 v[90:93], v23 offset:20480
	v_mfma_f32_16x16x32_f16 v[32:35], v[122:125], v[110:113], v[32:35]
	ds_read_b128 v[110:113], v23 offset:22528
	s_waitcnt lgkmcnt(1)
	v_mfma_f32_16x16x32_f16 v[98:101], v[62:65], v[90:93], v[98:101]
	s_waitcnt lgkmcnt(0)
	v_mfma_f32_16x16x32_f16 v[52:55], v[62:65], v[110:113], v[52:55]
	global_load_dwordx4 v[62:65], v[0:1], off offset:1408
	v_mfma_f32_16x16x32_f16 v[102:105], v[74:77], v[90:93], v[102:105]
	v_mfma_f32_16x16x32_f16 v[24:27], v[74:77], v[110:113], v[24:27]
	v_mfma_f32_16x16x32_f16 v[114:117], v[118:121], v[90:93], v[114:117]
	v_mfma_f32_16x16x32_f16 v[40:43], v[118:121], v[110:113], v[40:43]
	v_mfma_f32_16x16x32_f16 v[70:73], v[122:125], v[90:93], v[70:73]
	global_load_dwordx4 v[90:93], v[2:3], off offset:1408
	global_load_dwordx4 v[130:133], v[4:5], off offset:1408
	global_load_dwordx4 v[138:141], v[14:15], off offset:1408
	global_load_dwordx4 v[74:77], v[10:11], off offset:1408
	global_load_dwordx4 v[142:145], v[12:13], off offset:1408
	global_load_dwordx4 v[154:157], v[8:9], off offset:1408
	global_load_dwordx4 v[158:161], v[6:7], off offset:1408
	s_waitcnt lgkmcnt(0)
	s_barrier
; #define GL_LOAD(s_, kt_) if (VAR != 1) { a##s_##0 = GL_A(0, kt_); a##s_##1 = GL_A(1, kt_); a##s_##2 = GL_A(2, kt_); a##s_##3 = GL_A(3, kt_); b##s_##0 = GL_B(0, kt_); b##s_##1 = GL_B(1, kt_); b##s_##2 = GL_B(2, kt_); b##s_##3 = GL_B(3, kt_); }
; #define LDS_STORE(s_, buf_) if (VAR != 2) { LDS_ST1(sA, 0, buf_, a##s_##0) LDS_ST1(sA, 1, buf_, a##s_##1) LDS_ST1(sA, 2, buf_, a##s_##2) LDS_ST1(sA, 3, buf_, a##s_##3) LDS_ST1(sB, 0, buf_, b##s_##0) LDS_ST1(sB, 1, buf_, b##s_##1) LDS_ST1(sB, 2, buf_, b##s_##2) LDS_ST1(sB, 3, buf_, b##s_##3) }
;     ...
;   GL_LOAD(0, 0)
;   GL_LOAD(1, 1)
;   LDS_STORE(0, 0)
;   if (VAR != 4) __syncthreads();
; #pragma unroll
;   for (int kt = 0; kt < nk; kt += 2) {
;     if (kt + 2 < nk) { GL_LOAD(0, kt + 2) }
;     MMA_TILE(0)
;     LDS_STORE(1, 1)
;     if (VAR != 4) __syncthreads();
;     if (kt + 3 < nk) { GL_LOAD(1, kt + 3) }
;     MMA_TILE(1)
;     if (kt + 2 < nk) { LDS_STORE(0, 0) }
;     if (VAR != 4) __syncthreads();
	v_mfma_f32_16x16x32_f16 v[48:51], v[122:125], v[110:113], v[48:51]
	ds_read_b128 v[58:61], v16 offset:32768
	ds_read_b128 v[106:109], v21
	s_waitcnt lgkmcnt(0)
	v_mfma_f32_16x16x32_f16 v[36:39], v[58:61], v[106:109], v[36:39]
	ds_read_b128 v[94:97], v16 offset:34816
	ds_read_b128 v[110:113], v21 offset:2048
	s_waitcnt lgkmcnt(0)
	v_mfma_f32_16x16x32_f16 v[66:69], v[58:61], v[110:113], v[66:69]
	ds_read_b128 v[118:121], v16 offset:36864
	v_mfma_f32_16x16x32_f16 v[44:47], v[94:97], v[106:109], v[44:47]
	ds_read_b128 v[122:125], v16 offset:38912
	v_mfma_f32_16x16x32_f16 v[78:81], v[94:97], v[110:113], v[78:81]
	s_waitcnt vmcnt(7)
	ds_write_b128 v17, v[62:65] offset:16384
	s_waitcnt lgkmcnt(2)
	v_mfma_f32_16x16x32_f16 v[82:85], v[118:121], v[106:109], v[82:85]
	s_waitcnt vmcnt(6)
	ds_write_b128 v18, v[90:93] offset:16384
	v_mfma_f32_16x16x32_f16 v[86:89], v[118:121], v[110:113], v[86:89]
	s_waitcnt vmcnt(5)
	ds_write_b128 v19, v[130:133] offset:16384
	s_waitcnt lgkmcnt(3)
	v_mfma_f32_16x16x32_f16 v[28:31], v[122:125], v[106:109], v[28:31]
	ds_read_b128 v[106:109], v21 offset:4096
	v_mfma_f32_16x16x32_f16 v[32:35], v[122:125], v[110:113], v[32:35]
	ds_read_b128 v[110:113], v21 offset:6144
	s_waitcnt lgkmcnt(1)
	v_mfma_f32_16x16x32_f16 v[98:101], v[58:61], v[106:109], v[98:101]
	s_waitcnt vmcnt(4)
	ds_write_b128 v20, v[138:141] offset:16384
	s_waitcnt lgkmcnt(1)
	v_mfma_f32_16x16x32_f16 v[52:55], v[58:61], v[110:113], v[52:55]
	ds_read_b128 v[58:61], v22 offset:32768
	v_mfma_f32_16x16x32_f16 v[102:105], v[94:97], v[106:109], v[102:105]
	s_waitcnt vmcnt(3)
	ds_write_b128 v17, v[74:77] offset:49152
	v_mfma_f32_16x16x32_f16 v[24:27], v[94:97], v[110:113], v[24:27]
	ds_read_b128 v[94:97], v22 offset:34816
	v_mfma_f32_16x16x32_f16 v[114:117], v[118:121], v[106:109], v[114:117]
	s_waitcnt vmcnt(2)
	ds_write_b128 v18, v[142:145] offset:49152
	v_mfma_f32_16x16x32_f16 v[40:43], v[118:121], v[110:113], v[40:43]
	ds_read_b128 v[118:121], v22 offset:36864
	v_mfma_f32_16x16x32_f16 v[70:73], v[122:125], v[106:109], v[70:73]
	ds_read_b128 v[106:109], v23
	v_mfma_f32_16x16x32_f16 v[48:51], v[122:125], v[110:113], v[48:51]
	ds_read_b128 v[110:113], v23 offset:2048
	s_waitcnt lgkmcnt(1)
	v_mfma_f32_16x16x32_f16 v[36:39], v[58:61], v[106:109], v[36:39]
	ds_read_b128 v[122:125], v22 offset:38912
	s_waitcnt lgkmcnt(1)
	v_mfma_f32_16x16x32_f16 v[66:69], v[58:61], v[110:113], v[66:69]
	s_waitcnt vmcnt(1)
	ds_write_b128 v19, v[154:157] offset:49152
	v_mfma_f32_16x16x32_f16 v[44:47], v[94:97], v[106:109], v[44:47]
	s_waitcnt vmcnt(0)
	ds_write_b128 v20, v[158:161] offset:49152
	v_mfma_f32_16x16x32_f16 v[78:81], v[94:97], v[110:113], v[78:81]
	v_mfma_f32_16x16x32_f16 v[82:85], v[118:121], v[106:109], v[82:85]
	v_mfma_f32_16x16x32_f16 v[86:89], v[118:121], v[110:113], v[86:89]
	s_waitcnt lgkmcnt(2)
	v_mfma_f32_16x16x32_f16 v[28:31], v[122:125], v[106:109], v[28:31]
	ds_read_b128 v[106:109], v23 offset:4096
	v_mfma_f32_16x16x32_f16 v[32:35], v[122:125], v[110:113], v[32:35]
	ds_read_b128 v[110:113], v23 offset:6144
	s_waitcnt lgkmcnt(1)
	v_mfma_f32_16x16x32_f16 v[98:101], v[58:61], v[106:109], v[98:101]
	s_waitcnt lgkmcnt(0)
	v_mfma_f32_16x16x32_f16 v[52:55], v[58:61], v[110:113], v[52:55]
	global_load_dwordx4 v[58:61], v[0:1], off offset:1536
	v_mfma_f32_16x16x32_f16 v[102:105], v[94:97], v[106:109], v[102:105]
	v_mfma_f32_16x16x32_f16 v[24:27], v[94:97], v[110:113], v[24:27]
	v_mfma_f32_16x16x32_f16 v[114:117], v[118:121], v[106:109], v[114:117]
	v_mfma_f32_16x16x32_f16 v[40:43], v[118:121], v[110:113], v[40:43]
	v_mfma_f32_16x16x32_f16 v[70:73], v[122:125], v[106:109], v[70:73]
	global_load_dwordx4 v[106:109], v[2:3], off offset:1536
	global_load_dwordx4 v[126:129], v[4:5], off offset:1536
	global_load_dwordx4 v[134:137], v[14:15], off offset:1536
	global_load_dwordx4 v[94:97], v[10:11], off offset:1536
	global_load_dwordx4 v[162:165], v[12:13], off offset:1536
	global_load_dwordx4 v[166:169], v[8:9], off offset:1536
	global_load_dwordx4 v[190:193], v[6:7], off offset:1536
	s_waitcnt lgkmcnt(0)
	s_barrier
	v_mfma_f32_16x16x32_f16 v[48:51], v[122:125], v[110:113], v[48:51]
	ds_read_b128 v[62:65], v16 offset:49152
	ds_read_b128 v[90:93], v21 offset:16384
	s_waitcnt lgkmcnt(0)
	v_mfma_f32_16x16x32_f16 v[36:39], v[62:65], v[90:93], v[36:39]
	ds_read_b128 v[74:77], v16 offset:51200
	ds_read_b128 v[110:113], v21 offset:18432
	s_waitcnt lgkmcnt(0)
	v_mfma_f32_16x16x32_f16 v[66:69], v[62:65], v[110:113], v[66:69]
	ds_read_b128 v[118:121], v16 offset:53248
	v_mfma_f32_16x16x32_f16 v[44:47], v[74:77], v[90:93], v[44:47]
	ds_read_b128 v[122:125], v16 offset:55296
	v_mfma_f32_16x16x32_f16 v[78:81], v[74:77], v[110:113], v[78:81]
	s_waitcnt vmcnt(7)
	ds_write_b128 v17, v[58:61]
	s_waitcnt lgkmcnt(2)
	v_mfma_f32_16x16x32_f16 v[82:85], v[118:121], v[90:93], v[82:85]
	s_waitcnt vmcnt(6)
	ds_write_b128 v18, v[106:109]
	v_mfma_f32_16x16x32_f16 v[86:89], v[118:121], v[110:113], v[86:89]
	s_waitcnt vmcnt(5)
	ds_write_b128 v19, v[126:129]
	s_waitcnt lgkmcnt(3)
	v_mfma_f32_16x16x32_f16 v[28:31], v[122:125], v[90:93], v[28:31]
	ds_read_b128 v[90:93], v21 offset:20480
	v_mfma_f32_16x16x32_f16 v[32:35], v[122:125], v[110:113], v[32:35]
	ds_read_b128 v[110:113], v21 offset:22528
	s_waitcnt lgkmcnt(1)
	v_mfma_f32_16x16x32_f16 v[98:101], v[62:65], v[90:93], v[98:101]
	s_waitcnt vmcnt(4)
	ds_write_b128 v20, v[134:137]
	s_waitcnt lgkmcnt(1)
	v_mfma_f32_16x16x32_f16 v[52:55], v[62:65], v[110:113], v[52:55]
	ds_read_b128 v[62:65], v22 offset:49152
	v_mfma_f32_16x16x32_f16 v[102:105], v[74:77], v[90:93], v[102:105]
	s_waitcnt vmcnt(3)
; #define GL_LOAD(s_, kt_) if (VAR != 1) { a##s_##0 = GL_A(0, kt_); a##s_##1 = GL_A(1, kt_); a##s_##2 = GL_A(2, kt_); a##s_##3 = GL_A(3, kt_); b##s_##0 = GL_B(0, kt_); b##s_##1 = GL_B(1, kt_); b##s_##2 = GL_B(2, kt_); b##s_##3 = GL_B(3, kt_); }
; #define LDS_STORE(s_, buf_) if (VAR != 2) { LDS_ST1(sA, 0, buf_, a##s_##0) LDS_ST1(sA, 1, buf_, a##s_##1) LDS_ST1(sA, 2, buf_, a##s_##2) LDS_ST1(sA, 3, buf_, a##s_##3) LDS_ST1(sB, 0, buf_, b##s_##0) LDS_ST1(sB, 1, buf_, b##s_##1) LDS_ST1(sB, 2, buf_, b##s_##2) LDS_ST1(sB, 3, buf_, b##s_##3) }
;     ...
;   GL_LOAD(0, 0)
;   GL_LOAD(1, 1)
;   LDS_STORE(0, 0)
;   if (VAR != 4) __syncthreads();
; #pragma unroll
;   for (int kt = 0; kt < nk; kt += 2) {
;     if (kt + 2 < nk) { GL_LOAD(0, kt + 2) }
;     MMA_TILE(0)
;     LDS_STORE(1, 1)
;     if (VAR != 4) __syncthreads();
;     if (kt + 3 < nk) { GL_LOAD(1, kt + 3) }
;     MMA_TILE(1)
;     if (kt + 2 < nk) { LDS_STORE(0, 0) }
;     if (VAR != 4) __syncthreads();
	ds_write_b128 v17, v[94:97] offset:32768
	v_mfma_f32_16x16x32_f16 v[24:27], v[74:77], v[110:113], v[24:27]
	ds_read_b128 v[74:77], v22 offset:51200
	v_mfma_f32_16x16x32_f16 v[114:117], v[118:121], v[90:93], v[114:117]
	s_waitcnt vmcnt(2)
	ds_write_b128 v18, v[162:165] offset:32768
	v_mfma_f32_16x16x32_f16 v[40:43], v[118:121], v[110:113], v[40:43]
	ds_read_b128 v[118:121], v22 offset:53248
	v_mfma_f32_16x16x32_f16 v[70:73], v[122:125], v[90:93], v[70:73]
	ds_read_b128 v[90:93], v23 offset:16384
	v_mfma_f32_16x16x32_f16 v[48:51], v[122:125], v[110:113], v[48:51]
	ds_read_b128 v[110:113], v23 offset:18432
	s_waitcnt lgkmcnt(1)
	v_mfma_f32_16x16x32_f16 v[36:39], v[62:65], v[90:93], v[36:39]
	ds_read_b128 v[122:125], v22 offset:55296
	s_waitcnt lgkmcnt(1)
	v_mfma_f32_16x16x32_f16 v[66:69], v[62:65], v[110:113], v[66:69]
	s_waitcnt vmcnt(1)
	ds_write_b128 v19, v[166:169] offset:32768
	v_mfma_f32_16x16x32_f16 v[44:47], v[74:77], v[90:93], v[44:47]
	s_waitcnt vmcnt(0)
	ds_write_b128 v20, v[190:193] offset:32768
	v_mfma_f32_16x16x32_f16 v[78:81], v[74:77], v[110:113], v[78:81]
	v_mfma_f32_16x16x32_f16 v[82:85], v[118:121], v[90:93], v[82:85]
	v_mfma_f32_16x16x32_f16 v[86:89], v[118:121], v[110:113], v[86:89]
	s_waitcnt lgkmcnt(2)
	v_mfma_f32_16x16x32_f16 v[28:31], v[122:125], v[90:93], v[28:31]
	ds_read_b128 v[90:93], v23 offset:20480
	v_mfma_f32_16x16x32_f16 v[32:35], v[122:125], v[110:113], v[32:35]
	ds_read_b128 v[110:113], v23 offset:22528
	s_waitcnt lgkmcnt(1)
	v_mfma_f32_16x16x32_f16 v[98:101], v[62:65], v[90:93], v[98:101]
	s_waitcnt lgkmcnt(0)
	v_mfma_f32_16x16x32_f16 v[52:55], v[62:65], v[110:113], v[52:55]
	global_load_dwordx4 v[62:65], v[0:1], off offset:1664
	v_mfma_f32_16x16x32_f16 v[102:105], v[74:77], v[90:93], v[102:105]
	v_mfma_f32_16x16x32_f16 v[24:27], v[74:77], v[110:113], v[24:27]
	v_mfma_f32_16x16x32_f16 v[114:117], v[118:121], v[90:93], v[114:117]
	v_mfma_f32_16x16x32_f16 v[40:43], v[118:121], v[110:113], v[40:43]
	v_mfma_f32_16x16x32_f16 v[70:73], v[122:125], v[90:93], v[70:73]
	global_load_dwordx4 v[90:93], v[2:3], off offset:1664
	global_load_dwordx4 v[130:133], v[4:5], off offset:1664
	global_load_dwordx4 v[138:141], v[14:15], off offset:1664
	global_load_dwordx4 v[74:77], v[10:11], off offset:1664
	global_load_dwordx4 v[142:145], v[12:13], off offset:1664
	global_load_dwordx4 v[154:157], v[8:9], off offset:1664
	global_load_dwordx4 v[158:161], v[6:7], off offset:1664
	s_waitcnt lgkmcnt(0)
	s_barrier
	v_mfma_f32_16x16x32_f16 v[48:51], v[122:125], v[110:113], v[48:51]
	ds_read_b128 v[58:61], v16 offset:32768
	ds_read_b128 v[106:109], v21
	s_waitcnt lgkmcnt(0)
	v_mfma_f32_16x16x32_f16 v[36:39], v[58:61], v[106:109], v[36:39]
	ds_read_b128 v[94:97], v16 offset:34816
	ds_read_b128 v[110:113], v21 offset:2048
	s_waitcnt lgkmcnt(0)
	v_mfma_f32_16x16x32_f16 v[66:69], v[58:61], v[110:113], v[66:69]
	ds_read_b128 v[118:121], v16 offset:36864
	v_mfma_f32_16x16x32_f16 v[44:47], v[94:97], v[106:109], v[44:47]
	ds_read_b128 v[122:125], v16 offset:38912
	v_mfma_f32_16x16x32_f16 v[78:81], v[94:97], v[110:113], v[78:81]
	s_waitcnt vmcnt(7)
	ds_write_b128 v17, v[62:65] offset:16384
	s_waitcnt lgkmcnt(2)
	v_mfma_f32_16x16x32_f16 v[82:85], v[118:121], v[106:109], v[82:85]
	s_waitcnt vmcnt(6)
	ds_write_b128 v18, v[90:93] offset:16384
	v_mfma_f32_16x16x32_f16 v[86:89], v[118:121], v[110:113], v[86:89]
	s_waitcnt vmcnt(5)
	ds_write_b128 v19, v[130:133] offset:16384
	s_waitcnt lgkmcnt(3)
	v_mfma_f32_16x16x32_f16 v[28:31], v[122:125], v[106:109], v[28:31]
	ds_read_b128 v[106:109], v21 offset:4096
	v_mfma_f32_16x16x32_f16 v[32:35], v[122:125], v[110:113], v[32:35]
	ds_read_b128 v[110:113], v21 offset:6144
	s_waitcnt lgkmcnt(1)
	v_mfma_f32_16x16x32_f16 v[98:101], v[58:61], v[106:109], v[98:101]
	s_waitcnt vmcnt(4)
	ds_write_b128 v20, v[138:141] offset:16384
	s_waitcnt lgkmcnt(1)
	v_mfma_f32_16x16x32_f16 v[52:55], v[58:61], v[110:113], v[52:55]
	ds_read_b128 v[58:61], v22 offset:32768
	v_mfma_f32_16x16x32_f16 v[102:105], v[94:97], v[106:109], v[102:105]
	s_waitcnt vmcnt(3)
	ds_write_b128 v17, v[74:77] offset:49152
	v_mfma_f32_16x16x32_f16 v[24:27], v[94:97], v[110:113], v[24:27]
	ds_read_b128 v[94:97], v22 offset:34816
	v_mfma_f32_16x16x32_f16 v[114:117], v[118:121], v[106:109], v[114:117]
	s_waitcnt vmcnt(2)
	ds_write_b128 v18, v[142:145] offset:49152
	v_mfma_f32_16x16x32_f16 v[40:43], v[118:121], v[110:113], v[40:43]
	ds_read_b128 v[118:121], v22 offset:36864
	v_mfma_f32_16x16x32_f16 v[70:73], v[122:125], v[106:109], v[70:73]
	ds_read_b128 v[106:109], v23
	v_mfma_f32_16x16x32_f16 v[48:51], v[122:125], v[110:113], v[48:51]
	ds_read_b128 v[110:113], v23 offset:2048
	s_waitcnt lgkmcnt(1)
	v_mfma_f32_16x16x32_f16 v[36:39], v[58:61], v[106:109], v[36:39]
	ds_read_b128 v[122:125], v22 offset:38912
	s_waitcnt lgkmcnt(1)
	v_mfma_f32_16x16x32_f16 v[66:69], v[58:61], v[110:113], v[66:69]
	s_waitcnt vmcnt(1)
	ds_write_b128 v19, v[154:157] offset:49152
	v_mfma_f32_16x16x32_f16 v[44:47], v[94:97], v[106:109], v[44:47]
	s_waitcnt vmcnt(0)
	ds_write_b128 v20, v[158:161] offset:49152
	v_mfma_f32_16x16x32_f16 v[78:81], v[94:97], v[110:113], v[78:81]
	v_mfma_f32_16x16x32_f16 v[82:85], v[118:121], v[106:109], v[82:85]
	v_mfma_f32_16x16x32_f16 v[86:89], v[118:121], v[110:113], v[86:89]
	s_waitcnt lgkmcnt(2)
	v_mfma_f32_16x16x32_f16 v[28:31], v[122:125], v[106:109], v[28:31]
	ds_read_b128 v[106:109], v23 offset:4096
	v_mfma_f32_16x16x32_f16 v[32:35], v[122:125], v[110:113], v[32:35]
	ds_read_b128 v[110:113], v23 offset:6144
	s_waitcnt lgkmcnt(1)
	v_mfma_f32_16x16x32_f16 v[98:101], v[58:61], v[106:109], v[98:101]
	s_waitcnt lgkmcnt(0)
	v_mfma_f32_16x16x32_f16 v[52:55], v[58:61], v[110:113], v[52:55]
	global_load_dwordx4 v[58:61], v[0:1], off offset:1792
	v_mfma_f32_16x16x32_f16 v[102:105], v[94:97], v[106:109], v[102:105]
	v_mfma_f32_16x16x32_f16 v[24:27], v[94:97], v[110:113], v[24:27]
	v_mfma_f32_16x16x32_f16 v[114:117], v[118:121], v[106:109], v[114:117]
	v_mfma_f32_16x16x32_f16 v[40:43], v[118:121], v[110:113], v[40:43]
	v_mfma_f32_16x16x32_f16 v[70:73], v[122:125], v[106:109], v[70:73]
	global_load_dwordx4 v[106:109], v[2:3], off offset:1792
	global_load_dwordx4 v[126:129], v[4:5], off offset:1792
	global_load_dwordx4 v[134:137], v[14:15], off offset:1792
	global_load_dwordx4 v[94:97], v[10:11], off offset:1792
	global_load_dwordx4 v[162:165], v[12:13], off offset:1792
	global_load_dwordx4 v[166:169], v[8:9], off offset:1792
	global_load_dwordx4 v[190:193], v[6:7], off offset:1792
	s_waitcnt lgkmcnt(0)
	s_barrier
; #define GL_LOAD(s_, kt_) if (VAR != 1) { a##s_##0 = GL_A(0, kt_); a##s_##1 = GL_A(1, kt_); a##s_##2 = GL_A(2, kt_); a##s_##3 = GL_A(3, kt_); b##s_##0 = GL_B(0, kt_); b##s_##1 = GL_B(1, kt_); b##s_##2 = GL_B(2, kt_); b##s_##3 = GL_B(3, kt_); }
; #define LDS_STORE(s_, buf_) if (VAR != 2) { LDS_ST1(sA, 0, buf_, a##s_##0) LDS_ST1(sA, 1, buf_, a##s_##1) LDS_ST1(sA, 2, buf_, a##s_##2) LDS_ST1(sA, 3, buf_, a##s_##3) LDS_ST1(sB, 0, buf_, b##s_##0) LDS_ST1(sB, 1, buf_, b##s_##1) LDS_ST1(sB, 2, buf_, b##s_##2) LDS_ST1(sB, 3, buf_, b##s_##3) }
;     ...
;   GL_LOAD(0, 0)
;   GL_LOAD(1, 1)
;   LDS_STORE(0, 0)
;   if (VAR != 4) __syncthreads();
; #pragma unroll
;   for (int kt = 0; kt < nk; kt += 2) {
;     if (kt + 2 < nk) { GL_LOAD(0, kt + 2) }
;     MMA_TILE(0)
;     LDS_STORE(1, 1)
;     if (VAR != 4) __syncthreads();
;     if (kt + 3 < nk) { GL_LOAD(1, kt + 3) }
;     MMA_TILE(1)
;     if (kt + 2 < nk) { LDS_STORE(0, 0) }
;     if (VAR != 4) __syncthreads();
	v_mfma_f32_16x16x32_f16 v[48:51], v[122:125], v[110:113], v[48:51]
	ds_read_b128 v[62:65], v16 offset:49152
	ds_read_b128 v[90:93], v21 offset:16384
	s_waitcnt lgkmcnt(0)
	v_mfma_f32_16x16x32_f16 v[36:39], v[62:65], v[90:93], v[36:39]
	ds_read_b128 v[74:77], v16 offset:51200
	ds_read_b128 v[110:113], v21 offset:18432
	s_waitcnt lgkmcnt(0)
	v_mfma_f32_16x16x32_f16 v[66:69], v[62:65], v[110:113], v[66:69]
	ds_read_b128 v[118:121], v16 offset:53248
	v_mfma_f32_16x16x32_f16 v[44:47], v[74:77], v[90:93], v[44:47]
	ds_read_b128 v[122:125], v16 offset:55296
	v_mfma_f32_16x16x32_f16 v[78:81], v[74:77], v[110:113], v[78:81]
	s_waitcnt vmcnt(7)
	ds_write_b128 v17, v[58:61]
	s_waitcnt lgkmcnt(2)
	v_mfma_f32_16x16x32_f16 v[82:85], v[118:121], v[90:93], v[82:85]
	s_waitcnt vmcnt(6)
	ds_write_b128 v18, v[106:109]
	v_mfma_f32_16x16x32_f16 v[86:89], v[118:121], v[110:113], v[86:89]
	s_waitcnt vmcnt(5)
	ds_write_b128 v19, v[126:129]
	s_waitcnt lgkmcnt(3)
	v_mfma_f32_16x16x32_f16 v[28:31], v[122:125], v[90:93], v[28:31]
	ds_read_b128 v[90:93], v21 offset:20480
	v_mfma_f32_16x16x32_f16 v[32:35], v[122:125], v[110:113], v[32:35]
	ds_read_b128 v[110:113], v21 offset:22528
	s_waitcnt lgkmcnt(1)
	v_mfma_f32_16x16x32_f16 v[98:101], v[62:65], v[90:93], v[98:101]
	s_waitcnt vmcnt(4)
	ds_write_b128 v20, v[134:137]
	s_waitcnt lgkmcnt(1)
	v_mfma_f32_16x16x32_f16 v[52:55], v[62:65], v[110:113], v[52:55]
	ds_read_b128 v[62:65], v22 offset:49152
	v_mfma_f32_16x16x32_f16 v[102:105], v[74:77], v[90:93], v[102:105]
	s_waitcnt vmcnt(3)
	ds_write_b128 v17, v[94:97] offset:32768
	v_mfma_f32_16x16x32_f16 v[24:27], v[74:77], v[110:113], v[24:27]
	ds_read_b128 v[74:77], v22 offset:51200
	v_mfma_f32_16x16x32_f16 v[114:117], v[118:121], v[90:93], v[114:117]
	s_waitcnt vmcnt(2)
	ds_write_b128 v18, v[162:165] offset:32768
	v_mfma_f32_16x16x32_f16 v[40:43], v[118:121], v[110:113], v[40:43]
	ds_read_b128 v[118:121], v22 offset:53248
	v_mfma_f32_16x16x32_f16 v[70:73], v[122:125], v[90:93], v[70:73]
	ds_read_b128 v[90:93], v23 offset:16384
	v_mfma_f32_16x16x32_f16 v[48:51], v[122:125], v[110:113], v[48:51]
	ds_read_b128 v[110:113], v23 offset:18432
	s_waitcnt lgkmcnt(1)
	v_mfma_f32_16x16x32_f16 v[36:39], v[62:65], v[90:93], v[36:39]
	ds_read_b128 v[122:125], v22 offset:55296
	s_waitcnt lgkmcnt(1)
	v_mfma_f32_16x16x32_f16 v[66:69], v[62:65], v[110:113], v[66:69]
	s_waitcnt vmcnt(1)
	ds_write_b128 v19, v[166:169] offset:32768
	v_mfma_f32_16x16x32_f16 v[44:47], v[74:77], v[90:93], v[44:47]
	s_waitcnt vmcnt(0)
	ds_write_b128 v20, v[190:193] offset:32768
	v_mfma_f32_16x16x32_f16 v[78:81], v[74:77], v[110:113], v[78:81]
	v_mfma_f32_16x16x32_f16 v[82:85], v[118:121], v[90:93], v[82:85]
	v_mfma_f32_16x16x32_f16 v[86:89], v[118:121], v[110:113], v[86:89]
	s_waitcnt lgkmcnt(2)
	v_mfma_f32_16x16x32_f16 v[28:31], v[122:125], v[90:93], v[28:31]
	ds_read_b128 v[90:93], v23 offset:20480
	v_mfma_f32_16x16x32_f16 v[32:35], v[122:125], v[110:113], v[32:35]
	ds_read_b128 v[110:113], v23 offset:22528
	s_waitcnt lgkmcnt(1)
	v_mfma_f32_16x16x32_f16 v[98:101], v[62:65], v[90:93], v[98:101]
	s_waitcnt lgkmcnt(0)
	v_mfma_f32_16x16x32_f16 v[52:55], v[62:65], v[110:113], v[52:55]
	global_load_dwordx4 v[62:65], v[0:1], off offset:1920
	v_mfma_f32_16x16x32_f16 v[102:105], v[74:77], v[90:93], v[102:105]
	v_mfma_f32_16x16x32_f16 v[24:27], v[74:77], v[110:113], v[24:27]
	v_mfma_f32_16x16x32_f16 v[114:117], v[118:121], v[90:93], v[114:117]
	v_mfma_f32_16x16x32_f16 v[40:43], v[118:121], v[110:113], v[40:43]
	v_mfma_f32_16x16x32_f16 v[70:73], v[122:125], v[90:93], v[70:73]
	global_load_dwordx4 v[90:93], v[2:3], off offset:1920
	global_load_dwordx4 v[130:133], v[4:5], off offset:1920
	global_load_dwordx4 v[138:141], v[14:15], off offset:1920
	global_load_dwordx4 v[74:77], v[10:11], off offset:1920
	global_load_dwordx4 v[142:145], v[12:13], off offset:1920
	global_load_dwordx4 v[154:157], v[8:9], off offset:1920
	global_load_dwordx4 v[158:161], v[6:7], off offset:1920
	s_waitcnt lgkmcnt(0)
	s_barrier
	v_mfma_f32_16x16x32_f16 v[48:51], v[122:125], v[110:113], v[48:51]
	ds_read_b128 v[58:61], v16 offset:32768
	ds_read_b128 v[106:109], v21
	s_waitcnt lgkmcnt(0)
	v_mfma_f32_16x16x32_f16 v[36:39], v[58:61], v[106:109], v[36:39]
	ds_read_b128 v[94:97], v16 offset:34816
	ds_read_b128 v[110:113], v21 offset:2048
	s_waitcnt lgkmcnt(0)
	v_mfma_f32_16x16x32_f16 v[66:69], v[58:61], v[110:113], v[66:69]
	ds_read_b128 v[118:121], v16 offset:36864
	v_mfma_f32_16x16x32_f16 v[44:47], v[94:97], v[106:109], v[44:47]
	ds_read_b128 v[122:125], v16 offset:38912
	v_mfma_f32_16x16x32_f16 v[78:81], v[94:97], v[110:113], v[78:81]
	s_waitcnt vmcnt(7)
	ds_write_b128 v17, v[62:65] offset:16384
	s_waitcnt lgkmcnt(2)
	v_mfma_f32_16x16x32_f16 v[82:85], v[118:121], v[106:109], v[82:85]
	s_waitcnt vmcnt(6)
	ds_write_b128 v18, v[90:93] offset:16384
	v_mfma_f32_16x16x32_f16 v[86:89], v[118:121], v[110:113], v[86:89]
	s_waitcnt vmcnt(5)
	ds_write_b128 v19, v[130:133] offset:16384
	s_waitcnt lgkmcnt(3)
	v_mfma_f32_16x16x32_f16 v[28:31], v[122:125], v[106:109], v[28:31]
	ds_read_b128 v[106:109], v21 offset:4096
	v_mfma_f32_16x16x32_f16 v[32:35], v[122:125], v[110:113], v[32:35]
	ds_read_b128 v[110:113], v21 offset:6144
	s_waitcnt lgkmcnt(1)
	v_mfma_f32_16x16x32_f16 v[98:101], v[58:61], v[106:109], v[98:101]
	s_waitcnt vmcnt(4)
	ds_write_b128 v20, v[138:141] offset:16384
	s_waitcnt lgkmcnt(1)
	v_mfma_f32_16x16x32_f16 v[52:55], v[58:61], v[110:113], v[52:55]
	ds_read_b128 v[58:61], v22 offset:32768
	v_mfma_f32_16x16x32_f16 v[102:105], v[94:97], v[106:109], v[102:105]
	s_waitcnt vmcnt(3)
; #define GL_LOAD(s_, kt_) if (VAR != 1) { a##s_##0 = GL_A(0, kt_); a##s_##1 = GL_A(1, kt_); a##s_##2 = GL_A(2, kt_); a##s_##3 = GL_A(3, kt_); b##s_##0 = GL_B(0, kt_); b##s_##1 = GL_B(1, kt_); b##s_##2 = GL_B(2, kt_); b##s_##3 = GL_B(3, kt_); }
; #define LDS_STORE(s_, buf_) if (VAR != 2) { LDS_ST1(sA, 0, buf_, a##s_##0) LDS_ST1(sA, 1, buf_, a##s_##1) LDS_ST1(sA, 2, buf_, a##s_##2) LDS_ST1(sA, 3, buf_, a##s_##3) LDS_ST1(sB, 0, buf_, b##s_##0) LDS_ST1(sB, 1, buf_, b##s_##1) LDS_ST1(sB, 2, buf_, b##s_##2) LDS_ST1(sB, 3, buf_, b##s_##3) }
;     ...
;   GL_LOAD(0, 0)
;   GL_LOAD(1, 1)
;   LDS_STORE(0, 0)
;   if (VAR != 4) __syncthreads();
; #pragma unroll
;   for (int kt = 0; kt < nk; kt += 2) {
;     if (kt + 2 < nk) { GL_LOAD(0, kt + 2) }
;     MMA_TILE(0)
;     LDS_STORE(1, 1)
;     if (VAR != 4) __syncthreads();
;     if (kt + 3 < nk) { GL_LOAD(1, kt + 3) }
;     MMA_TILE(1)
;     if (kt + 2 < nk) { LDS_STORE(0, 0) }
;     if (VAR != 4) __syncthreads();
	ds_write_b128 v17, v[74:77] offset:49152
	v_mfma_f32_16x16x32_f16 v[24:27], v[94:97], v[110:113], v[24:27]
	ds_read_b128 v[94:97], v22 offset:34816
	v_mfma_f32_16x16x32_f16 v[114:117], v[118:121], v[106:109], v[114:117]
	s_waitcnt vmcnt(2)
	ds_write_b128 v18, v[142:145] offset:49152
	v_mfma_f32_16x16x32_f16 v[40:43], v[118:121], v[110:113], v[40:43]
	ds_read_b128 v[118:121], v22 offset:36864
	v_mfma_f32_16x16x32_f16 v[70:73], v[122:125], v[106:109], v[70:73]
	ds_read_b128 v[106:109], v23
	v_mfma_f32_16x16x32_f16 v[48:51], v[122:125], v[110:113], v[48:51]
	ds_read_b128 v[110:113], v23 offset:2048
	s_waitcnt lgkmcnt(1)
	v_mfma_f32_16x16x32_f16 v[36:39], v[58:61], v[106:109], v[36:39]
	ds_read_b128 v[122:125], v22 offset:38912
	s_waitcnt lgkmcnt(1)
	v_mfma_f32_16x16x32_f16 v[66:69], v[58:61], v[110:113], v[66:69]
	s_waitcnt vmcnt(1)
	ds_write_b128 v19, v[154:157] offset:49152
	v_mfma_f32_16x16x32_f16 v[44:47], v[94:97], v[106:109], v[44:47]
	s_waitcnt vmcnt(0)
	ds_write_b128 v20, v[158:161] offset:49152
	v_mfma_f32_16x16x32_f16 v[78:81], v[94:97], v[110:113], v[78:81]
	v_mfma_f32_16x16x32_f16 v[82:85], v[118:121], v[106:109], v[82:85]
	v_mfma_f32_16x16x32_f16 v[86:89], v[118:121], v[110:113], v[86:89]
	s_waitcnt lgkmcnt(2)
	v_mfma_f32_16x16x32_f16 v[28:31], v[122:125], v[106:109], v[28:31]
	ds_read_b128 v[106:109], v23 offset:4096
	v_mfma_f32_16x16x32_f16 v[32:35], v[122:125], v[110:113], v[32:35]
	ds_read_b128 v[110:113], v23 offset:6144
	s_waitcnt lgkmcnt(1)
	v_mfma_f32_16x16x32_f16 v[98:101], v[58:61], v[106:109], v[98:101]
	s_waitcnt lgkmcnt(0)
	v_mfma_f32_16x16x32_f16 v[52:55], v[58:61], v[110:113], v[52:55]
	global_load_dwordx4 v[58:61], v[0:1], off offset:2048
	v_mfma_f32_16x16x32_f16 v[102:105], v[94:97], v[106:109], v[102:105]
	v_mfma_f32_16x16x32_f16 v[24:27], v[94:97], v[110:113], v[24:27]
	v_mfma_f32_16x16x32_f16 v[114:117], v[118:121], v[106:109], v[114:117]
	v_mfma_f32_16x16x32_f16 v[40:43], v[118:121], v[110:113], v[40:43]
	v_mfma_f32_16x16x32_f16 v[70:73], v[122:125], v[106:109], v[70:73]
	global_load_dwordx4 v[106:109], v[2:3], off offset:2048
	global_load_dwordx4 v[126:129], v[4:5], off offset:2048
	global_load_dwordx4 v[134:137], v[14:15], off offset:2048
	global_load_dwordx4 v[94:97], v[10:11], off offset:2048
	global_load_dwordx4 v[162:165], v[12:13], off offset:2048
	global_load_dwordx4 v[166:169], v[8:9], off offset:2048
	global_load_dwordx4 v[190:193], v[6:7], off offset:2048
	s_waitcnt lgkmcnt(0)
	s_barrier
	v_mfma_f32_16x16x32_f16 v[48:51], v[122:125], v[110:113], v[48:51]
	ds_read_b128 v[62:65], v16 offset:49152
	ds_read_b128 v[90:93], v21 offset:16384
	s_waitcnt lgkmcnt(0)
	v_mfma_f32_16x16x32_f16 v[36:39], v[62:65], v[90:93], v[36:39]
	ds_read_b128 v[74:77], v16 offset:51200
	ds_read_b128 v[110:113], v21 offset:18432
	s_waitcnt lgkmcnt(0)
	v_mfma_f32_16x16x32_f16 v[66:69], v[62:65], v[110:113], v[66:69]
	ds_read_b128 v[118:121], v16 offset:53248
	v_mfma_f32_16x16x32_f16 v[44:47], v[74:77], v[90:93], v[44:47]
	ds_read_b128 v[122:125], v16 offset:55296
	v_mfma_f32_16x16x32_f16 v[78:81], v[74:77], v[110:113], v[78:81]
	s_waitcnt vmcnt(7)
	ds_write_b128 v17, v[58:61]
	s_waitcnt lgkmcnt(2)
	v_mfma_f32_16x16x32_f16 v[82:85], v[118:121], v[90:93], v[82:85]
	s_waitcnt vmcnt(6)
	ds_write_b128 v18, v[106:109]
	v_mfma_f32_16x16x32_f16 v[86:89], v[118:121], v[110:113], v[86:89]
	s_waitcnt vmcnt(5)
	ds_write_b128 v19, v[126:129]
	s_waitcnt lgkmcnt(3)
	v_mfma_f32_16x16x32_f16 v[28:31], v[122:125], v[90:93], v[28:31]
	ds_read_b128 v[90:93], v21 offset:20480
	v_mfma_f32_16x16x32_f16 v[32:35], v[122:125], v[110:113], v[32:35]
	ds_read_b128 v[110:113], v21 offset:22528
	s_waitcnt lgkmcnt(1)
	v_mfma_f32_16x16x32_f16 v[98:101], v[62:65], v[90:93], v[98:101]
	s_waitcnt vmcnt(4)
	ds_write_b128 v20, v[134:137]
	s_waitcnt lgkmcnt(1)
	v_mfma_f32_16x16x32_f16 v[52:55], v[62:65], v[110:113], v[52:55]
	ds_read_b128 v[62:65], v22 offset:49152
	v_mfma_f32_16x16x32_f16 v[102:105], v[74:77], v[90:93], v[102:105]
	s_waitcnt vmcnt(3)
	ds_write_b128 v17, v[94:97] offset:32768
	v_mfma_f32_16x16x32_f16 v[24:27], v[74:77], v[110:113], v[24:27]
	ds_read_b128 v[74:77], v22 offset:51200
	v_mfma_f32_16x16x32_f16 v[114:117], v[118:121], v[90:93], v[114:117]
	s_waitcnt vmcnt(2)
	ds_write_b128 v18, v[162:165] offset:32768
	v_mfma_f32_16x16x32_f16 v[40:43], v[118:121], v[110:113], v[40:43]
	ds_read_b128 v[118:121], v22 offset:53248
	v_mfma_f32_16x16x32_f16 v[70:73], v[122:125], v[90:93], v[70:73]
	ds_read_b128 v[90:93], v23 offset:16384
	v_mfma_f32_16x16x32_f16 v[48:51], v[122:125], v[110:113], v[48:51]
	ds_read_b128 v[110:113], v23 offset:18432
	s_waitcnt lgkmcnt(1)
	v_mfma_f32_16x16x32_f16 v[36:39], v[62:65], v[90:93], v[36:39]
	ds_read_b128 v[122:125], v22 offset:55296
	s_waitcnt lgkmcnt(1)
	v_mfma_f32_16x16x32_f16 v[66:69], v[62:65], v[110:113], v[66:69]
	s_waitcnt vmcnt(1)
	ds_write_b128 v19, v[166:169] offset:32768
	v_mfma_f32_16x16x32_f16 v[44:47], v[74:77], v[90:93], v[44:47]
	s_waitcnt vmcnt(0)
	ds_write_b128 v20, v[190:193] offset:32768
	v_mfma_f32_16x16x32_f16 v[78:81], v[74:77], v[110:113], v[78:81]
	v_mfma_f32_16x16x32_f16 v[82:85], v[118:121], v[90:93], v[82:85]
	v_mfma_f32_16x16x32_f16 v[86:89], v[118:121], v[110:113], v[86:89]
	s_waitcnt lgkmcnt(2)
	v_mfma_f32_16x16x32_f16 v[28:31], v[122:125], v[90:93], v[28:31]
	ds_read_b128 v[90:93], v23 offset:20480
	v_mfma_f32_16x16x32_f16 v[32:35], v[122:125], v[110:113], v[32:35]
	ds_read_b128 v[110:113], v23 offset:22528
	s_waitcnt lgkmcnt(1)
	v_mfma_f32_16x16x32_f16 v[98:101], v[62:65], v[90:93], v[98:101]
	s_waitcnt lgkmcnt(0)
	v_mfma_f32_16x16x32_f16 v[52:55], v[62:65], v[110:113], v[52:55]
	global_load_dwordx4 v[62:65], v[0:1], off offset:2176
	v_mfma_f32_16x16x32_f16 v[102:105], v[74:77], v[90:93], v[102:105]
	v_mfma_f32_16x16x32_f16 v[24:27], v[74:77], v[110:113], v[24:27]
	v_mfma_f32_16x16x32_f16 v[114:117], v[118:121], v[90:93], v[114:117]
	v_mfma_f32_16x16x32_f16 v[40:43], v[118:121], v[110:113], v[40:43]
	v_mfma_f32_16x16x32_f16 v[70:73], v[122:125], v[90:93], v[70:73]
	global_load_dwordx4 v[90:93], v[2:3], off offset:2176
	global_load_dwordx4 v[130:133], v[4:5], off offset:2176
	global_load_dwordx4 v[138:141], v[14:15], off offset:2176
	global_load_dwordx4 v[74:77], v[10:11], off offset:2176
	global_load_dwordx4 v[142:145], v[12:13], off offset:2176
	global_load_dwordx4 v[154:157], v[8:9], off offset:2176
	global_load_dwordx4 v[158:161], v[6:7], off offset:2176
	s_waitcnt lgkmcnt(0)
	s_barrier
; #define GL_LOAD(s_, kt_) if (VAR != 1) { a##s_##0 = GL_A(0, kt_); a##s_##1 = GL_A(1, kt_); a##s_##2 = GL_A(2, kt_); a##s_##3 = GL_A(3, kt_); b##s_##0 = GL_B(0, kt_); b##s_##1 = GL_B(1, kt_); b##s_##2 = GL_B(2, kt_); b##s_##3 = GL_B(3, kt_); }
; #define LDS_STORE(s_, buf_) if (VAR != 2) { LDS_ST1(sA, 0, buf_, a##s_##0) LDS_ST1(sA, 1, buf_, a##s_##1) LDS_ST1(sA, 2, buf_, a##s_##2) LDS_ST1(sA, 3, buf_, a##s_##3) LDS_ST1(sB, 0, buf_, b##s_##0) LDS_ST1(sB, 1, buf_, b##s_##1) LDS_ST1(sB, 2, buf_, b##s_##2) LDS_ST1(sB, 3, buf_, b##s_##3) }
;     ...
;   GL_LOAD(0, 0)
;   GL_LOAD(1, 1)
;   LDS_STORE(0, 0)
;   if (VAR != 4) __syncthreads();
; #pragma unroll
;   for (int kt = 0; kt < nk; kt += 2) {
;     if (kt + 2 < nk) { GL_LOAD(0, kt + 2) }
;     MMA_TILE(0)
;     LDS_STORE(1, 1)
;     if (VAR != 4) __syncthreads();
;     if (kt + 3 < nk) { GL_LOAD(1, kt + 3) }
;     MMA_TILE(1)
;     if (kt + 2 < nk) { LDS_STORE(0, 0) }
;     if (VAR != 4) __syncthreads();
	v_mfma_f32_16x16x32_f16 v[48:51], v[122:125], v[110:113], v[48:51]
	ds_read_b128 v[58:61], v16 offset:32768
	ds_read_b128 v[106:109], v21
	s_waitcnt lgkmcnt(0)
	v_mfma_f32_16x16x32_f16 v[36:39], v[58:61], v[106:109], v[36:39]
	ds_read_b128 v[94:97], v16 offset:34816
	ds_read_b128 v[110:113], v21 offset:2048
	s_waitcnt lgkmcnt(0)
	v_mfma_f32_16x16x32_f16 v[66:69], v[58:61], v[110:113], v[66:69]
	ds_read_b128 v[118:121], v16 offset:36864
	v_mfma_f32_16x16x32_f16 v[44:47], v[94:97], v[106:109], v[44:47]
	ds_read_b128 v[122:125], v16 offset:38912
	v_mfma_f32_16x16x32_f16 v[78:81], v[94:97], v[110:113], v[78:81]
	s_waitcnt vmcnt(7)
	ds_write_b128 v17, v[62:65] offset:16384
	s_waitcnt lgkmcnt(2)
	v_mfma_f32_16x16x32_f16 v[82:85], v[118:121], v[106:109], v[82:85]
	s_waitcnt vmcnt(6)
	ds_write_b128 v18, v[90:93] offset:16384
	v_mfma_f32_16x16x32_f16 v[86:89], v[118:121], v[110:113], v[86:89]
	s_waitcnt vmcnt(5)
	ds_write_b128 v19, v[130:133] offset:16384
	s_waitcnt lgkmcnt(3)
	v_mfma_f32_16x16x32_f16 v[28:31], v[122:125], v[106:109], v[28:31]
	ds_read_b128 v[106:109], v21 offset:4096
	v_mfma_f32_16x16x32_f16 v[32:35], v[122:125], v[110:113], v[32:35]
	ds_read_b128 v[110:113], v21 offset:6144
	s_waitcnt lgkmcnt(1)
	v_mfma_f32_16x16x32_f16 v[98:101], v[58:61], v[106:109], v[98:101]
	s_waitcnt vmcnt(4)
	ds_write_b128 v20, v[138:141] offset:16384
	s_waitcnt lgkmcnt(1)
	v_mfma_f32_16x16x32_f16 v[52:55], v[58:61], v[110:113], v[52:55]
	ds_read_b128 v[58:61], v22 offset:32768
	v_mfma_f32_16x16x32_f16 v[102:105], v[94:97], v[106:109], v[102:105]
	s_waitcnt vmcnt(3)
	ds_write_b128 v17, v[74:77] offset:49152
	v_mfma_f32_16x16x32_f16 v[24:27], v[94:97], v[110:113], v[24:27]
	ds_read_b128 v[94:97], v22 offset:34816
	v_mfma_f32_16x16x32_f16 v[114:117], v[118:121], v[106:109], v[114:117]
	s_waitcnt vmcnt(2)
	ds_write_b128 v18, v[142:145] offset:49152
	v_mfma_f32_16x16x32_f16 v[40:43], v[118:121], v[110:113], v[40:43]
	ds_read_b128 v[118:121], v22 offset:36864
	v_mfma_f32_16x16x32_f16 v[70:73], v[122:125], v[106:109], v[70:73]
	ds_read_b128 v[106:109], v23
	v_mfma_f32_16x16x32_f16 v[48:51], v[122:125], v[110:113], v[48:51]
	ds_read_b128 v[110:113], v23 offset:2048
	s_waitcnt lgkmcnt(1)
	v_mfma_f32_16x16x32_f16 v[36:39], v[58:61], v[106:109], v[36:39]
	ds_read_b128 v[122:125], v22 offset:38912
	s_waitcnt lgkmcnt(1)
	v_mfma_f32_16x16x32_f16 v[66:69], v[58:61], v[110:113], v[66:69]
	s_waitcnt vmcnt(1)
	ds_write_b128 v19, v[154:157] offset:49152
	v_mfma_f32_16x16x32_f16 v[44:47], v[94:97], v[106:109], v[44:47]
	s_waitcnt vmcnt(0)
	ds_write_b128 v20, v[158:161] offset:49152
	v_mfma_f32_16x16x32_f16 v[78:81], v[94:97], v[110:113], v[78:81]
	v_mfma_f32_16x16x32_f16 v[82:85], v[118:121], v[106:109], v[82:85]
	v_mfma_f32_16x16x32_f16 v[86:89], v[118:121], v[110:113], v[86:89]
	s_waitcnt lgkmcnt(2)
	v_mfma_f32_16x16x32_f16 v[28:31], v[122:125], v[106:109], v[28:31]
	ds_read_b128 v[106:109], v23 offset:4096
	v_mfma_f32_16x16x32_f16 v[32:35], v[122:125], v[110:113], v[32:35]
	ds_read_b128 v[110:113], v23 offset:6144
	s_waitcnt lgkmcnt(1)
	v_mfma_f32_16x16x32_f16 v[98:101], v[58:61], v[106:109], v[98:101]
	s_waitcnt lgkmcnt(0)
	v_mfma_f32_16x16x32_f16 v[52:55], v[58:61], v[110:113], v[52:55]
	global_load_dwordx4 v[58:61], v[0:1], off offset:2304
	v_mfma_f32_16x16x32_f16 v[102:105], v[94:97], v[106:109], v[102:105]
	v_mfma_f32_16x16x32_f16 v[24:27], v[94:97], v[110:113], v[24:27]
	v_mfma_f32_16x16x32_f16 v[114:117], v[118:121], v[106:109], v[114:117]
	v_mfma_f32_16x16x32_f16 v[40:43], v[118:121], v[110:113], v[40:43]
	v_mfma_f32_16x16x32_f16 v[70:73], v[122:125], v[106:109], v[70:73]
	global_load_dwordx4 v[106:109], v[2:3], off offset:2304
	global_load_dwordx4 v[126:129], v[4:5], off offset:2304
	global_load_dwordx4 v[134:137], v[14:15], off offset:2304
	global_load_dwordx4 v[94:97], v[10:11], off offset:2304
	global_load_dwordx4 v[162:165], v[12:13], off offset:2304
	global_load_dwordx4 v[166:169], v[8:9], off offset:2304
	global_load_dwordx4 v[190:193], v[6:7], off offset:2304
	s_waitcnt lgkmcnt(0)
	s_barrier
	v_mfma_f32_16x16x32_f16 v[48:51], v[122:125], v[110:113], v[48:51]
	ds_read_b128 v[62:65], v16 offset:49152
	ds_read_b128 v[90:93], v21 offset:16384
	s_waitcnt lgkmcnt(0)
	v_mfma_f32_16x16x32_f16 v[36:39], v[62:65], v[90:93], v[36:39]
	ds_read_b128 v[74:77], v16 offset:51200
	ds_read_b128 v[110:113], v21 offset:18432
	s_waitcnt lgkmcnt(0)
	v_mfma_f32_16x16x32_f16 v[66:69], v[62:65], v[110:113], v[66:69]
	ds_read_b128 v[118:121], v16 offset:53248
	v_mfma_f32_16x16x32_f16 v[44:47], v[74:77], v[90:93], v[44:47]
	ds_read_b128 v[122:125], v16 offset:55296
	v_mfma_f32_16x16x32_f16 v[78:81], v[74:77], v[110:113], v[78:81]
	s_waitcnt vmcnt(7)
	ds_write_b128 v17, v[58:61]
	s_waitcnt lgkmcnt(2)
	v_mfma_f32_16x16x32_f16 v[82:85], v[118:121], v[90:93], v[82:85]
	s_waitcnt vmcnt(6)
	ds_write_b128 v18, v[106:109]
	v_mfma_f32_16x16x32_f16 v[86:89], v[118:121], v[110:113], v[86:89]
	s_waitcnt vmcnt(5)
	ds_write_b128 v19, v[126:129]
	s_waitcnt lgkmcnt(3)
	v_mfma_f32_16x16x32_f16 v[28:31], v[122:125], v[90:93], v[28:31]
	ds_read_b128 v[90:93], v21 offset:20480
	v_mfma_f32_16x16x32_f16 v[32:35], v[122:125], v[110:113], v[32:35]
	ds_read_b128 v[110:113], v21 offset:22528
	s_waitcnt lgkmcnt(1)
	v_mfma_f32_16x16x32_f16 v[98:101], v[62:65], v[90:93], v[98:101]
	s_waitcnt vmcnt(4)
	ds_write_b128 v20, v[134:137]
	s_waitcnt lgkmcnt(1)
	v_mfma_f32_16x16x32_f16 v[52:55], v[62:65], v[110:113], v[52:55]
	ds_read_b128 v[62:65], v22 offset:49152
	v_mfma_f32_16x16x32_f16 v[102:105], v[74:77], v[90:93], v[102:105]
	s_waitcnt vmcnt(3)
; #define GL_LOAD(s_, kt_) if (VAR != 1) { a##s_##0 = GL_A(0, kt_); a##s_##1 = GL_A(1, kt_); a##s_##2 = GL_A(2, kt_); a##s_##3 = GL_A(3, kt_); b##s_##0 = GL_B(0, kt_); b##s_##1 = GL_B(1, kt_); b##s_##2 = GL_B(2, kt_); b##s_##3 = GL_B(3, kt_); }
; #define LDS_STORE(s_, buf_) if (VAR != 2) { LDS_ST1(sA, 0, buf_, a##s_##0) LDS_ST1(sA, 1, buf_, a##s_##1) LDS_ST1(sA, 2, buf_, a##s_##2) LDS_ST1(sA, 3, buf_, a##s_##3) LDS_ST1(sB, 0, buf_, b##s_##0) LDS_ST1(sB, 1, buf_, b##s_##1) LDS_ST1(sB, 2, buf_, b##s_##2) LDS_ST1(sB, 3, buf_, b##s_##3) }
;     ...
;   GL_LOAD(0, 0)
;   GL_LOAD(1, 1)
;   LDS_STORE(0, 0)
;   if (VAR != 4) __syncthreads();
; #pragma unroll
;   for (int kt = 0; kt < nk; kt += 2) {
;     if (kt + 2 < nk) { GL_LOAD(0, kt + 2) }
;     MMA_TILE(0)
;     LDS_STORE(1, 1)
;     if (VAR != 4) __syncthreads();
;     if (kt + 3 < nk) { GL_LOAD(1, kt + 3) }
;     MMA_TILE(1)
;     if (kt + 2 < nk) { LDS_STORE(0, 0) }
;     if (VAR != 4) __syncthreads();
	ds_write_b128 v17, v[94:97] offset:32768
	v_mfma_f32_16x16x32_f16 v[24:27], v[74:77], v[110:113], v[24:27]
	ds_read_b128 v[74:77], v22 offset:51200
	v_mfma_f32_16x16x32_f16 v[114:117], v[118:121], v[90:93], v[114:117]
	s_waitcnt vmcnt(2)
	ds_write_b128 v18, v[162:165] offset:32768
	v_mfma_f32_16x16x32_f16 v[40:43], v[118:121], v[110:113], v[40:43]
	ds_read_b128 v[118:121], v22 offset:53248
	v_mfma_f32_16x16x32_f16 v[70:73], v[122:125], v[90:93], v[70:73]
	ds_read_b128 v[90:93], v23 offset:16384
	v_mfma_f32_16x16x32_f16 v[48:51], v[122:125], v[110:113], v[48:51]
	ds_read_b128 v[110:113], v23 offset:18432
	s_waitcnt lgkmcnt(1)
	v_mfma_f32_16x16x32_f16 v[36:39], v[62:65], v[90:93], v[36:39]
	ds_read_b128 v[122:125], v22 offset:55296
	s_waitcnt lgkmcnt(1)
	v_mfma_f32_16x16x32_f16 v[66:69], v[62:65], v[110:113], v[66:69]
	s_waitcnt vmcnt(1)
	ds_write_b128 v19, v[166:169] offset:32768
	v_mfma_f32_16x16x32_f16 v[44:47], v[74:77], v[90:93], v[44:47]
	s_waitcnt vmcnt(0)
	ds_write_b128 v20, v[190:193] offset:32768
	v_mfma_f32_16x16x32_f16 v[78:81], v[74:77], v[110:113], v[78:81]
	v_mfma_f32_16x16x32_f16 v[82:85], v[118:121], v[90:93], v[82:85]
	v_mfma_f32_16x16x32_f16 v[86:89], v[118:121], v[110:113], v[86:89]
	s_waitcnt lgkmcnt(2)
	v_mfma_f32_16x16x32_f16 v[28:31], v[122:125], v[90:93], v[28:31]
	ds_read_b128 v[90:93], v23 offset:20480
	v_mfma_f32_16x16x32_f16 v[32:35], v[122:125], v[110:113], v[32:35]
	ds_read_b128 v[110:113], v23 offset:22528
	s_waitcnt lgkmcnt(1)
	v_mfma_f32_16x16x32_f16 v[98:101], v[62:65], v[90:93], v[98:101]
	s_waitcnt lgkmcnt(0)
	v_mfma_f32_16x16x32_f16 v[52:55], v[62:65], v[110:113], v[52:55]
	global_load_dwordx4 v[62:65], v[0:1], off offset:2432
	v_mfma_f32_16x16x32_f16 v[102:105], v[74:77], v[90:93], v[102:105]
	v_mfma_f32_16x16x32_f16 v[24:27], v[74:77], v[110:113], v[24:27]
	v_mfma_f32_16x16x32_f16 v[114:117], v[118:121], v[90:93], v[114:117]
	v_mfma_f32_16x16x32_f16 v[40:43], v[118:121], v[110:113], v[40:43]
	v_mfma_f32_16x16x32_f16 v[70:73], v[122:125], v[90:93], v[70:73]
	global_load_dwordx4 v[90:93], v[2:3], off offset:2432
	global_load_dwordx4 v[130:133], v[4:5], off offset:2432
	global_load_dwordx4 v[138:141], v[14:15], off offset:2432
	global_load_dwordx4 v[74:77], v[10:11], off offset:2432
	global_load_dwordx4 v[142:145], v[12:13], off offset:2432
	global_load_dwordx4 v[154:157], v[8:9], off offset:2432
	global_load_dwordx4 v[158:161], v[6:7], off offset:2432
	s_waitcnt lgkmcnt(0)
	s_barrier
	v_mfma_f32_16x16x32_f16 v[48:51], v[122:125], v[110:113], v[48:51]
	ds_read_b128 v[58:61], v16 offset:32768
	ds_read_b128 v[106:109], v21
	s_waitcnt lgkmcnt(0)
	v_mfma_f32_16x16x32_f16 v[36:39], v[58:61], v[106:109], v[36:39]
	ds_read_b128 v[94:97], v16 offset:34816
	ds_read_b128 v[110:113], v21 offset:2048
	s_waitcnt lgkmcnt(0)
	v_mfma_f32_16x16x32_f16 v[66:69], v[58:61], v[110:113], v[66:69]
	ds_read_b128 v[118:121], v16 offset:36864
	v_mfma_f32_16x16x32_f16 v[44:47], v[94:97], v[106:109], v[44:47]
	ds_read_b128 v[122:125], v16 offset:38912
	v_mfma_f32_16x16x32_f16 v[78:81], v[94:97], v[110:113], v[78:81]
	s_waitcnt vmcnt(7)
	ds_write_b128 v17, v[62:65] offset:16384
	s_waitcnt lgkmcnt(2)
	v_mfma_f32_16x16x32_f16 v[82:85], v[118:121], v[106:109], v[82:85]
	s_waitcnt vmcnt(6)
	ds_write_b128 v18, v[90:93] offset:16384
	v_mfma_f32_16x16x32_f16 v[86:89], v[118:121], v[110:113], v[86:89]
	s_waitcnt vmcnt(5)
	ds_write_b128 v19, v[130:133] offset:16384
	s_waitcnt lgkmcnt(3)
	v_mfma_f32_16x16x32_f16 v[28:31], v[122:125], v[106:109], v[28:31]
	ds_read_b128 v[106:109], v21 offset:4096
	v_mfma_f32_16x16x32_f16 v[32:35], v[122:125], v[110:113], v[32:35]
	ds_read_b128 v[110:113], v21 offset:6144
	s_waitcnt lgkmcnt(1)
	v_mfma_f32_16x16x32_f16 v[98:101], v[58:61], v[106:109], v[98:101]
	s_waitcnt vmcnt(4)
	ds_write_b128 v20, v[138:141] offset:16384
	s_waitcnt lgkmcnt(1)
	v_mfma_f32_16x16x32_f16 v[52:55], v[58:61], v[110:113], v[52:55]
	ds_read_b128 v[58:61], v22 offset:32768
	v_mfma_f32_16x16x32_f16 v[102:105], v[94:97], v[106:109], v[102:105]
	s_waitcnt vmcnt(3)
	ds_write_b128 v17, v[74:77] offset:49152
	v_mfma_f32_16x16x32_f16 v[24:27], v[94:97], v[110:113], v[24:27]
	ds_read_b128 v[94:97], v22 offset:34816
	v_mfma_f32_16x16x32_f16 v[114:117], v[118:121], v[106:109], v[114:117]
	s_waitcnt vmcnt(2)
	ds_write_b128 v18, v[142:145] offset:49152
	v_mfma_f32_16x16x32_f16 v[40:43], v[118:121], v[110:113], v[40:43]
	ds_read_b128 v[118:121], v22 offset:36864
	v_mfma_f32_16x16x32_f16 v[70:73], v[122:125], v[106:109], v[70:73]
	ds_read_b128 v[106:109], v23
	v_mfma_f32_16x16x32_f16 v[48:51], v[122:125], v[110:113], v[48:51]
	ds_read_b128 v[110:113], v23 offset:2048
	s_waitcnt lgkmcnt(1)
	v_mfma_f32_16x16x32_f16 v[36:39], v[58:61], v[106:109], v[36:39]
	ds_read_b128 v[122:125], v22 offset:38912
	s_waitcnt lgkmcnt(1)
	v_mfma_f32_16x16x32_f16 v[66:69], v[58:61], v[110:113], v[66:69]
	s_waitcnt vmcnt(1)
	ds_write_b128 v19, v[154:157] offset:49152
	v_mfma_f32_16x16x32_f16 v[44:47], v[94:97], v[106:109], v[44:47]
	s_waitcnt vmcnt(0)
	ds_write_b128 v20, v[158:161] offset:49152
	v_mfma_f32_16x16x32_f16 v[78:81], v[94:97], v[110:113], v[78:81]
	v_mfma_f32_16x16x32_f16 v[82:85], v[118:121], v[106:109], v[82:85]
	v_mfma_f32_16x16x32_f16 v[86:89], v[118:121], v[110:113], v[86:89]
	s_waitcnt lgkmcnt(2)
	v_mfma_f32_16x16x32_f16 v[28:31], v[122:125], v[106:109], v[28:31]
	ds_read_b128 v[106:109], v23 offset:4096
	v_mfma_f32_16x16x32_f16 v[32:35], v[122:125], v[110:113], v[32:35]
	ds_read_b128 v[110:113], v23 offset:6144
	s_waitcnt lgkmcnt(1)
	v_mfma_f32_16x16x32_f16 v[98:101], v[58:61], v[106:109], v[98:101]
	s_waitcnt lgkmcnt(0)
	v_mfma_f32_16x16x32_f16 v[52:55], v[58:61], v[110:113], v[52:55]
	global_load_dwordx4 v[58:61], v[0:1], off offset:2560
	v_mfma_f32_16x16x32_f16 v[102:105], v[94:97], v[106:109], v[102:105]
	v_mfma_f32_16x16x32_f16 v[24:27], v[94:97], v[110:113], v[24:27]
	v_mfma_f32_16x16x32_f16 v[114:117], v[118:121], v[106:109], v[114:117]
	v_mfma_f32_16x16x32_f16 v[40:43], v[118:121], v[110:113], v[40:43]
	v_mfma_f32_16x16x32_f16 v[70:73], v[122:125], v[106:109], v[70:73]
	global_load_dwordx4 v[106:109], v[2:3], off offset:2560
	global_load_dwordx4 v[126:129], v[4:5], off offset:2560
	global_load_dwordx4 v[134:137], v[14:15], off offset:2560
	global_load_dwordx4 v[94:97], v[10:11], off offset:2560
	global_load_dwordx4 v[162:165], v[12:13], off offset:2560
	global_load_dwordx4 v[166:169], v[8:9], off offset:2560
	global_load_dwordx4 v[190:193], v[6:7], off offset:2560
	s_waitcnt lgkmcnt(0)
	s_barrier
; #define GL_LOAD(s_, kt_) if (VAR != 1) { a##s_##0 = GL_A(0, kt_); a##s_##1 = GL_A(1, kt_); a##s_##2 = GL_A(2, kt_); a##s_##3 = GL_A(3, kt_); b##s_##0 = GL_B(0, kt_); b##s_##1 = GL_B(1, kt_); b##s_##2 = GL_B(2, kt_); b##s_##3 = GL_B(3, kt_); }
; #define LDS_STORE(s_, buf_) if (VAR != 2) { LDS_ST1(sA, 0, buf_, a##s_##0) LDS_ST1(sA, 1, buf_, a##s_##1) LDS_ST1(sA, 2, buf_, a##s_##2) LDS_ST1(sA, 3, buf_, a##s_##3) LDS_ST1(sB, 0, buf_, b##s_##0) LDS_ST1(sB, 1, buf_, b##s_##1) LDS_ST1(sB, 2, buf_, b##s_##2) LDS_ST1(sB, 3, buf_, b##s_##3) }
;     ...
;   GL_LOAD(0, 0)
;   GL_LOAD(1, 1)
;   LDS_STORE(0, 0)
;   if (VAR != 4) __syncthreads();
; #pragma unroll
;   for (int kt = 0; kt < nk; kt += 2) {
;     if (kt + 2 < nk) { GL_LOAD(0, kt + 2) }
;     MMA_TILE(0)
;     LDS_STORE(1, 1)
;     if (VAR != 4) __syncthreads();
;     if (kt + 3 < nk) { GL_LOAD(1, kt + 3) }
;     MMA_TILE(1)
;     if (kt + 2 < nk) { LDS_STORE(0, 0) }
;     if (VAR != 4) __syncthreads();
	v_mfma_f32_16x16x32_f16 v[48:51], v[122:125], v[110:113], v[48:51]
	ds_read_b128 v[62:65], v16 offset:49152
	ds_read_b128 v[90:93], v21 offset:16384
	s_waitcnt lgkmcnt(0)
	v_mfma_f32_16x16x32_f16 v[36:39], v[62:65], v[90:93], v[36:39]
	ds_read_b128 v[74:77], v16 offset:51200
	ds_read_b128 v[110:113], v21 offset:18432
	s_waitcnt lgkmcnt(0)
	v_mfma_f32_16x16x32_f16 v[66:69], v[62:65], v[110:113], v[66:69]
	ds_read_b128 v[118:121], v16 offset:53248
	v_mfma_f32_16x16x32_f16 v[44:47], v[74:77], v[90:93], v[44:47]
	ds_read_b128 v[122:125], v16 offset:55296
	v_mfma_f32_16x16x32_f16 v[78:81], v[74:77], v[110:113], v[78:81]
	s_waitcnt vmcnt(7)
	ds_write_b128 v17, v[58:61]
	s_waitcnt lgkmcnt(2)
	v_mfma_f32_16x16x32_f16 v[82:85], v[118:121], v[90:93], v[82:85]
	s_waitcnt vmcnt(6)
	ds_write_b128 v18, v[106:109]
	v_mfma_f32_16x16x32_f16 v[86:89], v[118:121], v[110:113], v[86:89]
	s_waitcnt vmcnt(5)
	ds_write_b128 v19, v[126:129]
	s_waitcnt lgkmcnt(3)
	v_mfma_f32_16x16x32_f16 v[28:31], v[122:125], v[90:93], v[28:31]
	ds_read_b128 v[90:93], v21 offset:20480
	v_mfma_f32_16x16x32_f16 v[32:35], v[122:125], v[110:113], v[32:35]
	ds_read_b128 v[110:113], v21 offset:22528
	s_waitcnt lgkmcnt(1)
	v_mfma_f32_16x16x32_f16 v[98:101], v[62:65], v[90:93], v[98:101]
	s_waitcnt vmcnt(4)
	ds_write_b128 v20, v[134:137]
	s_waitcnt lgkmcnt(1)
	v_mfma_f32_16x16x32_f16 v[52:55], v[62:65], v[110:113], v[52:55]
	ds_read_b128 v[62:65], v22 offset:49152
	v_mfma_f32_16x16x32_f16 v[102:105], v[74:77], v[90:93], v[102:105]
	s_waitcnt vmcnt(3)
	ds_write_b128 v17, v[94:97] offset:32768
	v_mfma_f32_16x16x32_f16 v[24:27], v[74:77], v[110:113], v[24:27]
	ds_read_b128 v[74:77], v22 offset:51200
	v_mfma_f32_16x16x32_f16 v[114:117], v[118:121], v[90:93], v[114:117]
	s_waitcnt vmcnt(2)
	ds_write_b128 v18, v[162:165] offset:32768
	v_mfma_f32_16x16x32_f16 v[40:43], v[118:121], v[110:113], v[40:43]
	ds_read_b128 v[118:121], v22 offset:53248
	v_mfma_f32_16x16x32_f16 v[70:73], v[122:125], v[90:93], v[70:73]
	ds_read_b128 v[90:93], v23 offset:16384
	v_mfma_f32_16x16x32_f16 v[48:51], v[122:125], v[110:113], v[48:51]
	ds_read_b128 v[110:113], v23 offset:18432
	s_waitcnt lgkmcnt(1)
	v_mfma_f32_16x16x32_f16 v[36:39], v[62:65], v[90:93], v[36:39]
	ds_read_b128 v[122:125], v22 offset:55296
	s_waitcnt lgkmcnt(1)
	v_mfma_f32_16x16x32_f16 v[66:69], v[62:65], v[110:113], v[66:69]
	s_waitcnt vmcnt(1)
	ds_write_b128 v19, v[166:169] offset:32768
	v_mfma_f32_16x16x32_f16 v[44:47], v[74:77], v[90:93], v[44:47]
	s_waitcnt vmcnt(0)
	ds_write_b128 v20, v[190:193] offset:32768
	v_mfma_f32_16x16x32_f16 v[78:81], v[74:77], v[110:113], v[78:81]
	v_mfma_f32_16x16x32_f16 v[82:85], v[118:121], v[90:93], v[82:85]
	v_mfma_f32_16x16x32_f16 v[86:89], v[118:121], v[110:113], v[86:89]
	s_waitcnt lgkmcnt(2)
	v_mfma_f32_16x16x32_f16 v[28:31], v[122:125], v[90:93], v[28:31]
	ds_read_b128 v[90:93], v23 offset:20480
	v_mfma_f32_16x16x32_f16 v[32:35], v[122:125], v[110:113], v[32:35]
	ds_read_b128 v[110:113], v23 offset:22528
	s_waitcnt lgkmcnt(1)
	v_mfma_f32_16x16x32_f16 v[98:101], v[62:65], v[90:93], v[98:101]
	s_waitcnt lgkmcnt(0)
	v_mfma_f32_16x16x32_f16 v[52:55], v[62:65], v[110:113], v[52:55]
	global_load_dwordx4 v[62:65], v[0:1], off offset:2688
	v_mfma_f32_16x16x32_f16 v[102:105], v[74:77], v[90:93], v[102:105]
	v_mfma_f32_16x16x32_f16 v[24:27], v[74:77], v[110:113], v[24:27]
	v_mfma_f32_16x16x32_f16 v[114:117], v[118:121], v[90:93], v[114:117]
	v_mfma_f32_16x16x32_f16 v[40:43], v[118:121], v[110:113], v[40:43]
	v_mfma_f32_16x16x32_f16 v[70:73], v[122:125], v[90:93], v[70:73]
	global_load_dwordx4 v[90:93], v[2:3], off offset:2688
	global_load_dwordx4 v[130:133], v[4:5], off offset:2688
	global_load_dwordx4 v[138:141], v[14:15], off offset:2688
	global_load_dwordx4 v[74:77], v[10:11], off offset:2688
	global_load_dwordx4 v[142:145], v[12:13], off offset:2688
	global_load_dwordx4 v[154:157], v[8:9], off offset:2688
	global_load_dwordx4 v[158:161], v[6:7], off offset:2688
	s_waitcnt lgkmcnt(0)
	s_barrier
	v_mfma_f32_16x16x32_f16 v[48:51], v[122:125], v[110:113], v[48:51]
	ds_read_b128 v[58:61], v16 offset:32768
	ds_read_b128 v[106:109], v21
	s_waitcnt lgkmcnt(0)
	v_mfma_f32_16x16x32_f16 v[36:39], v[58:61], v[106:109], v[36:39]
	ds_read_b128 v[94:97], v16 offset:34816
	ds_read_b128 v[110:113], v21 offset:2048
	s_waitcnt lgkmcnt(0)
	v_mfma_f32_16x16x32_f16 v[66:69], v[58:61], v[110:113], v[66:69]
	ds_read_b128 v[118:121], v16 offset:36864
	v_mfma_f32_16x16x32_f16 v[44:47], v[94:97], v[106:109], v[44:47]
	ds_read_b128 v[122:125], v16 offset:38912
	v_mfma_f32_16x16x32_f16 v[78:81], v[94:97], v[110:113], v[78:81]
	s_waitcnt vmcnt(7)
	ds_write_b128 v17, v[62:65] offset:16384
	s_waitcnt lgkmcnt(2)
	v_mfma_f32_16x16x32_f16 v[82:85], v[118:121], v[106:109], v[82:85]
	s_waitcnt vmcnt(6)
	ds_write_b128 v18, v[90:93] offset:16384
	v_mfma_f32_16x16x32_f16 v[86:89], v[118:121], v[110:113], v[86:89]
	s_waitcnt vmcnt(5)
	ds_write_b128 v19, v[130:133] offset:16384
	s_waitcnt lgkmcnt(3)
	v_mfma_f32_16x16x32_f16 v[28:31], v[122:125], v[106:109], v[28:31]
	ds_read_b128 v[106:109], v21 offset:4096
	v_mfma_f32_16x16x32_f16 v[32:35], v[122:125], v[110:113], v[32:35]
	ds_read_b128 v[110:113], v21 offset:6144
	s_waitcnt lgkmcnt(1)
	v_mfma_f32_16x16x32_f16 v[98:101], v[58:61], v[106:109], v[98:101]
	s_waitcnt vmcnt(4)
	ds_write_b128 v20, v[138:141] offset:16384
	s_waitcnt lgkmcnt(1)
	v_mfma_f32_16x16x32_f16 v[52:55], v[58:61], v[110:113], v[52:55]
	ds_read_b128 v[58:61], v22 offset:32768
	v_mfma_f32_16x16x32_f16 v[102:105], v[94:97], v[106:109], v[102:105]
	s_waitcnt vmcnt(3)
; #define GL_LOAD(s_, kt_) if (VAR != 1) { a##s_##0 = GL_A(0, kt_); a##s_##1 = GL_A(1, kt_); a##s_##2 = GL_A(2, kt_); a##s_##3 = GL_A(3, kt_); b##s_##0 = GL_B(0, kt_); b##s_##1 = GL_B(1, kt_); b##s_##2 = GL_B(2, kt_); b##s_##3 = GL_B(3, kt_); }
; #define LDS_STORE(s_, buf_) if (VAR != 2) { LDS_ST1(sA, 0, buf_, a##s_##0) LDS_ST1(sA, 1, buf_, a##s_##1) LDS_ST1(sA, 2, buf_, a##s_##2) LDS_ST1(sA, 3, buf_, a##s_##3) LDS_ST1(sB, 0, buf_, b##s_##0) LDS_ST1(sB, 1, buf_, b##s_##1) LDS_ST1(sB, 2, buf_, b##s_##2) LDS_ST1(sB, 3, buf_, b##s_##3) }
;     ...
;   GL_LOAD(0, 0)
;   GL_LOAD(1, 1)
;   LDS_STORE(0, 0)
;   if (VAR != 4) __syncthreads();
; #pragma unroll
;   for (int kt = 0; kt < nk; kt += 2) {
;     if (kt + 2 < nk) { GL_LOAD(0, kt + 2) }
;     MMA_TILE(0)
;     LDS_STORE(1, 1)
;     if (VAR != 4) __syncthreads();
;     if (kt + 3 < nk) { GL_LOAD(1, kt + 3) }
;     MMA_TILE(1)
;     if (kt + 2 < nk) { LDS_STORE(0, 0) }
;     if (VAR != 4) __syncthreads();
	ds_write_b128 v17, v[74:77] offset:49152
	v_mfma_f32_16x16x32_f16 v[24:27], v[94:97], v[110:113], v[24:27]
	ds_read_b128 v[94:97], v22 offset:34816
	v_mfma_f32_16x16x32_f16 v[114:117], v[118:121], v[106:109], v[114:117]
	s_waitcnt vmcnt(2)
	ds_write_b128 v18, v[142:145] offset:49152
	v_mfma_f32_16x16x32_f16 v[40:43], v[118:121], v[110:113], v[40:43]
	ds_read_b128 v[118:121], v22 offset:36864
	v_mfma_f32_16x16x32_f16 v[70:73], v[122:125], v[106:109], v[70:73]
	ds_read_b128 v[106:109], v23
	v_mfma_f32_16x16x32_f16 v[48:51], v[122:125], v[110:113], v[48:51]
	ds_read_b128 v[110:113], v23 offset:2048
	s_waitcnt lgkmcnt(1)
	v_mfma_f32_16x16x32_f16 v[36:39], v[58:61], v[106:109], v[36:39]
	ds_read_b128 v[122:125], v22 offset:38912
	s_waitcnt lgkmcnt(1)
	v_mfma_f32_16x16x32_f16 v[66:69], v[58:61], v[110:113], v[66:69]
	s_waitcnt vmcnt(1)
	ds_write_b128 v19, v[154:157] offset:49152
	v_mfma_f32_16x16x32_f16 v[44:47], v[94:97], v[106:109], v[44:47]
	s_waitcnt vmcnt(0)
	ds_write_b128 v20, v[158:161] offset:49152
	v_mfma_f32_16x16x32_f16 v[78:81], v[94:97], v[110:113], v[78:81]
	v_mfma_f32_16x16x32_f16 v[82:85], v[118:121], v[106:109], v[82:85]
	v_mfma_f32_16x16x32_f16 v[86:89], v[118:121], v[110:113], v[86:89]
	s_waitcnt lgkmcnt(2)
	v_mfma_f32_16x16x32_f16 v[28:31], v[122:125], v[106:109], v[28:31]
	ds_read_b128 v[106:109], v23 offset:4096
	v_mfma_f32_16x16x32_f16 v[32:35], v[122:125], v[110:113], v[32:35]
	ds_read_b128 v[110:113], v23 offset:6144
	s_waitcnt lgkmcnt(1)
	v_mfma_f32_16x16x32_f16 v[98:101], v[58:61], v[106:109], v[98:101]
	s_waitcnt lgkmcnt(0)
	v_mfma_f32_16x16x32_f16 v[52:55], v[58:61], v[110:113], v[52:55]
	global_load_dwordx4 v[58:61], v[0:1], off offset:2816
	v_mfma_f32_16x16x32_f16 v[102:105], v[94:97], v[106:109], v[102:105]
	v_mfma_f32_16x16x32_f16 v[24:27], v[94:97], v[110:113], v[24:27]
	v_mfma_f32_16x16x32_f16 v[114:117], v[118:121], v[106:109], v[114:117]
	v_mfma_f32_16x16x32_f16 v[40:43], v[118:121], v[110:113], v[40:43]
	v_mfma_f32_16x16x32_f16 v[70:73], v[122:125], v[106:109], v[70:73]
	global_load_dwordx4 v[106:109], v[2:3], off offset:2816
	global_load_dwordx4 v[126:129], v[4:5], off offset:2816
	global_load_dwordx4 v[134:137], v[14:15], off offset:2816
	global_load_dwordx4 v[94:97], v[10:11], off offset:2816
	global_load_dwordx4 v[162:165], v[12:13], off offset:2816
	global_load_dwordx4 v[166:169], v[8:9], off offset:2816
	global_load_dwordx4 v[190:193], v[6:7], off offset:2816
	s_waitcnt lgkmcnt(0)
	s_barrier
	v_mfma_f32_16x16x32_f16 v[48:51], v[122:125], v[110:113], v[48:51]
	ds_read_b128 v[62:65], v16 offset:49152
	ds_read_b128 v[90:93], v21 offset:16384
	s_waitcnt lgkmcnt(0)
	v_mfma_f32_16x16x32_f16 v[36:39], v[62:65], v[90:93], v[36:39]
	ds_read_b128 v[74:77], v16 offset:51200
	ds_read_b128 v[110:113], v21 offset:18432
	s_waitcnt lgkmcnt(0)
	v_mfma_f32_16x16x32_f16 v[66:69], v[62:65], v[110:113], v[66:69]
	ds_read_b128 v[118:121], v16 offset:53248
	v_mfma_f32_16x16x32_f16 v[44:47], v[74:77], v[90:93], v[44:47]
	ds_read_b128 v[122:125], v16 offset:55296
	v_mfma_f32_16x16x32_f16 v[78:81], v[74:77], v[110:113], v[78:81]
	s_waitcnt vmcnt(7)
	ds_write_b128 v17, v[58:61]
	s_waitcnt lgkmcnt(2)
	v_mfma_f32_16x16x32_f16 v[82:85], v[118:121], v[90:93], v[82:85]
	s_waitcnt vmcnt(6)
	ds_write_b128 v18, v[106:109]
	v_mfma_f32_16x16x32_f16 v[86:89], v[118:121], v[110:113], v[86:89]
	s_waitcnt vmcnt(5)
	ds_write_b128 v19, v[126:129]
	s_waitcnt lgkmcnt(3)
	v_mfma_f32_16x16x32_f16 v[28:31], v[122:125], v[90:93], v[28:31]
	ds_read_b128 v[90:93], v21 offset:20480
	v_mfma_f32_16x16x32_f16 v[32:35], v[122:125], v[110:113], v[32:35]
	ds_read_b128 v[110:113], v21 offset:22528
	s_waitcnt lgkmcnt(1)
	v_mfma_f32_16x16x32_f16 v[98:101], v[62:65], v[90:93], v[98:101]
	s_waitcnt vmcnt(4)
	ds_write_b128 v20, v[134:137]
	s_waitcnt lgkmcnt(1)
	v_mfma_f32_16x16x32_f16 v[52:55], v[62:65], v[110:113], v[52:55]
	ds_read_b128 v[62:65], v22 offset:49152
	v_mfma_f32_16x16x32_f16 v[102:105], v[74:77], v[90:93], v[102:105]
	s_waitcnt vmcnt(3)
	ds_write_b128 v17, v[94:97] offset:32768
	v_mfma_f32_16x16x32_f16 v[24:27], v[74:77], v[110:113], v[24:27]
	ds_read_b128 v[74:77], v22 offset:51200
	v_mfma_f32_16x16x32_f16 v[114:117], v[118:121], v[90:93], v[114:117]
	s_waitcnt vmcnt(2)
	ds_write_b128 v18, v[162:165] offset:32768
	v_mfma_f32_16x16x32_f16 v[40:43], v[118:121], v[110:113], v[40:43]
	ds_read_b128 v[118:121], v22 offset:53248
	v_mfma_f32_16x16x32_f16 v[70:73], v[122:125], v[90:93], v[70:73]
	ds_read_b128 v[90:93], v23 offset:16384
	v_mfma_f32_16x16x32_f16 v[48:51], v[122:125], v[110:113], v[48:51]
	ds_read_b128 v[110:113], v23 offset:18432
	s_waitcnt lgkmcnt(1)
	v_mfma_f32_16x16x32_f16 v[36:39], v[62:65], v[90:93], v[36:39]
	ds_read_b128 v[122:125], v22 offset:55296
	s_waitcnt lgkmcnt(1)
	v_mfma_f32_16x16x32_f16 v[66:69], v[62:65], v[110:113], v[66:69]
	s_waitcnt vmcnt(1)
	ds_write_b128 v19, v[166:169] offset:32768
	v_mfma_f32_16x16x32_f16 v[44:47], v[74:77], v[90:93], v[44:47]
	s_waitcnt vmcnt(0)
	ds_write_b128 v20, v[190:193] offset:32768
	v_mfma_f32_16x16x32_f16 v[78:81], v[74:77], v[110:113], v[78:81]
	v_mfma_f32_16x16x32_f16 v[82:85], v[118:121], v[90:93], v[82:85]
	v_mfma_f32_16x16x32_f16 v[86:89], v[118:121], v[110:113], v[86:89]
	s_waitcnt lgkmcnt(2)
	v_mfma_f32_16x16x32_f16 v[28:31], v[122:125], v[90:93], v[28:31]
	ds_read_b128 v[90:93], v23 offset:20480
	v_mfma_f32_16x16x32_f16 v[32:35], v[122:125], v[110:113], v[32:35]
	ds_read_b128 v[110:113], v23 offset:22528
	s_waitcnt lgkmcnt(1)
	v_mfma_f32_16x16x32_f16 v[98:101], v[62:65], v[90:93], v[98:101]
	s_waitcnt lgkmcnt(0)
	v_mfma_f32_16x16x32_f16 v[52:55], v[62:65], v[110:113], v[52:55]
	global_load_dwordx4 v[62:65], v[0:1], off offset:2944
	v_mfma_f32_16x16x32_f16 v[102:105], v[74:77], v[90:93], v[102:105]
	v_mfma_f32_16x16x32_f16 v[24:27], v[74:77], v[110:113], v[24:27]
	v_mfma_f32_16x16x32_f16 v[114:117], v[118:121], v[90:93], v[114:117]
	v_mfma_f32_16x16x32_f16 v[40:43], v[118:121], v[110:113], v[40:43]
	v_mfma_f32_16x16x32_f16 v[70:73], v[122:125], v[90:93], v[70:73]
	global_load_dwordx4 v[90:93], v[2:3], off offset:2944
	global_load_dwordx4 v[130:133], v[4:5], off offset:2944
	global_load_dwordx4 v[138:141], v[14:15], off offset:2944
	global_load_dwordx4 v[74:77], v[10:11], off offset:2944
	global_load_dwordx4 v[142:145], v[12:13], off offset:2944
	global_load_dwordx4 v[154:157], v[8:9], off offset:2944
	global_load_dwordx4 v[158:161], v[6:7], off offset:2944
	s_waitcnt lgkmcnt(0)
	s_barrier
; #define GL_LOAD(s_, kt_) if (VAR != 1) { a##s_##0 = GL_A(0, kt_); a##s_##1 = GL_A(1, kt_); a##s_##2 = GL_A(2, kt_); a##s_##3 = GL_A(3, kt_); b##s_##0 = GL_B(0, kt_); b##s_##1 = GL_B(1, kt_); b##s_##2 = GL_B(2, kt_); b##s_##3 = GL_B(3, kt_); }
; #define LDS_STORE(s_, buf_) if (VAR != 2) { LDS_ST1(sA, 0, buf_, a##s_##0) LDS_ST1(sA, 1, buf_, a##s_##1) LDS_ST1(sA, 2, buf_, a##s_##2) LDS_ST1(sA, 3, buf_, a##s_##3) LDS_ST1(sB, 0, buf_, b##s_##0) LDS_ST1(sB, 1, buf_, b##s_##1) LDS_ST1(sB, 2, buf_, b##s_##2) LDS_ST1(sB, 3, buf_, b##s_##3) }
;     ...
;   GL_LOAD(0, 0)
;   GL_LOAD(1, 1)
;   LDS_STORE(0, 0)
;   if (VAR != 4) __syncthreads();
; #pragma unroll
;   for (int kt = 0; kt < nk; kt += 2) {
;     if (kt + 2 < nk) { GL_LOAD(0, kt + 2) }
;     MMA_TILE(0)
;     LDS_STORE(1, 1)
;     if (VAR != 4) __syncthreads();
;     if (kt + 3 < nk) { GL_LOAD(1, kt + 3) }
;     MMA_TILE(1)
;     if (kt + 2 < nk) { LDS_STORE(0, 0) }
;     if (VAR != 4) __syncthreads();
	v_mfma_f32_16x16x32_f16 v[48:51], v[122:125], v[110:113], v[48:51]
	ds_read_b128 v[58:61], v16 offset:32768
	ds_read_b128 v[106:109], v21
	s_waitcnt lgkmcnt(0)
	v_mfma_f32_16x16x32_f16 v[36:39], v[58:61], v[106:109], v[36:39]
	ds_read_b128 v[94:97], v16 offset:34816
	ds_read_b128 v[110:113], v21 offset:2048
	s_waitcnt lgkmcnt(0)
	v_mfma_f32_16x16x32_f16 v[66:69], v[58:61], v[110:113], v[66:69]
	ds_read_b128 v[118:121], v16 offset:36864
	v_mfma_f32_16x16x32_f16 v[44:47], v[94:97], v[106:109], v[44:47]
	ds_read_b128 v[122:125], v16 offset:38912
	v_mfma_f32_16x16x32_f16 v[78:81], v[94:97], v[110:113], v[78:81]
	s_waitcnt vmcnt(7)
	ds_write_b128 v17, v[62:65] offset:16384
	s_waitcnt lgkmcnt(2)
	v_mfma_f32_16x16x32_f16 v[82:85], v[118:121], v[106:109], v[82:85]
	s_waitcnt vmcnt(6)
	ds_write_b128 v18, v[90:93] offset:16384
	v_mfma_f32_16x16x32_f16 v[86:89], v[118:121], v[110:113], v[86:89]
	s_waitcnt vmcnt(5)
	ds_write_b128 v19, v[130:133] offset:16384
	s_waitcnt lgkmcnt(3)
	v_mfma_f32_16x16x32_f16 v[28:31], v[122:125], v[106:109], v[28:31]
	ds_read_b128 v[106:109], v21 offset:4096
	v_mfma_f32_16x16x32_f16 v[32:35], v[122:125], v[110:113], v[32:35]
	ds_read_b128 v[110:113], v21 offset:6144
	s_waitcnt lgkmcnt(1)
	v_mfma_f32_16x16x32_f16 v[98:101], v[58:61], v[106:109], v[98:101]
	s_waitcnt vmcnt(4)
	ds_write_b128 v20, v[138:141] offset:16384
	s_waitcnt lgkmcnt(1)
	v_mfma_f32_16x16x32_f16 v[52:55], v[58:61], v[110:113], v[52:55]
	ds_read_b128 v[58:61], v22 offset:32768
	v_mfma_f32_16x16x32_f16 v[102:105], v[94:97], v[106:109], v[102:105]
	s_waitcnt vmcnt(3)
	ds_write_b128 v17, v[74:77] offset:49152
	v_mfma_f32_16x16x32_f16 v[24:27], v[94:97], v[110:113], v[24:27]
	ds_read_b128 v[94:97], v22 offset:34816
	v_mfma_f32_16x16x32_f16 v[114:117], v[118:121], v[106:109], v[114:117]
	s_waitcnt vmcnt(2)
	ds_write_b128 v18, v[142:145] offset:49152
	v_mfma_f32_16x16x32_f16 v[40:43], v[118:121], v[110:113], v[40:43]
	ds_read_b128 v[118:121], v22 offset:36864
	v_mfma_f32_16x16x32_f16 v[70:73], v[122:125], v[106:109], v[70:73]
	ds_read_b128 v[106:109], v23
	v_mfma_f32_16x16x32_f16 v[48:51], v[122:125], v[110:113], v[48:51]
	ds_read_b128 v[110:113], v23 offset:2048
	s_waitcnt lgkmcnt(1)
	v_mfma_f32_16x16x32_f16 v[36:39], v[58:61], v[106:109], v[36:39]
	ds_read_b128 v[122:125], v22 offset:38912
	s_waitcnt lgkmcnt(1)
	v_mfma_f32_16x16x32_f16 v[66:69], v[58:61], v[110:113], v[66:69]
	s_waitcnt vmcnt(1)
	ds_write_b128 v19, v[154:157] offset:49152
	v_mfma_f32_16x16x32_f16 v[44:47], v[94:97], v[106:109], v[44:47]
	s_waitcnt vmcnt(0)
	ds_write_b128 v20, v[158:161] offset:49152
	v_mfma_f32_16x16x32_f16 v[78:81], v[94:97], v[110:113], v[78:81]
	v_mfma_f32_16x16x32_f16 v[82:85], v[118:121], v[106:109], v[82:85]
	v_mfma_f32_16x16x32_f16 v[86:89], v[118:121], v[110:113], v[86:89]
	s_waitcnt lgkmcnt(2)
	v_mfma_f32_16x16x32_f16 v[28:31], v[122:125], v[106:109], v[28:31]
	ds_read_b128 v[106:109], v23 offset:4096
	v_mfma_f32_16x16x32_f16 v[32:35], v[122:125], v[110:113], v[32:35]
	ds_read_b128 v[110:113], v23 offset:6144
	s_waitcnt lgkmcnt(1)
	v_mfma_f32_16x16x32_f16 v[98:101], v[58:61], v[106:109], v[98:101]
	s_waitcnt lgkmcnt(0)
	v_mfma_f32_16x16x32_f16 v[52:55], v[58:61], v[110:113], v[52:55]
	global_load_dwordx4 v[58:61], v[0:1], off offset:3072
	v_mfma_f32_16x16x32_f16 v[102:105], v[94:97], v[106:109], v[102:105]
	v_mfma_f32_16x16x32_f16 v[24:27], v[94:97], v[110:113], v[24:27]
	v_mfma_f32_16x16x32_f16 v[114:117], v[118:121], v[106:109], v[114:117]
	v_mfma_f32_16x16x32_f16 v[40:43], v[118:121], v[110:113], v[40:43]
	v_mfma_f32_16x16x32_f16 v[70:73], v[122:125], v[106:109], v[70:73]
	global_load_dwordx4 v[106:109], v[2:3], off offset:3072
	global_load_dwordx4 v[126:129], v[4:5], off offset:3072
	global_load_dwordx4 v[134:137], v[14:15], off offset:3072
	global_load_dwordx4 v[94:97], v[10:11], off offset:3072
	global_load_dwordx4 v[162:165], v[12:13], off offset:3072
	global_load_dwordx4 v[166:169], v[8:9], off offset:3072
	global_load_dwordx4 v[190:193], v[6:7], off offset:3072
	s_waitcnt lgkmcnt(0)
	s_barrier
	v_mfma_f32_16x16x32_f16 v[48:51], v[122:125], v[110:113], v[48:51]
	ds_read_b128 v[62:65], v16 offset:49152
	ds_read_b128 v[90:93], v21 offset:16384
	s_waitcnt lgkmcnt(0)
	v_mfma_f32_16x16x32_f16 v[36:39], v[62:65], v[90:93], v[36:39]
	ds_read_b128 v[74:77], v16 offset:51200
	ds_read_b128 v[110:113], v21 offset:18432
	s_waitcnt lgkmcnt(0)
	v_mfma_f32_16x16x32_f16 v[66:69], v[62:65], v[110:113], v[66:69]
	ds_read_b128 v[118:121], v16 offset:53248
	v_mfma_f32_16x16x32_f16 v[44:47], v[74:77], v[90:93], v[44:47]
	ds_read_b128 v[122:125], v16 offset:55296
	v_mfma_f32_16x16x32_f16 v[78:81], v[74:77], v[110:113], v[78:81]
	s_waitcnt vmcnt(7)
	ds_write_b128 v17, v[58:61]
	s_waitcnt lgkmcnt(2)
	v_mfma_f32_16x16x32_f16 v[82:85], v[118:121], v[90:93], v[82:85]
	s_waitcnt vmcnt(6)
	ds_write_b128 v18, v[106:109]
	v_mfma_f32_16x16x32_f16 v[86:89], v[118:121], v[110:113], v[86:89]
	s_waitcnt vmcnt(5)
	ds_write_b128 v19, v[126:129]
	s_waitcnt lgkmcnt(3)
	v_mfma_f32_16x16x32_f16 v[28:31], v[122:125], v[90:93], v[28:31]
	ds_read_b128 v[90:93], v21 offset:20480
	v_mfma_f32_16x16x32_f16 v[32:35], v[122:125], v[110:113], v[32:35]
	ds_read_b128 v[110:113], v21 offset:22528
	s_waitcnt lgkmcnt(1)
	v_mfma_f32_16x16x32_f16 v[98:101], v[62:65], v[90:93], v[98:101]
	s_waitcnt vmcnt(4)
	ds_write_b128 v20, v[134:137]
	s_waitcnt lgkmcnt(1)
	v_mfma_f32_16x16x32_f16 v[52:55], v[62:65], v[110:113], v[52:55]
	ds_read_b128 v[62:65], v22 offset:49152
	v_mfma_f32_16x16x32_f16 v[102:105], v[74:77], v[90:93], v[102:105]
	s_waitcnt vmcnt(3)
; #define GL_LOAD(s_, kt_) if (VAR != 1) { a##s_##0 = GL_A(0, kt_); a##s_##1 = GL_A(1, kt_); a##s_##2 = GL_A(2, kt_); a##s_##3 = GL_A(3, kt_); b##s_##0 = GL_B(0, kt_); b##s_##1 = GL_B(1, kt_); b##s_##2 = GL_B(2, kt_); b##s_##3 = GL_B(3, kt_); }
; #define LDS_STORE(s_, buf_) if (VAR != 2) { LDS_ST1(sA, 0, buf_, a##s_##0) LDS_ST1(sA, 1, buf_, a##s_##1) LDS_ST1(sA, 2, buf_, a##s_##2) LDS_ST1(sA, 3, buf_, a##s_##3) LDS_ST1(sB, 0, buf_, b##s_##0) LDS_ST1(sB, 1, buf_, b##s_##1) LDS_ST1(sB, 2, buf_, b##s_##2) LDS_ST1(sB, 3, buf_, b##s_##3) }
;     ...
;   GL_LOAD(0, 0)
;   GL_LOAD(1, 1)
;   LDS_STORE(0, 0)
;   if (VAR != 4) __syncthreads();
; #pragma unroll
;   for (int kt = 0; kt < nk; kt += 2) {
;     if (kt + 2 < nk) { GL_LOAD(0, kt + 2) }
;     MMA_TILE(0)
;     LDS_STORE(1, 1)
;     if (VAR != 4) __syncthreads();
;     if (kt + 3 < nk) { GL_LOAD(1, kt + 3) }
;     MMA_TILE(1)
;     if (kt + 2 < nk) { LDS_STORE(0, 0) }
;     if (VAR != 4) __syncthreads();
	ds_write_b128 v17, v[94:97] offset:32768
	v_mfma_f32_16x16x32_f16 v[24:27], v[74:77], v[110:113], v[24:27]
	ds_read_b128 v[74:77], v22 offset:51200
	v_mfma_f32_16x16x32_f16 v[114:117], v[118:121], v[90:93], v[114:117]
	s_waitcnt vmcnt(2)
	ds_write_b128 v18, v[162:165] offset:32768
	v_mfma_f32_16x16x32_f16 v[40:43], v[118:121], v[110:113], v[40:43]
	ds_read_b128 v[118:121], v22 offset:53248
	v_mfma_f32_16x16x32_f16 v[70:73], v[122:125], v[90:93], v[70:73]
	ds_read_b128 v[90:93], v23 offset:16384
	v_mfma_f32_16x16x32_f16 v[48:51], v[122:125], v[110:113], v[48:51]
	ds_read_b128 v[110:113], v23 offset:18432
	s_waitcnt lgkmcnt(1)
	v_mfma_f32_16x16x32_f16 v[36:39], v[62:65], v[90:93], v[36:39]
	ds_read_b128 v[122:125], v22 offset:55296
	s_waitcnt lgkmcnt(1)
	v_mfma_f32_16x16x32_f16 v[66:69], v[62:65], v[110:113], v[66:69]
	s_waitcnt vmcnt(1)
	ds_write_b128 v19, v[166:169] offset:32768
	v_mfma_f32_16x16x32_f16 v[44:47], v[74:77], v[90:93], v[44:47]
	s_waitcnt vmcnt(0)
	ds_write_b128 v20, v[190:193] offset:32768
	v_mfma_f32_16x16x32_f16 v[78:81], v[74:77], v[110:113], v[78:81]
	v_mfma_f32_16x16x32_f16 v[82:85], v[118:121], v[90:93], v[82:85]
	v_mfma_f32_16x16x32_f16 v[86:89], v[118:121], v[110:113], v[86:89]
	s_waitcnt lgkmcnt(2)
	v_mfma_f32_16x16x32_f16 v[28:31], v[122:125], v[90:93], v[28:31]
	ds_read_b128 v[90:93], v23 offset:20480
	v_mfma_f32_16x16x32_f16 v[32:35], v[122:125], v[110:113], v[32:35]
	ds_read_b128 v[110:113], v23 offset:22528
	s_waitcnt lgkmcnt(1)
	v_mfma_f32_16x16x32_f16 v[98:101], v[62:65], v[90:93], v[98:101]
	s_waitcnt lgkmcnt(0)
	v_mfma_f32_16x16x32_f16 v[52:55], v[62:65], v[110:113], v[52:55]
	global_load_dwordx4 v[62:65], v[0:1], off offset:3200
	v_mfma_f32_16x16x32_f16 v[102:105], v[74:77], v[90:93], v[102:105]
	v_mfma_f32_16x16x32_f16 v[24:27], v[74:77], v[110:113], v[24:27]
	v_mfma_f32_16x16x32_f16 v[114:117], v[118:121], v[90:93], v[114:117]
	v_mfma_f32_16x16x32_f16 v[40:43], v[118:121], v[110:113], v[40:43]
	v_mfma_f32_16x16x32_f16 v[70:73], v[122:125], v[90:93], v[70:73]
	global_load_dwordx4 v[90:93], v[2:3], off offset:3200
	global_load_dwordx4 v[130:133], v[4:5], off offset:3200
	global_load_dwordx4 v[138:141], v[14:15], off offset:3200
	global_load_dwordx4 v[74:77], v[10:11], off offset:3200
	global_load_dwordx4 v[142:145], v[12:13], off offset:3200
	global_load_dwordx4 v[154:157], v[8:9], off offset:3200
	global_load_dwordx4 v[158:161], v[6:7], off offset:3200
	s_waitcnt lgkmcnt(0)
	s_barrier
	v_mfma_f32_16x16x32_f16 v[48:51], v[122:125], v[110:113], v[48:51]
	ds_read_b128 v[58:61], v16 offset:32768
	ds_read_b128 v[106:109], v21
	s_waitcnt lgkmcnt(0)
	v_mfma_f32_16x16x32_f16 v[36:39], v[58:61], v[106:109], v[36:39]
	ds_read_b128 v[94:97], v16 offset:34816
	ds_read_b128 v[110:113], v21 offset:2048
	s_waitcnt lgkmcnt(0)
	v_mfma_f32_16x16x32_f16 v[66:69], v[58:61], v[110:113], v[66:69]
	ds_read_b128 v[118:121], v16 offset:36864
	v_mfma_f32_16x16x32_f16 v[44:47], v[94:97], v[106:109], v[44:47]
	ds_read_b128 v[122:125], v16 offset:38912
	v_mfma_f32_16x16x32_f16 v[78:81], v[94:97], v[110:113], v[78:81]
	s_waitcnt vmcnt(7)
	ds_write_b128 v17, v[62:65] offset:16384
	s_waitcnt lgkmcnt(2)
	v_mfma_f32_16x16x32_f16 v[82:85], v[118:121], v[106:109], v[82:85]
	s_waitcnt vmcnt(6)
	ds_write_b128 v18, v[90:93] offset:16384
	v_mfma_f32_16x16x32_f16 v[86:89], v[118:121], v[110:113], v[86:89]
	s_waitcnt vmcnt(5)
	ds_write_b128 v19, v[130:133] offset:16384
	s_waitcnt lgkmcnt(3)
	v_mfma_f32_16x16x32_f16 v[28:31], v[122:125], v[106:109], v[28:31]
	ds_read_b128 v[106:109], v21 offset:4096
	v_mfma_f32_16x16x32_f16 v[32:35], v[122:125], v[110:113], v[32:35]
	ds_read_b128 v[110:113], v21 offset:6144
	s_waitcnt lgkmcnt(1)
	v_mfma_f32_16x16x32_f16 v[98:101], v[58:61], v[106:109], v[98:101]
	s_waitcnt vmcnt(4)
	ds_write_b128 v20, v[138:141] offset:16384
	s_waitcnt lgkmcnt(1)
	v_mfma_f32_16x16x32_f16 v[52:55], v[58:61], v[110:113], v[52:55]
	ds_read_b128 v[58:61], v22 offset:32768
	v_mfma_f32_16x16x32_f16 v[102:105], v[94:97], v[106:109], v[102:105]
	s_waitcnt vmcnt(3)
	ds_write_b128 v17, v[74:77] offset:49152
	v_mfma_f32_16x16x32_f16 v[24:27], v[94:97], v[110:113], v[24:27]
	ds_read_b128 v[94:97], v22 offset:34816
	v_mfma_f32_16x16x32_f16 v[114:117], v[118:121], v[106:109], v[114:117]
	s_waitcnt vmcnt(2)
	ds_write_b128 v18, v[142:145] offset:49152
	v_mfma_f32_16x16x32_f16 v[40:43], v[118:121], v[110:113], v[40:43]
	ds_read_b128 v[118:121], v22 offset:36864
	v_mfma_f32_16x16x32_f16 v[70:73], v[122:125], v[106:109], v[70:73]
	ds_read_b128 v[106:109], v23
	v_mfma_f32_16x16x32_f16 v[48:51], v[122:125], v[110:113], v[48:51]
	ds_read_b128 v[110:113], v23 offset:2048
	s_waitcnt lgkmcnt(1)
	v_mfma_f32_16x16x32_f16 v[36:39], v[58:61], v[106:109], v[36:39]
	ds_read_b128 v[122:125], v22 offset:38912
	s_waitcnt lgkmcnt(1)
	v_mfma_f32_16x16x32_f16 v[66:69], v[58:61], v[110:113], v[66:69]
	s_waitcnt vmcnt(1)
	ds_write_b128 v19, v[154:157] offset:49152
	v_mfma_f32_16x16x32_f16 v[44:47], v[94:97], v[106:109], v[44:47]
	s_waitcnt vmcnt(0)
	ds_write_b128 v20, v[158:161] offset:49152
	v_mfma_f32_16x16x32_f16 v[78:81], v[94:97], v[110:113], v[78:81]
	v_mfma_f32_16x16x32_f16 v[82:85], v[118:121], v[106:109], v[82:85]
	v_mfma_f32_16x16x32_f16 v[86:89], v[118:121], v[110:113], v[86:89]
	s_waitcnt lgkmcnt(2)
	v_mfma_f32_16x16x32_f16 v[28:31], v[122:125], v[106:109], v[28:31]
	ds_read_b128 v[106:109], v23 offset:4096
	v_mfma_f32_16x16x32_f16 v[32:35], v[122:125], v[110:113], v[32:35]
	ds_read_b128 v[110:113], v23 offset:6144
	s_waitcnt lgkmcnt(1)
	v_mfma_f32_16x16x32_f16 v[98:101], v[58:61], v[106:109], v[98:101]
	s_waitcnt lgkmcnt(0)
	v_mfma_f32_16x16x32_f16 v[52:55], v[58:61], v[110:113], v[52:55]
	global_load_dwordx4 v[58:61], v[0:1], off offset:3328
	v_mfma_f32_16x16x32_f16 v[102:105], v[94:97], v[106:109], v[102:105]
	v_mfma_f32_16x16x32_f16 v[24:27], v[94:97], v[110:113], v[24:27]
	v_mfma_f32_16x16x32_f16 v[114:117], v[118:121], v[106:109], v[114:117]
	v_mfma_f32_16x16x32_f16 v[40:43], v[118:121], v[110:113], v[40:43]
	v_mfma_f32_16x16x32_f16 v[70:73], v[122:125], v[106:109], v[70:73]
	global_load_dwordx4 v[106:109], v[2:3], off offset:3328
	global_load_dwordx4 v[126:129], v[4:5], off offset:3328
	global_load_dwordx4 v[134:137], v[14:15], off offset:3328
	global_load_dwordx4 v[94:97], v[10:11], off offset:3328
	global_load_dwordx4 v[162:165], v[12:13], off offset:3328
	global_load_dwordx4 v[166:169], v[8:9], off offset:3328
	global_load_dwordx4 v[190:193], v[6:7], off offset:3328
	s_waitcnt lgkmcnt(0)
	s_barrier
; #define GL_LOAD(s_, kt_) if (VAR != 1) { a##s_##0 = GL_A(0, kt_); a##s_##1 = GL_A(1, kt_); a##s_##2 = GL_A(2, kt_); a##s_##3 = GL_A(3, kt_); b##s_##0 = GL_B(0, kt_); b##s_##1 = GL_B(1, kt_); b##s_##2 = GL_B(2, kt_); b##s_##3 = GL_B(3, kt_); }
; #define LDS_STORE(s_, buf_) if (VAR != 2) { LDS_ST1(sA, 0, buf_, a##s_##0) LDS_ST1(sA, 1, buf_, a##s_##1) LDS_ST1(sA, 2, buf_, a##s_##2) LDS_ST1(sA, 3, buf_, a##s_##3) LDS_ST1(sB, 0, buf_, b##s_##0) LDS_ST1(sB, 1, buf_, b##s_##1) LDS_ST1(sB, 2, buf_, b##s_##2) LDS_ST1(sB, 3, buf_, b##s_##3) }
;     ...
;   GL_LOAD(0, 0)
;   GL_LOAD(1, 1)
;   LDS_STORE(0, 0)
;   if (VAR != 4) __syncthreads();
; #pragma unroll
;   for (int kt = 0; kt < nk; kt += 2) {
;     if (kt + 2 < nk) { GL_LOAD(0, kt + 2) }
;     MMA_TILE(0)
;     LDS_STORE(1, 1)
;     if (VAR != 4) __syncthreads();
;     if (kt + 3 < nk) { GL_LOAD(1, kt + 3) }
;     MMA_TILE(1)
;     if (kt + 2 < nk) { LDS_STORE(0, 0) }
;     if (VAR != 4) __syncthreads();
	v_mfma_f32_16x16x32_f16 v[48:51], v[122:125], v[110:113], v[48:51]
	ds_read_b128 v[62:65], v16 offset:49152
	ds_read_b128 v[90:93], v21 offset:16384
	s_waitcnt lgkmcnt(0)
	v_mfma_f32_16x16x32_f16 v[36:39], v[62:65], v[90:93], v[36:39]
	ds_read_b128 v[74:77], v16 offset:51200
	ds_read_b128 v[110:113], v21 offset:18432
	s_waitcnt lgkmcnt(0)
	v_mfma_f32_16x16x32_f16 v[66:69], v[62:65], v[110:113], v[66:69]
	ds_read_b128 v[118:121], v16 offset:53248
	v_mfma_f32_16x16x32_f16 v[44:47], v[74:77], v[90:93], v[44:47]
	ds_read_b128 v[122:125], v16 offset:55296
	v_mfma_f32_16x16x32_f16 v[78:81], v[74:77], v[110:113], v[78:81]
	s_waitcnt vmcnt(7)
	ds_write_b128 v17, v[58:61]
	s_waitcnt lgkmcnt(2)
	v_mfma_f32_16x16x32_f16 v[82:85], v[118:121], v[90:93], v[82:85]
	s_waitcnt vmcnt(6)
	ds_write_b128 v18, v[106:109]
	v_mfma_f32_16x16x32_f16 v[86:89], v[118:121], v[110:113], v[86:89]
	s_waitcnt vmcnt(5)
	ds_write_b128 v19, v[126:129]
	s_waitcnt lgkmcnt(3)
	v_mfma_f32_16x16x32_f16 v[28:31], v[122:125], v[90:93], v[28:31]
	ds_read_b128 v[90:93], v21 offset:20480
	v_mfma_f32_16x16x32_f16 v[32:35], v[122:125], v[110:113], v[32:35]
	ds_read_b128 v[110:113], v21 offset:22528
	s_waitcnt lgkmcnt(1)
	v_mfma_f32_16x16x32_f16 v[98:101], v[62:65], v[90:93], v[98:101]
	s_waitcnt vmcnt(4)
	ds_write_b128 v20, v[134:137]
	s_waitcnt lgkmcnt(1)
	v_mfma_f32_16x16x32_f16 v[52:55], v[62:65], v[110:113], v[52:55]
	ds_read_b128 v[62:65], v22 offset:49152
	v_mfma_f32_16x16x32_f16 v[102:105], v[74:77], v[90:93], v[102:105]
	s_waitcnt vmcnt(3)
	ds_write_b128 v17, v[94:97] offset:32768
	v_mfma_f32_16x16x32_f16 v[24:27], v[74:77], v[110:113], v[24:27]
	ds_read_b128 v[74:77], v22 offset:51200
	v_mfma_f32_16x16x32_f16 v[114:117], v[118:121], v[90:93], v[114:117]
	s_waitcnt vmcnt(2)
	ds_write_b128 v18, v[162:165] offset:32768
	v_mfma_f32_16x16x32_f16 v[40:43], v[118:121], v[110:113], v[40:43]
	ds_read_b128 v[118:121], v22 offset:53248
	v_mfma_f32_16x16x32_f16 v[70:73], v[122:125], v[90:93], v[70:73]
	ds_read_b128 v[90:93], v23 offset:16384
	v_mfma_f32_16x16x32_f16 v[48:51], v[122:125], v[110:113], v[48:51]
	ds_read_b128 v[110:113], v23 offset:18432
	s_waitcnt lgkmcnt(1)
	v_mfma_f32_16x16x32_f16 v[36:39], v[62:65], v[90:93], v[36:39]
	ds_read_b128 v[122:125], v22 offset:55296
	s_waitcnt lgkmcnt(1)
	v_mfma_f32_16x16x32_f16 v[66:69], v[62:65], v[110:113], v[66:69]
	s_waitcnt vmcnt(1)
	ds_write_b128 v19, v[166:169] offset:32768
	v_mfma_f32_16x16x32_f16 v[44:47], v[74:77], v[90:93], v[44:47]
	s_waitcnt vmcnt(0)
	ds_write_b128 v20, v[190:193] offset:32768
	v_mfma_f32_16x16x32_f16 v[78:81], v[74:77], v[110:113], v[78:81]
	v_mfma_f32_16x16x32_f16 v[82:85], v[118:121], v[90:93], v[82:85]
	v_mfma_f32_16x16x32_f16 v[86:89], v[118:121], v[110:113], v[86:89]
	s_waitcnt lgkmcnt(2)
	v_mfma_f32_16x16x32_f16 v[28:31], v[122:125], v[90:93], v[28:31]
	ds_read_b128 v[90:93], v23 offset:20480
	v_mfma_f32_16x16x32_f16 v[32:35], v[122:125], v[110:113], v[32:35]
	ds_read_b128 v[110:113], v23 offset:22528
	s_waitcnt lgkmcnt(1)
	v_mfma_f32_16x16x32_f16 v[98:101], v[62:65], v[90:93], v[98:101]
	s_waitcnt lgkmcnt(0)
	v_mfma_f32_16x16x32_f16 v[52:55], v[62:65], v[110:113], v[52:55]
	global_load_dwordx4 v[62:65], v[0:1], off offset:3456
	v_mfma_f32_16x16x32_f16 v[102:105], v[74:77], v[90:93], v[102:105]
	v_mfma_f32_16x16x32_f16 v[24:27], v[74:77], v[110:113], v[24:27]
	v_mfma_f32_16x16x32_f16 v[114:117], v[118:121], v[90:93], v[114:117]
	v_mfma_f32_16x16x32_f16 v[40:43], v[118:121], v[110:113], v[40:43]
	v_mfma_f32_16x16x32_f16 v[70:73], v[122:125], v[90:93], v[70:73]
	global_load_dwordx4 v[90:93], v[2:3], off offset:3456
	global_load_dwordx4 v[130:133], v[4:5], off offset:3456
	global_load_dwordx4 v[138:141], v[14:15], off offset:3456
	global_load_dwordx4 v[74:77], v[10:11], off offset:3456
	global_load_dwordx4 v[142:145], v[12:13], off offset:3456
	global_load_dwordx4 v[154:157], v[8:9], off offset:3456
	global_load_dwordx4 v[158:161], v[6:7], off offset:3456
	s_waitcnt lgkmcnt(0)
	s_barrier
	v_mfma_f32_16x16x32_f16 v[48:51], v[122:125], v[110:113], v[48:51]
	ds_read_b128 v[58:61], v16 offset:32768
	ds_read_b128 v[106:109], v21
	s_waitcnt lgkmcnt(0)
	v_mfma_f32_16x16x32_f16 v[36:39], v[58:61], v[106:109], v[36:39]
	ds_read_b128 v[94:97], v16 offset:34816
	ds_read_b128 v[110:113], v21 offset:2048
	s_waitcnt lgkmcnt(0)
	v_mfma_f32_16x16x32_f16 v[66:69], v[58:61], v[110:113], v[66:69]
	ds_read_b128 v[118:121], v16 offset:36864
	v_mfma_f32_16x16x32_f16 v[44:47], v[94:97], v[106:109], v[44:47]
	ds_read_b128 v[122:125], v16 offset:38912
	v_mfma_f32_16x16x32_f16 v[78:81], v[94:97], v[110:113], v[78:81]
	s_waitcnt vmcnt(7)
	ds_write_b128 v17, v[62:65] offset:16384
	s_waitcnt lgkmcnt(2)
	v_mfma_f32_16x16x32_f16 v[82:85], v[118:121], v[106:109], v[82:85]
	s_waitcnt vmcnt(6)
	ds_write_b128 v18, v[90:93] offset:16384
	v_mfma_f32_16x16x32_f16 v[86:89], v[118:121], v[110:113], v[86:89]
	s_waitcnt vmcnt(5)
	ds_write_b128 v19, v[130:133] offset:16384
	s_waitcnt lgkmcnt(3)
	v_mfma_f32_16x16x32_f16 v[28:31], v[122:125], v[106:109], v[28:31]
	ds_read_b128 v[106:109], v21 offset:4096
	v_mfma_f32_16x16x32_f16 v[32:35], v[122:125], v[110:113], v[32:35]
	ds_read_b128 v[110:113], v21 offset:6144
	s_waitcnt lgkmcnt(1)
	v_mfma_f32_16x16x32_f16 v[98:101], v[58:61], v[106:109], v[98:101]
	s_waitcnt vmcnt(4)
	ds_write_b128 v20, v[138:141] offset:16384
	s_waitcnt lgkmcnt(1)
	v_mfma_f32_16x16x32_f16 v[52:55], v[58:61], v[110:113], v[52:55]
	ds_read_b128 v[58:61], v22 offset:32768
	v_mfma_f32_16x16x32_f16 v[102:105], v[94:97], v[106:109], v[102:105]
	s_waitcnt vmcnt(3)
; #define GL_LOAD(s_, kt_) if (VAR != 1) { a##s_##0 = GL_A(0, kt_); a##s_##1 = GL_A(1, kt_); a##s_##2 = GL_A(2, kt_); a##s_##3 = GL_A(3, kt_); b##s_##0 = GL_B(0, kt_); b##s_##1 = GL_B(1, kt_); b##s_##2 = GL_B(2, kt_); b##s_##3 = GL_B(3, kt_); }
; #define LDS_STORE(s_, buf_) if (VAR != 2) { LDS_ST1(sA, 0, buf_, a##s_##0) LDS_ST1(sA, 1, buf_, a##s_##1) LDS_ST1(sA, 2, buf_, a##s_##2) LDS_ST1(sA, 3, buf_, a##s_##3) LDS_ST1(sB, 0, buf_, b##s_##0) LDS_ST1(sB, 1, buf_, b##s_##1) LDS_ST1(sB, 2, buf_, b##s_##2) LDS_ST1(sB, 3, buf_, b##s_##3) }
;     ...
;   for (int kt = 0; kt < nk; kt += 2) {
;     if (kt + 2 < nk) { GL_LOAD(0, kt + 2) }
;     MMA_TILE(0)
;     LDS_STORE(1, 1)
;     if (VAR != 4) __syncthreads();
;     if (kt + 3 < nk) { GL_LOAD(1, kt + 3) }
;     MMA_TILE(1)
;     if (kt + 2 < nk) { LDS_STORE(0, 0) }
;     if (VAR != 4) __syncthreads();
;   }
	ds_write_b128 v17, v[74:77] offset:49152
	v_mfma_f32_16x16x32_f16 v[24:27], v[94:97], v[110:113], v[24:27]
	ds_read_b128 v[94:97], v22 offset:34816
	v_mfma_f32_16x16x32_f16 v[114:117], v[118:121], v[106:109], v[114:117]
	s_waitcnt vmcnt(2)
	ds_write_b128 v18, v[142:145] offset:49152
	v_mfma_f32_16x16x32_f16 v[40:43], v[118:121], v[110:113], v[40:43]
	ds_read_b128 v[118:121], v22 offset:36864
	v_mfma_f32_16x16x32_f16 v[70:73], v[122:125], v[106:109], v[70:73]
	ds_read_b128 v[106:109], v23
	v_mfma_f32_16x16x32_f16 v[48:51], v[122:125], v[110:113], v[48:51]
	ds_read_b128 v[110:113], v23 offset:2048
	s_waitcnt lgkmcnt(1)
	v_mfma_f32_16x16x32_f16 v[36:39], v[58:61], v[106:109], v[36:39]
	ds_read_b128 v[122:125], v22 offset:38912
	s_waitcnt lgkmcnt(1)
	v_mfma_f32_16x16x32_f16 v[66:69], v[58:61], v[110:113], v[66:69]
	s_waitcnt vmcnt(1)
	ds_write_b128 v19, v[154:157] offset:49152
	v_mfma_f32_16x16x32_f16 v[44:47], v[94:97], v[106:109], v[44:47]
	s_waitcnt vmcnt(0)
	ds_write_b128 v20, v[158:161] offset:49152
	v_mfma_f32_16x16x32_f16 v[78:81], v[94:97], v[110:113], v[78:81]
	v_mfma_f32_16x16x32_f16 v[82:85], v[118:121], v[106:109], v[82:85]
	v_mfma_f32_16x16x32_f16 v[86:89], v[118:121], v[110:113], v[86:89]
	s_waitcnt lgkmcnt(2)
	v_mfma_f32_16x16x32_f16 v[28:31], v[122:125], v[106:109], v[28:31]
	ds_read_b128 v[106:109], v23 offset:4096
	v_mfma_f32_16x16x32_f16 v[32:35], v[122:125], v[110:113], v[32:35]
	ds_read_b128 v[110:113], v23 offset:6144
	s_waitcnt lgkmcnt(1)
	v_mfma_f32_16x16x32_f16 v[98:101], v[58:61], v[106:109], v[98:101]
	s_waitcnt lgkmcnt(0)
	v_mfma_f32_16x16x32_f16 v[52:55], v[58:61], v[110:113], v[52:55]
	global_load_dwordx4 v[58:61], v[0:1], off offset:3584
	v_mfma_f32_16x16x32_f16 v[102:105], v[94:97], v[106:109], v[102:105]
	v_mfma_f32_16x16x32_f16 v[24:27], v[94:97], v[110:113], v[24:27]
	v_mfma_f32_16x16x32_f16 v[114:117], v[118:121], v[106:109], v[114:117]
	v_mfma_f32_16x16x32_f16 v[40:43], v[118:121], v[110:113], v[40:43]
	v_mfma_f32_16x16x32_f16 v[70:73], v[122:125], v[106:109], v[70:73]
	global_load_dwordx4 v[106:109], v[2:3], off offset:3584
	global_load_dwordx4 v[126:129], v[4:5], off offset:3584
	global_load_dwordx4 v[134:137], v[14:15], off offset:3584
	global_load_dwordx4 v[94:97], v[10:11], off offset:3584
	global_load_dwordx4 v[162:165], v[12:13], off offset:3584
	global_load_dwordx4 v[166:169], v[8:9], off offset:3584
	global_load_dwordx4 v[190:193], v[6:7], off offset:3584
	s_waitcnt lgkmcnt(0)
	s_barrier
	v_mfma_f32_16x16x32_f16 v[48:51], v[122:125], v[110:113], v[48:51]
	ds_read_b128 v[62:65], v16 offset:49152
	ds_read_b128 v[90:93], v21 offset:16384
	s_waitcnt lgkmcnt(0)
	v_mfma_f32_16x16x32_f16 v[36:39], v[62:65], v[90:93], v[36:39]
	ds_read_b128 v[74:77], v16 offset:51200
	ds_read_b128 v[110:113], v21 offset:18432
	s_waitcnt lgkmcnt(0)
	v_mfma_f32_16x16x32_f16 v[66:69], v[62:65], v[110:113], v[66:69]
	ds_read_b128 v[118:121], v16 offset:53248
	v_mfma_f32_16x16x32_f16 v[44:47], v[74:77], v[90:93], v[44:47]
	ds_read_b128 v[122:125], v16 offset:55296
	v_mfma_f32_16x16x32_f16 v[78:81], v[74:77], v[110:113], v[78:81]
	s_waitcnt vmcnt(7)
	ds_write_b128 v17, v[58:61]
	s_waitcnt lgkmcnt(2)
	v_mfma_f32_16x16x32_f16 v[82:85], v[118:121], v[90:93], v[82:85]
	s_waitcnt vmcnt(6)
	ds_write_b128 v18, v[106:109]
	v_mfma_f32_16x16x32_f16 v[86:89], v[118:121], v[110:113], v[86:89]
	s_waitcnt vmcnt(5)
	ds_write_b128 v19, v[126:129]
	s_waitcnt lgkmcnt(3)
	v_mfma_f32_16x16x32_f16 v[28:31], v[122:125], v[90:93], v[28:31]
	ds_read_b128 v[90:93], v21 offset:20480
	v_mfma_f32_16x16x32_f16 v[32:35], v[122:125], v[110:113], v[32:35]
	ds_read_b128 v[110:113], v21 offset:22528
	s_waitcnt lgkmcnt(1)
	v_mfma_f32_16x16x32_f16 v[98:101], v[62:65], v[90:93], v[98:101]
	s_waitcnt vmcnt(4)
	ds_write_b128 v20, v[134:137]
	s_waitcnt lgkmcnt(1)
	v_mfma_f32_16x16x32_f16 v[52:55], v[62:65], v[110:113], v[52:55]
	ds_read_b128 v[62:65], v22 offset:49152
	v_mfma_f32_16x16x32_f16 v[102:105], v[74:77], v[90:93], v[102:105]
	s_waitcnt vmcnt(3)
	ds_write_b128 v17, v[94:97] offset:32768
	v_mfma_f32_16x16x32_f16 v[24:27], v[74:77], v[110:113], v[24:27]
	ds_read_b128 v[74:77], v22 offset:51200
	v_mfma_f32_16x16x32_f16 v[114:117], v[118:121], v[90:93], v[114:117]
	s_waitcnt vmcnt(2)
	ds_write_b128 v18, v[162:165] offset:32768
	v_mfma_f32_16x16x32_f16 v[40:43], v[118:121], v[110:113], v[40:43]
	ds_read_b128 v[118:121], v22 offset:53248
	v_mfma_f32_16x16x32_f16 v[70:73], v[122:125], v[90:93], v[70:73]
	ds_read_b128 v[90:93], v23 offset:16384
	v_mfma_f32_16x16x32_f16 v[48:51], v[122:125], v[110:113], v[48:51]
	ds_read_b128 v[110:113], v23 offset:18432
	s_waitcnt lgkmcnt(1)
	v_mfma_f32_16x16x32_f16 v[36:39], v[62:65], v[90:93], v[36:39]
	ds_read_b128 v[122:125], v22 offset:55296
	s_waitcnt lgkmcnt(1)
	v_mfma_f32_16x16x32_f16 v[66:69], v[62:65], v[110:113], v[66:69]
	s_waitcnt vmcnt(1)
	ds_write_b128 v19, v[166:169] offset:32768
	v_mfma_f32_16x16x32_f16 v[44:47], v[74:77], v[90:93], v[44:47]
	s_waitcnt vmcnt(0)
	ds_write_b128 v20, v[190:193] offset:32768
	v_mfma_f32_16x16x32_f16 v[78:81], v[74:77], v[110:113], v[78:81]
	v_mfma_f32_16x16x32_f16 v[82:85], v[118:121], v[90:93], v[82:85]
	v_mfma_f32_16x16x32_f16 v[86:89], v[118:121], v[110:113], v[86:89]
	s_waitcnt lgkmcnt(2)
	v_mfma_f32_16x16x32_f16 v[28:31], v[122:125], v[90:93], v[28:31]
	ds_read_b128 v[90:93], v23 offset:20480
	v_mfma_f32_16x16x32_f16 v[32:35], v[122:125], v[110:113], v[32:35]
	ds_read_b128 v[110:113], v23 offset:22528
	s_waitcnt lgkmcnt(1)
	v_mfma_f32_16x16x32_f16 v[98:101], v[62:65], v[90:93], v[98:101]
	s_waitcnt lgkmcnt(0)
	v_mfma_f32_16x16x32_f16 v[52:55], v[62:65], v[110:113], v[52:55]
	global_load_dwordx4 v[62:65], v[0:1], off offset:3712
	v_mfma_f32_16x16x32_f16 v[102:105], v[74:77], v[90:93], v[102:105]
	v_mfma_f32_16x16x32_f16 v[24:27], v[74:77], v[110:113], v[24:27]
	v_mfma_f32_16x16x32_f16 v[114:117], v[118:121], v[90:93], v[114:117]
	v_mfma_f32_16x16x32_f16 v[40:43], v[118:121], v[110:113], v[40:43]
	v_mfma_f32_16x16x32_f16 v[70:73], v[122:125], v[90:93], v[70:73]
	global_load_dwordx4 v[90:93], v[2:3], off offset:3712
	global_load_dwordx4 v[130:133], v[4:5], off offset:3712
	global_load_dwordx4 v[138:141], v[14:15], off offset:3712
	global_load_dwordx4 v[74:77], v[10:11], off offset:3712
	global_load_dwordx4 v[142:145], v[12:13], off offset:3712
	global_load_dwordx4 v[154:157], v[8:9], off offset:3712
	global_load_dwordx4 v[158:161], v[6:7], off offset:3712
	s_waitcnt lgkmcnt(0)
	s_barrier
; #define GL_LOAD(s_, kt_) if (VAR != 1) { a##s_##0 = GL_A(0, kt_); a##s_##1 = GL_A(1, kt_); a##s_##2 = GL_A(2, kt_); a##s_##3 = GL_A(3, kt_); b##s_##0 = GL_B(0, kt_); b##s_##1 = GL_B(1, kt_); b##s_##2 = GL_B(2, kt_); b##s_##3 = GL_B(3, kt_); }
; #define LDS_STORE(s_, buf_) if (VAR != 2) { LDS_ST1(sA, 0, buf_, a##s_##0) LDS_ST1(sA, 1, buf_, a##s_##1) LDS_ST1(sA, 2, buf_, a##s_##2) LDS_ST1(sA, 3, buf_, a##s_##3) LDS_ST1(sB, 0, buf_, b##s_##0) LDS_ST1(sB, 1, buf_, b##s_##1) LDS_ST1(sB, 2, buf_, b##s_##2) LDS_ST1(sB, 3, buf_, b##s_##3) }
;     ...
;   for (int kt = 0; kt < nk; kt += 2) {
;     if (kt + 2 < nk) { GL_LOAD(0, kt + 2) }
;     MMA_TILE(0)
;     LDS_STORE(1, 1)
;     if (VAR != 4) __syncthreads();
;     if (kt + 3 < nk) { GL_LOAD(1, kt + 3) }
;     MMA_TILE(1)
;     if (kt + 2 < nk) { LDS_STORE(0, 0) }
;     if (VAR != 4) __syncthreads();
;   }
	v_mfma_f32_16x16x32_f16 v[48:51], v[122:125], v[110:113], v[48:51]
	ds_read_b128 v[58:61], v16 offset:32768
	ds_read_b128 v[106:109], v21
	s_waitcnt lgkmcnt(0)
	v_mfma_f32_16x16x32_f16 v[36:39], v[58:61], v[106:109], v[36:39]
	ds_read_b128 v[94:97], v16 offset:34816
	ds_read_b128 v[110:113], v21 offset:2048
	s_waitcnt lgkmcnt(0)
	v_mfma_f32_16x16x32_f16 v[66:69], v[58:61], v[110:113], v[66:69]
	ds_read_b128 v[118:121], v16 offset:36864
	v_mfma_f32_16x16x32_f16 v[44:47], v[94:97], v[106:109], v[44:47]
	ds_read_b128 v[122:125], v16 offset:38912
	v_mfma_f32_16x16x32_f16 v[78:81], v[94:97], v[110:113], v[78:81]
	s_waitcnt vmcnt(7)
	ds_write_b128 v17, v[62:65] offset:16384
	s_waitcnt lgkmcnt(2)
	v_mfma_f32_16x16x32_f16 v[82:85], v[118:121], v[106:109], v[82:85]
	s_waitcnt vmcnt(6)
	ds_write_b128 v18, v[90:93] offset:16384
	v_mfma_f32_16x16x32_f16 v[86:89], v[118:121], v[110:113], v[86:89]
	s_waitcnt vmcnt(5)
	ds_write_b128 v19, v[130:133] offset:16384
	s_waitcnt lgkmcnt(3)
	v_mfma_f32_16x16x32_f16 v[28:31], v[122:125], v[106:109], v[28:31]
	ds_read_b128 v[106:109], v21 offset:4096
	v_mfma_f32_16x16x32_f16 v[32:35], v[122:125], v[110:113], v[32:35]
	ds_read_b128 v[110:113], v21 offset:6144
	s_waitcnt lgkmcnt(1)
	v_mfma_f32_16x16x32_f16 v[98:101], v[58:61], v[106:109], v[98:101]
	s_waitcnt vmcnt(4)
	ds_write_b128 v20, v[138:141] offset:16384
	s_waitcnt lgkmcnt(1)
	v_mfma_f32_16x16x32_f16 v[52:55], v[58:61], v[110:113], v[52:55]
	ds_read_b128 v[58:61], v22 offset:32768
	v_mfma_f32_16x16x32_f16 v[102:105], v[94:97], v[106:109], v[102:105]
	s_waitcnt vmcnt(3)
	ds_write_b128 v17, v[74:77] offset:49152
	v_mfma_f32_16x16x32_f16 v[24:27], v[94:97], v[110:113], v[24:27]
	ds_read_b128 v[94:97], v22 offset:34816
	v_mfma_f32_16x16x32_f16 v[114:117], v[118:121], v[106:109], v[114:117]
	s_waitcnt vmcnt(2)
	ds_write_b128 v18, v[142:145] offset:49152
	v_mfma_f32_16x16x32_f16 v[40:43], v[118:121], v[110:113], v[40:43]
	ds_read_b128 v[118:121], v22 offset:36864
	v_mfma_f32_16x16x32_f16 v[70:73], v[122:125], v[106:109], v[70:73]
	ds_read_b128 v[106:109], v23
	v_mfma_f32_16x16x32_f16 v[48:51], v[122:125], v[110:113], v[48:51]
	ds_read_b128 v[110:113], v23 offset:2048
	s_waitcnt lgkmcnt(1)
	v_mfma_f32_16x16x32_f16 v[36:39], v[58:61], v[106:109], v[36:39]
	ds_read_b128 v[122:125], v22 offset:38912
	s_waitcnt lgkmcnt(1)
	v_mfma_f32_16x16x32_f16 v[66:69], v[58:61], v[110:113], v[66:69]
	s_waitcnt vmcnt(1)
	ds_write_b128 v19, v[154:157] offset:49152
	v_mfma_f32_16x16x32_f16 v[44:47], v[94:97], v[106:109], v[44:47]
	s_waitcnt vmcnt(0)
	ds_write_b128 v20, v[158:161] offset:49152
	v_mfma_f32_16x16x32_f16 v[78:81], v[94:97], v[110:113], v[78:81]
	v_mfma_f32_16x16x32_f16 v[82:85], v[118:121], v[106:109], v[82:85]
	v_mfma_f32_16x16x32_f16 v[86:89], v[118:121], v[110:113], v[86:89]
	s_waitcnt lgkmcnt(2)
	v_mfma_f32_16x16x32_f16 v[28:31], v[122:125], v[106:109], v[28:31]
	ds_read_b128 v[106:109], v23 offset:4096
	v_mfma_f32_16x16x32_f16 v[32:35], v[122:125], v[110:113], v[32:35]
	ds_read_b128 v[110:113], v23 offset:6144
	s_waitcnt lgkmcnt(1)
	v_mfma_f32_16x16x32_f16 v[98:101], v[58:61], v[106:109], v[98:101]
	s_waitcnt lgkmcnt(0)
	v_mfma_f32_16x16x32_f16 v[52:55], v[58:61], v[110:113], v[52:55]
	global_load_dwordx4 v[58:61], v[0:1], off offset:3840
	v_mfma_f32_16x16x32_f16 v[102:105], v[94:97], v[106:109], v[102:105]
	v_mfma_f32_16x16x32_f16 v[24:27], v[94:97], v[110:113], v[24:27]
	v_mfma_f32_16x16x32_f16 v[114:117], v[118:121], v[106:109], v[114:117]
	v_mfma_f32_16x16x32_f16 v[40:43], v[118:121], v[110:113], v[40:43]
	v_mfma_f32_16x16x32_f16 v[70:73], v[122:125], v[106:109], v[70:73]
	global_load_dwordx4 v[106:109], v[2:3], off offset:3840
	global_load_dwordx4 v[126:129], v[4:5], off offset:3840
	global_load_dwordx4 v[134:137], v[14:15], off offset:3840
	global_load_dwordx4 v[94:97], v[10:11], off offset:3840
	global_load_dwordx4 v[162:165], v[12:13], off offset:3840
	global_load_dwordx4 v[166:169], v[8:9], off offset:3840
	global_load_dwordx4 v[190:193], v[6:7], off offset:3840
	s_waitcnt lgkmcnt(0)
	s_barrier
	v_mfma_f32_16x16x32_f16 v[48:51], v[122:125], v[110:113], v[48:51]
	ds_read_b128 v[62:65], v16 offset:49152
	ds_read_b128 v[90:93], v21 offset:16384
	s_waitcnt lgkmcnt(0)
	v_mfma_f32_16x16x32_f16 v[36:39], v[62:65], v[90:93], v[36:39]
	ds_read_b128 v[74:77], v16 offset:51200
	ds_read_b128 v[110:113], v21 offset:18432
	s_waitcnt lgkmcnt(0)
	v_mfma_f32_16x16x32_f16 v[66:69], v[62:65], v[110:113], v[66:69]
	ds_read_b128 v[118:121], v16 offset:53248
	v_mfma_f32_16x16x32_f16 v[44:47], v[74:77], v[90:93], v[44:47]
	ds_read_b128 v[122:125], v16 offset:55296
	v_mfma_f32_16x16x32_f16 v[78:81], v[74:77], v[110:113], v[78:81]
	s_waitcnt vmcnt(7)
	ds_write_b128 v17, v[58:61]
	s_waitcnt lgkmcnt(2)
	v_mfma_f32_16x16x32_f16 v[82:85], v[118:121], v[90:93], v[82:85]
	s_waitcnt vmcnt(6)
	ds_write_b128 v18, v[106:109]
	v_mfma_f32_16x16x32_f16 v[86:89], v[118:121], v[110:113], v[86:89]
	s_waitcnt vmcnt(5)
	ds_write_b128 v19, v[126:129]
	s_waitcnt lgkmcnt(3)
	v_mfma_f32_16x16x32_f16 v[28:31], v[122:125], v[90:93], v[28:31]
	ds_read_b128 v[90:93], v21 offset:20480
	v_mfma_f32_16x16x32_f16 v[32:35], v[122:125], v[110:113], v[32:35]
	ds_read_b128 v[110:113], v21 offset:22528
	s_waitcnt lgkmcnt(1)
	v_mfma_f32_16x16x32_f16 v[98:101], v[62:65], v[90:93], v[98:101]
	s_waitcnt vmcnt(4)
	ds_write_b128 v20, v[134:137]
	s_waitcnt lgkmcnt(1)
	v_mfma_f32_16x16x32_f16 v[52:55], v[62:65], v[110:113], v[52:55]
	ds_read_b128 v[62:65], v22 offset:49152
	v_mfma_f32_16x16x32_f16 v[102:105], v[74:77], v[90:93], v[102:105]
	s_waitcnt vmcnt(3)
; #define GL_LOAD(s_, kt_) if (VAR != 1) { a##s_##0 = GL_A(0, kt_); a##s_##1 = GL_A(1, kt_); a##s_##2 = GL_A(2, kt_); a##s_##3 = GL_A(3, kt_); b##s_##0 = GL_B(0, kt_); b##s_##1 = GL_B(1, kt_); b##s_##2 = GL_B(2, kt_); b##s_##3 = GL_B(3, kt_); }
; #define LDS_STORE(s_, buf_) if (VAR != 2) { LDS_ST1(sA, 0, buf_, a##s_##0) LDS_ST1(sA, 1, buf_, a##s_##1) LDS_ST1(sA, 2, buf_, a##s_##2) LDS_ST1(sA, 3, buf_, a##s_##3) LDS_ST1(sB, 0, buf_, b##s_##0) LDS_ST1(sB, 1, buf_, b##s_##1) LDS_ST1(sB, 2, buf_, b##s_##2) LDS_ST1(sB, 3, buf_, b##s_##3) }
;     ...
;   for (int kt = 0; kt < nk; kt += 2) {
;     if (kt + 2 < nk) { GL_LOAD(0, kt + 2) }
;     MMA_TILE(0)
;     LDS_STORE(1, 1)
;     if (VAR != 4) __syncthreads();
;     if (kt + 3 < nk) { GL_LOAD(1, kt + 3) }
;     MMA_TILE(1)
;     if (kt + 2 < nk) { LDS_STORE(0, 0) }
;     if (VAR != 4) __syncthreads();
;   }
	ds_write_b128 v17, v[94:97] offset:32768
	v_mfma_f32_16x16x32_f16 v[24:27], v[74:77], v[110:113], v[24:27]
	ds_read_b128 v[74:77], v22 offset:51200
	v_mfma_f32_16x16x32_f16 v[114:117], v[118:121], v[90:93], v[114:117]
	s_waitcnt vmcnt(2)
	ds_write_b128 v18, v[162:165] offset:32768
	v_mfma_f32_16x16x32_f16 v[40:43], v[118:121], v[110:113], v[40:43]
	ds_read_b128 v[118:121], v22 offset:53248
	v_mfma_f32_16x16x32_f16 v[70:73], v[122:125], v[90:93], v[70:73]
	ds_read_b128 v[90:93], v23 offset:16384
	v_mfma_f32_16x16x32_f16 v[48:51], v[122:125], v[110:113], v[48:51]
	ds_read_b128 v[110:113], v23 offset:18432
	s_waitcnt lgkmcnt(1)
	v_mfma_f32_16x16x32_f16 v[36:39], v[62:65], v[90:93], v[36:39]
	ds_read_b128 v[122:125], v22 offset:55296
	s_waitcnt lgkmcnt(1)
	v_mfma_f32_16x16x32_f16 v[66:69], v[62:65], v[110:113], v[66:69]
	s_waitcnt vmcnt(1)
	ds_write_b128 v19, v[166:169] offset:32768
	v_mfma_f32_16x16x32_f16 v[44:47], v[74:77], v[90:93], v[44:47]
	s_waitcnt vmcnt(0)
	ds_write_b128 v20, v[190:193] offset:32768
	v_mfma_f32_16x16x32_f16 v[78:81], v[74:77], v[110:113], v[78:81]
	v_mfma_f32_16x16x32_f16 v[82:85], v[118:121], v[90:93], v[82:85]
	v_mfma_f32_16x16x32_f16 v[86:89], v[118:121], v[110:113], v[86:89]
	s_waitcnt lgkmcnt(2)
	v_mfma_f32_16x16x32_f16 v[28:31], v[122:125], v[90:93], v[28:31]
	ds_read_b128 v[90:93], v23 offset:20480
	v_mfma_f32_16x16x32_f16 v[32:35], v[122:125], v[110:113], v[32:35]
	ds_read_b128 v[110:113], v23 offset:22528
	s_waitcnt lgkmcnt(1)
	v_mfma_f32_16x16x32_f16 v[98:101], v[62:65], v[90:93], v[98:101]
	s_waitcnt lgkmcnt(0)
	v_mfma_f32_16x16x32_f16 v[52:55], v[62:65], v[110:113], v[52:55]
	global_load_dwordx4 v[62:65], v[0:1], off offset:3968
	global_load_dwordx4 v[0:3], v[2:3], off offset:3968
	v_mfma_f32_16x16x32_f16 v[102:105], v[74:77], v[90:93], v[102:105]
	v_mfma_f32_16x16x32_f16 v[24:27], v[74:77], v[110:113], v[24:27]
	v_mfma_f32_16x16x32_f16 v[114:117], v[118:121], v[90:93], v[114:117]
	v_mfma_f32_16x16x32_f16 v[40:43], v[118:121], v[110:113], v[40:43]
	v_mfma_f32_16x16x32_f16 v[70:73], v[122:125], v[90:93], v[70:73]
	global_load_dwordx4 v[90:93], v[4:5], off offset:3968
	global_load_dwordx4 v[130:133], v[14:15], off offset:3968
	global_load_dwordx4 v[74:77], v[10:11], off offset:3968
	global_load_dwordx4 v[10:13], v[12:13], off offset:3968
	global_load_dwordx4 v[138:141], v[8:9], off offset:3968
	global_load_dwordx4 v[4:7], v[6:7], off offset:3968
	s_waitcnt lgkmcnt(0)
	s_barrier
	ds_read_b128 v[58:61], v16 offset:32768
	v_mfma_f32_16x16x32_f16 v[48:51], v[122:125], v[110:113], v[48:51]
	ds_read_b128 v[94:97], v16 offset:34816
	ds_read_b128 v[106:109], v21
	ds_read_b128 v[110:113], v21 offset:2048
	ds_read_b128 v[118:121], v16 offset:36864
	ds_read_b128 v[122:125], v16 offset:38912
	s_waitcnt lgkmcnt(3)
	v_mfma_f32_16x16x32_f16 v[36:39], v[58:61], v[106:109], v[36:39]
	v_mfma_f32_16x16x32_f16 v[44:47], v[94:97], v[106:109], v[44:47]
	s_waitcnt lgkmcnt(1)
	v_mfma_f32_16x16x32_f16 v[82:85], v[118:121], v[106:109], v[82:85]
	s_waitcnt lgkmcnt(0)
	v_mfma_f32_16x16x32_f16 v[28:31], v[122:125], v[106:109], v[28:31]
	v_mfma_f32_16x16x32_f16 v[66:69], v[58:61], v[110:113], v[66:69]
	v_mfma_f32_16x16x32_f16 v[78:81], v[94:97], v[110:113], v[78:81]
	v_mfma_f32_16x16x32_f16 v[86:89], v[118:121], v[110:113], v[86:89]
	v_mfma_f32_16x16x32_f16 v[32:35], v[122:125], v[110:113], v[32:35]
	ds_read_b128 v[106:109], v21 offset:4096
	ds_read_b128 v[110:113], v21 offset:6144
	s_waitcnt lgkmcnt(1)
	v_mfma_f32_16x16x32_f16 v[98:101], v[58:61], v[106:109], v[98:101]
	v_mfma_f32_16x16x32_f16 v[102:105], v[94:97], v[106:109], v[102:105]
	v_mfma_f32_16x16x32_f16 v[114:117], v[118:121], v[106:109], v[114:117]
	v_mfma_f32_16x16x32_f16 v[70:73], v[122:125], v[106:109], v[70:73]
	s_waitcnt lgkmcnt(0)
	v_mfma_f32_16x16x32_f16 v[52:55], v[58:61], v[110:113], v[52:55]
	ds_read_b128 v[58:61], v22 offset:32768
	v_mfma_f32_16x16x32_f16 v[24:27], v[94:97], v[110:113], v[24:27]
	v_mfma_f32_16x16x32_f16 v[40:43], v[118:121], v[110:113], v[40:43]
	v_mfma_f32_16x16x32_f16 v[48:51], v[122:125], v[110:113], v[48:51]
	ds_read_b128 v[94:97], v22 offset:34816
	ds_read_b128 v[106:109], v23
	ds_read_b128 v[110:113], v23 offset:2048
	ds_read_b128 v[118:121], v22 offset:36864
	ds_read_b128 v[122:125], v22 offset:38912
	s_waitcnt lgkmcnt(3)
	v_mfma_f32_16x16x32_f16 v[36:39], v[58:61], v[106:109], v[36:39]
	v_mfma_f32_16x16x32_f16 v[44:47], v[94:97], v[106:109], v[44:47]
	s_waitcnt lgkmcnt(1)
	v_mfma_f32_16x16x32_f16 v[82:85], v[118:121], v[106:109], v[82:85]
	s_waitcnt lgkmcnt(0)
	v_mfma_f32_16x16x32_f16 v[28:31], v[122:125], v[106:109], v[28:31]
	v_mfma_f32_16x16x32_f16 v[66:69], v[58:61], v[110:113], v[66:69]
	v_mfma_f32_16x16x32_f16 v[78:81], v[94:97], v[110:113], v[78:81]
	v_mfma_f32_16x16x32_f16 v[86:89], v[118:121], v[110:113], v[86:89]
	v_mfma_f32_16x16x32_f16 v[32:35], v[122:125], v[110:113], v[32:35]
	ds_read_b128 v[106:109], v23 offset:4096
	ds_read_b128 v[110:113], v23 offset:6144
	s_waitcnt vmcnt(7)
	ds_write_b128 v17, v[62:65] offset:16384
	s_waitcnt vmcnt(6)
	ds_write_b128 v18, v[0:3] offset:16384
	s_waitcnt vmcnt(5)
	ds_write_b128 v19, v[90:93] offset:16384
	s_waitcnt vmcnt(4)
	ds_write_b128 v20, v[130:133] offset:16384
	s_waitcnt lgkmcnt(5)
	v_mfma_f32_16x16x32_f16 v[98:101], v[58:61], v[106:109], v[98:101]
	s_waitcnt vmcnt(3)
	ds_write_b128 v17, v[74:77] offset:49152
	s_waitcnt vmcnt(2)
	ds_write_b128 v18, v[10:13] offset:49152
	s_waitcnt vmcnt(1)
	ds_write_b128 v19, v[138:141] offset:49152
	s_waitcnt vmcnt(0)
	ds_write_b128 v20, v[4:7] offset:49152
	s_waitcnt lgkmcnt(0)
	s_barrier
; DI int TIDX() { int t = threadIdx.x; asm volatile("" : "+v"(t)); return t; }
; DI unsigned pack2(float lo, float hi) { f2_t v = {lo, hi}; h2_t b = __builtin_convertvector(v, h2_t); return __builtin_bit_cast(unsigned, b); }
; #define LDS_STORE(s_, buf_) if (VAR != 2) { LDS_ST1(sA, 0, buf_, a##s_##0) LDS_ST1(sA, 1, buf_, a##s_##1) LDS_ST1(sA, 2, buf_, a##s_##2) LDS_ST1(sA, 3, buf_, a##s_##3) LDS_ST1(sB, 0, buf_, b##s_##0) LDS_ST1(sB, 1, buf_, b##s_##1) LDS_ST1(sB, 2, buf_, b##s_##2) LDS_ST1(sB, 3, buf_, b##s_##3) }
;     ...
;     MMA_TILE(1)
;     if (kt + 2 < nk) { LDS_STORE(0, 0) }
;     if (VAR != 4) __syncthreads();
; DI void epi_residual(const f32x4 (&v)[4][4], int row0, int col0, const float* xsrc, float* x, bf16_t* xb, float* ssq_out, bool write_xb, bool write_ssq) {
;   const int lane = TIDX() & 63, lr = lane & 15, g = lane >> 4;
; #pragma unroll
;   for (int mt = 0; mt < 4; ++mt) {
;     const int row = row0 + mt * 16 + lr;
;     float ss = 0.f;
; #pragma unroll
;     for (int nt = 0; nt < 4; ++nt) {
;       const int col = col0 + nt * 16 + 4 * g;
;       float4* px = (float4*)(x + (size_t)row * DM + col);
;       float4 o = *(const float4*)(xsrc + (size_t)row * DM + col);
;       o.x += v[mt][nt][0]; o.y += v[mt][nt][1]; o.z += v[mt][nt][2]; o.w += v[mt][nt][3];
;       *px = o;
;       ss += (o.x * o.x + o.y * o.y) + (o.z * o.z + o.w * o.w);
;       if (write_xb) *(uint2*)(xb + (size_t)row * DM + col) = make_uint2(pack2(o.x, o.y), pack2(o.z, o.w));
;     }
;     if (write_ssq) {
;       ss += __shfl_xor(ss, 16); ss += __shfl_xor(ss, 32);
;       if (g == 0) ssq_out[(size_t)row * 16 + (col0 >> 6)] = ss;
;     }
;   }
	v_mfma_f32_16x16x32_f16 v[52:55], v[58:61], v[110:113], v[52:55]
	ds_read_b128 v[4:7], v16 offset:49152
	v_add_u32_e32 v130, s4, v57
	v_mfma_f32_16x16x32_f16 v[0:3], v[118:121], v[110:113], v[40:43]
	v_readlane_b32 s4, v254, 45
	v_readlane_b32 s5, v254, 46
	v_mfma_f32_16x16x32_f16 v[8:11], v[122:125], v[110:113], v[48:51]
	ds_read_b128 v[12:15], v16 offset:51200
	ds_read_b128 v[40:43], v21 offset:16384
	s_nop 0
	ds_read_b128 v[48:51], v21 offset:18432
	ds_read_b128 v[58:61], v16 offset:53248
	ds_read_b128 v[16:19], v16 offset:55296
	v_mfma_f32_16x16x32_f16 v[102:105], v[94:97], v[106:109], v[102:105]
	v_mfma_f32_16x16x32_f16 v[114:117], v[118:121], v[106:109], v[114:117]
	v_mfma_f32_16x16x32_f16 v[70:73], v[122:125], v[106:109], v[70:73]
	v_mfma_f32_16x16x32_f16 v[24:27], v[94:97], v[110:113], v[24:27]
	s_waitcnt lgkmcnt(3)
	v_mfma_f32_16x16x32_f16 v[36:39], v[4:7], v[40:43], v[36:39]
	v_mfma_f32_16x16x32_f16 v[44:47], v[12:15], v[40:43], v[44:47]
	s_waitcnt lgkmcnt(1)
	v_mfma_f32_16x16x32_f16 v[62:65], v[58:61], v[40:43], v[82:85]
	s_waitcnt lgkmcnt(0)
	v_mfma_f32_16x16x32_f16 v[28:31], v[16:19], v[40:43], v[28:31]
	ds_read_b128 v[40:43], v21 offset:20480
	ds_read_b128 v[74:77], v21 offset:22528
	ds_read_b128 v[82:85], v23 offset:16384
	ds_read_b128 v[90:93], v23 offset:18432
	ds_read_b128 v[94:97], v22 offset:49152
	ds_read_b128 v[106:109], v22 offset:51200
	ds_read_b128 v[110:113], v23 offset:20480
	ds_read_b128 v[118:121], v23 offset:22528
	ds_read_b128 v[122:125], v22 offset:53248
	ds_read_b128 v[126:129], v22 offset:55296
	v_mfma_f32_16x16x32_f16 v[66:69], v[4:7], v[48:51], v[66:69]
	s_waitcnt lgkmcnt(0)
	s_barrier
	s_setprio 0
	v_mfma_f32_16x16x32_f16 v[78:81], v[12:15], v[48:51], v[78:81]
	v_mfma_f32_16x16x32_f16 v[20:23], v[58:61], v[48:51], v[86:89]
	v_mfma_f32_16x16x32_f16 v[32:35], v[16:19], v[48:51], v[32:35]
	v_mov_b32_e32 v49, v148
	v_or_b32_e32 v48, s10, v56
	v_and_or_b32 v50, v49, 15, v130
	v_bfe_u32 v134, v49, 4, 2
	v_ashrrev_i32_e32 v51, 31, v50
	v_mfma_f32_16x16x32_f16 v[86:89], v[4:7], v[40:43], v[98:101]
	v_lshl_or_b32 v135, v134, 2, v48
	v_lshrrev_b32_e32 v150, 4, v48
	v_lshl_add_u64 v[48:49], s[4:5], 0, v[150:151]
	v_mfma_f32_16x16x32_f16 v[98:101], v[12:15], v[40:43], v[102:105]
	v_lshlrev_b32_e32 v150, 2, v135
	v_readlane_b32 s4, v254, 43
	v_readlane_b32 s5, v254, 44
	v_mfma_f32_16x16x32_f16 v[102:105], v[58:61], v[40:43], v[114:117]
	v_cmp_eq_u32_e32 vcc, 0, v134
	s_nop 1
	v_lshlrev_b64 v[114:115], 12, v[50:51]
	v_lshl_add_u64 v[114:115], s[12:13], 0, v[114:115]
	v_lshl_add_u64 v[130:131], v[114:115], 0, v[150:151]
	v_mfma_f32_16x16x32_f16 v[70:73], v[16:19], v[40:43], v[70:73]
	global_load_dwordx4 v[40:43], v[130:131], off
	v_lshlrev_b64 v[114:115], 11, v[50:51]
	v_lshl_add_u64 v[132:133], s[4:5], 0, v[114:115]
	v_mfma_f32_16x16x32_f16 v[36:39], v[94:97], v[82:85], v[36:39]
	v_mfma_f32_16x16x32_f16 v[4:7], v[4:7], v[74:77], v[52:55]
	s_nop 2
	v_lshlrev_b32_e32 v52, 1, v135
	v_mov_b32_e32 v53, v151
	v_lshl_add_u64 v[54:55], v[132:133], 0, v[52:53]
	v_mfma_f32_16x16x32_f16 v[114:117], v[12:15], v[74:77], v[24:27]
	s_waitcnt vmcnt(0)
	v_pk_add_f32 v[36:37], v[36:37], v[40:41]
	v_pk_add_f32 v[38:39], v[38:39], v[42:43]
	v_cvt_pk_f16_f32 v40, v36, v37
	v_cvt_pk_f16_f32 v41, v38, v39
	global_store_dwordx4 v[130:131], v[36:39], off
	global_store_dwordx2 v[54:55], v[40:41], off
	global_load_dwordx4 v[24:27], v[130:131], off offset:64
	v_mfma_f32_16x16x32_f16 v[12:15], v[106:109], v[82:85], v[44:47]
	v_mfma_f32_16x16x32_f16 v[0:3], v[58:61], v[74:77], v[0:3]
	v_mfma_f32_16x16x32_f16 v[58:61], v[16:19], v[74:77], v[8:11]
	s_waitcnt vmcnt(0)
	s_nop 4
	v_pk_add_f32 v[12:13], v[12:13], v[24:25]
	v_pk_add_f32 v[14:15], v[14:15], v[26:27]
	v_cvt_pk_f16_f32 v24, v12, v13
	v_cvt_pk_f16_f32 v25, v14, v15
	global_store_dwordx4 v[130:131], v[12:15], off offset:64
	global_store_dwordx2 v[54:55], v[24:25], off offset:32
	global_load_dwordx4 v[8:11], v[130:131], off offset:128
	v_mfma_f32_16x16x32_f16 v[16:19], v[122:125], v[82:85], v[62:65]
	v_mul_f32_e64 v12, v12, v12
	v_mul_f32_e64 v13, v13, v13
	v_pk_mul_f32 v[14:15], v[14:15], v[14:15]
	v_add_f32_e32 v12, v12, v13
	v_mfma_f32_16x16x32_f16 v[44:47], v[94:97], v[90:93], v[66:69]
	v_add_f32_e32 v14, v14, v15
	v_add_f32_e32 v12, v12, v14
	s_waitcnt vmcnt(0)
	v_pk_add_f32 v[8:9], v[16:17], v[8:9]
	v_pk_add_f32 v[10:11], v[18:19], v[10:11]
	v_cvt_pk_f16_f32 v24, v8, v9
	v_cvt_pk_f16_f32 v25, v10, v11
	global_store_dwordx4 v[130:131], v[8:11], off offset:128
	global_store_dwordx2 v[54:55], v[24:25], off offset:64
	global_load_dwordx4 v[24:27], v[130:131], off offset:192
	v_mfma_f32_16x16x32_f16 v[16:19], v[126:129], v[82:85], v[28:31]
	v_mul_f32_e64 v66, v36, v36
	v_mul_f32_e64 v67, v37, v37
	v_pk_mul_f32 v[68:69], v[38:39], v[38:39]
	v_pk_mul_f32 v[8:9], v[8:9], v[8:9]
	v_pk_mul_f32 v[10:11], v[10:11], v[10:11]
	v_add_f32_e32 v8, v8, v9
	v_add_f32_e32 v10, v10, v11
	v_add_f32_e32 v8, v8, v10
	v_mfma_f32_16x16x32_f16 v[40:43], v[106:109], v[90:93], v[78:81]
	s_waitcnt vmcnt(0)
	v_pk_add_f32 v[62:63], v[16:17], v[24:25]
	v_add_f32_e32 v16, v68, v69
	v_add_f32_e32 v17, v66, v67
	v_pk_add_f32 v[64:65], v[18:19], v[26:27]
	v_add_f32_e32 v16, v17, v16
	v_pk_mul_f32 v[74:75], v[62:63], v[62:63]
	v_pk_mul_f32 v[76:77], v[64:65], v[64:65]
	v_add_f32_e32 v12, v16, v12
	v_add_f32_e32 v66, v12, v8
	v_mfma_f32_16x16x32_f16 v[12:15], v[94:97], v[118:121], v[4:7]
	global_store_dwordx4 v[130:131], v[62:65], off offset:192
	s_nop 1
	v_add_f32_e32 v4, v76, v77
	v_add_f32_e32 v5, v74, v75
	v_add_f32_e32 v4, v5, v4
	v_add_f32_e32 v66, v66, v4
	ds_bpermute_b32 v67, v189, v66
	v_cvt_pk_f16_f32 v62, v62, v63
	v_cvt_pk_f16_f32 v63, v64, v65
	global_store_dwordx2 v[54:55], v[62:63], off offset:96
	v_mfma_f32_16x16x32_f16 v[36:39], v[122:125], v[90:93], v[20:23]
	s_waitcnt lgkmcnt(0)
	v_add_f32_e32 v54, v66, v67
	ds_bpermute_b32 v55, v188, v54
	v_mfma_f32_16x16x32_f16 v[32:35], v[126:129], v[90:93], v[32:35]
	v_mfma_f32_16x16x32_f16 v[28:31], v[94:97], v[110:113], v[86:89]
	v_mfma_f32_16x16x32_f16 v[24:27], v[106:109], v[110:113], v[98:101]
	v_mfma_f32_16x16x32_f16 v[20:23], v[122:125], v[110:113], v[102:105]
	v_mfma_f32_16x16x32_f16 v[16:19], v[126:129], v[110:113], v[70:73]
	v_mfma_f32_16x16x32_f16 v[8:11], v[106:109], v[118:121], v[114:117]
	v_mfma_f32_16x16x32_f16 v[4:7], v[122:125], v[118:121], v[0:3]
	v_mfma_f32_16x16x32_f16 v[0:3], v[126:129], v[118:121], v[58:61]
	s_and_saveexec_b64 s[4:5], vcc
	s_cbranch_execz .LBB0_1374
	s_waitcnt lgkmcnt(0)
	v_add_f32_e32 v58, v54, v55
	v_lshlrev_b64 v[54:55], 6, v[50:51]
	v_lshl_add_u64 v[54:55], v[48:49], 0, v[54:55]
	global_store_dword v[54:55], v58, off
